# attention softmax: cross-half row-max exchange via v_permlane32_swap instead of ds_bpermute LDS round trip (GQA, NA, context units)
# baseline (speedup 1.0000x reference)
.LBB0_96:
	v_mov_b32_e32 v149, v186
	s_cmpk_gt_i32 s14, 0x1ff
	s_mov_b64 s[0:1], -1
	s_cbranch_scc0 .LBB0_521
	s_cmpk_gt_u32 s14, 0x3ff
	s_cbranch_scc0 .LBB0_224
	s_cmpk_gt_u32 s14, 0x7ff
	s_cbranch_scc0 .LBB0_183
	s_cmpk_gt_u32 s14, 0x81f
	s_cbranch_scc0 .LBB0_136
	s_cmpk_gt_u32 s14, 0x83f
	s_cbranch_scc0 .LBB0_118
	s_lshl_b32 s1, s14, 5
	v_readfirstlane_b32 s9, v149
	s_add_i32 s1, s1, 0x7ffef800
	s_lshr_b32 s0, s9, 1
	s_and_b32 s8, s1, 0x7fffff00
	s_lshl_b32 s1, s14, 7
	s_and_b32 s0, s0, 0x60
	s_and_b32 s1, s1, 0x80
	s_or_b32 s0, s1, s0
	s_waitcnt vmcnt(0)
	v_and_b32_e32 v12, 31, v149
	s_or_b32 s0, s0, s8
	s_bfe_u32 s10, s14, 0x10002
	v_or_b32_e32 v0, s0, v12
	s_lshl_b32 s0, s10, 2
	s_and_b32 s1, s14, 2
	v_or_b32_e32 v98, 0x8000, v0
	s_ashr_i32 s6, s9, 8
	s_or_b32 s0, s0, s1
	v_mov_b64_e32 v[4:5], s[90:91]
	s_add_i32 s6, s0, s6
	s_waitcnt lgkmcnt(0)
	v_mad_u64_u32 v[0:1], s[0:1], v98, s85, v[4:5]
	s_lshl_b32 s0, s6, 6
	s_ashr_i32 s7, s6, 31
	v_bfe_u32 v13, v149, 5, 1
	s_ashr_i32 s1, s0, 31
	s_lshl_b64 s[6:7], s[6:7], 2
	v_readlane_b32 s11, v255, 52
	v_ashrrev_i32_e32 v14, 3, v149
	v_lshl_add_u64 v[0:1], s[0:1], 1, v[0:1]
	v_lshlrev_b32_e32 v6, 4, v13
	v_mov_b32_e32 v7, v99
	s_add_u32 s6, s11, s6
	v_readlane_b32 s11, v255, 54
	v_add_u32_e32 v16, s8, v14
	v_lshl_add_u64 v[0:1], v[0:1], 0, v[6:7]
	s_addc_u32 s7, s11, s7
	v_add_u32_e32 v17, 0x8000, v16
	global_load_dwordx4 v[94:97], v[0:1], off
	global_load_dwordx4 v[90:93], v[0:1], off offset:32
	global_load_dwordx4 v[86:89], v[0:1], off offset:64
	global_load_dwordx4 v[82:85], v[0:1], off offset:96
	global_load_dword v7, v99, s[6:7]
	v_and_b32_e32 v15, 7, v149
	v_mad_i64_i32 v[0:1], s[6:7], v17, s85, v[4:5]
	s_lshl_b32 s68, s10, 7
	v_lshl_add_u64 v[0:1], v[0:1], 0, s[68:69]
	v_lshlrev_b32_e32 v8, 4, v15
	v_mov_b32_e32 v9, v99
	v_lshl_add_u64 v[10:11], v[0:1], 0, v[8:9]
	global_load_dwordx4 v[0:3], v[10:11], off offset:1024
	v_add_u32_e32 v18, 0x8040, v16
	v_mad_i64_i32 v[4:5], s[6:7], v18, s85, v[4:5]
	v_lshl_add_u64 v[4:5], v[4:5], 0, s[68:69]
	v_lshl_add_u64 v[116:117], v[4:5], 0, v[8:9]
	s_barrier
	global_load_dwordx4 v[100:103], v[116:117], off offset:1024
	global_load_dwordx4 v[104:107], v[10:11], off offset:1280
	s_movk_i32 s8, 0x90
	v_mul_lo_u32 v11, v14, s8
	v_add_u32_e32 v11, 0, v11
	v_add_u32_e32 v135, v11, v8
	v_lshrrev_b32_e32 v5, 2, v149
	v_and_b32_e32 v9, 16, v149
	v_lshlrev_b32_e32 v10, 2, v149
	v_lshlrev_b32_e32 v148, 2, v13
	v_and_b32_e32 v4, 63, v149
	v_and_or_b32 v9, v10, 12, v9
	v_and_or_b32 v5, v5, 3, v148
	v_cmp_gt_u32_e32 vcc, 32, v4
	v_lshlrev_b32_e32 v4, 3, v15
	v_mul_u32_u24_e32 v10, 0x90, v12
	v_lshlrev_b32_e32 v9, 1, v9
	v_add_u32_e32 v6, 0, v6
	v_mul_u32_u24_e32 v5, 0x90, v5
	s_lshl_b32 s8, s10, 6
	s_mov_b64 s[6:7], -1
	v_cndmask_b32_e64 v126, 0, 1.0, vcc
	v_add_u32_e32 v137, v6, v10
	v_add3_u32 v134, v9, v5, 0
	s_cmpk_lt_u32 s9, 0x100
	v_add_u32_e32 v127, 0x8080, v16
	v_add_u32_e32 v139, 0x80c0, v16
	v_add_u32_e32 v138, 0x80, v17
	v_lshlrev_b32_e32 v132, 1, v4
	s_waitcnt vmcnt(3)
	v_mul_f32_e32 v119, 0x3fb8aa3b, v7
	v_xor_b32_e32 v32, 0x80000000, v119
	s_waitcnt vmcnt(2)
	ds_write_b128 v135, v[0:3]
	s_waitcnt lgkmcnt(0)
	s_barrier
	s_cbranch_scc1 .LBB0_109
	ds_read_b128 v[0:3], v137 offset:4672
	ds_read_b128 v[4:7], v137 offset:4640
	ds_read_b128 v[8:11], v137
	ds_read_b128 v[12:15], v137 offset:32
	ds_read_b128 v[50:53], v137 offset:64
	ds_read_b128 v[54:57], v137 offset:4608
	v_mov_b32_e32 v33, v32
	v_mov_b32_e32 v34, v32
	v_mov_b32_e32 v35, v32
	v_mov_b32_e32 v36, v32
	v_mov_b32_e32 v37, v32
	v_mov_b32_e32 v38, v32
	v_mov_b32_e32 v39, v32
	v_mov_b32_e32 v40, v32
	v_mov_b32_e32 v41, v32
	v_mov_b32_e32 v42, v32
	v_mov_b32_e32 v43, v32
	v_mov_b32_e32 v44, v32
	v_mov_b32_e32 v45, v32
	v_mov_b32_e32 v46, v32
	v_mov_b32_e32 v47, v32
	s_waitcnt lgkmcnt(3)
	s_nop 0
	v_mfma_f32_32x32x16_bf16 v[16:31], v[8:11], v[94:97], v[32:47]
	v_mov_b64_e32 v[48:49], v[46:47]
	s_nop 5
	v_mov_b64_e32 v[46:47], v[44:45]
	v_mov_b64_e32 v[44:45], v[42:43]
	v_mov_b64_e32 v[42:43], v[40:41]
	v_mov_b64_e32 v[40:41], v[38:39]
	v_mov_b64_e32 v[38:39], v[36:37]
	v_mov_b64_e32 v[36:37], v[34:35]
	v_mov_b64_e32 v[34:35], v[32:33]
	s_waitcnt lgkmcnt(0)
	s_nop 0
	v_mfma_f32_32x32x16_bf16 v[34:49], v[54:57], v[94:97], v[34:49]
	ds_read_b128 v[8:11], v137 offset:96
	ds_read_b128 v[54:57], v137 offset:4704
	v_mfma_f32_32x32x16_bf16 v[16:31], v[12:15], v[90:93], v[16:31]
	v_mfma_f32_32x32x16_bf16 v[34:49], v[4:7], v[90:93], v[34:49]
	v_mfma_f32_32x32x16_bf16 v[16:31], v[50:53], v[86:89], v[16:31]
	v_mfma_f32_32x32x16_bf16 v[34:49], v[0:3], v[86:89], v[34:49]
	s_waitcnt lgkmcnt(1)
	v_mfma_f32_32x32x16_bf16 v[16:31], v[8:11], v[82:85], v[16:31]
	s_waitcnt lgkmcnt(0)
	v_mfma_f32_32x32x16_bf16 v[34:49], v[54:57], v[82:85], v[34:49]
	v_mov_b64_e32 v[124:125], s[90:91]
	v_mad_i64_i32 v[0:1], s[6:7], v127, s85, v[124:125]
	s_lshl_b32 s68, s8, 1
	v_lshl_add_u64 v[0:1], v[0:1], 0, s[68:69]
	v_mov_b32_e32 v133, v99
	s_waitcnt vmcnt(1)
	ds_write_b128 v135, v[100:103] offset:13312
	s_waitcnt vmcnt(0)
	ds_write_b128 v135, v[104:107] offset:26624
	v_lshl_add_u64 v[0:1], v[0:1], 0, v[132:133]
	global_load_dwordx4 v[108:111], v[0:1], off offset:1024
	global_load_dwordx4 v[112:115], v[116:117], off offset:1280
	v_max3_f32 v2, v16, v17, v34
	v_max3_f32 v3, v18, v19, v35
	v_cmp_lt_i32_e32 vcc, v232, v226
	v_max3_f32 v2, v2, v36, v37
	v_max3_f32 v3, v3, v22, v23
	s_waitcnt lgkmcnt(0)
	s_barrier
	s_nop 0
	v_max3_f32 v2, v2, v20, v21
	v_max3_f32 v3, v3, v40, v41
	s_nop 0
	v_max3_f32 v2, v2, v38, v39
	v_max3_f32 v3, v3, v26, v27
	s_nop 0
	v_max3_f32 v2, v2, v24, v25
	v_max3_f32 v3, v3, v44, v45
	s_nop 0
	v_max3_f32 v2, v2, v42, v43
	v_max3_f32 v3, v3, v30, v31
	s_nop 0
	v_max3_f32 v2, v2, v28, v29
	v_max3_f32 v3, v3, v48, v49
	s_nop 0
	v_max3_f32 v2, v2, v46, v47
	s_nop 0
	v_max3_f32 v2, v2, v3, v3
	v_cndmask_b32_e32 v3, v225, v232, vcc
	v_lshlrev_b32_e32 v136, 2, v3
	v_mov_b32_e32 v3, v2
	s_nop 1
	v_permlane32_swap_b32 v3, v2
	v_max_f32_e32 v2, v2, v3
	s_waitcnt lgkmcnt(0)
	s_nop 0
	v_max_f32_e32 v2, v2, v2
	v_max_f32_e32 v33, 0, v2
	v_sub_f32_e32 v34, v34, v33
	v_sub_f32_e32 v16, v16, v33
	v_sub_f32_e32 v15, v49, v33
	v_sub_f32_e32 v49, v31, v33
	v_sub_f32_e32 v31, v47, v33
	v_sub_f32_e32 v47, v29, v33
	v_sub_f32_e32 v29, v45, v33
	v_sub_f32_e32 v45, v27, v33
	v_sub_f32_e32 v27, v43, v33
	v_sub_f32_e32 v43, v25, v33
	v_sub_f32_e32 v25, v41, v33
	v_sub_f32_e32 v41, v23, v33
	v_sub_f32_e32 v23, v39, v33
	v_sub_f32_e32 v39, v21, v33
	v_sub_f32_e32 v21, v37, v33
	v_sub_f32_e32 v37, v19, v33
	v_sub_f32_e32 v19, v35, v33
	v_sub_f32_e32 v17, v17, v33
	v_exp_f32_e32 v52, v16
	v_exp_f32_e32 v53, v34
	v_exp_f32_e32 v16, v17
	v_exp_f32_e32 v34, v19
	v_mov_b32_e32 v17, v99
	v_add_f32_e32 v35, v53, v52
	v_sub_f32_e32 v36, v36, v33
	v_sub_f32_e32 v51, v18, v33
	v_pk_add_f32 v[18:19], v[34:35], v[16:17]
	v_exp_f32_e32 v17, v51
	v_pk_add_f32 v[18:19], v[18:19], v[18:19] op_sel_hi:[0,1]
	v_exp_f32_e32 v35, v36
	v_exp_f32_e32 v18, v37
	v_exp_f32_e32 v36, v21
	v_sub_f32_e32 v38, v38, v33
	v_add_f32_e32 v37, v35, v17
	v_sub_f32_e32 v51, v20, v33
	v_pk_add_f32 v[20:21], v[36:37], v[18:19]
	v_exp_f32_e32 v19, v51
	v_pk_add_f32 v[20:21], v[20:21], v[20:21] op_sel_hi:[0,1]
	v_exp_f32_e32 v37, v38
	v_exp_f32_e32 v20, v39
	v_exp_f32_e32 v38, v23
	v_sub_f32_e32 v40, v40, v33
	v_add_f32_e32 v39, v37, v19
	v_sub_f32_e32 v51, v22, v33
	v_pk_add_f32 v[22:23], v[38:39], v[20:21]
	v_exp_f32_e32 v21, v51
	v_pk_add_f32 v[22:23], v[22:23], v[22:23] op_sel_hi:[0,1]
	v_exp_f32_e32 v39, v40
	v_exp_f32_e32 v22, v41
	v_exp_f32_e32 v40, v25
	v_sub_f32_e32 v42, v42, v33
	v_add_f32_e32 v41, v39, v21
	v_sub_f32_e32 v51, v24, v33
	v_pk_add_f32 v[24:25], v[40:41], v[22:23]
	v_exp_f32_e32 v23, v51
	v_pk_add_f32 v[24:25], v[24:25], v[24:25] op_sel_hi:[0,1]
	v_exp_f32_e32 v41, v42
	v_exp_f32_e32 v24, v43
	v_exp_f32_e32 v42, v27
	v_sub_f32_e32 v44, v44, v33
	v_add_f32_e32 v43, v41, v23
	v_sub_f32_e32 v51, v26, v33
	v_pk_add_f32 v[26:27], v[42:43], v[24:25]
	v_exp_f32_e32 v25, v51
	v_pk_add_f32 v[26:27], v[26:27], v[26:27] op_sel_hi:[0,1]
	v_exp_f32_e32 v43, v44
	v_exp_f32_e32 v26, v45
	v_exp_f32_e32 v44, v29
	v_sub_f32_e32 v46, v46, v33
	v_add_f32_e32 v45, v43, v25
	v_sub_f32_e32 v51, v28, v33
	v_pk_add_f32 v[28:29], v[44:45], v[26:27]
	v_exp_f32_e32 v27, v51
	v_pk_add_f32 v[28:29], v[28:29], v[28:29] op_sel_hi:[0,1]
	v_exp_f32_e32 v45, v46
	v_exp_f32_e32 v28, v47
	v_exp_f32_e32 v46, v31
	v_sub_f32_e32 v48, v48, v33
	v_add_f32_e32 v47, v45, v27
	v_sub_f32_e32 v51, v30, v33
	v_pk_add_f32 v[30:31], v[46:47], v[28:29]
	v_exp_f32_e32 v29, v51
	v_pk_add_f32 v[30:31], v[30:31], v[30:31] op_sel_hi:[0,1]
	v_exp_f32_e32 v47, v48
	v_exp_f32_e64 v50, -v33
	v_exp_f32_e32 v30, v49
	v_exp_f32_e32 v48, v15
	v_add_f32_e32 v49, v47, v29
	v_mul_f32_e32 v0, 0, v50
	v_mul_f32_e32 v118, v126, v50
	v_pk_add_f32 v[50:51], v[48:49], v[30:31]
	v_cvt_pk_bf16_f32 v128, v52, v16
	v_cvt_pk_bf16_f32 v129, v17, v18
	v_cvt_pk_bf16_f32 v130, v19, v20
	v_cvt_pk_bf16_f32 v131, v21, v22
	v_cvt_pk_bf16_f32 v140, v23, v24
	v_cvt_pk_bf16_f32 v141, v25, v26
	v_cvt_pk_bf16_f32 v142, v27, v28
	v_cvt_pk_bf16_f32 v143, v29, v30
	ds_read_b128 v[16:19], v137 offset:13312
	ds_read_b128 v[20:23], v137 offset:13344
	ds_read_b128 v[24:27], v137 offset:17920
	ds_read_b128 v[28:31], v137 offset:13376
	ds_read_b128 v[154:157], v137 offset:17952
	ds_read_b128 v[158:161], v137 offset:17984
	v_pk_add_f32 v[50:51], v[50:51], v[50:51] op_sel:[0,1] op_sel_hi:[1,0]
	v_mov_b32_e32 v1, v0
	v_mov_b32_e32 v51, v33
	v_pk_add_f32 v[120:121], v[118:119], v[50:51]
	v_mov_b32_e32 v2, v0
	v_mov_b32_e32 v3, v0
	v_mov_b32_e32 v4, v0
	v_mov_b32_e32 v5, v0
	v_mov_b32_e32 v6, v0
	v_mov_b32_e32 v7, v0
	v_mov_b32_e32 v8, v0
	v_mov_b32_e32 v9, v0
	v_mov_b32_e32 v10, v0
	v_mov_b32_e32 v11, v0
	v_mov_b32_e32 v12, v0
	v_mov_b32_e32 v13, v0
	v_mov_b32_e32 v14, v0
	v_mov_b32_e32 v15, v0
	v_cvt_pk_bf16_f32 v144, v53, v34
	v_xor_b32_e32 v34, 0x80000000, v121
	v_cvt_pk_bf16_f32 v145, v35, v36
	v_cvt_pk_bf16_f32 v146, v37, v38
	v_cvt_pk_bf16_f32 v147, v39, v40
	v_cvt_pk_bf16_f32 v150, v41, v42
	v_cvt_pk_bf16_f32 v151, v43, v44
	v_cvt_pk_bf16_f32 v152, v45, v46
	v_cvt_pk_bf16_f32 v153, v47, v48
	v_mov_b32_e32 v35, v34
	v_mov_b32_e32 v36, v34
	v_mov_b32_e32 v37, v34
	v_mov_b32_e32 v38, v34
	v_mov_b32_e32 v39, v34
	v_mov_b32_e32 v40, v34
	v_mov_b32_e32 v41, v34
	v_mov_b32_e32 v42, v34
	v_mov_b32_e32 v43, v34
	v_mov_b32_e32 v44, v34
	v_mov_b32_e32 v45, v34
	v_mov_b32_e32 v46, v34
	v_mov_b32_e32 v47, v34
	v_mov_b32_e32 v48, v34
	v_mov_b32_e32 v49, v34
	v_mov_b64_e32 v[80:81], v[48:49]
	v_mov_b64_e32 v[78:79], v[46:47]
	v_mov_b64_e32 v[76:77], v[44:45]
	v_mov_b64_e32 v[74:75], v[42:43]
	v_mov_b64_e32 v[72:73], v[40:41]
	v_mov_b64_e32 v[70:71], v[38:39]
	v_mov_b64_e32 v[68:69], v[36:37]
	v_mov_b64_e32 v[66:67], v[34:35]
	s_waitcnt lgkmcnt(5)
	v_mfma_f32_32x32x16_bf16 v[50:65], v[16:19], v[94:97], v[34:49]
	s_waitcnt lgkmcnt(3)
	v_mfma_f32_32x32x16_bf16 v[66:81], v[24:27], v[94:97], v[66:81]
	ds_read_b128 v[16:19], v137 offset:13408
	ds_read_b128 v[24:27], v137 offset:18016
	v_mfma_f32_32x32x16_bf16 v[50:65], v[20:23], v[90:93], v[50:65]
	s_waitcnt lgkmcnt(3)
	v_mfma_f32_32x32x16_bf16 v[66:81], v[154:157], v[90:93], v[66:81]
	ds_read_b64_tr_b16 v[36:37], v134 offset:26624
	ds_read_b64_tr_b16 v[38:39], v134 offset:27776
	ds_read_b64_tr_b16 v[42:43], v134 offset:27840
	ds_read_b64_tr_b16 v[40:41], v134 offset:26688
	v_mfma_f32_32x32x16_bf16 v[50:65], v[28:31], v[86:89], v[50:65]
	s_waitcnt lgkmcnt(6)
	v_mfma_f32_32x32x16_bf16 v[66:81], v[158:161], v[86:89], v[66:81]
	ds_read_b64_tr_b16 v[44:45], v134 offset:28928
	ds_read_b64_tr_b16 v[46:47], v134 offset:30080
	ds_read_b64_tr_b16 v[156:157], v134 offset:30144
	ds_read_b64_tr_b16 v[154:155], v134 offset:28992
	s_waitcnt lgkmcnt(9)
	v_mfma_f32_32x32x16_bf16 v[50:65], v[16:19], v[82:85], v[50:65]
	s_waitcnt lgkmcnt(8)
	v_mfma_f32_32x32x16_bf16 v[66:81], v[24:27], v[82:85], v[66:81]
	ds_read_b64_tr_b16 v[158:159], v134 offset:31232
	ds_read_b64_tr_b16 v[160:161], v134 offset:32384
	ds_read_b64_tr_b16 v[164:165], v134 offset:32448
	ds_read_b64_tr_b16 v[162:163], v134 offset:31296
	s_waitcnt lgkmcnt(10)
	v_mfma_f32_32x32x16_bf16 v[16:31], v[36:39], v[128:131], v[0:15]
	s_waitcnt lgkmcnt(8)
	v_mfma_f32_32x32x16_bf16 v[0:15], v[40:43], v[128:131], v[0:15]
	ds_read_b64_tr_b16 v[36:37], v134 offset:33536
	ds_read_b64_tr_b16 v[38:39], v134 offset:34688
	ds_read_b64_tr_b16 v[42:43], v134 offset:34752
	ds_read_b64_tr_b16 v[40:41], v134 offset:33600
	s_waitcnt lgkmcnt(10)
	v_mfma_f32_32x32x16_bf16 v[16:31], v[44:47], v[140:143], v[16:31]
	s_waitcnt lgkmcnt(8)
	v_mfma_f32_32x32x16_bf16 v[0:15], v[154:157], v[140:143], v[0:15]
	s_waitcnt lgkmcnt(6)
	v_mfma_f32_32x32x16_bf16 v[16:31], v[158:161], v[144:147], v[16:31]
	s_waitcnt lgkmcnt(4)
	v_mfma_f32_32x32x16_bf16 v[0:15], v[162:165], v[144:147], v[0:15]
	s_waitcnt lgkmcnt(2)
	v_mfma_f32_32x32x16_bf16 v[16:31], v[36:39], v[150:153], v[16:31]
	s_waitcnt lgkmcnt(0)
	v_mfma_f32_32x32x16_bf16 v[0:15], v[40:43], v[150:153], v[0:15]
	v_mad_i64_i32 v[36:37], s[6:7], v139, s85, v[124:125]
	v_lshl_add_u64 v[36:37], v[36:37], 0, s[68:69]
	v_lshl_add_u64 v[122:123], v[36:37], 0, v[132:133]
	v_mad_i64_i32 v[36:37], s[6:7], v138, s85, v[124:125]
	v_lshl_add_u64 v[36:37], v[36:37], 0, s[68:69]
	s_waitcnt vmcnt(1)
	ds_write_b128 v135, v[108:111]
	s_waitcnt vmcnt(0)
	ds_write_b128 v135, v[112:115] offset:35840
	v_lshl_add_u64 v[36:37], v[36:37], 0, v[132:133]
	global_load_dwordx4 v[108:111], v[122:123], off offset:1024
	global_load_dwordx4 v[112:115], v[36:37], off offset:1280
	v_max3_f32 v33, v50, v51, v66
	v_max3_f32 v35, v52, v53, v67
	s_waitcnt lgkmcnt(0)
	s_barrier
	s_nop 0
	v_max3_f32 v33, v33, v68, v69
	v_max3_f32 v35, v35, v56, v57
	s_nop 0
	v_max3_f32 v33, v33, v54, v55
	v_max3_f32 v35, v35, v72, v73
	s_nop 0
	v_max3_f32 v33, v33, v70, v71
	v_max3_f32 v35, v35, v60, v61
	s_nop 0
	v_max3_f32 v33, v33, v58, v59
	v_max3_f32 v35, v35, v76, v77
	s_nop 0
	v_max3_f32 v33, v33, v74, v75
	v_max3_f32 v35, v35, v64, v65
	s_nop 0
	v_max3_f32 v33, v33, v62, v63
	v_max3_f32 v35, v35, v80, v81
	s_nop 0
	v_max3_f32 v33, v33, v78, v79
	s_nop 0
	v_max3_f32 v33, v33, v35, v35
	v_mov_b32_e32 v35, v33
	s_nop 1
	v_permlane32_swap_b32 v35, v33
	v_max_f32_e32 v33, v33, v35
	s_waitcnt lgkmcnt(0)
	s_nop 0
	v_cmp_lt_f32_e32 vcc, s78, v33
	s_cbranch_vccz .LBB0_104
	v_max_f32_e32 v33, v33, v33
	v_max_f32_e32 v34, 0, v33
	v_exp_f32_e64 v36, -v34
	v_add_f32_e32 v121, v121, v34
	v_pk_add_f32 v[50:51], v[50:51], v[34:35] op_sel_hi:[1,0] neg_lo:[0,1] neg_hi:[0,1]
	v_pk_add_f32 v[66:67], v[66:67], v[34:35] op_sel_hi:[1,0] neg_lo:[0,1] neg_hi:[0,1]
	v_pk_add_f32 v[52:53], v[52:53], v[34:35] op_sel_hi:[1,0] neg_lo:[0,1] neg_hi:[0,1]
	v_pk_add_f32 v[68:69], v[68:69], v[34:35] op_sel_hi:[1,0] neg_lo:[0,1] neg_hi:[0,1]
	v_pk_add_f32 v[54:55], v[54:55], v[34:35] op_sel_hi:[1,0] neg_lo:[0,1] neg_hi:[0,1]
	v_pk_add_f32 v[70:71], v[70:71], v[34:35] op_sel_hi:[1,0] neg_lo:[0,1] neg_hi:[0,1]
	v_pk_add_f32 v[56:57], v[56:57], v[34:35] op_sel_hi:[1,0] neg_lo:[0,1] neg_hi:[0,1]
	v_pk_add_f32 v[72:73], v[72:73], v[34:35] op_sel_hi:[1,0] neg_lo:[0,1] neg_hi:[0,1]
	v_pk_add_f32 v[58:59], v[58:59], v[34:35] op_sel_hi:[1,0] neg_lo:[0,1] neg_hi:[0,1]
	v_pk_add_f32 v[74:75], v[74:75], v[34:35] op_sel_hi:[1,0] neg_lo:[0,1] neg_hi:[0,1]
	v_pk_add_f32 v[60:61], v[60:61], v[34:35] op_sel_hi:[1,0] neg_lo:[0,1] neg_hi:[0,1]
	v_pk_add_f32 v[76:77], v[76:77], v[34:35] op_sel_hi:[1,0] neg_lo:[0,1] neg_hi:[0,1]
	v_pk_add_f32 v[62:63], v[62:63], v[34:35] op_sel_hi:[1,0] neg_lo:[0,1] neg_hi:[0,1]
	v_pk_add_f32 v[78:79], v[78:79], v[34:35] op_sel_hi:[1,0] neg_lo:[0,1] neg_hi:[0,1]
	v_pk_add_f32 v[64:65], v[64:65], v[34:35] op_sel_hi:[1,0] neg_lo:[0,1] neg_hi:[0,1]
	v_pk_add_f32 v[80:81], v[80:81], v[34:35] op_sel_hi:[1,0] neg_lo:[0,1] neg_hi:[0,1]
	v_pk_mul_f32 v[30:31], v[30:31], v[36:37] op_sel_hi:[1,0]
	v_pk_mul_f32 v[28:29], v[28:29], v[36:37] op_sel_hi:[1,0]
	v_pk_mul_f32 v[26:27], v[26:27], v[36:37] op_sel_hi:[1,0]
	v_pk_mul_f32 v[24:25], v[24:25], v[36:37] op_sel_hi:[1,0]
	v_pk_mul_f32 v[22:23], v[22:23], v[36:37] op_sel_hi:[1,0]
	v_pk_mul_f32 v[20:21], v[20:21], v[36:37] op_sel_hi:[1,0]
	v_pk_mul_f32 v[18:19], v[18:19], v[36:37] op_sel_hi:[1,0]
	v_pk_mul_f32 v[16:17], v[16:17], v[36:37] op_sel_hi:[1,0]
	v_pk_mul_f32 v[14:15], v[14:15], v[36:37] op_sel_hi:[1,0]
	v_pk_mul_f32 v[12:13], v[12:13], v[36:37] op_sel_hi:[1,0]
	v_pk_mul_f32 v[10:11], v[10:11], v[36:37] op_sel_hi:[1,0]
	v_pk_mul_f32 v[8:9], v[8:9], v[36:37] op_sel_hi:[1,0]
	v_pk_mul_f32 v[6:7], v[6:7], v[36:37] op_sel_hi:[1,0]
	v_pk_mul_f32 v[4:5], v[4:5], v[36:37] op_sel_hi:[1,0]
	v_pk_mul_f32 v[2:3], v[2:3], v[36:37] op_sel_hi:[1,0]
	v_pk_mul_f32 v[0:1], v[0:1], v[36:37] op_sel_hi:[1,0]
	v_xor_b32_e32 v34, 0x80000000, v121
	v_mul_f32_e32 v120, v120, v36
.LBB0_104:
	v_exp_f32_e32 v118, v50
	v_exp_f32_e32 v133, v66
	v_exp_f32_e32 v50, v51
	v_exp_f32_e32 v124, v67
	v_mov_b32_e32 v51, v99
	v_add_f32_e32 v125, v133, v118
	v_exp_f32_e32 v146, v69
	v_pk_add_f32 v[66:67], v[124:125], v[50:51]
	v_exp_f32_e32 v51, v52
	v_pk_add_f32 v[66:67], v[66:67], v[66:67] op_sel_hi:[0,1]
	v_exp_f32_e32 v125, v68
	v_exp_f32_e32 v66, v53
	v_exp_f32_e32 v68, v71
	v_cvt_pk_bf16_f32 v128, v118, v50
	v_add_f32_e32 v147, v125, v51
	v_pk_add_f32 v[52:53], v[146:147], v[66:67]
	v_exp_f32_e32 v67, v54
	v_pk_add_f32 v[52:53], v[52:53], v[52:53] op_sel_hi:[0,1]
	v_exp_f32_e32 v147, v70
	v_exp_f32_e32 v52, v55
	v_exp_f32_e32 v70, v73
	v_cvt_pk_bf16_f32 v129, v51, v66
	v_add_f32_e32 v69, v147, v67
	v_pk_add_f32 v[54:55], v[68:69], v[52:53]
	v_exp_f32_e32 v53, v56
	v_pk_add_f32 v[54:55], v[54:55], v[54:55] op_sel_hi:[0,1]
	v_exp_f32_e32 v69, v72
	v_exp_f32_e32 v54, v57
	v_exp_f32_e32 v72, v75
	v_cvt_pk_bf16_f32 v130, v67, v52
	v_add_f32_e32 v71, v69, v53
	v_pk_add_f32 v[56:57], v[70:71], v[54:55]
	v_exp_f32_e32 v55, v58
	v_pk_add_f32 v[56:57], v[56:57], v[56:57] op_sel_hi:[0,1]
	v_exp_f32_e32 v71, v74
	v_exp_f32_e32 v56, v59
	v_exp_f32_e32 v74, v77
	v_cvt_pk_bf16_f32 v131, v53, v54
	v_add_f32_e32 v73, v71, v55
	v_pk_add_f32 v[58:59], v[72:73], v[56:57]
	v_exp_f32_e32 v57, v60
	v_pk_add_f32 v[58:59], v[58:59], v[58:59] op_sel_hi:[0,1]
	v_exp_f32_e32 v73, v76
	v_exp_f32_e32 v58, v61
	v_exp_f32_e32 v76, v79
	ds_read_b128 v[154:157], v137 offset:4608
	ds_read_b128 v[50:53], v137
	ds_read_b128 v[158:161], v137 offset:32
	ds_read_b128 v[162:165], v137 offset:4640
	ds_read_b128 v[166:169], v137 offset:64
	ds_read_b128 v[170:173], v137 offset:4672
	v_add_f32_e32 v75, v73, v57
	v_pk_add_f32 v[60:61], v[74:75], v[58:59]
	v_exp_f32_e32 v59, v62
	v_pk_add_f32 v[60:61], v[60:61], v[60:61] op_sel_hi:[0,1]
	v_exp_f32_e32 v75, v78
	v_exp_f32_e32 v60, v63
	v_exp_f32_e32 v78, v81
	v_mov_b32_e32 v35, v34
	v_add_f32_e32 v77, v75, v59
	v_pk_add_f32 v[62:63], v[76:77], v[60:61]
	v_exp_f32_e32 v61, v64
	v_pk_add_f32 v[62:63], v[62:63], v[62:63] op_sel_hi:[0,1]
	v_exp_f32_e32 v77, v80
	v_exp_f32_e32 v62, v65
	v_mov_b32_e32 v36, v34
	v_mov_b32_e32 v37, v34
	v_add_f32_e32 v79, v77, v61
	v_pk_add_f32 v[64:65], v[78:79], v[62:63]
	v_mov_b32_e32 v38, v34
	v_add_f32_e32 v33, v64, v65
	v_mov_b32_e32 v39, v34
	v_mov_b32_e32 v40, v34
	v_mov_b32_e32 v41, v34
	v_mov_b32_e32 v42, v34
	v_mov_b32_e32 v43, v34
	v_mov_b32_e32 v44, v34
	v_mov_b32_e32 v45, v34
	v_mov_b32_e32 v46, v34
	v_mov_b32_e32 v47, v34
	v_mov_b32_e32 v48, v34
	v_mov_b32_e32 v49, v34
	v_add_f32_e32 v33, v120, v33
	v_cvt_pk_bf16_f32 v140, v55, v56
	v_cvt_pk_bf16_f32 v141, v57, v58
	v_cvt_pk_bf16_f32 v142, v59, v60
	v_cvt_pk_bf16_f32 v143, v61, v62
	v_cvt_pk_bf16_f32 v144, v133, v124
	v_cvt_pk_bf16_f32 v145, v125, v146
	v_cvt_pk_bf16_f32 v146, v147, v68
	v_cvt_pk_bf16_f32 v147, v69, v70
	v_cvt_pk_bf16_f32 v150, v71, v72
	v_cvt_pk_bf16_f32 v151, v73, v74
	v_cvt_pk_bf16_f32 v152, v75, v76
	v_cvt_pk_bf16_f32 v153, v77, v78
	s_waitcnt lgkmcnt(4)
	v_mfma_f32_32x32x16_bf16 v[66:81], v[50:53], v[94:97], v[34:49]
	v_mfma_f32_32x32x16_bf16 v[50:65], v[154:157], v[94:97], v[34:49]
	ds_read_b128 v[154:157], v137 offset:96
	ds_read_b128 v[174:177], v137 offset:4704
	s_waitcnt lgkmcnt(5)
	v_mfma_f32_32x32x16_bf16 v[66:81], v[158:161], v[90:93], v[66:81]
	s_waitcnt lgkmcnt(4)
	v_mfma_f32_32x32x16_bf16 v[50:65], v[162:165], v[90:93], v[50:65]
	ds_read_b64_tr_b16 v[158:159], v134 offset:35840
	ds_read_b64_tr_b16 v[160:161], v134 offset:36992
	ds_read_b64_tr_b16 v[164:165], v134 offset:37056
	ds_read_b64_tr_b16 v[162:163], v134 offset:35904
	s_waitcnt lgkmcnt(7)
	v_mfma_f32_32x32x16_bf16 v[66:81], v[166:169], v[86:89], v[66:81]
	s_waitcnt lgkmcnt(6)
	v_mfma_f32_32x32x16_bf16 v[50:65], v[170:173], v[86:89], v[50:65]
	ds_read_b64_tr_b16 v[166:167], v134 offset:38144
	ds_read_b64_tr_b16 v[168:169], v134 offset:39296
	ds_read_b64_tr_b16 v[172:173], v134 offset:39360
	ds_read_b64_tr_b16 v[170:171], v134 offset:38208
	s_waitcnt lgkmcnt(9)
	v_mfma_f32_32x32x16_bf16 v[66:81], v[154:157], v[82:85], v[66:81]
	s_waitcnt lgkmcnt(8)
	v_mfma_f32_32x32x16_bf16 v[50:65], v[174:177], v[82:85], v[50:65]
	ds_read_b64_tr_b16 v[154:155], v134 offset:40448
	ds_read_b64_tr_b16 v[156:157], v134 offset:41600
	ds_read_b64_tr_b16 v[176:177], v134 offset:41664
	ds_read_b64_tr_b16 v[174:175], v134 offset:40512
	s_waitcnt lgkmcnt(10)
	v_mfma_f32_32x32x16_bf16 v[16:31], v[158:161], v[128:131], v[16:31]
	s_waitcnt lgkmcnt(8)
	v_mfma_f32_32x32x16_bf16 v[0:15], v[162:165], v[128:131], v[0:15]
	ds_read_b64_tr_b16 v[128:129], v134 offset:42752
	ds_read_b64_tr_b16 v[130:131], v134 offset:43904
	ds_read_b64_tr_b16 v[160:161], v134 offset:43968
	ds_read_b64_tr_b16 v[158:159], v134 offset:42816
	s_waitcnt lgkmcnt(10)
	v_mfma_f32_32x32x16_bf16 v[16:31], v[166:169], v[140:143], v[16:31]
	s_waitcnt lgkmcnt(8)
	v_mfma_f32_32x32x16_bf16 v[0:15], v[170:173], v[140:143], v[0:15]
	s_waitcnt lgkmcnt(6)
	v_mfma_f32_32x32x16_bf16 v[16:31], v[154:157], v[144:147], v[16:31]
	s_waitcnt lgkmcnt(4)
	v_mfma_f32_32x32x16_bf16 v[0:15], v[174:177], v[144:147], v[0:15]
	s_waitcnt lgkmcnt(2)
	v_mfma_f32_32x32x16_bf16 v[16:31], v[128:131], v[150:153], v[16:31]
	s_waitcnt lgkmcnt(0)
	v_mfma_f32_32x32x16_bf16 v[0:15], v[158:161], v[150:153], v[0:15]
	s_waitcnt vmcnt(1)
	ds_write_b128 v135, v[108:111] offset:13312
	s_waitcnt vmcnt(0)
	ds_write_b128 v135, v[112:115] offset:26624
	global_load_dwordx4 v[108:111], v[122:123], off offset:1280
	v_max3_f32 v112, v66, v67, v50
	v_max3_f32 v113, v68, v69, v51
	s_waitcnt lgkmcnt(0)
	s_barrier
	s_nop 0
	v_max3_f32 v112, v112, v52, v53
	v_max3_f32 v113, v113, v72, v73
	s_nop 0
	v_max3_f32 v112, v112, v70, v71
	v_max3_f32 v113, v113, v56, v57
	s_nop 0
	v_max3_f32 v112, v112, v54, v55
	v_max3_f32 v113, v113, v76, v77
	s_nop 0
	v_max3_f32 v112, v112, v74, v75
	v_max3_f32 v113, v113, v60, v61
	s_nop 0
	v_max3_f32 v112, v112, v58, v59
	v_max3_f32 v113, v113, v80, v81
	s_nop 0
	v_max3_f32 v112, v112, v78, v79
	v_max3_f32 v113, v113, v64, v65
	s_nop 0
	v_max3_f32 v112, v112, v62, v63
	s_nop 0
	v_max3_f32 v112, v112, v113, v113
	v_mov_b32_e32 v113, v112
	s_nop 1
	v_permlane32_swap_b32 v113, v112
	v_max_f32_e32 v112, v112, v113
	s_waitcnt lgkmcnt(0)
	s_nop 0
	v_cmp_lt_f32_e32 vcc, s78, v112
	s_cbranch_vccz .LBB0_106
	v_max_f32_e32 v34, v112, v112
	v_max_f32_e32 v34, 0, v34
	v_exp_f32_e64 v36, -v34
	v_add_f32_e32 v35, v121, v34
	v_pk_add_f32 v[66:67], v[66:67], v[34:35] op_sel_hi:[1,0] neg_lo:[0,1] neg_hi:[0,1]
	v_pk_add_f32 v[50:51], v[50:51], v[34:35] op_sel_hi:[1,0] neg_lo:[0,1] neg_hi:[0,1]
	v_pk_add_f32 v[68:69], v[68:69], v[34:35] op_sel_hi:[1,0] neg_lo:[0,1] neg_hi:[0,1]
	v_pk_add_f32 v[52:53], v[52:53], v[34:35] op_sel_hi:[1,0] neg_lo:[0,1] neg_hi:[0,1]
	v_pk_add_f32 v[70:71], v[70:71], v[34:35] op_sel_hi:[1,0] neg_lo:[0,1] neg_hi:[0,1]
	v_pk_add_f32 v[54:55], v[54:55], v[34:35] op_sel_hi:[1,0] neg_lo:[0,1] neg_hi:[0,1]
	v_pk_add_f32 v[72:73], v[72:73], v[34:35] op_sel_hi:[1,0] neg_lo:[0,1] neg_hi:[0,1]
	v_pk_add_f32 v[56:57], v[56:57], v[34:35] op_sel_hi:[1,0] neg_lo:[0,1] neg_hi:[0,1]
	v_pk_add_f32 v[74:75], v[74:75], v[34:35] op_sel_hi:[1,0] neg_lo:[0,1] neg_hi:[0,1]
	v_pk_add_f32 v[58:59], v[58:59], v[34:35] op_sel_hi:[1,0] neg_lo:[0,1] neg_hi:[0,1]
	v_pk_add_f32 v[76:77], v[76:77], v[34:35] op_sel_hi:[1,0] neg_lo:[0,1] neg_hi:[0,1]
	v_pk_add_f32 v[60:61], v[60:61], v[34:35] op_sel_hi:[1,0] neg_lo:[0,1] neg_hi:[0,1]
	v_pk_add_f32 v[78:79], v[78:79], v[34:35] op_sel_hi:[1,0] neg_lo:[0,1] neg_hi:[0,1]
	v_pk_add_f32 v[62:63], v[62:63], v[34:35] op_sel_hi:[1,0] neg_lo:[0,1] neg_hi:[0,1]
	v_pk_add_f32 v[80:81], v[80:81], v[34:35] op_sel_hi:[1,0] neg_lo:[0,1] neg_hi:[0,1]
	v_pk_add_f32 v[64:65], v[64:65], v[34:35] op_sel_hi:[1,0] neg_lo:[0,1] neg_hi:[0,1]
	v_xor_b32_e32 v34, 0x80000000, v35
	v_mul_f32_e32 v33, v33, v36
	v_pk_mul_f32 v[30:31], v[30:31], v[36:37] op_sel_hi:[1,0]
	v_pk_mul_f32 v[28:29], v[28:29], v[36:37] op_sel_hi:[1,0]
	v_pk_mul_f32 v[26:27], v[26:27], v[36:37] op_sel_hi:[1,0]
	v_pk_mul_f32 v[24:25], v[24:25], v[36:37] op_sel_hi:[1,0]
	v_pk_mul_f32 v[22:23], v[22:23], v[36:37] op_sel_hi:[1,0]
	v_pk_mul_f32 v[20:21], v[20:21], v[36:37] op_sel_hi:[1,0]
	v_pk_mul_f32 v[18:19], v[18:19], v[36:37] op_sel_hi:[1,0]
	v_pk_mul_f32 v[16:17], v[16:17], v[36:37] op_sel_hi:[1,0]
	v_pk_mul_f32 v[14:15], v[14:15], v[36:37] op_sel_hi:[1,0]
	v_pk_mul_f32 v[12:13], v[12:13], v[36:37] op_sel_hi:[1,0]
	v_pk_mul_f32 v[10:11], v[10:11], v[36:37] op_sel_hi:[1,0]
	v_pk_mul_f32 v[8:9], v[8:9], v[36:37] op_sel_hi:[1,0]
	v_pk_mul_f32 v[6:7], v[6:7], v[36:37] op_sel_hi:[1,0]
	v_pk_mul_f32 v[4:5], v[4:5], v[36:37] op_sel_hi:[1,0]
	v_pk_mul_f32 v[2:3], v[2:3], v[36:37] op_sel_hi:[1,0]
	v_pk_mul_f32 v[0:1], v[0:1], v[36:37] op_sel_hi:[1,0]
	v_mov_b32_e32 v35, v34
	v_mov_b32_e32 v36, v34
	v_mov_b32_e32 v37, v34
	v_mov_b32_e32 v38, v34
	v_mov_b32_e32 v39, v34
	v_mov_b32_e32 v40, v34
	v_mov_b32_e32 v41, v34
	v_mov_b32_e32 v42, v34
	v_mov_b32_e32 v43, v34
	v_mov_b32_e32 v44, v34
	v_mov_b32_e32 v45, v34
	v_mov_b32_e32 v46, v34
	v_mov_b32_e32 v47, v34
	v_mov_b32_e32 v48, v34
	v_mov_b32_e32 v49, v34
.LBB0_106:
	v_exp_f32_e32 v118, v66
	v_exp_f32_e32 v133, v50
	v_exp_f32_e32 v50, v67
	v_exp_f32_e32 v112, v51
	v_mov_b32_e32 v51, v99
	v_add_f32_e32 v113, v133, v118
	v_exp_f32_e32 v120, v53
	v_pk_add_f32 v[66:67], v[112:113], v[50:51]
	v_exp_f32_e32 v51, v68
	v_pk_add_f32 v[114:115], v[66:67], v[66:67] op_sel_hi:[0,1]
	v_exp_f32_e32 v113, v52
	v_exp_f32_e32 v114, v69
	v_exp_f32_e32 v68, v70
	v_exp_f32_e32 v122, v55
	v_add_f32_e32 v121, v113, v51
	v_pk_add_f32 v[52:53], v[120:121], v[114:115]
	v_exp_f32_e32 v115, v54
	v_pk_add_f32 v[52:53], v[52:53], v[52:53] op_sel_hi:[0,1]
	v_exp_f32_e32 v52, v71
	v_exp_f32_e32 v121, v56
	v_add_f32_e32 v123, v115, v68
	v_exp_f32_e32 v124, v57
	v_pk_add_f32 v[54:55], v[122:123], v[52:53]
	v_exp_f32_e32 v53, v72
	v_pk_add_f32 v[54:55], v[54:55], v[54:55] op_sel_hi:[0,1]
	v_exp_f32_e32 v54, v73
	v_exp_f32_e32 v123, v58
	v_add_f32_e32 v125, v121, v53
	v_exp_f32_e32 v128, v59
	v_pk_add_f32 v[56:57], v[124:125], v[54:55]
	v_exp_f32_e32 v55, v74
	v_pk_add_f32 v[56:57], v[56:57], v[56:57] op_sel_hi:[0,1]
	v_exp_f32_e32 v56, v75
	v_exp_f32_e32 v125, v60
	v_add_f32_e32 v129, v123, v55
	v_exp_f32_e32 v130, v61
	v_pk_add_f32 v[58:59], v[128:129], v[56:57]
	v_exp_f32_e32 v57, v76
	v_pk_add_f32 v[58:59], v[58:59], v[58:59] op_sel_hi:[0,1]
	v_exp_f32_e32 v58, v77
	v_exp_f32_e32 v129, v62
	v_add_f32_e32 v131, v125, v57
	v_exp_f32_e32 v140, v63
	v_pk_add_f32 v[60:61], v[130:131], v[58:59]
	v_exp_f32_e32 v59, v78
	v_pk_add_f32 v[60:61], v[60:61], v[60:61] op_sel_hi:[0,1]
	v_exp_f32_e32 v60, v79
	v_exp_f32_e32 v131, v64
	v_add_f32_e32 v141, v129, v59
	v_exp_f32_e32 v142, v65
	v_pk_add_f32 v[62:63], v[140:141], v[60:61]
	v_exp_f32_e32 v61, v80
	v_pk_add_f32 v[62:63], v[62:63], v[62:63] op_sel_hi:[0,1]
	v_exp_f32_e32 v62, v81
	v_cvt_pk_bf16_f32 v67, v51, v114
	v_add_f32_e32 v143, v131, v61
	v_cvt_pk_bf16_f32 v74, v133, v112
	v_pk_add_f32 v[64:65], v[142:143], v[62:63]
	v_cvt_pk_bf16_f32 v75, v113, v120
	v_cvt_pk_bf16_f32 v76, v115, v122
	v_cvt_pk_bf16_f32 v77, v121, v124
	v_cvt_pk_bf16_f32 v78, v123, v128
	v_cvt_pk_bf16_f32 v79, v125, v130
	v_cvt_pk_bf16_f32 v80, v129, v140
	v_cvt_pk_bf16_f32 v81, v131, v142
	ds_read_b128 v[112:115], v137 offset:17920
	ds_read_b128 v[120:123], v137 offset:13312
	ds_read_b128 v[128:131], v137 offset:13344
	ds_read_b128 v[140:143], v137 offset:17952
	ds_read_b128 v[144:147], v137 offset:13376
	ds_read_b128 v[150:153], v137 offset:17984
	v_add_f32_e32 v63, v64, v65
	v_add_f32_e32 v33, v33, v63
	v_cvt_pk_bf16_f32 v66, v118, v50
	v_cvt_pk_bf16_f32 v68, v68, v52
	v_cvt_pk_bf16_f32 v69, v53, v54
	v_cvt_pk_bf16_f32 v70, v55, v56
	v_cvt_pk_bf16_f32 v71, v57, v58
	v_cvt_pk_bf16_f32 v72, v59, v60
	v_cvt_pk_bf16_f32 v73, v61, v62
	s_waitcnt lgkmcnt(4)
	v_mfma_f32_32x32x16_bf16 v[50:65], v[120:123], v[94:97], v[34:49]
	v_mfma_f32_32x32x16_bf16 v[34:49], v[112:115], v[94:97], v[34:49]
	ds_read_b128 v[112:115], v137 offset:13408
	ds_read_b128 v[120:123], v137 offset:18016
	s_waitcnt lgkmcnt(5)
	v_mfma_f32_32x32x16_bf16 v[50:65], v[128:131], v[90:93], v[50:65]
	s_waitcnt lgkmcnt(4)
	v_mfma_f32_32x32x16_bf16 v[34:49], v[140:143], v[90:93], v[34:49]
	ds_read_b64_tr_b16 v[128:129], v134 offset:26624
	ds_read_b64_tr_b16 v[130:131], v134 offset:27776
	ds_read_b64_tr_b16 v[142:143], v134 offset:27840
	ds_read_b64_tr_b16 v[140:141], v134 offset:26688
	s_waitcnt lgkmcnt(7)
	v_mfma_f32_32x32x16_bf16 v[50:65], v[144:147], v[86:89], v[50:65]
	s_waitcnt lgkmcnt(6)
	v_mfma_f32_32x32x16_bf16 v[34:49], v[150:153], v[86:89], v[34:49]
	ds_read_b64_tr_b16 v[144:145], v134 offset:28928
	ds_read_b64_tr_b16 v[146:147], v134 offset:30080
	ds_read_b64_tr_b16 v[152:153], v134 offset:30144
	ds_read_b64_tr_b16 v[150:151], v134 offset:28992
	s_waitcnt lgkmcnt(9)
	v_mfma_f32_32x32x16_bf16 v[50:65], v[112:115], v[82:85], v[50:65]
	s_waitcnt lgkmcnt(8)
	v_mfma_f32_32x32x16_bf16 v[34:49], v[120:123], v[82:85], v[34:49]
	ds_read_b64_tr_b16 v[112:113], v134 offset:31232
	ds_read_b64_tr_b16 v[114:115], v134 offset:32384
	ds_read_b64_tr_b16 v[122:123], v134 offset:32448
	ds_read_b64_tr_b16 v[120:121], v134 offset:31296
	s_waitcnt lgkmcnt(10)
	v_mfma_f32_32x32x16_bf16 v[16:31], v[128:131], v[66:69], v[16:31]
	s_waitcnt lgkmcnt(8)
	v_mfma_f32_32x32x16_bf16 v[0:15], v[140:143], v[66:69], v[0:15]
	ds_read_b64_tr_b16 v[66:67], v134 offset:33536
	ds_read_b64_tr_b16 v[68:69], v134 offset:34688
	ds_read_b64_tr_b16 v[130:131], v134 offset:34752
	ds_read_b64_tr_b16 v[128:129], v134 offset:33600
	s_waitcnt lgkmcnt(10)
	v_mfma_f32_32x32x16_bf16 v[16:31], v[144:147], v[70:73], v[16:31]
	s_waitcnt lgkmcnt(8)
	v_mfma_f32_32x32x16_bf16 v[0:15], v[150:153], v[70:73], v[0:15]
	s_waitcnt lgkmcnt(6)
	v_mfma_f32_32x32x16_bf16 v[16:31], v[112:115], v[74:77], v[16:31]
	s_waitcnt lgkmcnt(4)
	v_mfma_f32_32x32x16_bf16 v[0:15], v[120:123], v[74:77], v[0:15]
	s_waitcnt lgkmcnt(2)
	v_mfma_f32_32x32x16_bf16 v[16:31], v[66:69], v[78:81], v[16:31]
	s_waitcnt lgkmcnt(0)
	v_mfma_f32_32x32x16_bf16 v[0:15], v[128:131], v[78:81], v[0:15]
	v_max3_f32 v66, v50, v51, v34
	v_max3_f32 v67, v52, v53, v35
	s_waitcnt vmcnt(0)
	ds_write_b128 v135, v[108:111] offset:35840
	v_max3_f32 v66, v66, v36, v37
	v_max3_f32 v67, v67, v56, v57
	s_waitcnt lgkmcnt(0)
	s_barrier
	s_nop 0
	v_max3_f32 v66, v66, v54, v55
	v_max3_f32 v67, v67, v40, v41
	s_nop 0
	v_max3_f32 v66, v66, v38, v39
	v_max3_f32 v67, v67, v60, v61
	s_nop 0
	v_max3_f32 v66, v66, v58, v59
	v_max3_f32 v67, v67, v44, v45
	s_nop 0
	v_max3_f32 v66, v66, v42, v43
	v_max3_f32 v67, v67, v64, v65
	s_nop 0
	v_max3_f32 v66, v66, v62, v63
	v_max3_f32 v67, v67, v48, v49
	s_nop 0
	v_max3_f32 v66, v66, v46, v47
	s_nop 0
	v_max3_f32 v66, v66, v67, v67
	v_mov_b32_e32 v67, v66
	s_nop 1
	v_permlane32_swap_b32 v67, v66
	v_max_f32_e32 v66, v66, v67
	s_waitcnt lgkmcnt(0)
	s_nop 0
	v_cmp_lt_f32_e32 vcc, s78, v66
	s_cbranch_vccz .LBB0_108
	v_max_f32_e32 v66, v66, v66
	v_max_f32_e32 v66, 0, v66
	v_exp_f32_e64 v68, -v66
	v_pk_add_f32 v[50:51], v[50:51], v[66:67] op_sel_hi:[1,0] neg_lo:[0,1] neg_hi:[0,1]
	v_pk_add_f32 v[34:35], v[34:35], v[66:67] op_sel_hi:[1,0] neg_lo:[0,1] neg_hi:[0,1]
	v_pk_add_f32 v[52:53], v[52:53], v[66:67] op_sel_hi:[1,0] neg_lo:[0,1] neg_hi:[0,1]
	v_mul_f32_e32 v33, v33, v68
	v_pk_add_f32 v[36:37], v[36:37], v[66:67] op_sel_hi:[1,0] neg_lo:[0,1] neg_hi:[0,1]
	v_pk_add_f32 v[54:55], v[54:55], v[66:67] op_sel_hi:[1,0] neg_lo:[0,1] neg_hi:[0,1]
	v_pk_add_f32 v[38:39], v[38:39], v[66:67] op_sel_hi:[1,0] neg_lo:[0,1] neg_hi:[0,1]
	v_pk_add_f32 v[56:57], v[56:57], v[66:67] op_sel_hi:[1,0] neg_lo:[0,1] neg_hi:[0,1]
	v_pk_add_f32 v[40:41], v[40:41], v[66:67] op_sel_hi:[1,0] neg_lo:[0,1] neg_hi:[0,1]
	v_pk_add_f32 v[58:59], v[58:59], v[66:67] op_sel_hi:[1,0] neg_lo:[0,1] neg_hi:[0,1]
	v_pk_add_f32 v[42:43], v[42:43], v[66:67] op_sel_hi:[1,0] neg_lo:[0,1] neg_hi:[0,1]
	v_pk_add_f32 v[60:61], v[60:61], v[66:67] op_sel_hi:[1,0] neg_lo:[0,1] neg_hi:[0,1]
	v_pk_add_f32 v[44:45], v[44:45], v[66:67] op_sel_hi:[1,0] neg_lo:[0,1] neg_hi:[0,1]
	v_pk_add_f32 v[62:63], v[62:63], v[66:67] op_sel_hi:[1,0] neg_lo:[0,1] neg_hi:[0,1]
	v_pk_add_f32 v[46:47], v[46:47], v[66:67] op_sel_hi:[1,0] neg_lo:[0,1] neg_hi:[0,1]
	v_pk_add_f32 v[64:65], v[64:65], v[66:67] op_sel_hi:[1,0] neg_lo:[0,1] neg_hi:[0,1]
	v_pk_add_f32 v[48:49], v[48:49], v[66:67] op_sel_hi:[1,0] neg_lo:[0,1] neg_hi:[0,1]
	v_pk_mul_f32 v[30:31], v[30:31], v[68:69] op_sel_hi:[1,0]
	v_pk_mul_f32 v[28:29], v[28:29], v[68:69] op_sel_hi:[1,0]
	v_pk_mul_f32 v[26:27], v[26:27], v[68:69] op_sel_hi:[1,0]
	v_pk_mul_f32 v[24:25], v[24:25], v[68:69] op_sel_hi:[1,0]
	v_pk_mul_f32 v[22:23], v[22:23], v[68:69] op_sel_hi:[1,0]
	v_pk_mul_f32 v[20:21], v[20:21], v[68:69] op_sel_hi:[1,0]
	v_pk_mul_f32 v[18:19], v[18:19], v[68:69] op_sel_hi:[1,0]
	v_pk_mul_f32 v[16:17], v[16:17], v[68:69] op_sel_hi:[1,0]
	v_pk_mul_f32 v[14:15], v[14:15], v[68:69] op_sel_hi:[1,0]
	v_pk_mul_f32 v[12:13], v[12:13], v[68:69] op_sel_hi:[1,0]
	v_pk_mul_f32 v[10:11], v[10:11], v[68:69] op_sel_hi:[1,0]
	v_pk_mul_f32 v[8:9], v[8:9], v[68:69] op_sel_hi:[1,0]
	v_pk_mul_f32 v[6:7], v[6:7], v[68:69] op_sel_hi:[1,0]
	v_pk_mul_f32 v[4:5], v[4:5], v[68:69] op_sel_hi:[1,0]
	v_pk_mul_f32 v[2:3], v[2:3], v[68:69] op_sel_hi:[1,0]
	v_pk_mul_f32 v[0:1], v[0:1], v[68:69] op_sel_hi:[1,0]

.LBB0_109:
	s_and_b64 vcc, exec, s[6:7]
	s_movk_i32 s68, 0x21ff
	s_cbranch_vccz .LBB0_117
	s_nop 7
	ds_read_b128 v[0:3], v137
	ds_read_b128 v[4:7], v137 offset:32
	ds_read_b128 v[8:11], v137 offset:4608
	ds_read_b128 v[12:15], v137 offset:64
	ds_read_b128 v[48:51], v137 offset:4640
	ds_read_b128 v[52:55], v137 offset:4672
	v_mov_b32_e32 v33, v32
	v_mov_b32_e32 v34, v32
	v_mov_b32_e32 v35, v32
	v_mov_b32_e32 v36, v32
	v_mov_b32_e32 v37, v32
	v_mov_b32_e32 v38, v32
	v_mov_b32_e32 v39, v32
	v_mov_b32_e32 v40, v32
	v_mov_b32_e32 v41, v32
	v_mov_b32_e32 v42, v32
	v_mov_b32_e32 v43, v32
	v_mov_b32_e32 v44, v32
	v_mov_b32_e32 v45, v32
	v_mov_b32_e32 v46, v32
	v_mov_b32_e32 v47, v32
	s_waitcnt lgkmcnt(5)
	s_nop 0
	v_mfma_f32_32x32x16_bf16 v[16:31], v[0:3], v[94:97], v[32:47]
	s_waitcnt lgkmcnt(3)
	v_mfma_f32_32x32x16_bf16 v[32:47], v[8:11], v[94:97], v[32:47]
	ds_read_b128 v[0:3], v137 offset:96
	ds_read_b128 v[8:11], v137 offset:4704
	v_mfma_f32_32x32x16_bf16 v[16:31], v[4:7], v[90:93], v[16:31]
	s_waitcnt lgkmcnt(3)
	v_mfma_f32_32x32x16_bf16 v[32:47], v[48:51], v[90:93], v[32:47]
	v_mfma_f32_32x32x16_bf16 v[16:31], v[12:15], v[86:89], v[16:31]
	s_waitcnt lgkmcnt(2)
	v_mfma_f32_32x32x16_bf16 v[32:47], v[52:55], v[86:89], v[32:47]
	s_waitcnt lgkmcnt(1)
	v_mfma_f32_32x32x16_bf16 v[16:31], v[0:3], v[82:85], v[16:31]
	s_waitcnt lgkmcnt(0)
	v_mfma_f32_32x32x16_bf16 v[32:47], v[8:11], v[82:85], v[32:47]
	s_nop 15
	s_nop 7
	v_cmp_lt_i32_e32 vcc, v232, v226
	v_max3_f32 v0, v16, v17, v32
	v_max3_f32 v1, v18, v19, v33
	s_lshl_b32 s68, s8, 1
	v_max3_f32 v0, v0, v34, v35
	v_max3_f32 v1, v1, v22, v23
	v_mov_b32_e32 v133, v99
	v_max3_f32 v0, v0, v20, v21
	v_max3_f32 v1, v1, v38, v39
	s_nop 0
	v_max3_f32 v0, v0, v36, v37
	v_max3_f32 v1, v1, v26, v27
	s_nop 0
	v_max3_f32 v0, v0, v24, v25
	v_max3_f32 v1, v1, v42, v43
	s_nop 0
	v_max3_f32 v0, v0, v40, v41
	v_max3_f32 v1, v1, v30, v31
	s_nop 0
	v_max3_f32 v0, v0, v28, v29
	v_max3_f32 v1, v1, v46, v47
	s_nop 0
	v_max3_f32 v0, v0, v44, v45
	s_nop 0
	v_max3_f32 v0, v0, v1, v1
	v_cndmask_b32_e32 v1, v225, v232, vcc
	v_lshlrev_b32_e32 v136, 2, v1
	v_mov_b32_e32 v1, v0
	s_nop 1
	v_permlane32_swap_b32 v1, v0
	v_max_f32_e32 v0, v0, v1
	s_waitcnt lgkmcnt(0)
	s_nop 0
	v_max_f32_e32 v0, v0, v0
	v_max_f32_e32 v50, 0, v0
	v_sub_f32_e32 v15, v32, v50
	v_sub_f32_e32 v16, v16, v50
	v_sub_f32_e32 v32, v33, v50
	v_sub_f32_e32 v17, v17, v50
	v_exp_f32_e32 v52, v16
	v_exp_f32_e32 v53, v15
	v_sub_f32_e32 v49, v40, v50
	v_sub_f32_e32 v40, v18, v50
	v_exp_f32_e32 v16, v17
	v_exp_f32_e32 v18, v32
	v_sub_f32_e32 v15, v19, v50
	v_add_f32_e32 v19, v53, v52
	v_mov_b32_e32 v17, v99
	v_sub_f32_e32 v34, v34, v50
	v_pk_add_f32 v[32:33], v[18:19], v[16:17]
	v_sub_f32_e32 v35, v35, v50
	v_pk_add_f32 v[32:33], v[32:33], v[32:33] op_sel_hi:[0,1]
	v_exp_f32_e32 v17, v40
	v_exp_f32_e32 v19, v34
	v_exp_f32_e32 v32, v15
	v_exp_f32_e32 v34, v35
	v_sub_f32_e32 v36, v36, v50
	v_add_f32_e32 v35, v19, v17
	v_sub_f32_e32 v15, v20, v50
	v_sub_f32_e32 v40, v21, v50
	v_pk_add_f32 v[20:21], v[34:35], v[32:33]
	v_sub_f32_e32 v37, v37, v50
	v_pk_add_f32 v[20:21], v[20:21], v[20:21] op_sel_hi:[0,1]
	v_exp_f32_e32 v33, v15
	v_exp_f32_e32 v35, v36
	v_exp_f32_e32 v20, v40
	v_exp_f32_e32 v36, v37
	v_sub_f32_e32 v15, v22, v50
	v_add_f32_e32 v37, v35, v33
	v_sub_f32_e32 v40, v23, v50
	v_pk_add_f32 v[22:23], v[36:37], v[20:21]
	v_sub_f32_e32 v51, v41, v50
	v_pk_add_f32 v[22:23], v[22:23], v[22:23] op_sel_hi:[0,1]
	v_exp_f32_e32 v22, v40
	v_mov_b64_e32 v[40:41], s[90:91]
	v_mad_i64_i32 v[40:41], s[6:7], v127, s85, v[40:41]
	v_lshl_add_u64 v[40:41], v[40:41], 0, s[68:69]
	v_lshl_add_u64 v[40:41], v[40:41], 0, v[132:133]
	global_load_dwordx4 v[108:111], v[40:41], off offset:1024
	global_load_dwordx4 v[112:115], v[116:117], off offset:1280
	v_sub_f32_e32 v38, v38, v50
	v_sub_f32_e32 v39, v39, v50
	v_exp_f32_e32 v21, v15
	v_exp_f32_e32 v37, v38
	v_exp_f32_e32 v38, v39
	v_sub_f32_e32 v15, v24, v50
	v_sub_f32_e32 v54, v25, v50
	v_add_f32_e32 v39, v37, v21
	v_pk_add_f32 v[24:25], v[38:39], v[22:23]
	v_exp_f32_e32 v23, v15
	v_pk_add_f32 v[24:25], v[24:25], v[24:25] op_sel_hi:[0,1]
	v_exp_f32_e32 v39, v49
	v_exp_f32_e32 v24, v54
	v_exp_f32_e32 v40, v51
	v_sub_f32_e32 v42, v42, v50
	v_add_f32_e32 v41, v39, v23
	v_sub_f32_e32 v15, v26, v50
	v_sub_f32_e32 v49, v27, v50
	v_pk_add_f32 v[26:27], v[40:41], v[24:25]
	v_sub_f32_e32 v43, v43, v50
	v_pk_add_f32 v[26:27], v[26:27], v[26:27] op_sel_hi:[0,1]
	v_exp_f32_e32 v25, v15
	v_exp_f32_e32 v41, v42
	v_exp_f32_e32 v26, v49
	v_exp_f32_e32 v42, v43
	v_sub_f32_e32 v44, v44, v50
	v_add_f32_e32 v43, v41, v25
	v_sub_f32_e32 v15, v28, v50
	v_sub_f32_e32 v49, v29, v50
	v_pk_add_f32 v[28:29], v[42:43], v[26:27]
	v_sub_f32_e32 v45, v45, v50
	v_pk_add_f32 v[28:29], v[28:29], v[28:29] op_sel_hi:[0,1]
	v_exp_f32_e32 v27, v15
	v_exp_f32_e32 v43, v44
	v_exp_f32_e32 v28, v49
	v_exp_f32_e32 v44, v45
	v_sub_f32_e32 v46, v46, v50
	v_add_f32_e32 v45, v43, v27
	v_sub_f32_e32 v15, v30, v50
	v_sub_f32_e32 v49, v31, v50
	v_pk_add_f32 v[30:31], v[44:45], v[28:29]
	v_sub_f32_e32 v47, v47, v50
	v_pk_add_f32 v[30:31], v[30:31], v[30:31] op_sel_hi:[0,1]
	v_exp_f32_e32 v29, v15
	v_exp_f32_e32 v45, v46
	v_exp_f32_e64 v48, -v50
	v_exp_f32_e32 v30, v49
	v_exp_f32_e32 v46, v47
	v_add_f32_e32 v47, v45, v29
	v_mul_f32_e32 v0, 0, v48
	v_mul_f32_e32 v118, v126, v48
	v_pk_add_f32 v[48:49], v[46:47], v[30:31]
	s_waitcnt vmcnt(3)
	ds_write_b128 v135, v[100:103] offset:13312
	s_waitcnt vmcnt(2)
	ds_write_b128 v135, v[104:107] offset:26624
	v_pk_add_f32 v[48:49], v[48:49], v[48:49] op_sel:[0,1] op_sel_hi:[1,0]
	s_waitcnt lgkmcnt(0)
	s_barrier
	v_cvt_pk_bf16_f32 v116, v52, v16
	v_mov_b32_e32 v49, v50
	v_pk_add_f32 v[80:81], v[118:119], v[48:49]
	v_cvt_pk_bf16_f32 v117, v17, v32
	v_cvt_pk_bf16_f32 v118, v33, v20
	v_cvt_pk_bf16_f32 v119, v21, v22
	v_cvt_pk_bf16_f32 v120, v23, v24
	v_cvt_pk_bf16_f32 v121, v25, v26
	v_cvt_pk_bf16_f32 v122, v27, v28
	v_cvt_pk_bf16_f32 v123, v29, v30
	v_cvt_pk_bf16_f32 v124, v53, v18
	v_cvt_pk_bf16_f32 v125, v19, v34
	ds_read_b128 v[16:19], v137 offset:13312
	ds_read_b128 v[20:23], v137 offset:13344
	ds_read_b128 v[24:27], v137 offset:17920
	ds_read_b128 v[28:31], v137 offset:13376
	ds_read_b128 v[100:103], v137 offset:17952
	ds_read_b128 v[104:107], v137 offset:17984
	v_xor_b32_e32 v32, 0x80000000, v81
	v_mov_b32_e32 v1, v0
	v_mov_b32_e32 v2, v0
	v_mov_b32_e32 v3, v0
	v_mov_b32_e32 v4, v0
	v_mov_b32_e32 v5, v0
	v_mov_b32_e32 v6, v0
	v_mov_b32_e32 v7, v0
	v_mov_b32_e32 v8, v0
	v_mov_b32_e32 v9, v0
	v_mov_b32_e32 v10, v0
	v_mov_b32_e32 v11, v0
	v_mov_b32_e32 v12, v0
	v_mov_b32_e32 v13, v0
	v_mov_b32_e32 v14, v0
	v_mov_b32_e32 v15, v0
	v_mov_b32_e32 v33, v32
	v_cvt_pk_bf16_f32 v126, v35, v36
	v_cvt_pk_bf16_f32 v127, v37, v38
	v_cvt_pk_bf16_f32 v128, v39, v40
	v_cvt_pk_bf16_f32 v129, v41, v42
	v_cvt_pk_bf16_f32 v130, v43, v44
	v_cvt_pk_bf16_f32 v131, v45, v46
	v_mov_b32_e32 v34, v32
	v_mov_b32_e32 v35, v32
	v_mov_b32_e32 v36, v32
	v_mov_b32_e32 v37, v32
	v_mov_b32_e32 v38, v32
	v_mov_b32_e32 v39, v32
	v_mov_b32_e32 v40, v32
	v_mov_b32_e32 v41, v32
	v_mov_b32_e32 v42, v32
	v_mov_b32_e32 v43, v32
	v_mov_b32_e32 v44, v32
	v_mov_b32_e32 v45, v32
	v_mov_b32_e32 v46, v32
	v_mov_b32_e32 v47, v32
	v_mov_b64_e32 v[78:79], v[46:47]
	v_mov_b64_e32 v[76:77], v[44:45]
	v_mov_b64_e32 v[74:75], v[42:43]
	v_mov_b64_e32 v[72:73], v[40:41]
	v_mov_b64_e32 v[70:71], v[38:39]
	v_mov_b64_e32 v[68:69], v[36:37]
	v_mov_b64_e32 v[66:67], v[34:35]
	v_mov_b64_e32 v[64:65], v[32:33]
	s_waitcnt lgkmcnt(5)
	v_mfma_f32_32x32x16_bf16 v[48:63], v[16:19], v[94:97], v[32:47]
	s_waitcnt lgkmcnt(3)
	v_mfma_f32_32x32x16_bf16 v[64:79], v[24:27], v[94:97], v[64:79]
	ds_read_b128 v[16:19], v137 offset:13408
	ds_read_b128 v[24:27], v137 offset:18016
	v_mfma_f32_32x32x16_bf16 v[48:63], v[20:23], v[90:93], v[48:63]
	s_waitcnt lgkmcnt(3)
	v_mfma_f32_32x32x16_bf16 v[64:79], v[100:103], v[90:93], v[64:79]
	ds_read_b64_tr_b16 v[34:35], v134 offset:26624
	ds_read_b64_tr_b16 v[36:37], v134 offset:27776
	ds_read_b64_tr_b16 v[40:41], v134 offset:27840
	ds_read_b64_tr_b16 v[38:39], v134 offset:26688
	v_mfma_f32_32x32x16_bf16 v[48:63], v[28:31], v[86:89], v[48:63]
	s_waitcnt lgkmcnt(6)
	v_mfma_f32_32x32x16_bf16 v[64:79], v[104:107], v[86:89], v[64:79]
	ds_read_b64_tr_b16 v[42:43], v134 offset:28928
	ds_read_b64_tr_b16 v[44:45], v134 offset:30080
	ds_read_b64_tr_b16 v[102:103], v134 offset:30144
	ds_read_b64_tr_b16 v[100:101], v134 offset:28992
	s_waitcnt lgkmcnt(9)
	v_mfma_f32_32x32x16_bf16 v[48:63], v[16:19], v[82:85], v[48:63]
	s_waitcnt lgkmcnt(8)
	v_mfma_f32_32x32x16_bf16 v[64:79], v[24:27], v[82:85], v[64:79]
	ds_read_b64_tr_b16 v[104:105], v134 offset:31232
	ds_read_b64_tr_b16 v[106:107], v134 offset:32384
	ds_read_b64_tr_b16 v[142:143], v134 offset:32448
	ds_read_b64_tr_b16 v[140:141], v134 offset:31296
	s_waitcnt lgkmcnt(10)
	v_mfma_f32_32x32x16_bf16 v[16:31], v[34:37], v[116:119], v[0:15]
	s_waitcnt lgkmcnt(8)
	v_mfma_f32_32x32x16_bf16 v[0:15], v[38:41], v[116:119], v[0:15]
	ds_read_b64_tr_b16 v[34:35], v134 offset:33536
	ds_read_b64_tr_b16 v[36:37], v134 offset:34688
	ds_read_b64_tr_b16 v[40:41], v134 offset:34752
	ds_read_b64_tr_b16 v[38:39], v134 offset:33600
	s_waitcnt lgkmcnt(10)
	v_mfma_f32_32x32x16_bf16 v[16:31], v[42:45], v[120:123], v[16:31]
	s_waitcnt lgkmcnt(8)
	v_mfma_f32_32x32x16_bf16 v[0:15], v[100:103], v[120:123], v[0:15]
	s_waitcnt lgkmcnt(6)
	v_mfma_f32_32x32x16_bf16 v[16:31], v[104:107], v[124:127], v[16:31]
	s_waitcnt lgkmcnt(4)
	v_mfma_f32_32x32x16_bf16 v[0:15], v[140:143], v[124:127], v[0:15]
	s_waitcnt lgkmcnt(2)
	v_mfma_f32_32x32x16_bf16 v[16:31], v[34:37], v[128:131], v[16:31]
	s_waitcnt lgkmcnt(0)
	v_mfma_f32_32x32x16_bf16 v[0:15], v[38:41], v[128:131], v[0:15]
	s_nop 15
	s_nop 7
	s_nop 0
	v_max3_f32 v33, v48, v49, v64
	v_max3_f32 v34, v50, v51, v65
	s_nop 0
	v_max3_f32 v33, v33, v66, v67
	v_max3_f32 v34, v34, v54, v55
	s_nop 0
	v_max3_f32 v33, v33, v52, v53
	v_max3_f32 v34, v34, v70, v71
	s_nop 0
	v_max3_f32 v33, v33, v68, v69
	v_max3_f32 v34, v34, v58, v59
	s_nop 0
	v_max3_f32 v33, v33, v56, v57
	v_max3_f32 v34, v34, v74, v75
	s_nop 0
	v_max3_f32 v33, v33, v72, v73
	v_max3_f32 v34, v34, v62, v63
	s_nop 0
	v_max3_f32 v33, v33, v60, v61
	v_max3_f32 v34, v34, v78, v79
	s_nop 0
	v_max3_f32 v33, v33, v76, v77
	s_nop 0
	v_max3_f32 v33, v33, v34, v34
	v_mov_b32_e32 v34, v33
	s_nop 1
	v_permlane32_swap_b32 v34, v33
	v_max_f32_e32 v33, v33, v34
	s_waitcnt lgkmcnt(0)
	s_nop 0
	v_cmp_lt_f32_e32 vcc, s78, v33
	s_cbranch_vccz .LBB0_112
	v_max_f32_e32 v32, v33, v33
	v_max_f32_e32 v32, 0, v32
	v_exp_f32_e64 v34, -v32
	v_add_f32_e32 v81, v81, v32
	v_pk_add_f32 v[48:49], v[48:49], v[32:33] op_sel_hi:[1,0] neg_lo:[0,1] neg_hi:[0,1]
	v_pk_add_f32 v[64:65], v[64:65], v[32:33] op_sel_hi:[1,0] neg_lo:[0,1] neg_hi:[0,1]
	v_pk_add_f32 v[50:51], v[50:51], v[32:33] op_sel_hi:[1,0] neg_lo:[0,1] neg_hi:[0,1]
	v_pk_add_f32 v[66:67], v[66:67], v[32:33] op_sel_hi:[1,0] neg_lo:[0,1] neg_hi:[0,1]
	v_pk_add_f32 v[52:53], v[52:53], v[32:33] op_sel_hi:[1,0] neg_lo:[0,1] neg_hi:[0,1]
	v_pk_add_f32 v[68:69], v[68:69], v[32:33] op_sel_hi:[1,0] neg_lo:[0,1] neg_hi:[0,1]
	v_pk_add_f32 v[54:55], v[54:55], v[32:33] op_sel_hi:[1,0] neg_lo:[0,1] neg_hi:[0,1]
	v_pk_add_f32 v[70:71], v[70:71], v[32:33] op_sel_hi:[1,0] neg_lo:[0,1] neg_hi:[0,1]
	v_pk_add_f32 v[56:57], v[56:57], v[32:33] op_sel_hi:[1,0] neg_lo:[0,1] neg_hi:[0,1]
	v_pk_add_f32 v[72:73], v[72:73], v[32:33] op_sel_hi:[1,0] neg_lo:[0,1] neg_hi:[0,1]
	v_pk_add_f32 v[58:59], v[58:59], v[32:33] op_sel_hi:[1,0] neg_lo:[0,1] neg_hi:[0,1]
	v_pk_add_f32 v[74:75], v[74:75], v[32:33] op_sel_hi:[1,0] neg_lo:[0,1] neg_hi:[0,1]
	v_pk_add_f32 v[60:61], v[60:61], v[32:33] op_sel_hi:[1,0] neg_lo:[0,1] neg_hi:[0,1]
	v_pk_add_f32 v[76:77], v[76:77], v[32:33] op_sel_hi:[1,0] neg_lo:[0,1] neg_hi:[0,1]
	v_pk_add_f32 v[62:63], v[62:63], v[32:33] op_sel_hi:[1,0] neg_lo:[0,1] neg_hi:[0,1]
	v_pk_add_f32 v[78:79], v[78:79], v[32:33] op_sel_hi:[1,0] neg_lo:[0,1] neg_hi:[0,1]
	v_pk_mul_f32 v[30:31], v[30:31], v[34:35] op_sel_hi:[1,0]
	v_pk_mul_f32 v[28:29], v[28:29], v[34:35] op_sel_hi:[1,0]
	v_pk_mul_f32 v[26:27], v[26:27], v[34:35] op_sel_hi:[1,0]
	v_pk_mul_f32 v[24:25], v[24:25], v[34:35] op_sel_hi:[1,0]
	v_pk_mul_f32 v[22:23], v[22:23], v[34:35] op_sel_hi:[1,0]
	v_pk_mul_f32 v[20:21], v[20:21], v[34:35] op_sel_hi:[1,0]
	v_pk_mul_f32 v[18:19], v[18:19], v[34:35] op_sel_hi:[1,0]
	v_pk_mul_f32 v[16:17], v[16:17], v[34:35] op_sel_hi:[1,0]
	v_pk_mul_f32 v[14:15], v[14:15], v[34:35] op_sel_hi:[1,0]
	v_pk_mul_f32 v[12:13], v[12:13], v[34:35] op_sel_hi:[1,0]
	v_pk_mul_f32 v[10:11], v[10:11], v[34:35] op_sel_hi:[1,0]
	v_pk_mul_f32 v[8:9], v[8:9], v[34:35] op_sel_hi:[1,0]
	v_pk_mul_f32 v[6:7], v[6:7], v[34:35] op_sel_hi:[1,0]
	v_pk_mul_f32 v[4:5], v[4:5], v[34:35] op_sel_hi:[1,0]
	v_pk_mul_f32 v[2:3], v[2:3], v[34:35] op_sel_hi:[1,0]
	v_pk_mul_f32 v[0:1], v[0:1], v[34:35] op_sel_hi:[1,0]
	v_xor_b32_e32 v32, 0x80000000, v81
	v_mul_f32_e32 v80, v80, v34
.LBB0_112:
	v_exp_f32_e32 v104, v48
	v_exp_f32_e32 v105, v64
	v_exp_f32_e32 v48, v49
	v_exp_f32_e32 v100, v65
	v_mov_b32_e32 v49, v99
	v_add_f32_e32 v101, v105, v104
	v_exp_f32_e32 v102, v67
	v_pk_add_f32 v[64:65], v[100:101], v[48:49]
	v_exp_f32_e32 v49, v50
	v_pk_add_f32 v[64:65], v[64:65], v[64:65] op_sel_hi:[0,1]
	v_exp_f32_e32 v101, v66
	v_exp_f32_e32 v64, v51
	v_exp_f32_e32 v66, v69
	v_cvt_pk_bf16_f32 v128, v104, v48
	v_add_f32_e32 v103, v101, v49
	v_pk_add_f32 v[50:51], v[102:103], v[64:65]
	v_exp_f32_e32 v65, v52
	v_pk_add_f32 v[50:51], v[50:51], v[50:51] op_sel_hi:[0,1]
	v_exp_f32_e32 v103, v68
	v_exp_f32_e32 v50, v53
	v_cvt_pk_bf16_f32 v129, v49, v64
	v_mov_b64_e32 v[48:49], s[90:91]
	v_add_f32_e32 v67, v103, v65
	v_pk_add_f32 v[52:53], v[66:67], v[50:51]
	v_exp_f32_e32 v51, v54
	v_pk_add_f32 v[52:53], v[52:53], v[52:53] op_sel_hi:[0,1]
	v_exp_f32_e32 v67, v70
	v_exp_f32_e32 v52, v55
	v_cvt_pk_bf16_f32 v130, v65, v50
	v_mov_b32_e32 v133, v99
	v_add_f32_e32 v69, v67, v51
	v_cvt_pk_bf16_f32 v131, v51, v52
	v_mad_i64_i32 v[50:51], s[6:7], v139, s85, v[48:49]
	v_mad_i64_i32 v[48:49], s[6:7], v138, s85, v[48:49]
	v_lshl_add_u64 v[50:51], v[50:51], 0, s[68:69]
	v_lshl_add_u64 v[48:49], v[48:49], 0, s[68:69]
	s_waitcnt vmcnt(1)
	ds_write_b128 v135, v[108:111]
	s_waitcnt vmcnt(0)
	ds_write_b128 v135, v[112:115] offset:35840
	v_lshl_add_u64 v[112:113], v[50:51], 0, v[132:133]
	v_lshl_add_u64 v[48:49], v[48:49], 0, v[132:133]
	v_cvt_pk_bf16_f32 v120, v105, v100
	v_cvt_pk_bf16_f32 v121, v101, v102
	v_cvt_pk_bf16_f32 v122, v103, v66
	global_load_dwordx4 v[100:103], v[112:113], off offset:1024
	global_load_dwordx4 v[104:107], v[48:49], off offset:1280
	v_exp_f32_e32 v68, v71
	v_exp_f32_e32 v70, v73
	s_waitcnt lgkmcnt(0)
	s_barrier
	v_mov_b32_e32 v33, v32
	v_pk_add_f32 v[54:55], v[68:69], v[52:53]
	v_exp_f32_e32 v53, v56
	v_pk_add_f32 v[54:55], v[54:55], v[54:55] op_sel_hi:[0,1]
	v_exp_f32_e32 v69, v72
	v_exp_f32_e32 v54, v57
	v_exp_f32_e32 v72, v75
	v_cvt_pk_bf16_f32 v123, v67, v68
	v_add_f32_e32 v71, v69, v53
	v_pk_add_f32 v[56:57], v[70:71], v[54:55]
	v_exp_f32_e32 v55, v58
	v_pk_add_f32 v[56:57], v[56:57], v[56:57] op_sel_hi:[0,1]
	v_exp_f32_e32 v71, v74
	v_exp_f32_e32 v56, v59
	v_exp_f32_e32 v74, v77
	ds_read_b128 v[108:111], v137 offset:4608
	ds_read_b128 v[64:67], v137
	ds_read_b128 v[138:141], v137 offset:32
	ds_read_b128 v[142:145], v137 offset:4640
	ds_read_b128 v[150:153], v137 offset:64
	ds_read_b128 v[154:157], v137 offset:4672
	v_add_f32_e32 v73, v71, v55
	v_pk_add_f32 v[58:59], v[72:73], v[56:57]
	v_exp_f32_e32 v57, v60
	v_pk_add_f32 v[58:59], v[58:59], v[58:59] op_sel_hi:[0,1]
	v_exp_f32_e32 v73, v76
	v_exp_f32_e32 v58, v61
	v_exp_f32_e32 v76, v79
	v_mov_b32_e32 v34, v32
	v_add_f32_e32 v75, v73, v57
	v_pk_add_f32 v[60:61], v[74:75], v[58:59]
	v_exp_f32_e32 v59, v62
	v_pk_add_f32 v[60:61], v[60:61], v[60:61] op_sel_hi:[0,1]
	v_exp_f32_e32 v75, v78
	v_exp_f32_e32 v60, v63
	v_mov_b32_e32 v35, v32
	v_mov_b32_e32 v36, v32
	v_add_f32_e32 v77, v75, v59
	v_pk_add_f32 v[62:63], v[76:77], v[60:61]
	v_mov_b32_e32 v37, v32
	v_add_f32_e32 v61, v62, v63
	v_mov_b32_e32 v38, v32
	v_mov_b32_e32 v39, v32
	v_mov_b32_e32 v40, v32
	v_mov_b32_e32 v41, v32
	v_mov_b32_e32 v42, v32
	v_mov_b32_e32 v43, v32
	v_mov_b32_e32 v44, v32
	v_mov_b32_e32 v45, v32
	v_mov_b32_e32 v46, v32
	v_mov_b32_e32 v47, v32
	v_add_f32_e32 v80, v80, v61
	v_cvt_pk_bf16_f32 v124, v53, v54
	v_cvt_pk_bf16_f32 v125, v55, v56
	v_cvt_pk_bf16_f32 v126, v57, v58
	v_cvt_pk_bf16_f32 v127, v59, v60
	v_cvt_pk_bf16_f32 v116, v69, v70
	v_cvt_pk_bf16_f32 v117, v71, v72
	v_cvt_pk_bf16_f32 v118, v73, v74
	v_cvt_pk_bf16_f32 v119, v75, v76
	s_waitcnt lgkmcnt(4)
	v_mfma_f32_32x32x16_bf16 v[48:63], v[64:67], v[94:97], v[32:47]
	v_mfma_f32_32x32x16_bf16 v[64:79], v[108:111], v[94:97], v[32:47]
	ds_read_b128 v[108:111], v137 offset:96
	ds_read_b128 v[158:161], v137 offset:4704
	s_waitcnt lgkmcnt(5)
	v_mfma_f32_32x32x16_bf16 v[48:63], v[138:141], v[90:93], v[48:63]
	s_waitcnt lgkmcnt(4)
	v_mfma_f32_32x32x16_bf16 v[64:79], v[142:145], v[90:93], v[64:79]
	ds_read_b64_tr_b16 v[138:139], v134 offset:35840
	ds_read_b64_tr_b16 v[140:141], v134 offset:36992
	ds_read_b64_tr_b16 v[144:145], v134 offset:37056
	ds_read_b64_tr_b16 v[142:143], v134 offset:35904
	s_waitcnt lgkmcnt(7)
	v_mfma_f32_32x32x16_bf16 v[48:63], v[150:153], v[86:89], v[48:63]
	s_waitcnt lgkmcnt(6)
	v_mfma_f32_32x32x16_bf16 v[64:79], v[154:157], v[86:89], v[64:79]
	ds_read_b64_tr_b16 v[150:151], v134 offset:38144
	ds_read_b64_tr_b16 v[152:153], v134 offset:39296
	ds_read_b64_tr_b16 v[156:157], v134 offset:39360
	ds_read_b64_tr_b16 v[154:155], v134 offset:38208
	s_waitcnt lgkmcnt(9)
	v_mfma_f32_32x32x16_bf16 v[48:63], v[108:111], v[82:85], v[48:63]
	s_waitcnt lgkmcnt(8)
	v_mfma_f32_32x32x16_bf16 v[64:79], v[158:161], v[82:85], v[64:79]
	ds_read_b64_tr_b16 v[108:109], v134 offset:40448
	ds_read_b64_tr_b16 v[110:111], v134 offset:41600
	ds_read_b64_tr_b16 v[160:161], v134 offset:41664
	ds_read_b64_tr_b16 v[158:159], v134 offset:40512
	s_waitcnt lgkmcnt(10)
	v_mfma_f32_32x32x16_bf16 v[16:31], v[138:141], v[128:131], v[16:31]
	s_waitcnt lgkmcnt(8)
	v_mfma_f32_32x32x16_bf16 v[0:15], v[142:145], v[128:131], v[0:15]
	ds_read_b64_tr_b16 v[128:129], v134 offset:42752
	ds_read_b64_tr_b16 v[130:131], v134 offset:43904
	ds_read_b64_tr_b16 v[140:141], v134 offset:43968
	ds_read_b64_tr_b16 v[138:139], v134 offset:42816
	s_waitcnt lgkmcnt(10)
	v_mfma_f32_32x32x16_bf16 v[16:31], v[150:153], v[124:127], v[16:31]
	s_waitcnt lgkmcnt(8)
	v_mfma_f32_32x32x16_bf16 v[0:15], v[154:157], v[124:127], v[0:15]
	s_waitcnt lgkmcnt(6)
	v_mfma_f32_32x32x16_bf16 v[16:31], v[108:111], v[120:123], v[16:31]
	s_waitcnt lgkmcnt(4)
	v_mfma_f32_32x32x16_bf16 v[0:15], v[158:161], v[120:123], v[0:15]
	s_waitcnt lgkmcnt(2)
	v_mfma_f32_32x32x16_bf16 v[16:31], v[128:131], v[116:119], v[16:31]
	s_waitcnt lgkmcnt(0)
	v_mfma_f32_32x32x16_bf16 v[0:15], v[138:141], v[116:119], v[0:15]
	s_nop 15
	s_nop 7
	s_nop 0
	v_max3_f32 v108, v48, v49, v64
	v_max3_f32 v109, v50, v51, v65
	s_nop 0
	v_max3_f32 v108, v108, v66, v67
	v_max3_f32 v109, v109, v54, v55
	s_nop 0
	v_max3_f32 v108, v108, v52, v53
	v_max3_f32 v109, v109, v70, v71
	s_nop 0
	v_max3_f32 v108, v108, v68, v69
	v_max3_f32 v109, v109, v58, v59
	s_nop 0
	v_max3_f32 v108, v108, v56, v57
	v_max3_f32 v109, v109, v74, v75
	s_nop 0
	v_max3_f32 v108, v108, v72, v73
	v_max3_f32 v109, v109, v62, v63
	s_nop 0
	v_max3_f32 v108, v108, v60, v61
	v_max3_f32 v109, v109, v78, v79
	s_nop 0
	v_max3_f32 v108, v108, v76, v77
	s_nop 0
	v_max3_f32 v108, v108, v109, v109
	v_mov_b32_e32 v109, v108
	s_nop 1
	v_permlane32_swap_b32 v109, v108
	v_max_f32_e32 v108, v108, v109
	s_waitcnt lgkmcnt(0)
	s_nop 0
	v_cmp_lt_f32_e32 vcc, s78, v108
	s_cbranch_vccz .LBB0_114
	v_max_f32_e32 v32, v108, v108
	v_max_f32_e32 v32, 0, v32
	v_exp_f32_e64 v34, -v32
	v_add_f32_e32 v33, v81, v32
	v_pk_add_f32 v[48:49], v[48:49], v[32:33] op_sel_hi:[1,0] neg_lo:[0,1] neg_hi:[0,1]
	v_pk_add_f32 v[64:65], v[64:65], v[32:33] op_sel_hi:[1,0] neg_lo:[0,1] neg_hi:[0,1]
	v_pk_add_f32 v[50:51], v[50:51], v[32:33] op_sel_hi:[1,0] neg_lo:[0,1] neg_hi:[0,1]
	v_pk_add_f32 v[66:67], v[66:67], v[32:33] op_sel_hi:[1,0] neg_lo:[0,1] neg_hi:[0,1]
	v_pk_add_f32 v[52:53], v[52:53], v[32:33] op_sel_hi:[1,0] neg_lo:[0,1] neg_hi:[0,1]
	v_pk_add_f32 v[68:69], v[68:69], v[32:33] op_sel_hi:[1,0] neg_lo:[0,1] neg_hi:[0,1]
	v_pk_add_f32 v[54:55], v[54:55], v[32:33] op_sel_hi:[1,0] neg_lo:[0,1] neg_hi:[0,1]
	v_pk_add_f32 v[70:71], v[70:71], v[32:33] op_sel_hi:[1,0] neg_lo:[0,1] neg_hi:[0,1]
	v_pk_add_f32 v[56:57], v[56:57], v[32:33] op_sel_hi:[1,0] neg_lo:[0,1] neg_hi:[0,1]
	v_pk_add_f32 v[72:73], v[72:73], v[32:33] op_sel_hi:[1,0] neg_lo:[0,1] neg_hi:[0,1]
	v_pk_add_f32 v[58:59], v[58:59], v[32:33] op_sel_hi:[1,0] neg_lo:[0,1] neg_hi:[0,1]
	v_pk_add_f32 v[74:75], v[74:75], v[32:33] op_sel_hi:[1,0] neg_lo:[0,1] neg_hi:[0,1]
	v_pk_add_f32 v[60:61], v[60:61], v[32:33] op_sel_hi:[1,0] neg_lo:[0,1] neg_hi:[0,1]
	v_pk_add_f32 v[76:77], v[76:77], v[32:33] op_sel_hi:[1,0] neg_lo:[0,1] neg_hi:[0,1]
	v_pk_add_f32 v[62:63], v[62:63], v[32:33] op_sel_hi:[1,0] neg_lo:[0,1] neg_hi:[0,1]
	v_pk_add_f32 v[78:79], v[78:79], v[32:33] op_sel_hi:[1,0] neg_lo:[0,1] neg_hi:[0,1]
	v_xor_b32_e32 v32, 0x80000000, v33
	v_mul_f32_e32 v80, v80, v34
	v_pk_mul_f32 v[30:31], v[30:31], v[34:35] op_sel_hi:[1,0]
	v_pk_mul_f32 v[28:29], v[28:29], v[34:35] op_sel_hi:[1,0]
	v_pk_mul_f32 v[26:27], v[26:27], v[34:35] op_sel_hi:[1,0]
	v_pk_mul_f32 v[24:25], v[24:25], v[34:35] op_sel_hi:[1,0]
	v_pk_mul_f32 v[22:23], v[22:23], v[34:35] op_sel_hi:[1,0]
	v_pk_mul_f32 v[20:21], v[20:21], v[34:35] op_sel_hi:[1,0]
	v_pk_mul_f32 v[18:19], v[18:19], v[34:35] op_sel_hi:[1,0]
	v_pk_mul_f32 v[16:17], v[16:17], v[34:35] op_sel_hi:[1,0]
	v_pk_mul_f32 v[14:15], v[14:15], v[34:35] op_sel_hi:[1,0]
	v_pk_mul_f32 v[12:13], v[12:13], v[34:35] op_sel_hi:[1,0]
	v_pk_mul_f32 v[10:11], v[10:11], v[34:35] op_sel_hi:[1,0]
	v_pk_mul_f32 v[8:9], v[8:9], v[34:35] op_sel_hi:[1,0]
	v_pk_mul_f32 v[6:7], v[6:7], v[34:35] op_sel_hi:[1,0]
	v_pk_mul_f32 v[4:5], v[4:5], v[34:35] op_sel_hi:[1,0]
	v_pk_mul_f32 v[2:3], v[2:3], v[34:35] op_sel_hi:[1,0]
	v_pk_mul_f32 v[0:1], v[0:1], v[34:35] op_sel_hi:[1,0]
	v_mov_b32_e32 v33, v32
	v_mov_b32_e32 v34, v32
	v_mov_b32_e32 v35, v32
	v_mov_b32_e32 v36, v32
	v_mov_b32_e32 v37, v32
	v_mov_b32_e32 v38, v32
	v_mov_b32_e32 v39, v32
	v_mov_b32_e32 v40, v32
	v_mov_b32_e32 v41, v32
	v_mov_b32_e32 v42, v32
	v_mov_b32_e32 v43, v32
	v_mov_b32_e32 v44, v32
	v_mov_b32_e32 v45, v32
	v_mov_b32_e32 v46, v32
	v_mov_b32_e32 v47, v32
.LBB0_114:
	v_exp_f32_e32 v81, v48
	v_exp_f32_e32 v124, v64
	v_exp_f32_e32 v48, v49
	v_exp_f32_e32 v114, v65
	v_mov_b32_e32 v49, v99
	v_add_f32_e32 v115, v124, v81
	v_exp_f32_e32 v116, v67
	v_pk_add_f32 v[64:65], v[114:115], v[48:49]
	v_exp_f32_e32 v49, v50
	v_pk_add_f32 v[64:65], v[64:65], v[64:65] op_sel_hi:[0,1]
	v_exp_f32_e32 v115, v66
	v_exp_f32_e32 v64, v51
	v_exp_f32_e32 v66, v69
	s_waitcnt vmcnt(1)
	ds_write_b128 v135, v[100:103] offset:13312
	s_waitcnt vmcnt(0)
	ds_write_b128 v135, v[104:107] offset:26624
	v_add_f32_e32 v117, v115, v49
	v_pk_add_f32 v[50:51], v[116:117], v[64:65]
	v_exp_f32_e32 v65, v52
	v_pk_add_f32 v[50:51], v[50:51], v[50:51] op_sel_hi:[0,1]
	v_exp_f32_e32 v117, v68
	v_exp_f32_e32 v50, v53
	v_exp_f32_e32 v68, v71
	v_exp_f32_e32 v118, v75
	v_add_f32_e32 v67, v117, v65
	v_pk_add_f32 v[52:53], v[66:67], v[50:51]
	v_exp_f32_e32 v51, v54
	v_pk_add_f32 v[52:53], v[52:53], v[52:53] op_sel_hi:[0,1]
	v_exp_f32_e32 v67, v70
	v_exp_f32_e32 v52, v55
	v_exp_f32_e32 v70, v73
	v_cvt_pk_bf16_f32 v109, v49, v64
	v_add_f32_e32 v69, v67, v51
	v_pk_add_f32 v[54:55], v[68:69], v[52:53]
	v_exp_f32_e32 v53, v56
	v_pk_add_f32 v[54:55], v[54:55], v[54:55] op_sel_hi:[0,1]
	v_exp_f32_e32 v69, v72
	v_exp_f32_e32 v54, v57
	v_cvt_pk_bf16_f32 v110, v65, v50
	v_cvt_pk_bf16_f32 v75, v67, v68
	v_add_f32_e32 v71, v69, v53
	v_pk_add_f32 v[56:57], v[70:71], v[54:55]
	v_exp_f32_e32 v71, v74
	v_cvt_pk_bf16_f32 v74, v117, v66
	global_load_dwordx4 v[64:67], v[112:113], off offset:1280
	v_pk_add_f32 v[56:57], v[56:57], v[56:57] op_sel_hi:[0,1]
	v_exp_f32_e32 v55, v58
	v_exp_f32_e32 v56, v59
	v_exp_f32_e32 v120, v77
	v_exp_f32_e32 v122, v79
	v_add_f32_e32 v119, v71, v55
	v_pk_add_f32 v[58:59], v[118:119], v[56:57]
	v_exp_f32_e32 v57, v60
	v_pk_add_f32 v[58:59], v[58:59], v[58:59] op_sel_hi:[0,1]
	v_exp_f32_e32 v119, v76
	v_exp_f32_e32 v58, v61
	s_waitcnt lgkmcnt(0)
	s_barrier
	v_cvt_pk_bf16_f32 v72, v124, v114
	v_add_f32_e32 v121, v119, v57
	v_pk_add_f32 v[60:61], v[120:121], v[58:59]
	v_exp_f32_e32 v59, v62
	v_pk_add_f32 v[60:61], v[60:61], v[60:61] op_sel_hi:[0,1]
	v_exp_f32_e32 v121, v78
	v_exp_f32_e32 v60, v63
	v_cvt_pk_bf16_f32 v73, v115, v116
	v_cvt_pk_bf16_f32 v68, v69, v70
	v_add_f32_e32 v123, v121, v59
	v_pk_add_f32 v[62:63], v[122:123], v[60:61]
	v_cvt_pk_bf16_f32 v69, v71, v118
	v_cvt_pk_bf16_f32 v70, v119, v120
	v_cvt_pk_bf16_f32 v71, v121, v122
	ds_read_b128 v[100:103], v137 offset:17920
	ds_read_b128 v[104:107], v137 offset:13312
	ds_read_b128 v[112:115], v137 offset:13344
	ds_read_b128 v[116:119], v137 offset:17952
	ds_read_b128 v[120:123], v137 offset:13376
	ds_read_b128 v[124:127], v137 offset:17984
	v_add_f32_e32 v61, v62, v63
	s_movk_i32 s68, 0x21ff
	v_add_f32_e32 v80, v80, v61
	v_cvt_pk_bf16_f32 v108, v81, v48
	v_cvt_pk_bf16_f32 v111, v51, v52
	v_cvt_pk_bf16_f32 v76, v53, v54
	v_cvt_pk_bf16_f32 v77, v55, v56
	v_cvt_pk_bf16_f32 v78, v57, v58
	v_cvt_pk_bf16_f32 v79, v59, v60
	s_waitcnt lgkmcnt(4)
	v_mfma_f32_32x32x16_bf16 v[48:63], v[104:107], v[94:97], v[32:47]
	v_mfma_f32_32x32x16_bf16 v[32:47], v[100:103], v[94:97], v[32:47]
	ds_read_b128 v[94:97], v137 offset:13408
	ds_read_b128 v[100:103], v137 offset:18016
	s_waitcnt lgkmcnt(5)
	v_mfma_f32_32x32x16_bf16 v[48:63], v[112:115], v[90:93], v[48:63]
	s_waitcnt lgkmcnt(4)
	v_mfma_f32_32x32x16_bf16 v[32:47], v[116:119], v[90:93], v[32:47]
	ds_read_b64_tr_b16 v[90:91], v134 offset:26624
	ds_read_b64_tr_b16 v[92:93], v134 offset:27776
	ds_read_b64_tr_b16 v[106:107], v134 offset:27840
	ds_read_b64_tr_b16 v[104:105], v134 offset:26688
	s_waitcnt lgkmcnt(7)
	v_mfma_f32_32x32x16_bf16 v[48:63], v[120:123], v[86:89], v[48:63]
	s_waitcnt lgkmcnt(6)
	v_mfma_f32_32x32x16_bf16 v[32:47], v[124:127], v[86:89], v[32:47]
	ds_read_b64_tr_b16 v[86:87], v134 offset:28928
	ds_read_b64_tr_b16 v[88:89], v134 offset:30080
	ds_read_b64_tr_b16 v[114:115], v134 offset:30144
	ds_read_b64_tr_b16 v[112:113], v134 offset:28992
	s_waitcnt lgkmcnt(9)
	v_mfma_f32_32x32x16_bf16 v[48:63], v[94:97], v[82:85], v[48:63]
	s_waitcnt lgkmcnt(8)
	v_mfma_f32_32x32x16_bf16 v[32:47], v[100:103], v[82:85], v[32:47]
	ds_read_b64_tr_b16 v[82:83], v134 offset:31232
	ds_read_b64_tr_b16 v[84:85], v134 offset:32384
	ds_read_b64_tr_b16 v[96:97], v134 offset:32448
	ds_read_b64_tr_b16 v[94:95], v134 offset:31296
	s_waitcnt lgkmcnt(10)
	v_mfma_f32_32x32x16_bf16 v[16:31], v[90:93], v[108:111], v[16:31]
	s_waitcnt lgkmcnt(8)
	v_mfma_f32_32x32x16_bf16 v[0:15], v[104:107], v[108:111], v[0:15]
	ds_read_b64_tr_b16 v[90:91], v134 offset:33536
	ds_read_b64_tr_b16 v[92:93], v134 offset:34688
	ds_read_b64_tr_b16 v[102:103], v134 offset:34752
	ds_read_b64_tr_b16 v[100:101], v134 offset:33600
	s_waitcnt lgkmcnt(10)
	v_mfma_f32_32x32x16_bf16 v[16:31], v[86:89], v[76:79], v[16:31]
	s_waitcnt lgkmcnt(8)
	v_mfma_f32_32x32x16_bf16 v[0:15], v[112:115], v[76:79], v[0:15]
	s_waitcnt lgkmcnt(6)
	v_mfma_f32_32x32x16_bf16 v[16:31], v[82:85], v[72:75], v[16:31]
	s_waitcnt lgkmcnt(4)
	v_mfma_f32_32x32x16_bf16 v[0:15], v[94:97], v[72:75], v[0:15]
	s_waitcnt lgkmcnt(2)
	v_mfma_f32_32x32x16_bf16 v[16:31], v[90:93], v[68:71], v[16:31]
	s_waitcnt lgkmcnt(0)
	v_mfma_f32_32x32x16_bf16 v[0:15], v[100:103], v[68:71], v[0:15]
	s_nop 15
	s_nop 7
	s_nop 0
	v_max3_f32 v68, v48, v49, v32
	v_max3_f32 v69, v50, v51, v33
	s_nop 0
	v_max3_f32 v68, v68, v34, v35
	v_max3_f32 v69, v69, v54, v55
	s_nop 0
	v_max3_f32 v68, v68, v52, v53
	v_max3_f32 v69, v69, v38, v39
	s_nop 0
	v_max3_f32 v68, v68, v36, v37
	v_max3_f32 v69, v69, v58, v59
	s_nop 0
	v_max3_f32 v68, v68, v56, v57
	v_max3_f32 v69, v69, v42, v43
	s_nop 0
	v_max3_f32 v68, v68, v40, v41
	v_max3_f32 v69, v69, v62, v63
	s_nop 0
	v_max3_f32 v68, v68, v60, v61
	v_max3_f32 v69, v69, v46, v47
	s_nop 0
	v_max3_f32 v68, v68, v44, v45
	s_nop 0
	v_max3_f32 v68, v68, v69, v69
	v_mov_b32_e32 v69, v68
	s_nop 1
	v_permlane32_swap_b32 v69, v68
	v_max_f32_e32 v68, v68, v69
	s_waitcnt lgkmcnt(0)
	s_nop 0
	v_cmp_lt_f32_e32 vcc, s78, v68
	s_cbranch_vccz .LBB0_116
	v_max_f32_e32 v68, v68, v68
	v_max_f32_e32 v68, 0, v68
	v_exp_f32_e64 v70, -v68
	v_pk_add_f32 v[48:49], v[48:49], v[68:69] op_sel_hi:[1,0] neg_lo:[0,1] neg_hi:[0,1]
	v_pk_add_f32 v[32:33], v[32:33], v[68:69] op_sel_hi:[1,0] neg_lo:[0,1] neg_hi:[0,1]
	v_pk_add_f32 v[50:51], v[50:51], v[68:69] op_sel_hi:[1,0] neg_lo:[0,1] neg_hi:[0,1]
	v_mul_f32_e32 v80, v80, v70
	v_pk_add_f32 v[34:35], v[34:35], v[68:69] op_sel_hi:[1,0] neg_lo:[0,1] neg_hi:[0,1]
	v_pk_add_f32 v[52:53], v[52:53], v[68:69] op_sel_hi:[1,0] neg_lo:[0,1] neg_hi:[0,1]
	v_pk_add_f32 v[36:37], v[36:37], v[68:69] op_sel_hi:[1,0] neg_lo:[0,1] neg_hi:[0,1]
	v_pk_add_f32 v[54:55], v[54:55], v[68:69] op_sel_hi:[1,0] neg_lo:[0,1] neg_hi:[0,1]
	v_pk_add_f32 v[38:39], v[38:39], v[68:69] op_sel_hi:[1,0] neg_lo:[0,1] neg_hi:[0,1]
	v_pk_add_f32 v[56:57], v[56:57], v[68:69] op_sel_hi:[1,0] neg_lo:[0,1] neg_hi:[0,1]
	v_pk_add_f32 v[40:41], v[40:41], v[68:69] op_sel_hi:[1,0] neg_lo:[0,1] neg_hi:[0,1]
	v_pk_add_f32 v[58:59], v[58:59], v[68:69] op_sel_hi:[1,0] neg_lo:[0,1] neg_hi:[0,1]
	v_pk_add_f32 v[42:43], v[42:43], v[68:69] op_sel_hi:[1,0] neg_lo:[0,1] neg_hi:[0,1]
	v_pk_add_f32 v[60:61], v[60:61], v[68:69] op_sel_hi:[1,0] neg_lo:[0,1] neg_hi:[0,1]
	v_pk_add_f32 v[44:45], v[44:45], v[68:69] op_sel_hi:[1,0] neg_lo:[0,1] neg_hi:[0,1]
	v_pk_add_f32 v[62:63], v[62:63], v[68:69] op_sel_hi:[1,0] neg_lo:[0,1] neg_hi:[0,1]
	v_pk_add_f32 v[46:47], v[46:47], v[68:69] op_sel_hi:[1,0] neg_lo:[0,1] neg_hi:[0,1]
	v_pk_mul_f32 v[30:31], v[30:31], v[70:71] op_sel_hi:[1,0]
	v_pk_mul_f32 v[28:29], v[28:29], v[70:71] op_sel_hi:[1,0]
	v_pk_mul_f32 v[26:27], v[26:27], v[70:71] op_sel_hi:[1,0]
	v_pk_mul_f32 v[24:25], v[24:25], v[70:71] op_sel_hi:[1,0]
	v_pk_mul_f32 v[22:23], v[22:23], v[70:71] op_sel_hi:[1,0]
	v_pk_mul_f32 v[20:21], v[20:21], v[70:71] op_sel_hi:[1,0]
	v_pk_mul_f32 v[18:19], v[18:19], v[70:71] op_sel_hi:[1,0]
	v_pk_mul_f32 v[16:17], v[16:17], v[70:71] op_sel_hi:[1,0]
	v_pk_mul_f32 v[14:15], v[14:15], v[70:71] op_sel_hi:[1,0]
	v_pk_mul_f32 v[12:13], v[12:13], v[70:71] op_sel_hi:[1,0]
	v_pk_mul_f32 v[10:11], v[10:11], v[70:71] op_sel_hi:[1,0]
	v_pk_mul_f32 v[8:9], v[8:9], v[70:71] op_sel_hi:[1,0]
	v_pk_mul_f32 v[6:7], v[6:7], v[70:71] op_sel_hi:[1,0]
	v_pk_mul_f32 v[4:5], v[4:5], v[70:71] op_sel_hi:[1,0]
	v_pk_mul_f32 v[2:3], v[2:3], v[70:71] op_sel_hi:[1,0]
	v_pk_mul_f32 v[0:1], v[0:1], v[70:71] op_sel_hi:[1,0]

.LBB0_118:
	s_and_b64 vcc, exec, s[0:1]
	s_cbranch_vccz .LBB0_597
	v_readfirstlane_b32 s6, v149
	s_lshl_b32 s7, s14, 6
	s_waitcnt vmcnt(0)
	v_and_b32_e32 v10, 31, v149
	s_and_b32 s8, s7, 0x700
	s_ashr_i32 s0, s6, 1
	s_andn2_b32 s0, s0, 31
	v_or_b32_e32 v0, s8, v10
	v_add_u32_e32 v0, s0, v0
	v_add_u32_e32 v96, 0x8000, v0
	v_mov_b64_e32 v[4:5], s[90:91]
	s_waitcnt lgkmcnt(0)
	v_mad_i64_i32 v[0:1], s[0:1], v96, s85, v[4:5]
	s_and_b32 s0, s7, 0xc0
	v_bfe_u32 v11, v149, 5, 1
	s_lshl_b32 s68, s0, 1
	v_ashrrev_i32_e32 v12, 3, v149
	v_lshl_add_u64 v[0:1], v[0:1], 0, s[68:69]
	v_lshlrev_b32_e32 v98, 4, v11
	v_add_u32_e32 v14, s8, v12
	v_lshl_add_u64 v[0:1], v[0:1], 0, v[98:99]
	v_add_u32_e32 v46, 0x8000, v14
	global_load_dwordx4 v[92:95], v[0:1], off offset:1536
	global_load_dwordx4 v[88:91], v[0:1], off offset:1568
	global_load_dwordx4 v[84:87], v[0:1], off offset:1600
	global_load_dwordx4 v[80:83], v[0:1], off offset:1632
	v_and_b32_e32 v13, 7, v149
	v_mad_i64_i32 v[0:1], s[0:1], v46, s85, v[4:5]
	v_lshl_add_u64 v[0:1], v[0:1], 0, s[68:69]
	v_lshlrev_b32_e32 v6, 4, v13
	v_mov_b32_e32 v7, v99
	v_lshl_add_u64 v[8:9], v[0:1], 0, v[6:7]
	global_load_dwordx4 v[0:3], v[8:9], off offset:2048
	v_add_u32_e32 v15, 0x8040, v14
	v_mad_i64_i32 v[4:5], s[0:1], v15, s85, v[4:5]
	v_lshl_add_u64 v[4:5], v[4:5], 0, s[68:69]
	v_lshl_add_u64 v[116:117], v[4:5], 0, v[6:7]
	s_barrier
	global_load_dwordx4 v[100:103], v[116:117], off offset:2048
	global_load_dwordx4 v[104:107], v[8:9], off offset:2560
	s_movk_i32 s7, 0x90
	v_mul_lo_u32 v9, v12, s7
	v_add_u32_e32 v9, 0, v9
	v_add_u32_e32 v136, v9, v6
	v_lshrrev_b32_e32 v4, 2, v149
	v_and_b32_e32 v5, 16, v149
	v_lshlrev_b32_e32 v7, 2, v149
	v_lshlrev_b32_e32 v148, 2, v11
	v_and_or_b32 v5, v7, 12, v5
	v_and_or_b32 v4, v4, 3, v148
	v_lshlrev_b32_e32 v8, 3, v13
	v_mul_u32_u24_e32 v7, 0x90, v10
	v_lshlrev_b32_e32 v5, 1, v5
	v_add_u32_e32 v10, 0, v98
	v_mul_u32_u24_e32 v4, 0x90, v4
	v_add_u32_e32 v124, 0x8080, v14
	s_mov_b64 s[0:1], -1
	s_cmpk_lt_u32 s6, 0x100
	v_add3_u32 v97, v5, v4, 0
	v_add_u32_e32 v138, v10, v7
	v_add_u32_e32 v140, 64, v124
	v_add_u32_e32 v139, 0x80, v46
	v_lshlrev_b32_e32 v132, 1, v8
	s_waitcnt vmcnt(2)
	ds_write_b128 v136, v[0:3]
	s_waitcnt lgkmcnt(0)
	s_barrier
	s_cbranch_scc1 .LBB0_127
	ds_read_b128 v[0:3], v138 offset:4672
	ds_read_b128 v[4:7], v138 offset:4640
	ds_read_b128 v[8:11], v138
	ds_read_b128 v[48:51], v138 offset:32
	ds_read_b128 v[52:55], v138 offset:64
	ds_read_b128 v[56:59], v138 offset:4608
	v_readlane_b32 s36, v254, 47
	s_mov_b32 s0, s36
	v_readlane_b32 s37, v254, 48
	v_readlane_b32 s38, v254, 49
	v_readlane_b32 s39, v254, 50
	v_readlane_b32 s40, v254, 51
	v_readlane_b32 s41, v254, 52
	v_readlane_b32 s42, v254, 53
	v_readlane_b32 s43, v254, 54
	v_readlane_b32 s44, v254, 55
	v_readlane_b32 s45, v254, 56
	v_readlane_b32 s46, v254, 57
	v_readlane_b32 s47, v254, 58
	v_readlane_b32 s48, v254, 59
	v_readlane_b32 s49, v254, 60
	v_readlane_b32 s50, v254, 61
	v_readlane_b32 s51, v254, 62
	v_writelane_b32 v254, s0, 47
	s_mov_b32 s37, s36
	s_mov_b32 s38, s36
	v_writelane_b32 v254, s1, 48
	v_writelane_b32 v254, s2, 49
	v_writelane_b32 v254, s3, 50
	v_writelane_b32 v254, s4, 51
	v_writelane_b32 v254, s5, 52
	s_mov_b32 s39, s36
	s_mov_b32 s40, s36
	s_mov_b32 s41, s36
	s_mov_b32 s42, s36
	s_mov_b32 s43, s36
	s_mov_b32 s44, s36
	s_mov_b32 s45, s36
	s_mov_b32 s46, s36
	s_mov_b32 s47, s36
	s_mov_b32 s48, s36
	s_mov_b32 s49, s36
	s_mov_b32 s50, s36
	s_mov_b32 s51, s36
	v_writelane_b32 v254, s6, 53
	v_mov_b64_e32 v[30:31], s[36:37]
	v_writelane_b32 v254, s7, 54
	v_mov_b64_e32 v[32:33], s[38:39]
	v_mov_b64_e32 v[34:35], s[40:41]
	v_mov_b64_e32 v[36:37], s[42:43]
	v_mov_b64_e32 v[38:39], s[44:45]
	v_mov_b64_e32 v[40:41], s[46:47]
	v_mov_b64_e32 v[42:43], s[48:49]
	v_mov_b64_e32 v[44:45], s[50:51]
	v_writelane_b32 v254, s8, 55
	v_writelane_b32 v254, s9, 56
	s_waitcnt lgkmcnt(3)
	v_mfma_f32_32x32x16_bf16 v[14:29], v[8:11], v[92:95], v[30:45]
	v_writelane_b32 v254, s10, 57
	v_writelane_b32 v254, s11, 58
	v_writelane_b32 v254, s12, 59
	v_writelane_b32 v254, s13, 60
	v_writelane_b32 v254, s14, 61
	v_writelane_b32 v254, s15, 62
	s_waitcnt lgkmcnt(0)
	v_mfma_f32_32x32x16_bf16 v[30:45], v[56:59], v[92:95], v[30:45]
	ds_read_b128 v[8:11], v138 offset:96
	ds_read_b128 v[56:59], v138 offset:4704
	v_mfma_f32_32x32x16_bf16 v[14:29], v[48:51], v[88:91], v[14:29]
	v_mfma_f32_32x32x16_bf16 v[30:45], v[4:7], v[88:91], v[30:45]
	v_mfma_f32_32x32x16_bf16 v[14:29], v[52:55], v[84:87], v[14:29]
	v_mfma_f32_32x32x16_bf16 v[30:45], v[0:3], v[84:87], v[30:45]
	s_waitcnt lgkmcnt(1)
	v_mfma_f32_32x32x16_bf16 v[14:29], v[8:11], v[80:83], v[14:29]
	s_waitcnt lgkmcnt(0)
	v_mfma_f32_32x32x16_bf16 v[30:45], v[56:59], v[80:83], v[30:45]
	v_max3_f32 v3, v14, v15, v30
	v_max3_f32 v4, v16, v17, v31
	v_mov_b64_e32 v[122:123], s[90:91]
	v_max3_f32 v3, v3, v32, v33
	v_max3_f32 v4, v4, v20, v21
	v_cmp_lt_i32_e32 vcc, v232, v226
	v_max3_f32 v3, v3, v18, v19
	v_max3_f32 v4, v4, v36, v37
	v_mad_i64_i32 v[0:1], s[0:1], v124, s85, v[122:123]
	v_max3_f32 v3, v3, v34, v35
	v_max3_f32 v4, v4, v24, v25
	v_add_u32_e32 v2, 64, v46
	v_max3_f32 v3, v3, v22, v23
	v_max3_f32 v4, v4, v40, v41
	v_lshl_add_u64 v[0:1], v[0:1], 0, s[68:69]
	v_max3_f32 v3, v3, v38, v39
	v_max3_f32 v4, v4, v28, v29
	v_mov_b32_e32 v133, v99
	v_max3_f32 v3, v3, v26, v27
	v_max3_f32 v4, v4, v44, v45
	s_waitcnt vmcnt(1)
	ds_write_b128 v136, v[100:103] offset:13312
	s_waitcnt vmcnt(0)
	ds_write_b128 v136, v[104:107] offset:26624
	v_max3_f32 v3, v3, v42, v43
	v_lshl_add_u64 v[0:1], v[0:1], 0, v[132:133]
	v_max3_f32 v4, v3, v4, v4
	v_cndmask_b32_e32 v3, v225, v232, vcc
	v_lshlrev_b32_e32 v137, 2, v3
	v_mad_i64_i32 v[2:3], s[0:1], v2, s85, v[122:123]
	v_lshl_add_u64 v[2:3], v[2:3], 0, s[68:69]
	v_lshl_add_u64 v[2:3], v[2:3], 0, v[132:133]
	global_load_dwordx4 v[108:111], v[0:1], off offset:2048
	global_load_dwordx4 v[112:115], v[2:3], off offset:2560
	ds_bpermute_b32 v5, v137, v4
	s_waitcnt lgkmcnt(0)
	v_max3_f32 v47, v4, v5, v4
	s_waitcnt lgkmcnt(0)
	s_barrier
	s_nop 0
	v_sub_f32_e32 v30, v30, v47
	v_sub_f32_e32 v14, v14, v47
	v_sub_f32_e32 v31, v31, v47
	v_sub_f32_e32 v15, v15, v47
	v_exp_f32_e32 v50, v14
	v_exp_f32_e32 v51, v30
	v_exp_f32_e32 v98, v15
	v_exp_f32_e32 v30, v31
	v_sub_f32_e32 v32, v32, v47
	v_add_f32_e32 v31, v51, v50
	v_sub_f32_e32 v46, v16, v47
	v_pk_add_f32 v[14:15], v[30:31], v[98:99]
	v_sub_f32_e32 v33, v33, v47
	v_sub_f32_e32 v48, v17, v47
	v_pk_add_f32 v[16:17], v[14:15], v[14:15] op_sel_hi:[0,1]
	v_exp_f32_e32 v31, v46
	v_exp_f32_e32 v52, v32
	v_exp_f32_e32 v16, v48
	v_exp_f32_e32 v32, v33
	v_sub_f32_e32 v34, v34, v47
	v_add_f32_e32 v33, v52, v31
	v_sub_f32_e32 v46, v18, v47
	v_pk_add_f32 v[14:15], v[32:33], v[16:17]
	v_sub_f32_e32 v35, v35, v47
	v_sub_f32_e32 v48, v19, v47
	v_pk_add_f32 v[18:19], v[14:15], v[14:15] op_sel_hi:[0,1]
	v_exp_f32_e32 v17, v46
	v_exp_f32_e32 v33, v34
	v_exp_f32_e32 v18, v48
	v_exp_f32_e32 v34, v35
	v_sub_f32_e32 v36, v36, v47
	v_add_f32_e32 v35, v33, v17
	v_sub_f32_e32 v46, v20, v47
	v_pk_add_f32 v[14:15], v[34:35], v[18:19]
	v_sub_f32_e32 v37, v37, v47
	v_sub_f32_e32 v48, v21, v47
	v_pk_add_f32 v[20:21], v[14:15], v[14:15] op_sel_hi:[0,1]
	v_exp_f32_e32 v19, v46
	v_exp_f32_e32 v35, v36
	v_exp_f32_e32 v20, v48
	v_exp_f32_e32 v36, v37
	v_sub_f32_e32 v38, v38, v47
	v_add_f32_e32 v37, v35, v19
	v_sub_f32_e32 v46, v22, v47
	v_pk_add_f32 v[14:15], v[36:37], v[20:21]
	v_sub_f32_e32 v39, v39, v47
	v_sub_f32_e32 v48, v23, v47
	v_pk_add_f32 v[22:23], v[14:15], v[14:15] op_sel_hi:[0,1]
	v_exp_f32_e32 v21, v46
	v_exp_f32_e32 v37, v38
	v_exp_f32_e32 v22, v48
	v_exp_f32_e32 v38, v39
	v_sub_f32_e32 v40, v40, v47
	v_add_f32_e32 v39, v37, v21
	v_sub_f32_e32 v46, v24, v47
	v_pk_add_f32 v[14:15], v[38:39], v[22:23]
	v_sub_f32_e32 v41, v41, v47
	v_sub_f32_e32 v48, v25, v47
	v_pk_add_f32 v[24:25], v[14:15], v[14:15] op_sel_hi:[0,1]
	v_exp_f32_e32 v23, v46
	v_exp_f32_e32 v39, v40
	v_exp_f32_e32 v24, v48
	v_exp_f32_e32 v40, v41
	v_sub_f32_e32 v42, v42, v47
	v_add_f32_e32 v41, v39, v23
	v_sub_f32_e32 v46, v26, v47
	v_pk_add_f32 v[14:15], v[40:41], v[24:25]
	v_sub_f32_e32 v43, v43, v47
	v_sub_f32_e32 v48, v27, v47
	v_pk_add_f32 v[26:27], v[14:15], v[14:15] op_sel_hi:[0,1]
	v_exp_f32_e32 v25, v46
	v_exp_f32_e32 v41, v42
	v_exp_f32_e32 v26, v48
	v_exp_f32_e32 v42, v43
	v_sub_f32_e32 v44, v44, v47
	v_add_f32_e32 v43, v41, v25
	v_sub_f32_e32 v46, v28, v47
	v_pk_add_f32 v[14:15], v[42:43], v[26:27]
	v_sub_f32_e32 v45, v45, v47
	v_sub_f32_e32 v48, v29, v47
	v_pk_add_f32 v[28:29], v[14:15], v[14:15] op_sel_hi:[0,1]
	v_exp_f32_e32 v27, v46
	v_exp_f32_e32 v43, v44
	v_exp_f32_e32 v28, v48
	v_exp_f32_e32 v44, v45
	v_exp_f32_e64 v4, -v47
	v_add_f32_e32 v45, v43, v27
	v_cvt_pk_bf16_f32 v127, v31, v16
	v_pk_add_f32 v[48:49], v[44:45], v[28:29]
	v_cvt_pk_bf16_f32 v128, v17, v18
	v_cvt_pk_bf16_f32 v129, v19, v20
	v_cvt_pk_bf16_f32 v142, v21, v22
	v_cvt_pk_bf16_f32 v143, v23, v24
	v_cvt_pk_bf16_f32 v144, v25, v26
	v_cvt_pk_bf16_f32 v145, v27, v28
	v_cvt_pk_bf16_f32 v150, v51, v30
	ds_read_b128 v[16:19], v138 offset:13312
	ds_read_b128 v[20:23], v138 offset:13344
	ds_read_b128 v[24:27], v138 offset:17920
	ds_read_b128 v[28:31], v138 offset:13376
	ds_read_b128 v[158:161], v138 offset:17952
	ds_read_b128 v[162:165], v138 offset:17984
	v_mul_f32_e32 v0, 0, v4
	v_pk_add_f32 v[48:49], v[48:49], v[48:49] op_sel:[0,1] op_sel_hi:[1,0]
	v_mov_b32_e32 v46, v0
	v_mov_b32_e32 v49, v99
	v_pk_add_f32 v[118:119], v[46:47], v[48:49]
	v_cvt_pk_bf16_f32 v151, v52, v32
	v_xor_b32_e32 v32, 0x80000000, v119
	v_mov_b32_e32 v1, v0
	v_mov_b32_e32 v2, v0
	v_mov_b32_e32 v3, v0
	v_mov_b32_e32 v4, v0
	v_mov_b32_e32 v5, v0
	v_mov_b32_e32 v6, v0
	v_mov_b32_e32 v7, v0
	v_mov_b32_e32 v8, v0
	v_mov_b32_e32 v9, v0
	v_mov_b32_e32 v10, v0
	v_mov_b32_e32 v11, v0
	v_mov_b32_e32 v12, v0
	v_mov_b32_e32 v13, v0
	v_mov_b32_e32 v14, v0
	v_mov_b32_e32 v15, v0
	v_cvt_pk_bf16_f32 v152, v33, v34
	v_mov_b32_e32 v33, v32
	v_cvt_pk_bf16_f32 v126, v50, v98
	v_cvt_pk_bf16_f32 v153, v35, v36
	v_cvt_pk_bf16_f32 v154, v37, v38
	v_cvt_pk_bf16_f32 v155, v39, v40
	v_cvt_pk_bf16_f32 v156, v41, v42
	v_cvt_pk_bf16_f32 v157, v43, v44
	v_mov_b32_e32 v34, v32
	v_mov_b32_e32 v35, v32
	v_mov_b32_e32 v36, v32
	v_mov_b32_e32 v37, v32
	v_mov_b32_e32 v38, v32
	v_mov_b32_e32 v39, v32
	v_mov_b32_e32 v40, v32
	v_mov_b32_e32 v41, v32
	v_mov_b32_e32 v42, v32
	v_mov_b32_e32 v43, v32
	v_mov_b32_e32 v44, v32
	v_mov_b32_e32 v45, v32
	v_mov_b32_e32 v46, v32
	v_mov_b32_e32 v47, v32
	v_mov_b64_e32 v[78:79], v[46:47]
	v_mov_b64_e32 v[76:77], v[44:45]
	v_mov_b64_e32 v[74:75], v[42:43]
	v_mov_b64_e32 v[72:73], v[40:41]
	v_mov_b64_e32 v[70:71], v[38:39]
	v_mov_b64_e32 v[68:69], v[36:37]
	v_mov_b64_e32 v[66:67], v[34:35]
	v_mov_b64_e32 v[64:65], v[32:33]
	s_waitcnt lgkmcnt(5)
	v_mfma_f32_32x32x16_bf16 v[48:63], v[16:19], v[92:95], v[32:47]
	s_waitcnt lgkmcnt(3)
	v_mfma_f32_32x32x16_bf16 v[64:79], v[24:27], v[92:95], v[64:79]
	ds_read_b128 v[16:19], v138 offset:13408
	ds_read_b128 v[24:27], v138 offset:18016
	v_mfma_f32_32x32x16_bf16 v[48:63], v[20:23], v[88:91], v[48:63]
	s_waitcnt lgkmcnt(3)
	v_mfma_f32_32x32x16_bf16 v[64:79], v[158:161], v[88:91], v[64:79]
	ds_read_b64_tr_b16 v[34:35], v97 offset:26624
	ds_read_b64_tr_b16 v[36:37], v97 offset:27776
	ds_read_b64_tr_b16 v[40:41], v97 offset:27840
	ds_read_b64_tr_b16 v[38:39], v97 offset:26688
	v_mfma_f32_32x32x16_bf16 v[48:63], v[28:31], v[84:87], v[48:63]
	s_waitcnt lgkmcnt(6)
	v_mfma_f32_32x32x16_bf16 v[64:79], v[162:165], v[84:87], v[64:79]
	ds_read_b64_tr_b16 v[42:43], v97 offset:28928
	ds_read_b64_tr_b16 v[44:45], v97 offset:30080
	ds_read_b64_tr_b16 v[160:161], v97 offset:30144
	ds_read_b64_tr_b16 v[158:159], v97 offset:28992
	s_waitcnt lgkmcnt(9)
	v_mfma_f32_32x32x16_bf16 v[48:63], v[16:19], v[80:83], v[48:63]
	s_waitcnt lgkmcnt(8)
	v_mfma_f32_32x32x16_bf16 v[64:79], v[24:27], v[80:83], v[64:79]
	ds_read_b64_tr_b16 v[162:163], v97 offset:31232
	ds_read_b64_tr_b16 v[164:165], v97 offset:32384
	ds_read_b64_tr_b16 v[168:169], v97 offset:32448
	ds_read_b64_tr_b16 v[166:167], v97 offset:31296
	s_waitcnt lgkmcnt(10)
	v_mfma_f32_32x32x16_bf16 v[16:31], v[34:37], v[126:129], v[0:15]
	s_waitcnt lgkmcnt(8)
	v_mfma_f32_32x32x16_bf16 v[0:15], v[38:41], v[126:129], v[0:15]
	ds_read_b64_tr_b16 v[34:35], v97 offset:33536
	ds_read_b64_tr_b16 v[36:37], v97 offset:34688
	ds_read_b64_tr_b16 v[40:41], v97 offset:34752
	ds_read_b64_tr_b16 v[38:39], v97 offset:33600
	s_waitcnt lgkmcnt(10)
	v_mfma_f32_32x32x16_bf16 v[16:31], v[42:45], v[142:145], v[16:31]
	s_waitcnt lgkmcnt(8)
	v_mfma_f32_32x32x16_bf16 v[0:15], v[158:161], v[142:145], v[0:15]
	s_waitcnt lgkmcnt(6)
	v_mfma_f32_32x32x16_bf16 v[16:31], v[162:165], v[150:153], v[16:31]
	s_waitcnt lgkmcnt(4)
	v_mfma_f32_32x32x16_bf16 v[0:15], v[166:169], v[150:153], v[0:15]
	s_waitcnt lgkmcnt(2)
	v_mfma_f32_32x32x16_bf16 v[16:31], v[34:37], v[154:157], v[16:31]
	s_waitcnt lgkmcnt(0)
	v_mfma_f32_32x32x16_bf16 v[0:15], v[38:41], v[154:157], v[0:15]
	v_mad_i64_i32 v[34:35], s[0:1], v140, s85, v[122:123]
	v_lshl_add_u64 v[34:35], v[34:35], 0, s[68:69]
	v_lshl_add_u64 v[120:121], v[34:35], 0, v[132:133]
	v_mad_i64_i32 v[34:35], s[0:1], v139, s85, v[122:123]
	v_lshl_add_u64 v[34:35], v[34:35], 0, s[68:69]
	s_waitcnt vmcnt(1)
	ds_write_b128 v136, v[108:111]
	s_waitcnt vmcnt(0)
	ds_write_b128 v136, v[112:115] offset:35840
	v_lshl_add_u64 v[34:35], v[34:35], 0, v[132:133]
	global_load_dwordx4 v[108:111], v[120:121], off offset:2048
	global_load_dwordx4 v[112:115], v[34:35], off offset:2560
	v_max3_f32 v33, v48, v49, v64
	v_max3_f32 v34, v50, v51, v65
	s_waitcnt lgkmcnt(0)
	s_barrier
	s_nop 0
	v_max3_f32 v33, v33, v66, v67
	v_max3_f32 v34, v34, v54, v55
	s_nop 0
	v_max3_f32 v33, v33, v52, v53
	v_max3_f32 v34, v34, v70, v71
	s_nop 0
	v_max3_f32 v33, v33, v68, v69
	v_max3_f32 v34, v34, v58, v59
	s_nop 0
	v_max3_f32 v33, v33, v56, v57
	v_max3_f32 v34, v34, v74, v75
	s_nop 0
	v_max3_f32 v33, v33, v72, v73
	v_max3_f32 v34, v34, v62, v63
	s_nop 0
	v_max3_f32 v33, v33, v60, v61
	v_max3_f32 v34, v34, v78, v79
	s_nop 0
	v_max3_f32 v33, v33, v76, v77
	s_nop 0
	v_max3_f32 v33, v33, v34, v34
	v_mov_b32_e32 v34, v33
	s_nop 1
	v_permlane32_swap_b32 v34, v33
	v_max_f32_e32 v33, v33, v34
	s_waitcnt lgkmcnt(0)
	s_nop 0
	v_cmp_lt_f32_e32 vcc, s78, v33
	s_cbranch_vccz .LBB0_122
	v_max_f32_e32 v32, v33, v33
	v_max_f32_e32 v32, 0, v32
	v_exp_f32_e64 v34, -v32
	v_add_f32_e32 v119, v119, v32
	v_pk_add_f32 v[48:49], v[48:49], v[32:33] op_sel_hi:[1,0] neg_lo:[0,1] neg_hi:[0,1]
	v_pk_add_f32 v[64:65], v[64:65], v[32:33] op_sel_hi:[1,0] neg_lo:[0,1] neg_hi:[0,1]
	v_pk_add_f32 v[50:51], v[50:51], v[32:33] op_sel_hi:[1,0] neg_lo:[0,1] neg_hi:[0,1]
	v_pk_add_f32 v[66:67], v[66:67], v[32:33] op_sel_hi:[1,0] neg_lo:[0,1] neg_hi:[0,1]
	v_pk_add_f32 v[52:53], v[52:53], v[32:33] op_sel_hi:[1,0] neg_lo:[0,1] neg_hi:[0,1]
	v_pk_add_f32 v[68:69], v[68:69], v[32:33] op_sel_hi:[1,0] neg_lo:[0,1] neg_hi:[0,1]
	v_pk_add_f32 v[54:55], v[54:55], v[32:33] op_sel_hi:[1,0] neg_lo:[0,1] neg_hi:[0,1]
	v_pk_add_f32 v[70:71], v[70:71], v[32:33] op_sel_hi:[1,0] neg_lo:[0,1] neg_hi:[0,1]
	v_pk_add_f32 v[56:57], v[56:57], v[32:33] op_sel_hi:[1,0] neg_lo:[0,1] neg_hi:[0,1]
	v_pk_add_f32 v[72:73], v[72:73], v[32:33] op_sel_hi:[1,0] neg_lo:[0,1] neg_hi:[0,1]
	v_pk_add_f32 v[58:59], v[58:59], v[32:33] op_sel_hi:[1,0] neg_lo:[0,1] neg_hi:[0,1]
	v_pk_add_f32 v[74:75], v[74:75], v[32:33] op_sel_hi:[1,0] neg_lo:[0,1] neg_hi:[0,1]
	v_pk_add_f32 v[60:61], v[60:61], v[32:33] op_sel_hi:[1,0] neg_lo:[0,1] neg_hi:[0,1]
	v_pk_add_f32 v[76:77], v[76:77], v[32:33] op_sel_hi:[1,0] neg_lo:[0,1] neg_hi:[0,1]
	v_pk_add_f32 v[62:63], v[62:63], v[32:33] op_sel_hi:[1,0] neg_lo:[0,1] neg_hi:[0,1]
	v_pk_add_f32 v[78:79], v[78:79], v[32:33] op_sel_hi:[1,0] neg_lo:[0,1] neg_hi:[0,1]
	v_pk_mul_f32 v[30:31], v[30:31], v[34:35] op_sel_hi:[1,0]
	v_pk_mul_f32 v[28:29], v[28:29], v[34:35] op_sel_hi:[1,0]
	v_pk_mul_f32 v[26:27], v[26:27], v[34:35] op_sel_hi:[1,0]
	v_pk_mul_f32 v[24:25], v[24:25], v[34:35] op_sel_hi:[1,0]
	v_pk_mul_f32 v[22:23], v[22:23], v[34:35] op_sel_hi:[1,0]
	v_pk_mul_f32 v[20:21], v[20:21], v[34:35] op_sel_hi:[1,0]
	v_pk_mul_f32 v[18:19], v[18:19], v[34:35] op_sel_hi:[1,0]
	v_pk_mul_f32 v[16:17], v[16:17], v[34:35] op_sel_hi:[1,0]
	v_pk_mul_f32 v[14:15], v[14:15], v[34:35] op_sel_hi:[1,0]
	v_pk_mul_f32 v[12:13], v[12:13], v[34:35] op_sel_hi:[1,0]
	v_pk_mul_f32 v[10:11], v[10:11], v[34:35] op_sel_hi:[1,0]
	v_pk_mul_f32 v[8:9], v[8:9], v[34:35] op_sel_hi:[1,0]
	v_pk_mul_f32 v[6:7], v[6:7], v[34:35] op_sel_hi:[1,0]
	v_pk_mul_f32 v[4:5], v[4:5], v[34:35] op_sel_hi:[1,0]
	v_pk_mul_f32 v[2:3], v[2:3], v[34:35] op_sel_hi:[1,0]
	v_pk_mul_f32 v[0:1], v[0:1], v[34:35] op_sel_hi:[1,0]
	v_xor_b32_e32 v32, 0x80000000, v119
	v_mul_f32_e32 v118, v118, v34
.LBB0_122:
	v_exp_f32_e32 v125, v48
	v_exp_f32_e32 v130, v64
	v_exp_f32_e32 v98, v49
	v_exp_f32_e32 v122, v65
	v_exp_f32_e32 v131, v66
	v_add_f32_e32 v123, v130, v125
	v_exp_f32_e32 v64, v67
	v_pk_add_f32 v[48:49], v[122:123], v[98:99]
	v_exp_f32_e32 v123, v50
	v_pk_add_f32 v[48:49], v[48:49], v[48:49] op_sel_hi:[0,1]
	v_exp_f32_e32 v48, v51
	v_exp_f32_e32 v66, v69
	v_add_f32_e32 v65, v131, v123
	v_mov_b32_e32 v33, v32
	v_pk_add_f32 v[50:51], v[64:65], v[48:49]
	v_exp_f32_e32 v49, v52
	v_pk_add_f32 v[50:51], v[50:51], v[50:51] op_sel_hi:[0,1]
	v_exp_f32_e32 v65, v68
	v_exp_f32_e32 v50, v53
	v_exp_f32_e32 v68, v71
	v_cvt_pk_bf16_f32 v127, v123, v48
	v_add_f32_e32 v67, v65, v49
	v_pk_add_f32 v[52:53], v[66:67], v[50:51]
	v_exp_f32_e32 v51, v54
	v_pk_add_f32 v[52:53], v[52:53], v[52:53] op_sel_hi:[0,1]
	v_exp_f32_e32 v67, v70
	v_exp_f32_e32 v52, v55
	v_exp_f32_e32 v70, v73
	v_cvt_pk_bf16_f32 v128, v49, v50
	v_add_f32_e32 v69, v67, v51
	v_pk_add_f32 v[54:55], v[68:69], v[52:53]
	v_exp_f32_e32 v53, v56
	v_pk_add_f32 v[54:55], v[54:55], v[54:55] op_sel_hi:[0,1]
	v_exp_f32_e32 v69, v72
	v_exp_f32_e32 v54, v57
	v_exp_f32_e32 v72, v75
	v_cvt_pk_bf16_f32 v129, v51, v52
	v_add_f32_e32 v71, v69, v53
	v_pk_add_f32 v[56:57], v[70:71], v[54:55]
	v_exp_f32_e32 v55, v58
	v_pk_add_f32 v[56:57], v[56:57], v[56:57] op_sel_hi:[0,1]
	v_exp_f32_e32 v71, v74
	v_exp_f32_e32 v56, v59
	v_exp_f32_e32 v74, v77
	ds_read_b128 v[158:161], v138 offset:4608
	ds_read_b128 v[48:51], v138
	ds_read_b128 v[162:165], v138 offset:32
	ds_read_b128 v[166:169], v138 offset:4640
	ds_read_b128 v[170:173], v138 offset:64
	ds_read_b128 v[174:177], v138 offset:4672
	v_add_f32_e32 v73, v71, v55
	v_pk_add_f32 v[58:59], v[72:73], v[56:57]
	v_exp_f32_e32 v57, v60
	v_pk_add_f32 v[58:59], v[58:59], v[58:59] op_sel_hi:[0,1]
	v_exp_f32_e32 v73, v76
	v_exp_f32_e32 v58, v61
	v_exp_f32_e32 v76, v79
	v_mov_b32_e32 v34, v32
	v_add_f32_e32 v75, v73, v57
	v_pk_add_f32 v[60:61], v[74:75], v[58:59]
	v_exp_f32_e32 v59, v62
	v_pk_add_f32 v[60:61], v[60:61], v[60:61] op_sel_hi:[0,1]
	v_exp_f32_e32 v75, v78
	v_exp_f32_e32 v60, v63
	v_mov_b32_e32 v35, v32
	v_mov_b32_e32 v36, v32
	v_add_f32_e32 v77, v75, v59
	v_pk_add_f32 v[62:63], v[76:77], v[60:61]
	v_mov_b32_e32 v37, v32
	v_add_f32_e32 v61, v62, v63
	v_mov_b32_e32 v38, v32
	v_mov_b32_e32 v39, v32
	v_mov_b32_e32 v40, v32
	v_mov_b32_e32 v41, v32
	v_mov_b32_e32 v42, v32
	v_mov_b32_e32 v43, v32
	v_mov_b32_e32 v44, v32
	v_mov_b32_e32 v45, v32
	v_mov_b32_e32 v46, v32
	v_mov_b32_e32 v47, v32
	v_add_f32_e32 v118, v118, v61
	v_cvt_pk_bf16_f32 v126, v125, v98
	v_cvt_pk_bf16_f32 v142, v53, v54
	v_cvt_pk_bf16_f32 v143, v55, v56
	v_cvt_pk_bf16_f32 v144, v57, v58
	v_cvt_pk_bf16_f32 v145, v59, v60
	v_cvt_pk_bf16_f32 v150, v130, v122
	v_cvt_pk_bf16_f32 v151, v131, v64
	v_cvt_pk_bf16_f32 v152, v65, v66
	v_cvt_pk_bf16_f32 v153, v67, v68
	v_cvt_pk_bf16_f32 v154, v69, v70
	v_cvt_pk_bf16_f32 v155, v71, v72
	v_cvt_pk_bf16_f32 v156, v73, v74
	v_cvt_pk_bf16_f32 v157, v75, v76
	s_waitcnt lgkmcnt(4)
	v_mfma_f32_32x32x16_bf16 v[64:79], v[48:51], v[92:95], v[32:47]
	v_mfma_f32_32x32x16_bf16 v[48:63], v[158:161], v[92:95], v[32:47]
	ds_read_b128 v[158:161], v138 offset:96
	ds_read_b128 v[188:191], v138 offset:4704
	s_waitcnt lgkmcnt(5)
	v_mfma_f32_32x32x16_bf16 v[64:79], v[162:165], v[88:91], v[64:79]
	s_waitcnt lgkmcnt(4)
	v_mfma_f32_32x32x16_bf16 v[48:63], v[166:169], v[88:91], v[48:63]
	ds_read_b64_tr_b16 v[162:163], v97 offset:35840
	ds_read_b64_tr_b16 v[164:165], v97 offset:36992
	ds_read_b64_tr_b16 v[168:169], v97 offset:37056
	ds_read_b64_tr_b16 v[166:167], v97 offset:35904
	s_waitcnt lgkmcnt(7)
	v_mfma_f32_32x32x16_bf16 v[64:79], v[170:173], v[84:87], v[64:79]
	s_waitcnt lgkmcnt(6)
	v_mfma_f32_32x32x16_bf16 v[48:63], v[174:177], v[84:87], v[48:63]
	ds_read_b64_tr_b16 v[170:171], v97 offset:38144
	ds_read_b64_tr_b16 v[172:173], v97 offset:39296
	ds_read_b64_tr_b16 v[176:177], v97 offset:39360
	ds_read_b64_tr_b16 v[174:175], v97 offset:38208
	s_waitcnt lgkmcnt(9)
	v_mfma_f32_32x32x16_bf16 v[64:79], v[158:161], v[80:83], v[64:79]
	s_waitcnt lgkmcnt(8)
	v_mfma_f32_32x32x16_bf16 v[48:63], v[188:191], v[80:83], v[48:63]
	ds_read_b64_tr_b16 v[158:159], v97 offset:40448
	ds_read_b64_tr_b16 v[160:161], v97 offset:41600
	ds_read_b64_tr_b16 v[190:191], v97 offset:41664
	ds_read_b64_tr_b16 v[188:189], v97 offset:40512
	s_waitcnt lgkmcnt(10)
	v_mfma_f32_32x32x16_bf16 v[16:31], v[162:165], v[126:129], v[16:31]
	s_waitcnt lgkmcnt(8)
	v_mfma_f32_32x32x16_bf16 v[0:15], v[166:169], v[126:129], v[0:15]
	ds_read_b64_tr_b16 v[126:127], v97 offset:42752
	ds_read_b64_tr_b16 v[128:129], v97 offset:43904
	ds_read_b64_tr_b16 v[164:165], v97 offset:43968
	ds_read_b64_tr_b16 v[162:163], v97 offset:42816
	s_waitcnt lgkmcnt(10)
	v_mfma_f32_32x32x16_bf16 v[16:31], v[170:173], v[142:145], v[16:31]
	s_waitcnt lgkmcnt(8)
	v_mfma_f32_32x32x16_bf16 v[0:15], v[174:177], v[142:145], v[0:15]
	s_waitcnt lgkmcnt(6)
	v_mfma_f32_32x32x16_bf16 v[16:31], v[158:161], v[150:153], v[16:31]
	s_waitcnt lgkmcnt(4)
	v_mfma_f32_32x32x16_bf16 v[0:15], v[188:191], v[150:153], v[0:15]
	s_waitcnt lgkmcnt(2)
	v_mfma_f32_32x32x16_bf16 v[16:31], v[126:129], v[154:157], v[16:31]
	s_waitcnt lgkmcnt(0)
	v_mfma_f32_32x32x16_bf16 v[0:15], v[162:165], v[154:157], v[0:15]
	s_waitcnt vmcnt(1)
	ds_write_b128 v136, v[108:111] offset:13312
	s_waitcnt vmcnt(0)
	ds_write_b128 v136, v[112:115] offset:26624
	global_load_dwordx4 v[108:111], v[120:121], off offset:2560
	v_max3_f32 v98, v64, v65, v48
	v_max3_f32 v112, v66, v67, v49
	s_waitcnt lgkmcnt(0)
	s_barrier
	v_readlane_b32 s26, v255, 43
	v_max3_f32 v98, v98, v50, v51
	v_max3_f32 v112, v112, v70, v71
	v_readlane_b32 s27, v255, 44
	v_max3_f32 v98, v98, v68, v69
	v_max3_f32 v112, v112, v54, v55
	s_nop 0
	v_max3_f32 v98, v98, v52, v53
	v_max3_f32 v112, v112, v74, v75
	s_nop 0
	v_max3_f32 v98, v98, v72, v73
	v_max3_f32 v112, v112, v58, v59
	s_nop 0
	v_max3_f32 v98, v98, v56, v57
	v_max3_f32 v112, v112, v78, v79
	s_nop 0
	v_max3_f32 v98, v98, v76, v77
	v_max3_f32 v112, v112, v62, v63
	s_nop 0
	v_max3_f32 v98, v98, v60, v61
	s_nop 0
	v_max3_f32 v98, v98, v112, v112
	v_mov_b32_e32 v112, v98
	s_nop 1
	v_permlane32_swap_b32 v112, v98
	v_max_f32_e32 v98, v98, v112
	s_waitcnt lgkmcnt(0)
	s_nop 0
	v_cmp_lt_f32_e32 vcc, s78, v98
	s_cbranch_vccz .LBB0_124
	v_max_f32_e32 v32, v98, v98
	v_max_f32_e32 v32, 0, v32
	v_exp_f32_e64 v34, -v32
	v_add_f32_e32 v33, v119, v32
	v_pk_add_f32 v[64:65], v[64:65], v[32:33] op_sel_hi:[1,0] neg_lo:[0,1] neg_hi:[0,1]
	v_pk_add_f32 v[48:49], v[48:49], v[32:33] op_sel_hi:[1,0] neg_lo:[0,1] neg_hi:[0,1]
	v_pk_add_f32 v[66:67], v[66:67], v[32:33] op_sel_hi:[1,0] neg_lo:[0,1] neg_hi:[0,1]
	v_pk_add_f32 v[50:51], v[50:51], v[32:33] op_sel_hi:[1,0] neg_lo:[0,1] neg_hi:[0,1]
	v_pk_add_f32 v[68:69], v[68:69], v[32:33] op_sel_hi:[1,0] neg_lo:[0,1] neg_hi:[0,1]
	v_pk_add_f32 v[52:53], v[52:53], v[32:33] op_sel_hi:[1,0] neg_lo:[0,1] neg_hi:[0,1]
	v_pk_add_f32 v[70:71], v[70:71], v[32:33] op_sel_hi:[1,0] neg_lo:[0,1] neg_hi:[0,1]
	v_pk_add_f32 v[54:55], v[54:55], v[32:33] op_sel_hi:[1,0] neg_lo:[0,1] neg_hi:[0,1]
	v_pk_add_f32 v[72:73], v[72:73], v[32:33] op_sel_hi:[1,0] neg_lo:[0,1] neg_hi:[0,1]
	v_pk_add_f32 v[56:57], v[56:57], v[32:33] op_sel_hi:[1,0] neg_lo:[0,1] neg_hi:[0,1]
	v_pk_add_f32 v[74:75], v[74:75], v[32:33] op_sel_hi:[1,0] neg_lo:[0,1] neg_hi:[0,1]
	v_pk_add_f32 v[58:59], v[58:59], v[32:33] op_sel_hi:[1,0] neg_lo:[0,1] neg_hi:[0,1]
	v_pk_add_f32 v[76:77], v[76:77], v[32:33] op_sel_hi:[1,0] neg_lo:[0,1] neg_hi:[0,1]
	v_pk_add_f32 v[60:61], v[60:61], v[32:33] op_sel_hi:[1,0] neg_lo:[0,1] neg_hi:[0,1]
	v_pk_add_f32 v[78:79], v[78:79], v[32:33] op_sel_hi:[1,0] neg_lo:[0,1] neg_hi:[0,1]
	v_pk_add_f32 v[62:63], v[62:63], v[32:33] op_sel_hi:[1,0] neg_lo:[0,1] neg_hi:[0,1]
	v_xor_b32_e32 v32, 0x80000000, v33
	v_mul_f32_e32 v118, v118, v34
	v_pk_mul_f32 v[30:31], v[30:31], v[34:35] op_sel_hi:[1,0]
	v_pk_mul_f32 v[28:29], v[28:29], v[34:35] op_sel_hi:[1,0]
	v_pk_mul_f32 v[26:27], v[26:27], v[34:35] op_sel_hi:[1,0]
	v_pk_mul_f32 v[24:25], v[24:25], v[34:35] op_sel_hi:[1,0]
	v_pk_mul_f32 v[22:23], v[22:23], v[34:35] op_sel_hi:[1,0]
	v_pk_mul_f32 v[20:21], v[20:21], v[34:35] op_sel_hi:[1,0]
	v_pk_mul_f32 v[18:19], v[18:19], v[34:35] op_sel_hi:[1,0]
	v_pk_mul_f32 v[16:17], v[16:17], v[34:35] op_sel_hi:[1,0]
	v_pk_mul_f32 v[14:15], v[14:15], v[34:35] op_sel_hi:[1,0]
	v_pk_mul_f32 v[12:13], v[12:13], v[34:35] op_sel_hi:[1,0]
	v_pk_mul_f32 v[10:11], v[10:11], v[34:35] op_sel_hi:[1,0]
	v_pk_mul_f32 v[8:9], v[8:9], v[34:35] op_sel_hi:[1,0]
	v_pk_mul_f32 v[6:7], v[6:7], v[34:35] op_sel_hi:[1,0]
	v_pk_mul_f32 v[4:5], v[4:5], v[34:35] op_sel_hi:[1,0]
	v_pk_mul_f32 v[2:3], v[2:3], v[34:35] op_sel_hi:[1,0]
	v_pk_mul_f32 v[0:1], v[0:1], v[34:35] op_sel_hi:[1,0]
	v_mov_b32_e32 v33, v32
	v_mov_b32_e32 v34, v32
	v_mov_b32_e32 v35, v32
	v_mov_b32_e32 v36, v32
	v_mov_b32_e32 v37, v32
	v_mov_b32_e32 v38, v32
	v_mov_b32_e32 v39, v32
	v_mov_b32_e32 v40, v32
	v_mov_b32_e32 v41, v32
	v_mov_b32_e32 v42, v32
	v_mov_b32_e32 v43, v32
	v_mov_b32_e32 v44, v32
	v_mov_b32_e32 v45, v32
	v_mov_b32_e32 v46, v32
	v_mov_b32_e32 v47, v32
.LBB0_124:
	v_exp_f32_e32 v119, v64
	v_exp_f32_e32 v125, v48
	v_exp_f32_e32 v98, v65
	v_exp_f32_e32 v112, v49
	v_exp_f32_e32 v65, v66
	v_add_f32_e32 v113, v125, v119
	v_exp_f32_e32 v114, v51
	v_pk_add_f32 v[48:49], v[112:113], v[98:99]
	v_exp_f32_e32 v113, v50
	v_pk_add_f32 v[48:49], v[48:49], v[48:49] op_sel_hi:[0,1]
	v_exp_f32_e32 v48, v67
	v_exp_f32_e32 v120, v53
	v_add_f32_e32 v115, v113, v65
	v_exp_f32_e32 v122, v55
	v_pk_add_f32 v[50:51], v[114:115], v[48:49]
	v_exp_f32_e32 v49, v68
	v_pk_add_f32 v[50:51], v[50:51], v[50:51] op_sel_hi:[0,1]
	v_exp_f32_e32 v115, v52
	v_exp_f32_e32 v50, v69
	v_exp_f32_e32 v126, v57
	v_exp_f32_e32 v128, v59
	v_add_f32_e32 v121, v115, v49
	v_pk_add_f32 v[52:53], v[120:121], v[50:51]
	v_exp_f32_e32 v51, v70
	v_pk_add_f32 v[52:53], v[52:53], v[52:53] op_sel_hi:[0,1]
	v_exp_f32_e32 v121, v54
	v_exp_f32_e32 v52, v71
	v_exp_f32_e32 v130, v61
	v_exp_f32_e32 v134, v63
	v_add_f32_e32 v123, v121, v51
	v_pk_add_f32 v[54:55], v[122:123], v[52:53]
	v_exp_f32_e32 v53, v72
	v_pk_add_f32 v[54:55], v[54:55], v[54:55] op_sel_hi:[0,1]
	v_exp_f32_e32 v123, v56
	v_exp_f32_e32 v54, v73
	v_cvt_pk_bf16_f32 v66, v119, v98
	v_cvt_pk_bf16_f32 v67, v65, v48
	v_add_f32_e32 v127, v123, v53
	v_pk_add_f32 v[56:57], v[126:127], v[54:55]
	v_exp_f32_e32 v55, v74
	v_pk_add_f32 v[56:57], v[56:57], v[56:57] op_sel_hi:[0,1]
	v_exp_f32_e32 v127, v58
	v_exp_f32_e32 v56, v75
	v_cvt_pk_bf16_f32 v74, v125, v112
	v_cvt_pk_bf16_f32 v75, v113, v114
	v_add_f32_e32 v129, v127, v55
	v_pk_add_f32 v[58:59], v[128:129], v[56:57]
	v_exp_f32_e32 v57, v76
	v_pk_add_f32 v[58:59], v[58:59], v[58:59] op_sel_hi:[0,1]
	v_exp_f32_e32 v129, v60
	v_exp_f32_e32 v58, v77
	v_cvt_pk_bf16_f32 v76, v115, v120
	v_cvt_pk_bf16_f32 v77, v121, v122
	v_add_f32_e32 v131, v129, v57
	v_pk_add_f32 v[60:61], v[130:131], v[58:59]
	v_exp_f32_e32 v59, v78
	v_pk_add_f32 v[60:61], v[60:61], v[60:61] op_sel_hi:[0,1]
	v_exp_f32_e32 v78, v62
	v_exp_f32_e32 v60, v79
	v_cvt_pk_bf16_f32 v112, v123, v126
	v_cvt_pk_bf16_f32 v113, v127, v128
	v_add_f32_e32 v135, v78, v59
	v_pk_add_f32 v[62:63], v[134:135], v[60:61]
	v_cvt_pk_bf16_f32 v114, v129, v130
	v_add_f32_e32 v61, v62, v63
	v_add_f32_e32 v64, v118, v61
	ds_read_b128 v[118:121], v138 offset:17920
	ds_read_b128 v[126:129], v138 offset:13312
	ds_read_b128 v[142:145], v138 offset:13344
	ds_read_b128 v[150:153], v138 offset:17952
	ds_read_b128 v[154:157], v138 offset:13376
	ds_read_b128 v[158:161], v138 offset:17984
	v_cvt_pk_bf16_f32 v68, v49, v50
	v_cvt_pk_bf16_f32 v69, v51, v52
	v_cvt_pk_bf16_f32 v70, v53, v54
	v_cvt_pk_bf16_f32 v71, v55, v56
	v_cvt_pk_bf16_f32 v72, v57, v58
	v_cvt_pk_bf16_f32 v73, v59, v60
	v_cvt_pk_bf16_f32 v115, v78, v134
	s_waitcnt lgkmcnt(4)
	v_mfma_f32_32x32x16_bf16 v[48:63], v[126:129], v[92:95], v[32:47]
	v_mfma_f32_32x32x16_bf16 v[32:47], v[118:121], v[92:95], v[32:47]
	ds_read_b128 v[118:121], v138 offset:13408
	ds_read_b128 v[126:129], v138 offset:18016
	s_waitcnt lgkmcnt(5)
	v_mfma_f32_32x32x16_bf16 v[48:63], v[142:145], v[88:91], v[48:63]
	s_waitcnt lgkmcnt(4)
	v_mfma_f32_32x32x16_bf16 v[32:47], v[150:153], v[88:91], v[32:47]
	ds_read_b64_tr_b16 v[142:143], v97 offset:26624
	ds_read_b64_tr_b16 v[144:145], v97 offset:27776
	ds_read_b64_tr_b16 v[152:153], v97 offset:27840
	ds_read_b64_tr_b16 v[150:151], v97 offset:26688
	s_waitcnt lgkmcnt(7)
	v_mfma_f32_32x32x16_bf16 v[48:63], v[154:157], v[84:87], v[48:63]
	s_waitcnt lgkmcnt(6)
	v_mfma_f32_32x32x16_bf16 v[32:47], v[158:161], v[84:87], v[32:47]
	ds_read_b64_tr_b16 v[154:155], v97 offset:28928
	ds_read_b64_tr_b16 v[156:157], v97 offset:30080
	ds_read_b64_tr_b16 v[160:161], v97 offset:30144
	ds_read_b64_tr_b16 v[158:159], v97 offset:28992
	s_waitcnt lgkmcnt(9)
	v_mfma_f32_32x32x16_bf16 v[48:63], v[118:121], v[80:83], v[48:63]
	s_waitcnt lgkmcnt(8)
	v_mfma_f32_32x32x16_bf16 v[32:47], v[126:129], v[80:83], v[32:47]
	ds_read_b64_tr_b16 v[118:119], v97 offset:31232
	ds_read_b64_tr_b16 v[120:121], v97 offset:32384
	ds_read_b64_tr_b16 v[128:129], v97 offset:32448
	ds_read_b64_tr_b16 v[126:127], v97 offset:31296
	s_waitcnt lgkmcnt(10)
	v_mfma_f32_32x32x16_bf16 v[16:31], v[142:145], v[66:69], v[16:31]
	s_waitcnt lgkmcnt(8)
	v_mfma_f32_32x32x16_bf16 v[0:15], v[150:153], v[66:69], v[0:15]
	ds_read_b64_tr_b16 v[66:67], v97 offset:33536
	ds_read_b64_tr_b16 v[68:69], v97 offset:34688
	ds_read_b64_tr_b16 v[144:145], v97 offset:34752
	ds_read_b64_tr_b16 v[142:143], v97 offset:33600
	s_waitcnt lgkmcnt(10)
	v_mfma_f32_32x32x16_bf16 v[16:31], v[154:157], v[70:73], v[16:31]
	s_waitcnt lgkmcnt(8)
	v_mfma_f32_32x32x16_bf16 v[0:15], v[158:161], v[70:73], v[0:15]
	s_waitcnt lgkmcnt(6)
	v_mfma_f32_32x32x16_bf16 v[16:31], v[118:121], v[74:77], v[16:31]
	s_waitcnt lgkmcnt(4)
	v_mfma_f32_32x32x16_bf16 v[0:15], v[126:129], v[74:77], v[0:15]
	s_waitcnt lgkmcnt(2)
	v_mfma_f32_32x32x16_bf16 v[16:31], v[66:69], v[112:115], v[16:31]
	s_waitcnt lgkmcnt(0)
	v_mfma_f32_32x32x16_bf16 v[0:15], v[142:145], v[112:115], v[0:15]
	v_max3_f32 v65, v48, v49, v32
	v_max3_f32 v66, v50, v51, v33
	s_waitcnt vmcnt(0)
	ds_write_b128 v136, v[108:111] offset:35840
	v_max3_f32 v65, v65, v34, v35
	v_max3_f32 v66, v66, v54, v55
	s_waitcnt lgkmcnt(0)
	s_barrier
	s_nop 0
	v_max3_f32 v65, v65, v52, v53
	v_max3_f32 v66, v66, v38, v39
	s_nop 0
	v_max3_f32 v65, v65, v36, v37
	v_max3_f32 v66, v66, v58, v59
	s_nop 0
	v_max3_f32 v65, v65, v56, v57
	v_max3_f32 v66, v66, v42, v43
	s_nop 0
	v_max3_f32 v65, v65, v40, v41
	v_max3_f32 v66, v66, v62, v63
	s_nop 0
	v_max3_f32 v65, v65, v60, v61
	v_max3_f32 v66, v66, v46, v47
	s_nop 0
	v_max3_f32 v65, v65, v44, v45
	s_nop 0
	v_max3_f32 v65, v65, v66, v66
	v_mov_b32_e32 v66, v65
	s_nop 1
	v_permlane32_swap_b32 v66, v65
	v_max_f32_e32 v65, v65, v66
	s_waitcnt lgkmcnt(0)
	s_nop 0
	v_cmp_lt_f32_e32 vcc, s78, v65
	s_cbranch_vccz .LBB0_126
	v_max_f32_e32 v65, v65, v65
	v_max_f32_e32 v66, 0, v65
	v_exp_f32_e64 v68, -v66
	v_pk_add_f32 v[48:49], v[48:49], v[66:67] op_sel_hi:[1,0] neg_lo:[0,1] neg_hi:[0,1]
	v_pk_add_f32 v[32:33], v[32:33], v[66:67] op_sel_hi:[1,0] neg_lo:[0,1] neg_hi:[0,1]
	v_pk_add_f32 v[50:51], v[50:51], v[66:67] op_sel_hi:[1,0] neg_lo:[0,1] neg_hi:[0,1]
	v_mul_f32_e32 v64, v64, v68
	v_pk_add_f32 v[34:35], v[34:35], v[66:67] op_sel_hi:[1,0] neg_lo:[0,1] neg_hi:[0,1]
	v_pk_add_f32 v[52:53], v[52:53], v[66:67] op_sel_hi:[1,0] neg_lo:[0,1] neg_hi:[0,1]
	v_pk_add_f32 v[36:37], v[36:37], v[66:67] op_sel_hi:[1,0] neg_lo:[0,1] neg_hi:[0,1]
	v_pk_add_f32 v[54:55], v[54:55], v[66:67] op_sel_hi:[1,0] neg_lo:[0,1] neg_hi:[0,1]
	v_pk_add_f32 v[38:39], v[38:39], v[66:67] op_sel_hi:[1,0] neg_lo:[0,1] neg_hi:[0,1]
	v_pk_add_f32 v[56:57], v[56:57], v[66:67] op_sel_hi:[1,0] neg_lo:[0,1] neg_hi:[0,1]
	v_pk_add_f32 v[40:41], v[40:41], v[66:67] op_sel_hi:[1,0] neg_lo:[0,1] neg_hi:[0,1]
	v_pk_add_f32 v[58:59], v[58:59], v[66:67] op_sel_hi:[1,0] neg_lo:[0,1] neg_hi:[0,1]
	v_pk_add_f32 v[42:43], v[42:43], v[66:67] op_sel_hi:[1,0] neg_lo:[0,1] neg_hi:[0,1]
	v_pk_add_f32 v[60:61], v[60:61], v[66:67] op_sel_hi:[1,0] neg_lo:[0,1] neg_hi:[0,1]
	v_pk_add_f32 v[44:45], v[44:45], v[66:67] op_sel_hi:[1,0] neg_lo:[0,1] neg_hi:[0,1]
	v_pk_add_f32 v[62:63], v[62:63], v[66:67] op_sel_hi:[1,0] neg_lo:[0,1] neg_hi:[0,1]
	v_pk_add_f32 v[46:47], v[46:47], v[66:67] op_sel_hi:[1,0] neg_lo:[0,1] neg_hi:[0,1]
	v_pk_mul_f32 v[30:31], v[30:31], v[68:69] op_sel_hi:[1,0]
	v_pk_mul_f32 v[28:29], v[28:29], v[68:69] op_sel_hi:[1,0]
	v_pk_mul_f32 v[26:27], v[26:27], v[68:69] op_sel_hi:[1,0]
	v_pk_mul_f32 v[24:25], v[24:25], v[68:69] op_sel_hi:[1,0]
	v_pk_mul_f32 v[22:23], v[22:23], v[68:69] op_sel_hi:[1,0]
	v_pk_mul_f32 v[20:21], v[20:21], v[68:69] op_sel_hi:[1,0]
	v_pk_mul_f32 v[18:19], v[18:19], v[68:69] op_sel_hi:[1,0]
	v_pk_mul_f32 v[16:17], v[16:17], v[68:69] op_sel_hi:[1,0]
	v_pk_mul_f32 v[14:15], v[14:15], v[68:69] op_sel_hi:[1,0]
	v_pk_mul_f32 v[12:13], v[12:13], v[68:69] op_sel_hi:[1,0]
	v_pk_mul_f32 v[10:11], v[10:11], v[68:69] op_sel_hi:[1,0]
	v_pk_mul_f32 v[8:9], v[8:9], v[68:69] op_sel_hi:[1,0]
	v_pk_mul_f32 v[6:7], v[6:7], v[68:69] op_sel_hi:[1,0]
	v_pk_mul_f32 v[4:5], v[4:5], v[68:69] op_sel_hi:[1,0]
	v_pk_mul_f32 v[2:3], v[2:3], v[68:69] op_sel_hi:[1,0]
	v_pk_mul_f32 v[0:1], v[0:1], v[68:69] op_sel_hi:[1,0]

.LBB0_127:
	s_and_b64 vcc, exec, s[0:1]
	s_cbranch_vccz .LBB0_135
	s_nop 8
	ds_read_b128 v[0:3], v138
	ds_read_b128 v[4:7], v138 offset:32
	ds_read_b128 v[8:11], v138 offset:4608
	ds_read_b128 v[46:49], v138 offset:64
	ds_read_b128 v[50:53], v138 offset:4640
	ds_read_b128 v[54:57], v138 offset:4672
	v_readlane_b32 s36, v254, 47
	s_mov_b32 s0, s36
	v_readlane_b32 s37, v254, 48
	v_readlane_b32 s38, v254, 49
	v_readlane_b32 s39, v254, 50
	v_readlane_b32 s40, v254, 51
	v_readlane_b32 s41, v254, 52
	v_readlane_b32 s42, v254, 53
	v_readlane_b32 s43, v254, 54
	v_readlane_b32 s44, v254, 55
	v_readlane_b32 s45, v254, 56
	v_readlane_b32 s46, v254, 57
	v_readlane_b32 s47, v254, 58
	v_readlane_b32 s48, v254, 59
	v_readlane_b32 s49, v254, 60
	v_readlane_b32 s50, v254, 61
	v_readlane_b32 s51, v254, 62
	v_writelane_b32 v254, s0, 47
	s_mov_b32 s37, s36
	s_mov_b32 s38, s36
	v_writelane_b32 v254, s1, 48
	v_writelane_b32 v254, s2, 49
	v_writelane_b32 v254, s3, 50
	v_writelane_b32 v254, s4, 51
	v_writelane_b32 v254, s5, 52
	s_mov_b32 s39, s36
	s_mov_b32 s40, s36
	s_mov_b32 s41, s36
	s_mov_b32 s42, s36
	s_mov_b32 s43, s36
	s_mov_b32 s44, s36
	s_mov_b32 s45, s36
	s_mov_b32 s46, s36
	s_mov_b32 s47, s36
	s_mov_b32 s48, s36
	s_mov_b32 s49, s36
	s_mov_b32 s50, s36
	s_mov_b32 s51, s36
	v_writelane_b32 v254, s6, 53
	v_mov_b64_e32 v[30:31], s[36:37]
	v_writelane_b32 v254, s7, 54
	v_mov_b64_e32 v[32:33], s[38:39]
	v_mov_b64_e32 v[34:35], s[40:41]
	v_mov_b64_e32 v[36:37], s[42:43]
	v_mov_b64_e32 v[38:39], s[44:45]
	v_mov_b64_e32 v[40:41], s[46:47]
	v_mov_b64_e32 v[42:43], s[48:49]
	v_mov_b64_e32 v[44:45], s[50:51]
	v_writelane_b32 v254, s8, 55
	v_writelane_b32 v254, s9, 56
	s_waitcnt lgkmcnt(5)
	v_mfma_f32_32x32x16_bf16 v[14:29], v[0:3], v[92:95], v[30:45]
	v_writelane_b32 v254, s10, 57
	v_writelane_b32 v254, s11, 58
	v_writelane_b32 v254, s12, 59
	v_writelane_b32 v254, s13, 60
	v_writelane_b32 v254, s14, 61
	v_writelane_b32 v254, s15, 62
	s_waitcnt lgkmcnt(3)
	v_mfma_f32_32x32x16_bf16 v[30:45], v[8:11], v[92:95], v[30:45]
	ds_read_b128 v[0:3], v138 offset:96
	ds_read_b128 v[8:11], v138 offset:4704
	v_mfma_f32_32x32x16_bf16 v[14:29], v[4:7], v[88:91], v[14:29]
	s_waitcnt lgkmcnt(3)
	v_mfma_f32_32x32x16_bf16 v[30:45], v[50:53], v[88:91], v[30:45]
	v_mfma_f32_32x32x16_bf16 v[14:29], v[46:49], v[84:87], v[14:29]
	s_waitcnt lgkmcnt(2)
	v_mfma_f32_32x32x16_bf16 v[30:45], v[54:57], v[84:87], v[30:45]
	s_waitcnt lgkmcnt(1)
	v_mfma_f32_32x32x16_bf16 v[14:29], v[0:3], v[80:83], v[14:29]
	s_waitcnt lgkmcnt(0)
	v_mfma_f32_32x32x16_bf16 v[30:45], v[8:11], v[80:83], v[30:45]
	s_nop 15
	s_nop 7
	v_cmp_lt_i32_e32 vcc, v232, v226
	v_max3_f32 v0, v14, v15, v30
	v_max3_f32 v1, v16, v17, v31
	v_mov_b32_e32 v133, v99
	v_max3_f32 v0, v0, v32, v33
	v_max3_f32 v1, v1, v20, v21
	s_nop 0
	v_max3_f32 v0, v0, v18, v19
	v_max3_f32 v1, v1, v36, v37
	s_nop 0
	v_max3_f32 v0, v0, v34, v35
	v_max3_f32 v1, v1, v24, v25
	s_nop 0
	v_max3_f32 v0, v0, v22, v23
	v_max3_f32 v1, v1, v40, v41
	s_nop 0
	v_max3_f32 v0, v0, v38, v39
	v_max3_f32 v1, v1, v28, v29
	s_nop 0
	v_max3_f32 v0, v0, v26, v27
	v_max3_f32 v1, v1, v44, v45
	s_nop 0
	v_max3_f32 v0, v0, v42, v43
	s_nop 0
	v_max3_f32 v0, v0, v1, v1
	v_cndmask_b32_e32 v1, v225, v232, vcc
	v_lshlrev_b32_e32 v137, 2, v1
	ds_bpermute_b32 v1, v137, v0
	s_waitcnt lgkmcnt(0)
	v_max3_f32 v47, v0, v1, v0
	s_nop 0
	v_sub_f32_e32 v30, v30, v47
	v_sub_f32_e32 v14, v14, v47
	v_sub_f32_e32 v31, v31, v47
	v_sub_f32_e32 v15, v15, v47
	v_exp_f32_e32 v50, v14
	v_exp_f32_e32 v51, v30
	v_exp_f32_e32 v98, v15
	v_exp_f32_e32 v30, v31
	v_sub_f32_e32 v32, v32, v47
	v_add_f32_e32 v31, v51, v50
	v_sub_f32_e32 v46, v16, v47
	v_pk_add_f32 v[14:15], v[30:31], v[98:99]
	v_sub_f32_e32 v33, v33, v47
	v_sub_f32_e32 v48, v17, v47
	v_pk_add_f32 v[16:17], v[14:15], v[14:15] op_sel_hi:[0,1]
	v_exp_f32_e32 v31, v46
	v_exp_f32_e32 v52, v32
	v_exp_f32_e32 v16, v48
	v_exp_f32_e32 v32, v33
	v_sub_f32_e32 v34, v34, v47
	v_add_f32_e32 v33, v52, v31
	v_sub_f32_e32 v46, v18, v47
	v_pk_add_f32 v[14:15], v[32:33], v[16:17]
	v_sub_f32_e32 v35, v35, v47
	v_sub_f32_e32 v48, v19, v47
	v_pk_add_f32 v[18:19], v[14:15], v[14:15] op_sel_hi:[0,1]
	v_exp_f32_e32 v17, v46
	v_exp_f32_e32 v33, v34
	v_exp_f32_e32 v18, v48
	v_exp_f32_e32 v34, v35
	v_sub_f32_e32 v36, v36, v47
	v_add_f32_e32 v35, v33, v17
	v_sub_f32_e32 v46, v20, v47
	v_pk_add_f32 v[14:15], v[34:35], v[18:19]
	v_sub_f32_e32 v37, v37, v47
	v_sub_f32_e32 v48, v21, v47
	v_pk_add_f32 v[20:21], v[14:15], v[14:15] op_sel_hi:[0,1]
	v_exp_f32_e32 v19, v46
	v_exp_f32_e32 v35, v36
	v_exp_f32_e32 v20, v48
	v_exp_f32_e32 v36, v37
	v_sub_f32_e32 v46, v22, v47
	v_add_f32_e32 v37, v35, v19
	v_sub_f32_e32 v48, v23, v47
	v_pk_add_f32 v[14:15], v[36:37], v[20:21]
	v_sub_f32_e32 v38, v38, v47
	v_pk_add_f32 v[22:23], v[14:15], v[14:15] op_sel_hi:[0,1]
	v_mov_b64_e32 v[14:15], s[90:91]
	v_mad_i64_i32 v[14:15], s[0:1], v124, s85, v[14:15]
	v_lshl_add_u64 v[14:15], v[14:15], 0, s[68:69]
	v_lshl_add_u64 v[14:15], v[14:15], 0, v[132:133]
	global_load_dwordx4 v[108:111], v[14:15], off offset:2048
	global_load_dwordx4 v[112:115], v[116:117], off offset:2560
	v_sub_f32_e32 v39, v39, v47
	v_exp_f32_e32 v21, v46
	v_exp_f32_e32 v37, v38
	v_exp_f32_e32 v22, v48
	v_exp_f32_e32 v38, v39
	v_sub_f32_e32 v40, v40, v47
	v_add_f32_e32 v39, v37, v21
	v_sub_f32_e32 v46, v24, v47
	v_pk_add_f32 v[14:15], v[38:39], v[22:23]
	v_sub_f32_e32 v41, v41, v47
	v_sub_f32_e32 v48, v25, v47
	v_pk_add_f32 v[24:25], v[14:15], v[14:15] op_sel_hi:[0,1]
	v_exp_f32_e32 v23, v46
	v_exp_f32_e32 v39, v40
	v_exp_f32_e32 v24, v48
	v_exp_f32_e32 v40, v41
	v_sub_f32_e32 v42, v42, v47
	v_add_f32_e32 v41, v39, v23
	v_sub_f32_e32 v46, v26, v47
	v_pk_add_f32 v[14:15], v[40:41], v[24:25]
	v_sub_f32_e32 v43, v43, v47
	v_sub_f32_e32 v48, v27, v47
	v_pk_add_f32 v[26:27], v[14:15], v[14:15] op_sel_hi:[0,1]
	v_exp_f32_e32 v25, v46
	v_exp_f32_e32 v41, v42
	v_exp_f32_e32 v26, v48
	v_exp_f32_e32 v42, v43
	v_sub_f32_e32 v44, v44, v47
	v_add_f32_e32 v43, v41, v25
	v_sub_f32_e32 v46, v28, v47
	v_pk_add_f32 v[14:15], v[42:43], v[26:27]
	v_sub_f32_e32 v45, v45, v47
	v_sub_f32_e32 v48, v29, v47
	v_pk_add_f32 v[28:29], v[14:15], v[14:15] op_sel_hi:[0,1]
	v_exp_f32_e32 v27, v46
	v_exp_f32_e32 v43, v44
	v_exp_f32_e32 v28, v48
	v_exp_f32_e32 v44, v45
	s_waitcnt vmcnt(3)
	ds_write_b128 v136, v[100:103] offset:13312
	s_waitcnt vmcnt(2)
	ds_write_b128 v136, v[104:107] offset:26624
	v_add_f32_e32 v45, v43, v27
	s_waitcnt lgkmcnt(0)
	s_barrier
	v_exp_f32_e64 v0, -v47
	v_pk_add_f32 v[48:49], v[44:45], v[28:29]
	v_cvt_pk_bf16_f32 v117, v31, v16
	v_cvt_pk_bf16_f32 v118, v17, v18
	v_cvt_pk_bf16_f32 v119, v19, v20
	v_cvt_pk_bf16_f32 v120, v21, v22
	v_cvt_pk_bf16_f32 v121, v23, v24
	v_cvt_pk_bf16_f32 v122, v25, v26
	v_cvt_pk_bf16_f32 v123, v27, v28
	v_cvt_pk_bf16_f32 v124, v51, v30
	ds_read_b128 v[16:19], v138 offset:13312
	ds_read_b128 v[20:23], v138 offset:13344
	ds_read_b128 v[24:27], v138 offset:17920
	ds_read_b128 v[28:31], v138 offset:13376
	ds_read_b128 v[100:103], v138 offset:17952
	ds_read_b128 v[104:107], v138 offset:17984
	v_mul_f32_e32 v0, 0, v0
	v_pk_add_f32 v[48:49], v[48:49], v[48:49] op_sel:[0,1] op_sel_hi:[1,0]
	v_mov_b32_e32 v46, v0
	v_mov_b32_e32 v49, v99
	v_pk_add_f32 v[134:135], v[46:47], v[48:49]
	v_cvt_pk_bf16_f32 v125, v52, v32
	v_xor_b32_e32 v32, 0x80000000, v135
	v_mov_b32_e32 v1, v0
	v_mov_b32_e32 v2, v0
	v_mov_b32_e32 v3, v0
	v_mov_b32_e32 v4, v0
	v_mov_b32_e32 v5, v0
	v_mov_b32_e32 v6, v0
	v_mov_b32_e32 v7, v0
	v_mov_b32_e32 v8, v0
	v_mov_b32_e32 v9, v0
	v_mov_b32_e32 v10, v0
	v_mov_b32_e32 v11, v0
	v_mov_b32_e32 v12, v0
	v_mov_b32_e32 v13, v0
	v_mov_b32_e32 v14, v0
	v_mov_b32_e32 v15, v0
	v_cvt_pk_bf16_f32 v126, v33, v34
	v_mov_b32_e32 v33, v32
	v_cvt_pk_bf16_f32 v116, v50, v98
	v_cvt_pk_bf16_f32 v127, v35, v36
	v_cvt_pk_bf16_f32 v128, v37, v38
	v_cvt_pk_bf16_f32 v129, v39, v40
	v_cvt_pk_bf16_f32 v130, v41, v42
	v_cvt_pk_bf16_f32 v131, v43, v44
	v_mov_b32_e32 v34, v32
	v_mov_b32_e32 v35, v32
	v_mov_b32_e32 v36, v32
	v_mov_b32_e32 v37, v32
	v_mov_b32_e32 v38, v32
	v_mov_b32_e32 v39, v32
	v_mov_b32_e32 v40, v32
	v_mov_b32_e32 v41, v32
	v_mov_b32_e32 v42, v32
	v_mov_b32_e32 v43, v32
	v_mov_b32_e32 v44, v32
	v_mov_b32_e32 v45, v32
	v_mov_b32_e32 v46, v32
	v_mov_b32_e32 v47, v32
	v_mov_b64_e32 v[78:79], v[46:47]
	v_mov_b64_e32 v[76:77], v[44:45]
	v_mov_b64_e32 v[74:75], v[42:43]
	v_mov_b64_e32 v[72:73], v[40:41]
	v_mov_b64_e32 v[70:71], v[38:39]
	v_mov_b64_e32 v[68:69], v[36:37]
	v_mov_b64_e32 v[66:67], v[34:35]
	v_mov_b64_e32 v[64:65], v[32:33]
	s_waitcnt lgkmcnt(5)
	v_mfma_f32_32x32x16_bf16 v[48:63], v[16:19], v[92:95], v[32:47]
	s_waitcnt lgkmcnt(3)
	v_mfma_f32_32x32x16_bf16 v[64:79], v[24:27], v[92:95], v[64:79]
	ds_read_b128 v[16:19], v138 offset:13408
	ds_read_b128 v[24:27], v138 offset:18016
	v_mfma_f32_32x32x16_bf16 v[48:63], v[20:23], v[88:91], v[48:63]
	s_waitcnt lgkmcnt(3)
	v_mfma_f32_32x32x16_bf16 v[64:79], v[100:103], v[88:91], v[64:79]
	ds_read_b64_tr_b16 v[34:35], v97 offset:26624
	ds_read_b64_tr_b16 v[36:37], v97 offset:27776
	ds_read_b64_tr_b16 v[40:41], v97 offset:27840
	ds_read_b64_tr_b16 v[38:39], v97 offset:26688
	v_mfma_f32_32x32x16_bf16 v[48:63], v[28:31], v[84:87], v[48:63]
	s_waitcnt lgkmcnt(6)
	v_mfma_f32_32x32x16_bf16 v[64:79], v[104:107], v[84:87], v[64:79]
	ds_read_b64_tr_b16 v[42:43], v97 offset:28928
	ds_read_b64_tr_b16 v[44:45], v97 offset:30080
	ds_read_b64_tr_b16 v[102:103], v97 offset:30144
	ds_read_b64_tr_b16 v[100:101], v97 offset:28992
	s_waitcnt lgkmcnt(9)
	v_mfma_f32_32x32x16_bf16 v[48:63], v[16:19], v[80:83], v[48:63]
	s_waitcnt lgkmcnt(8)
	v_mfma_f32_32x32x16_bf16 v[64:79], v[24:27], v[80:83], v[64:79]
	ds_read_b64_tr_b16 v[104:105], v97 offset:31232
	ds_read_b64_tr_b16 v[106:107], v97 offset:32384
	ds_read_b64_tr_b16 v[144:145], v97 offset:32448
	ds_read_b64_tr_b16 v[142:143], v97 offset:31296
	s_waitcnt lgkmcnt(10)
	v_mfma_f32_32x32x16_bf16 v[16:31], v[34:37], v[116:119], v[0:15]
	s_waitcnt lgkmcnt(8)
	v_mfma_f32_32x32x16_bf16 v[0:15], v[38:41], v[116:119], v[0:15]
	ds_read_b64_tr_b16 v[34:35], v97 offset:33536
	ds_read_b64_tr_b16 v[36:37], v97 offset:34688
	ds_read_b64_tr_b16 v[40:41], v97 offset:34752
	ds_read_b64_tr_b16 v[38:39], v97 offset:33600
	s_waitcnt lgkmcnt(10)
	v_mfma_f32_32x32x16_bf16 v[16:31], v[42:45], v[120:123], v[16:31]
	s_waitcnt lgkmcnt(8)
	v_mfma_f32_32x32x16_bf16 v[0:15], v[100:103], v[120:123], v[0:15]
	s_waitcnt lgkmcnt(6)
	v_mfma_f32_32x32x16_bf16 v[16:31], v[104:107], v[124:127], v[16:31]
	s_waitcnt lgkmcnt(4)
	v_mfma_f32_32x32x16_bf16 v[0:15], v[142:145], v[124:127], v[0:15]
	s_waitcnt lgkmcnt(2)
	v_mfma_f32_32x32x16_bf16 v[16:31], v[34:37], v[128:131], v[16:31]
	s_waitcnt lgkmcnt(0)
	v_mfma_f32_32x32x16_bf16 v[0:15], v[38:41], v[128:131], v[0:15]
	s_nop 15
	s_nop 7
	s_nop 0
	v_max3_f32 v33, v48, v49, v64
	v_max3_f32 v34, v50, v51, v65
	s_nop 0
	v_max3_f32 v33, v33, v66, v67
	v_max3_f32 v34, v34, v54, v55
	s_nop 0
	v_max3_f32 v33, v33, v52, v53
	v_max3_f32 v34, v34, v70, v71
	s_nop 0
	v_max3_f32 v33, v33, v68, v69
	v_max3_f32 v34, v34, v58, v59
	s_nop 0
	v_max3_f32 v33, v33, v56, v57
	v_max3_f32 v34, v34, v74, v75
	s_nop 0
	v_max3_f32 v33, v33, v72, v73
	v_max3_f32 v34, v34, v62, v63
	s_nop 0
	v_max3_f32 v33, v33, v60, v61
	v_max3_f32 v34, v34, v78, v79
	s_nop 0
	v_max3_f32 v33, v33, v76, v77
	s_nop 0
	v_max3_f32 v33, v33, v34, v34
	v_mov_b32_e32 v34, v33
	s_nop 1
	v_permlane32_swap_b32 v34, v33
	v_max_f32_e32 v33, v33, v34
	s_waitcnt lgkmcnt(0)
	s_nop 0
	v_cmp_lt_f32_e32 vcc, s78, v33
	s_cbranch_vccz .LBB0_130
	v_max_f32_e32 v32, v33, v33
	v_max_f32_e32 v32, 0, v32
	v_exp_f32_e64 v34, -v32
	v_add_f32_e32 v135, v135, v32
	v_pk_add_f32 v[48:49], v[48:49], v[32:33] op_sel_hi:[1,0] neg_lo:[0,1] neg_hi:[0,1]
	v_pk_add_f32 v[64:65], v[64:65], v[32:33] op_sel_hi:[1,0] neg_lo:[0,1] neg_hi:[0,1]
	v_pk_add_f32 v[50:51], v[50:51], v[32:33] op_sel_hi:[1,0] neg_lo:[0,1] neg_hi:[0,1]
	v_pk_add_f32 v[66:67], v[66:67], v[32:33] op_sel_hi:[1,0] neg_lo:[0,1] neg_hi:[0,1]
	v_pk_add_f32 v[52:53], v[52:53], v[32:33] op_sel_hi:[1,0] neg_lo:[0,1] neg_hi:[0,1]
	v_pk_add_f32 v[68:69], v[68:69], v[32:33] op_sel_hi:[1,0] neg_lo:[0,1] neg_hi:[0,1]
	v_pk_add_f32 v[54:55], v[54:55], v[32:33] op_sel_hi:[1,0] neg_lo:[0,1] neg_hi:[0,1]
	v_pk_add_f32 v[70:71], v[70:71], v[32:33] op_sel_hi:[1,0] neg_lo:[0,1] neg_hi:[0,1]
	v_pk_add_f32 v[56:57], v[56:57], v[32:33] op_sel_hi:[1,0] neg_lo:[0,1] neg_hi:[0,1]
	v_pk_add_f32 v[72:73], v[72:73], v[32:33] op_sel_hi:[1,0] neg_lo:[0,1] neg_hi:[0,1]
	v_pk_add_f32 v[58:59], v[58:59], v[32:33] op_sel_hi:[1,0] neg_lo:[0,1] neg_hi:[0,1]
	v_pk_add_f32 v[74:75], v[74:75], v[32:33] op_sel_hi:[1,0] neg_lo:[0,1] neg_hi:[0,1]
	v_pk_add_f32 v[60:61], v[60:61], v[32:33] op_sel_hi:[1,0] neg_lo:[0,1] neg_hi:[0,1]
	v_pk_add_f32 v[76:77], v[76:77], v[32:33] op_sel_hi:[1,0] neg_lo:[0,1] neg_hi:[0,1]
	v_pk_add_f32 v[62:63], v[62:63], v[32:33] op_sel_hi:[1,0] neg_lo:[0,1] neg_hi:[0,1]
	v_pk_add_f32 v[78:79], v[78:79], v[32:33] op_sel_hi:[1,0] neg_lo:[0,1] neg_hi:[0,1]
	v_pk_mul_f32 v[30:31], v[30:31], v[34:35] op_sel_hi:[1,0]
	v_pk_mul_f32 v[28:29], v[28:29], v[34:35] op_sel_hi:[1,0]
	v_pk_mul_f32 v[26:27], v[26:27], v[34:35] op_sel_hi:[1,0]
	v_pk_mul_f32 v[24:25], v[24:25], v[34:35] op_sel_hi:[1,0]
	v_pk_mul_f32 v[22:23], v[22:23], v[34:35] op_sel_hi:[1,0]
	v_pk_mul_f32 v[20:21], v[20:21], v[34:35] op_sel_hi:[1,0]
	v_pk_mul_f32 v[18:19], v[18:19], v[34:35] op_sel_hi:[1,0]
	v_pk_mul_f32 v[16:17], v[16:17], v[34:35] op_sel_hi:[1,0]
	v_pk_mul_f32 v[14:15], v[14:15], v[34:35] op_sel_hi:[1,0]
	v_pk_mul_f32 v[12:13], v[12:13], v[34:35] op_sel_hi:[1,0]
	v_pk_mul_f32 v[10:11], v[10:11], v[34:35] op_sel_hi:[1,0]
	v_pk_mul_f32 v[8:9], v[8:9], v[34:35] op_sel_hi:[1,0]
	v_pk_mul_f32 v[6:7], v[6:7], v[34:35] op_sel_hi:[1,0]
	v_pk_mul_f32 v[4:5], v[4:5], v[34:35] op_sel_hi:[1,0]
	v_pk_mul_f32 v[2:3], v[2:3], v[34:35] op_sel_hi:[1,0]
	v_pk_mul_f32 v[0:1], v[0:1], v[34:35] op_sel_hi:[1,0]
	v_xor_b32_e32 v32, 0x80000000, v135
	v_mul_f32_e32 v134, v134, v34
.LBB0_130:
	v_exp_f32_e32 v102, v48
	v_exp_f32_e32 v103, v64
	v_exp_f32_e32 v98, v49
	v_exp_f32_e32 v100, v65
	v_exp_f32_e32 v104, v66
	v_add_f32_e32 v101, v103, v102
	v_exp_f32_e32 v64, v67
	v_pk_add_f32 v[48:49], v[100:101], v[98:99]
	v_exp_f32_e32 v101, v50
	v_pk_add_f32 v[48:49], v[48:49], v[48:49] op_sel_hi:[0,1]
	v_exp_f32_e32 v48, v51
	v_exp_f32_e32 v66, v69
	v_add_f32_e32 v65, v104, v101
	v_mov_b32_e32 v133, v99
	v_pk_add_f32 v[50:51], v[64:65], v[48:49]
	v_exp_f32_e32 v49, v52
	v_pk_add_f32 v[50:51], v[50:51], v[50:51] op_sel_hi:[0,1]
	v_exp_f32_e32 v65, v68
	v_exp_f32_e32 v50, v53
	v_cvt_pk_bf16_f32 v129, v101, v48
	s_waitcnt vmcnt(1)
	ds_write_b128 v136, v[108:111]
	s_waitcnt vmcnt(0)
	ds_write_b128 v136, v[112:115] offset:35840
	v_add_f32_e32 v67, v65, v49
	v_pk_add_f32 v[52:53], v[66:67], v[50:51]
	v_exp_f32_e32 v51, v54
	v_pk_add_f32 v[52:53], v[52:53], v[52:53] op_sel_hi:[0,1]
	v_exp_f32_e32 v67, v70
	v_exp_f32_e32 v52, v55
	v_cvt_pk_bf16_f32 v130, v49, v50
	v_mov_b64_e32 v[48:49], s[90:91]
	v_add_f32_e32 v69, v67, v51
	v_cvt_pk_bf16_f32 v131, v51, v52
	v_mad_i64_i32 v[50:51], s[0:1], v140, s85, v[48:49]
	v_mad_i64_i32 v[48:49], s[0:1], v139, s85, v[48:49]
	v_lshl_add_u64 v[50:51], v[50:51], 0, s[68:69]
	v_lshl_add_u64 v[48:49], v[48:49], 0, s[68:69]
	v_lshl_add_u64 v[112:113], v[50:51], 0, v[132:133]
	v_lshl_add_u64 v[48:49], v[48:49], 0, v[132:133]
	v_cvt_pk_bf16_f32 v128, v102, v98
	v_cvt_pk_bf16_f32 v120, v103, v100
	v_cvt_pk_bf16_f32 v121, v104, v64
	global_load_dwordx4 v[100:103], v[112:113], off offset:2048
	global_load_dwordx4 v[104:107], v[48:49], off offset:2560
	v_exp_f32_e32 v68, v71
	v_exp_f32_e32 v70, v73
	s_waitcnt lgkmcnt(0)
	s_barrier
	v_cvt_pk_bf16_f32 v122, v65, v66
	v_pk_add_f32 v[54:55], v[68:69], v[52:53]
	v_exp_f32_e32 v53, v56
	v_pk_add_f32 v[54:55], v[54:55], v[54:55] op_sel_hi:[0,1]
	v_exp_f32_e32 v69, v72
	v_exp_f32_e32 v54, v57
	v_exp_f32_e32 v72, v75
	v_cvt_pk_bf16_f32 v123, v67, v68
	v_add_f32_e32 v71, v69, v53
	v_pk_add_f32 v[56:57], v[70:71], v[54:55]
	v_exp_f32_e32 v55, v58
	v_pk_add_f32 v[56:57], v[56:57], v[56:57] op_sel_hi:[0,1]
	v_exp_f32_e32 v71, v74
	v_exp_f32_e32 v56, v59
	v_exp_f32_e32 v74, v77
	ds_read_b128 v[108:111], v138 offset:4608
	ds_read_b128 v[64:67], v138
	ds_read_b128 v[140:143], v138 offset:32
	ds_read_b128 v[144:147], v138 offset:4640
	ds_read_b128 v[150:153], v138 offset:64
	ds_read_b128 v[154:157], v138 offset:4672
	v_add_f32_e32 v73, v71, v55
	v_pk_add_f32 v[58:59], v[72:73], v[56:57]
	v_exp_f32_e32 v57, v60
	v_pk_add_f32 v[58:59], v[58:59], v[58:59] op_sel_hi:[0,1]
	v_exp_f32_e32 v73, v76
	v_exp_f32_e32 v58, v61
	v_exp_f32_e32 v76, v79
	v_mov_b32_e32 v33, v32
	v_add_f32_e32 v75, v73, v57
	v_pk_add_f32 v[60:61], v[74:75], v[58:59]
	v_exp_f32_e32 v59, v62
	v_pk_add_f32 v[60:61], v[60:61], v[60:61] op_sel_hi:[0,1]
	v_exp_f32_e32 v75, v78
	v_exp_f32_e32 v60, v63
	v_mov_b32_e32 v34, v32
	v_mov_b32_e32 v35, v32
	v_add_f32_e32 v77, v75, v59
	v_pk_add_f32 v[62:63], v[76:77], v[60:61]
	v_mov_b32_e32 v36, v32
	v_add_f32_e32 v61, v62, v63
	v_mov_b32_e32 v37, v32
	v_mov_b32_e32 v38, v32
	v_mov_b32_e32 v39, v32
	v_mov_b32_e32 v40, v32
	v_mov_b32_e32 v41, v32
	v_mov_b32_e32 v42, v32
	v_mov_b32_e32 v43, v32
	v_mov_b32_e32 v44, v32
	v_mov_b32_e32 v45, v32
	v_mov_b32_e32 v46, v32
	v_mov_b32_e32 v47, v32
	v_add_f32_e32 v134, v134, v61
	v_cvt_pk_bf16_f32 v124, v53, v54
	v_cvt_pk_bf16_f32 v125, v55, v56
	v_cvt_pk_bf16_f32 v126, v57, v58
	v_cvt_pk_bf16_f32 v127, v59, v60
	v_cvt_pk_bf16_f32 v116, v69, v70
	v_cvt_pk_bf16_f32 v117, v71, v72
	v_cvt_pk_bf16_f32 v118, v73, v74
	v_cvt_pk_bf16_f32 v119, v75, v76
	s_waitcnt lgkmcnt(4)
	v_mfma_f32_32x32x16_bf16 v[48:63], v[64:67], v[92:95], v[32:47]
	v_mfma_f32_32x32x16_bf16 v[64:79], v[108:111], v[92:95], v[32:47]
	ds_read_b128 v[108:111], v138 offset:96
	ds_read_b128 v[158:161], v138 offset:4704
	s_waitcnt lgkmcnt(5)
	v_mfma_f32_32x32x16_bf16 v[48:63], v[140:143], v[88:91], v[48:63]
	s_waitcnt lgkmcnt(4)
	v_mfma_f32_32x32x16_bf16 v[64:79], v[144:147], v[88:91], v[64:79]
	ds_read_b64_tr_b16 v[140:141], v97 offset:35840
	ds_read_b64_tr_b16 v[142:143], v97 offset:36992
	ds_read_b64_tr_b16 v[146:147], v97 offset:37056
	ds_read_b64_tr_b16 v[144:145], v97 offset:35904
	s_waitcnt lgkmcnt(7)
	v_mfma_f32_32x32x16_bf16 v[48:63], v[150:153], v[84:87], v[48:63]
	s_waitcnt lgkmcnt(6)
	v_mfma_f32_32x32x16_bf16 v[64:79], v[154:157], v[84:87], v[64:79]
	ds_read_b64_tr_b16 v[150:151], v97 offset:38144
	ds_read_b64_tr_b16 v[152:153], v97 offset:39296
	ds_read_b64_tr_b16 v[156:157], v97 offset:39360
	ds_read_b64_tr_b16 v[154:155], v97 offset:38208
	s_waitcnt lgkmcnt(9)
	v_mfma_f32_32x32x16_bf16 v[48:63], v[108:111], v[80:83], v[48:63]
	s_waitcnt lgkmcnt(8)
	v_mfma_f32_32x32x16_bf16 v[64:79], v[158:161], v[80:83], v[64:79]
	ds_read_b64_tr_b16 v[108:109], v97 offset:40448
	ds_read_b64_tr_b16 v[110:111], v97 offset:41600
	ds_read_b64_tr_b16 v[160:161], v97 offset:41664
	ds_read_b64_tr_b16 v[158:159], v97 offset:40512
	s_waitcnt lgkmcnt(10)
	v_mfma_f32_32x32x16_bf16 v[16:31], v[140:143], v[128:131], v[16:31]
	s_waitcnt lgkmcnt(8)
	v_mfma_f32_32x32x16_bf16 v[0:15], v[144:147], v[128:131], v[0:15]
	ds_read_b64_tr_b16 v[128:129], v97 offset:42752
	ds_read_b64_tr_b16 v[130:131], v97 offset:43904
	ds_read_b64_tr_b16 v[142:143], v97 offset:43968
	ds_read_b64_tr_b16 v[140:141], v97 offset:42816
	s_waitcnt lgkmcnt(10)
	v_mfma_f32_32x32x16_bf16 v[16:31], v[150:153], v[124:127], v[16:31]
	s_waitcnt lgkmcnt(8)
	v_mfma_f32_32x32x16_bf16 v[0:15], v[154:157], v[124:127], v[0:15]
	s_waitcnt lgkmcnt(6)
	v_mfma_f32_32x32x16_bf16 v[16:31], v[108:111], v[120:123], v[16:31]
	s_waitcnt lgkmcnt(4)
	v_mfma_f32_32x32x16_bf16 v[0:15], v[158:161], v[120:123], v[0:15]
	s_waitcnt lgkmcnt(2)
	v_mfma_f32_32x32x16_bf16 v[16:31], v[128:131], v[116:119], v[16:31]
	s_waitcnt lgkmcnt(0)
	v_mfma_f32_32x32x16_bf16 v[0:15], v[140:143], v[116:119], v[0:15]
	s_nop 15
	s_nop 7
	v_readlane_b32 s26, v255, 43
	v_max3_f32 v98, v48, v49, v64
	v_max3_f32 v108, v50, v51, v65
	v_readlane_b32 s27, v255, 44
	v_max3_f32 v98, v98, v66, v67
	v_max3_f32 v108, v108, v54, v55
	s_nop 0
	v_max3_f32 v98, v98, v52, v53
	v_max3_f32 v108, v108, v70, v71
	s_nop 0
	v_max3_f32 v98, v98, v68, v69
	v_max3_f32 v108, v108, v58, v59
	s_nop 0
	v_max3_f32 v98, v98, v56, v57
	v_max3_f32 v108, v108, v74, v75
	s_nop 0
	v_max3_f32 v98, v98, v72, v73
	v_max3_f32 v108, v108, v62, v63
	s_nop 0
	v_max3_f32 v98, v98, v60, v61
	v_max3_f32 v108, v108, v78, v79
	s_nop 0
	v_max3_f32 v98, v98, v76, v77
	s_nop 0
	v_max3_f32 v98, v98, v108, v108
	v_mov_b32_e32 v108, v98
	s_nop 1
	v_permlane32_swap_b32 v108, v98
	v_max_f32_e32 v98, v98, v108
	s_waitcnt lgkmcnt(0)
	s_nop 0
	v_cmp_lt_f32_e32 vcc, s78, v98
	s_cbranch_vccz .LBB0_132
	v_max_f32_e32 v32, v98, v98
	v_max_f32_e32 v32, 0, v32
	v_exp_f32_e64 v34, -v32
	v_add_f32_e32 v33, v135, v32
	v_pk_add_f32 v[48:49], v[48:49], v[32:33] op_sel_hi:[1,0] neg_lo:[0,1] neg_hi:[0,1]
	v_pk_add_f32 v[64:65], v[64:65], v[32:33] op_sel_hi:[1,0] neg_lo:[0,1] neg_hi:[0,1]
	v_pk_add_f32 v[50:51], v[50:51], v[32:33] op_sel_hi:[1,0] neg_lo:[0,1] neg_hi:[0,1]
	v_pk_add_f32 v[66:67], v[66:67], v[32:33] op_sel_hi:[1,0] neg_lo:[0,1] neg_hi:[0,1]
	v_pk_add_f32 v[52:53], v[52:53], v[32:33] op_sel_hi:[1,0] neg_lo:[0,1] neg_hi:[0,1]
	v_pk_add_f32 v[68:69], v[68:69], v[32:33] op_sel_hi:[1,0] neg_lo:[0,1] neg_hi:[0,1]
	v_pk_add_f32 v[54:55], v[54:55], v[32:33] op_sel_hi:[1,0] neg_lo:[0,1] neg_hi:[0,1]
	v_pk_add_f32 v[70:71], v[70:71], v[32:33] op_sel_hi:[1,0] neg_lo:[0,1] neg_hi:[0,1]
	v_pk_add_f32 v[56:57], v[56:57], v[32:33] op_sel_hi:[1,0] neg_lo:[0,1] neg_hi:[0,1]
	v_pk_add_f32 v[72:73], v[72:73], v[32:33] op_sel_hi:[1,0] neg_lo:[0,1] neg_hi:[0,1]
	v_pk_add_f32 v[58:59], v[58:59], v[32:33] op_sel_hi:[1,0] neg_lo:[0,1] neg_hi:[0,1]
	v_pk_add_f32 v[74:75], v[74:75], v[32:33] op_sel_hi:[1,0] neg_lo:[0,1] neg_hi:[0,1]
	v_pk_add_f32 v[60:61], v[60:61], v[32:33] op_sel_hi:[1,0] neg_lo:[0,1] neg_hi:[0,1]
	v_pk_add_f32 v[76:77], v[76:77], v[32:33] op_sel_hi:[1,0] neg_lo:[0,1] neg_hi:[0,1]
	v_pk_add_f32 v[62:63], v[62:63], v[32:33] op_sel_hi:[1,0] neg_lo:[0,1] neg_hi:[0,1]
	v_pk_add_f32 v[78:79], v[78:79], v[32:33] op_sel_hi:[1,0] neg_lo:[0,1] neg_hi:[0,1]
	v_xor_b32_e32 v32, 0x80000000, v33
	v_mul_f32_e32 v134, v134, v34
	v_pk_mul_f32 v[30:31], v[30:31], v[34:35] op_sel_hi:[1,0]
	v_pk_mul_f32 v[28:29], v[28:29], v[34:35] op_sel_hi:[1,0]
	v_pk_mul_f32 v[26:27], v[26:27], v[34:35] op_sel_hi:[1,0]
	v_pk_mul_f32 v[24:25], v[24:25], v[34:35] op_sel_hi:[1,0]
	v_pk_mul_f32 v[22:23], v[22:23], v[34:35] op_sel_hi:[1,0]
	v_pk_mul_f32 v[20:21], v[20:21], v[34:35] op_sel_hi:[1,0]
	v_pk_mul_f32 v[18:19], v[18:19], v[34:35] op_sel_hi:[1,0]
	v_pk_mul_f32 v[16:17], v[16:17], v[34:35] op_sel_hi:[1,0]
	v_pk_mul_f32 v[14:15], v[14:15], v[34:35] op_sel_hi:[1,0]
	v_pk_mul_f32 v[12:13], v[12:13], v[34:35] op_sel_hi:[1,0]
	v_pk_mul_f32 v[10:11], v[10:11], v[34:35] op_sel_hi:[1,0]
	v_pk_mul_f32 v[8:9], v[8:9], v[34:35] op_sel_hi:[1,0]
	v_pk_mul_f32 v[6:7], v[6:7], v[34:35] op_sel_hi:[1,0]
	v_pk_mul_f32 v[4:5], v[4:5], v[34:35] op_sel_hi:[1,0]
	v_pk_mul_f32 v[2:3], v[2:3], v[34:35] op_sel_hi:[1,0]
	v_pk_mul_f32 v[0:1], v[0:1], v[34:35] op_sel_hi:[1,0]
	v_mov_b32_e32 v33, v32
	v_mov_b32_e32 v34, v32
	v_mov_b32_e32 v35, v32
	v_mov_b32_e32 v36, v32
	v_mov_b32_e32 v37, v32
	v_mov_b32_e32 v38, v32
	v_mov_b32_e32 v39, v32
	v_mov_b32_e32 v40, v32
	v_mov_b32_e32 v41, v32
	v_mov_b32_e32 v42, v32
	v_mov_b32_e32 v43, v32
	v_mov_b32_e32 v44, v32
	v_mov_b32_e32 v45, v32
	v_mov_b32_e32 v46, v32
	v_mov_b32_e32 v47, v32
.LBB0_132:
	v_exp_f32_e32 v108, v48
	v_exp_f32_e32 v115, v64
	v_exp_f32_e32 v98, v49
	v_exp_f32_e32 v116, v65
	v_exp_f32_e32 v109, v50
	v_add_f32_e32 v117, v115, v108
	v_exp_f32_e32 v64, v67
	v_pk_add_f32 v[48:49], v[116:117], v[98:99]
	v_exp_f32_e32 v117, v66
	v_pk_add_f32 v[48:49], v[48:49], v[48:49] op_sel_hi:[0,1]
	v_exp_f32_e32 v48, v51
	v_exp_f32_e32 v66, v69
	v_add_f32_e32 v65, v117, v109
	s_waitcnt vmcnt(1)
	ds_write_b128 v136, v[100:103] offset:13312
	s_waitcnt vmcnt(0)
	ds_write_b128 v136, v[104:107] offset:26624
	v_pk_add_f32 v[50:51], v[64:65], v[48:49]
	v_exp_f32_e32 v49, v52
	v_pk_add_f32 v[50:51], v[50:51], v[50:51] op_sel_hi:[0,1]
	v_exp_f32_e32 v65, v68
	v_exp_f32_e32 v50, v53
	v_exp_f32_e32 v68, v71
	v_exp_f32_e32 v118, v75
	v_add_f32_e32 v67, v65, v49
	v_pk_add_f32 v[52:53], v[66:67], v[50:51]
	v_exp_f32_e32 v51, v54
	v_pk_add_f32 v[52:53], v[52:53], v[52:53] op_sel_hi:[0,1]
	v_exp_f32_e32 v67, v70
	v_exp_f32_e32 v52, v55
	v_exp_f32_e32 v70, v73
	v_cvt_pk_bf16_f32 v73, v117, v64
	v_add_f32_e32 v69, v67, v51
	v_pk_add_f32 v[54:55], v[68:69], v[52:53]
	v_exp_f32_e32 v53, v56
	v_pk_add_f32 v[54:55], v[54:55], v[54:55] op_sel_hi:[0,1]
	v_exp_f32_e32 v69, v72
	v_exp_f32_e32 v54, v57
	v_cvt_pk_bf16_f32 v75, v67, v68
	v_exp_f32_e32 v120, v77
	v_add_f32_e32 v71, v69, v53
	v_pk_add_f32 v[56:57], v[70:71], v[54:55]
	v_exp_f32_e32 v71, v74
	v_cvt_pk_bf16_f32 v74, v65, v66
	global_load_dwordx4 v[64:67], v[112:113], off offset:2560
	v_pk_add_f32 v[56:57], v[56:57], v[56:57] op_sel_hi:[0,1]
	v_exp_f32_e32 v55, v58
	v_exp_f32_e32 v56, v59
	v_exp_f32_e32 v122, v79
	s_waitcnt lgkmcnt(0)
	s_barrier
	v_add_f32_e32 v119, v71, v55
	v_pk_add_f32 v[58:59], v[118:119], v[56:57]
	v_exp_f32_e32 v57, v60
	v_pk_add_f32 v[58:59], v[58:59], v[58:59] op_sel_hi:[0,1]
	v_exp_f32_e32 v119, v76
	v_exp_f32_e32 v58, v61
	v_cvt_pk_bf16_f32 v72, v115, v116
	v_cvt_pk_bf16_f32 v68, v69, v70
	v_add_f32_e32 v121, v119, v57
	v_pk_add_f32 v[60:61], v[120:121], v[58:59]
	v_exp_f32_e32 v59, v62
	v_pk_add_f32 v[60:61], v[60:61], v[60:61] op_sel_hi:[0,1]
	v_exp_f32_e32 v121, v78
	v_exp_f32_e32 v60, v63
	v_cvt_pk_bf16_f32 v69, v71, v118
	v_cvt_pk_bf16_f32 v70, v119, v120
	v_add_f32_e32 v123, v121, v59
	v_pk_add_f32 v[62:63], v[122:123], v[60:61]
	v_cvt_pk_bf16_f32 v71, v121, v122
	ds_read_b128 v[100:103], v138 offset:17920
	ds_read_b128 v[104:107], v138 offset:13312
	ds_read_b128 v[116:119], v138 offset:13344
	ds_read_b128 v[120:123], v138 offset:17952
	ds_read_b128 v[124:127], v138 offset:13376
	ds_read_b128 v[128:131], v138 offset:17984
	v_add_f32_e32 v61, v62, v63
	v_add_f32_e32 v114, v134, v61
	v_cvt_pk_bf16_f32 v108, v108, v98
	v_cvt_pk_bf16_f32 v109, v109, v48
	v_cvt_pk_bf16_f32 v110, v49, v50
	v_cvt_pk_bf16_f32 v111, v51, v52
	v_cvt_pk_bf16_f32 v76, v53, v54
	v_cvt_pk_bf16_f32 v77, v55, v56
	v_cvt_pk_bf16_f32 v78, v57, v58
	v_cvt_pk_bf16_f32 v79, v59, v60
	s_waitcnt lgkmcnt(4)
	v_mfma_f32_32x32x16_bf16 v[48:63], v[104:107], v[92:95], v[32:47]
	v_mfma_f32_32x32x16_bf16 v[32:47], v[100:103], v[92:95], v[32:47]
	ds_read_b128 v[92:95], v138 offset:13408
	ds_read_b128 v[100:103], v138 offset:18016
	s_waitcnt lgkmcnt(5)
	v_mfma_f32_32x32x16_bf16 v[48:63], v[116:119], v[88:91], v[48:63]
	s_waitcnt lgkmcnt(4)
	v_mfma_f32_32x32x16_bf16 v[32:47], v[120:123], v[88:91], v[32:47]
	ds_read_b64_tr_b16 v[88:89], v97 offset:26624
	ds_read_b64_tr_b16 v[90:91], v97 offset:27776
	ds_read_b64_tr_b16 v[106:107], v97 offset:27840
	ds_read_b64_tr_b16 v[104:105], v97 offset:26688
	s_waitcnt lgkmcnt(7)
	v_mfma_f32_32x32x16_bf16 v[48:63], v[124:127], v[84:87], v[48:63]
	s_waitcnt lgkmcnt(6)
	v_mfma_f32_32x32x16_bf16 v[32:47], v[128:131], v[84:87], v[32:47]
	ds_read_b64_tr_b16 v[84:85], v97 offset:28928
	ds_read_b64_tr_b16 v[86:87], v97 offset:30080
	ds_read_b64_tr_b16 v[118:119], v97 offset:30144
	ds_read_b64_tr_b16 v[116:117], v97 offset:28992
	s_waitcnt lgkmcnt(9)
	v_mfma_f32_32x32x16_bf16 v[48:63], v[92:95], v[80:83], v[48:63]
	s_waitcnt lgkmcnt(8)
	v_mfma_f32_32x32x16_bf16 v[32:47], v[100:103], v[80:83], v[32:47]
	ds_read_b64_tr_b16 v[80:81], v97 offset:31232
	ds_read_b64_tr_b16 v[82:83], v97 offset:32384
	ds_read_b64_tr_b16 v[94:95], v97 offset:32448
	ds_read_b64_tr_b16 v[92:93], v97 offset:31296
	s_waitcnt lgkmcnt(10)
	v_mfma_f32_32x32x16_bf16 v[16:31], v[88:91], v[108:111], v[16:31]
	s_waitcnt lgkmcnt(8)
	v_mfma_f32_32x32x16_bf16 v[0:15], v[104:107], v[108:111], v[0:15]
	ds_read_b64_tr_b16 v[88:89], v97 offset:33536
	ds_read_b64_tr_b16 v[90:91], v97 offset:34688
	ds_read_b64_tr_b16 v[102:103], v97 offset:34752
	ds_read_b64_tr_b16 v[100:101], v97 offset:33600
	s_waitcnt lgkmcnt(10)
	v_mfma_f32_32x32x16_bf16 v[16:31], v[84:87], v[76:79], v[16:31]
	s_waitcnt lgkmcnt(8)
	v_mfma_f32_32x32x16_bf16 v[0:15], v[116:119], v[76:79], v[0:15]
	s_waitcnt lgkmcnt(6)
	v_mfma_f32_32x32x16_bf16 v[16:31], v[80:83], v[72:75], v[16:31]
	s_waitcnt lgkmcnt(4)
	v_mfma_f32_32x32x16_bf16 v[0:15], v[92:95], v[72:75], v[0:15]
	s_waitcnt lgkmcnt(2)
	v_mfma_f32_32x32x16_bf16 v[16:31], v[88:91], v[68:71], v[16:31]
	s_waitcnt lgkmcnt(0)
	v_mfma_f32_32x32x16_bf16 v[0:15], v[100:103], v[68:71], v[0:15]
	s_nop 15
	s_nop 7
	s_nop 0
	v_max3_f32 v68, v48, v49, v32
	v_max3_f32 v69, v50, v51, v33
	s_nop 0
	v_max3_f32 v68, v68, v34, v35
	v_max3_f32 v69, v69, v54, v55
	s_nop 0
	v_max3_f32 v68, v68, v52, v53
	v_max3_f32 v69, v69, v38, v39
	s_nop 0
	v_max3_f32 v68, v68, v36, v37
	v_max3_f32 v69, v69, v58, v59
	s_nop 0
	v_max3_f32 v68, v68, v56, v57
	v_max3_f32 v69, v69, v42, v43
	s_nop 0
	v_max3_f32 v68, v68, v40, v41
	v_max3_f32 v69, v69, v62, v63
	s_nop 0
	v_max3_f32 v68, v68, v60, v61
	v_max3_f32 v69, v69, v46, v47
	s_nop 0
	v_max3_f32 v68, v68, v44, v45
	s_nop 0
	v_max3_f32 v68, v68, v69, v69
	v_mov_b32_e32 v69, v68
	s_nop 1
	v_permlane32_swap_b32 v69, v68
	v_max_f32_e32 v68, v68, v69
	s_waitcnt lgkmcnt(0)
	s_nop 0
	v_cmp_lt_f32_e32 vcc, s78, v68
	s_cbranch_vccz .LBB0_134
	v_max_f32_e32 v68, v68, v68
	v_max_f32_e32 v68, 0, v68
	v_exp_f32_e64 v70, -v68
	v_pk_add_f32 v[48:49], v[48:49], v[68:69] op_sel_hi:[1,0] neg_lo:[0,1] neg_hi:[0,1]
	v_pk_add_f32 v[32:33], v[32:33], v[68:69] op_sel_hi:[1,0] neg_lo:[0,1] neg_hi:[0,1]
	v_pk_add_f32 v[50:51], v[50:51], v[68:69] op_sel_hi:[1,0] neg_lo:[0,1] neg_hi:[0,1]
	v_mul_f32_e32 v114, v114, v70
	v_pk_add_f32 v[34:35], v[34:35], v[68:69] op_sel_hi:[1,0] neg_lo:[0,1] neg_hi:[0,1]
	v_pk_add_f32 v[52:53], v[52:53], v[68:69] op_sel_hi:[1,0] neg_lo:[0,1] neg_hi:[0,1]
	v_pk_add_f32 v[36:37], v[36:37], v[68:69] op_sel_hi:[1,0] neg_lo:[0,1] neg_hi:[0,1]
	v_pk_add_f32 v[54:55], v[54:55], v[68:69] op_sel_hi:[1,0] neg_lo:[0,1] neg_hi:[0,1]
	v_pk_add_f32 v[38:39], v[38:39], v[68:69] op_sel_hi:[1,0] neg_lo:[0,1] neg_hi:[0,1]
	v_pk_add_f32 v[56:57], v[56:57], v[68:69] op_sel_hi:[1,0] neg_lo:[0,1] neg_hi:[0,1]
	v_pk_add_f32 v[40:41], v[40:41], v[68:69] op_sel_hi:[1,0] neg_lo:[0,1] neg_hi:[0,1]
	v_pk_add_f32 v[58:59], v[58:59], v[68:69] op_sel_hi:[1,0] neg_lo:[0,1] neg_hi:[0,1]
	v_pk_add_f32 v[42:43], v[42:43], v[68:69] op_sel_hi:[1,0] neg_lo:[0,1] neg_hi:[0,1]
	v_pk_add_f32 v[60:61], v[60:61], v[68:69] op_sel_hi:[1,0] neg_lo:[0,1] neg_hi:[0,1]
	v_pk_add_f32 v[44:45], v[44:45], v[68:69] op_sel_hi:[1,0] neg_lo:[0,1] neg_hi:[0,1]
	v_pk_add_f32 v[62:63], v[62:63], v[68:69] op_sel_hi:[1,0] neg_lo:[0,1] neg_hi:[0,1]
	v_pk_add_f32 v[46:47], v[46:47], v[68:69] op_sel_hi:[1,0] neg_lo:[0,1] neg_hi:[0,1]
	v_pk_mul_f32 v[30:31], v[30:31], v[70:71] op_sel_hi:[1,0]
	v_pk_mul_f32 v[28:29], v[28:29], v[70:71] op_sel_hi:[1,0]
	v_pk_mul_f32 v[26:27], v[26:27], v[70:71] op_sel_hi:[1,0]
	v_pk_mul_f32 v[24:25], v[24:25], v[70:71] op_sel_hi:[1,0]
	v_pk_mul_f32 v[22:23], v[22:23], v[70:71] op_sel_hi:[1,0]
	v_pk_mul_f32 v[20:21], v[20:21], v[70:71] op_sel_hi:[1,0]
	v_pk_mul_f32 v[18:19], v[18:19], v[70:71] op_sel_hi:[1,0]
	v_pk_mul_f32 v[16:17], v[16:17], v[70:71] op_sel_hi:[1,0]
	v_pk_mul_f32 v[14:15], v[14:15], v[70:71] op_sel_hi:[1,0]
	v_pk_mul_f32 v[12:13], v[12:13], v[70:71] op_sel_hi:[1,0]
	v_pk_mul_f32 v[10:11], v[10:11], v[70:71] op_sel_hi:[1,0]
	v_pk_mul_f32 v[8:9], v[8:9], v[70:71] op_sel_hi:[1,0]
	v_pk_mul_f32 v[6:7], v[6:7], v[70:71] op_sel_hi:[1,0]
	v_pk_mul_f32 v[4:5], v[4:5], v[70:71] op_sel_hi:[1,0]
	v_pk_mul_f32 v[2:3], v[2:3], v[70:71] op_sel_hi:[1,0]
	v_pk_mul_f32 v[0:1], v[0:1], v[70:71] op_sel_hi:[1,0]

.LBB0_154:
	s_or_b64 exec, exec, s[6:7]
	v_lshlrev_b64 v[34:35], 10, v[138:139]
	v_lshl_add_u64 v[34:35], s[92:93], 0, v[34:35]
	v_lshl_add_u64 v[34:35], v[34:35], 0, s[68:69]
	v_lshl_add_u64 v[34:35], v[34:35], 0, v[98:99]
	v_add_co_u32_e32 v34, vcc, 0x2020000, v34
	v_max3_f32 v33, v48, v49, v64
	s_nop 1
	v_addc_co_u32_e32 v35, vcc, 0, v35, vcc
	global_load_dwordx4 v[126:129], v[34:35], off offset:128
	v_max3_f32 v33, v33, v66, v67
	v_max3_f32 v34, v50, v51, v65
	s_waitcnt lgkmcnt(0)
	s_barrier
	s_nop 0
	v_max3_f32 v33, v33, v52, v53
	v_max3_f32 v34, v34, v54, v55
	s_nop 0
	v_max3_f32 v33, v33, v68, v69
	v_max3_f32 v34, v34, v70, v71
	s_nop 0
	v_max3_f32 v33, v33, v56, v57
	v_max3_f32 v34, v34, v58, v59
	s_nop 0
	v_max3_f32 v33, v33, v72, v73
	v_max3_f32 v34, v34, v74, v75
	s_nop 0
	v_max3_f32 v33, v33, v60, v61
	v_max3_f32 v34, v34, v62, v63
	s_nop 0
	v_max3_f32 v33, v33, v76, v77
	v_max3_f32 v34, v34, v78, v79
	s_nop 0
	v_max3_f32 v33, v33, v34, v34
	v_mov_b32_e32 v34, v33
	s_nop 1
	v_permlane32_swap_b32 v34, v33
	v_max_f32_e32 v33, v33, v34
	s_waitcnt lgkmcnt(0)
	s_nop 0
	v_cmp_lt_f32_e32 vcc, s78, v33
	s_cbranch_vccz .LBB0_156
	v_max_f32_e32 v32, v33, v33
	v_max_f32_e32 v32, 0, v32
	v_exp_f32_e64 v34, -v32
	v_add_f32_e32 v137, v137, v32
	v_pk_add_f32 v[48:49], v[48:49], v[32:33] op_sel_hi:[1,0] neg_lo:[0,1] neg_hi:[0,1]
	v_pk_add_f32 v[64:65], v[64:65], v[32:33] op_sel_hi:[1,0] neg_lo:[0,1] neg_hi:[0,1]
	v_pk_add_f32 v[50:51], v[50:51], v[32:33] op_sel_hi:[1,0] neg_lo:[0,1] neg_hi:[0,1]
	v_pk_add_f32 v[66:67], v[66:67], v[32:33] op_sel_hi:[1,0] neg_lo:[0,1] neg_hi:[0,1]
	v_pk_add_f32 v[52:53], v[52:53], v[32:33] op_sel_hi:[1,0] neg_lo:[0,1] neg_hi:[0,1]
	v_pk_add_f32 v[68:69], v[68:69], v[32:33] op_sel_hi:[1,0] neg_lo:[0,1] neg_hi:[0,1]
	v_pk_add_f32 v[54:55], v[54:55], v[32:33] op_sel_hi:[1,0] neg_lo:[0,1] neg_hi:[0,1]
	v_pk_add_f32 v[70:71], v[70:71], v[32:33] op_sel_hi:[1,0] neg_lo:[0,1] neg_hi:[0,1]
	v_pk_add_f32 v[56:57], v[56:57], v[32:33] op_sel_hi:[1,0] neg_lo:[0,1] neg_hi:[0,1]
	v_pk_add_f32 v[72:73], v[72:73], v[32:33] op_sel_hi:[1,0] neg_lo:[0,1] neg_hi:[0,1]
	v_pk_add_f32 v[58:59], v[58:59], v[32:33] op_sel_hi:[1,0] neg_lo:[0,1] neg_hi:[0,1]
	v_pk_add_f32 v[74:75], v[74:75], v[32:33] op_sel_hi:[1,0] neg_lo:[0,1] neg_hi:[0,1]
	v_pk_add_f32 v[60:61], v[60:61], v[32:33] op_sel_hi:[1,0] neg_lo:[0,1] neg_hi:[0,1]
	v_pk_add_f32 v[76:77], v[76:77], v[32:33] op_sel_hi:[1,0] neg_lo:[0,1] neg_hi:[0,1]
	v_pk_add_f32 v[62:63], v[62:63], v[32:33] op_sel_hi:[1,0] neg_lo:[0,1] neg_hi:[0,1]
	v_pk_add_f32 v[78:79], v[78:79], v[32:33] op_sel_hi:[1,0] neg_lo:[0,1] neg_hi:[0,1]
	v_pk_mul_f32 v[30:31], v[30:31], v[34:35] op_sel_hi:[1,0]
	v_pk_mul_f32 v[28:29], v[28:29], v[34:35] op_sel_hi:[1,0]
	v_pk_mul_f32 v[26:27], v[26:27], v[34:35] op_sel_hi:[1,0]
	v_pk_mul_f32 v[24:25], v[24:25], v[34:35] op_sel_hi:[1,0]
	v_pk_mul_f32 v[22:23], v[22:23], v[34:35] op_sel_hi:[1,0]
	v_pk_mul_f32 v[20:21], v[20:21], v[34:35] op_sel_hi:[1,0]
	v_pk_mul_f32 v[18:19], v[18:19], v[34:35] op_sel_hi:[1,0]
	v_pk_mul_f32 v[16:17], v[16:17], v[34:35] op_sel_hi:[1,0]
	v_pk_mul_f32 v[14:15], v[14:15], v[34:35] op_sel_hi:[1,0]
	v_pk_mul_f32 v[12:13], v[12:13], v[34:35] op_sel_hi:[1,0]
	v_pk_mul_f32 v[10:11], v[10:11], v[34:35] op_sel_hi:[1,0]
	v_pk_mul_f32 v[8:9], v[8:9], v[34:35] op_sel_hi:[1,0]
	v_pk_mul_f32 v[6:7], v[6:7], v[34:35] op_sel_hi:[1,0]
	v_pk_mul_f32 v[4:5], v[4:5], v[34:35] op_sel_hi:[1,0]
	v_pk_mul_f32 v[2:3], v[2:3], v[34:35] op_sel_hi:[1,0]
	v_pk_mul_f32 v[0:1], v[0:1], v[34:35] op_sel_hi:[1,0]
	v_xor_b32_e32 v32, 0x80000000, v137
	v_mul_f32_e32 v136, v136, v34
.LBB0_156:
	v_exp_f32_e32 v151, v48
	v_exp_f32_e32 v152, v49
	v_exp_f32_e32 v153, v50
	v_exp_f32_e32 v154, v51
	ds_read_b128 v[48:51], v140
	ds_read_b128 v[202:205], v140 offset:32
	ds_read_b128 v[206:209], v140 offset:6656
	ds_read_b128 v[210:213], v140 offset:64
	ds_read_b128 v[214:217], v140 offset:6688
	ds_read_b128 v[218:221], v140 offset:6720
	v_exp_f32_e32 v167, v64
	v_exp_f32_e32 v168, v65
	v_exp_f32_e32 v169, v66
	v_exp_f32_e32 v170, v67
	v_exp_f32_e32 v155, v52
	v_exp_f32_e32 v171, v68
	v_exp_f32_e32 v156, v53
	v_exp_f32_e32 v172, v69
	v_exp_f32_e32 v157, v54
	v_exp_f32_e32 v173, v70
	v_exp_f32_e32 v158, v55
	v_exp_f32_e32 v174, v71
	v_exp_f32_e32 v159, v56
	v_exp_f32_e32 v175, v72
	v_exp_f32_e32 v160, v57
	v_exp_f32_e32 v176, v73
	v_exp_f32_e32 v161, v58
	v_exp_f32_e32 v177, v74
	v_exp_f32_e32 v162, v59
	v_exp_f32_e32 v178, v75
	v_exp_f32_e32 v163, v60
	v_exp_f32_e32 v179, v76
	v_exp_f32_e32 v164, v61
	v_exp_f32_e32 v187, v77
	v_exp_f32_e32 v165, v62
	v_exp_f32_e32 v188, v78
	v_exp_f32_e32 v166, v63
	v_exp_f32_e32 v189, v79
	v_mov_b32_e32 v33, v32
	v_mov_b32_e32 v34, v32
	v_mov_b32_e32 v35, v32
	v_mov_b32_e32 v36, v32
	v_mov_b32_e32 v37, v32
	v_mov_b32_e32 v38, v32
	v_mov_b32_e32 v39, v32
	v_mov_b32_e32 v40, v32
	v_mov_b32_e32 v41, v32
	v_mov_b32_e32 v42, v32
	v_mov_b32_e32 v43, v32
	v_mov_b32_e32 v44, v32
	v_mov_b32_e32 v45, v32
	v_mov_b32_e32 v46, v32
	v_mov_b32_e32 v47, v32
	v_cvt_pk_bf16_f32 v190, v151, v152
	v_cvt_pk_bf16_f32 v191, v153, v154
	v_cvt_pk_bf16_f32 v192, v155, v156
	v_cvt_pk_bf16_f32 v193, v157, v158
	v_cvt_pk_bf16_f32 v194, v159, v160
	v_cvt_pk_bf16_f32 v195, v161, v162
	v_cvt_pk_bf16_f32 v196, v163, v164
	v_cvt_pk_bf16_f32 v197, v165, v166
	v_cvt_pk_bf16_f32 v198, v167, v168
	v_cvt_pk_bf16_f32 v199, v169, v170
	v_cvt_pk_bf16_f32 v200, v171, v172
	v_cvt_pk_bf16_f32 v201, v173, v174
	v_cvt_pk_bf16_f32 v234, v175, v176
	v_cvt_pk_bf16_f32 v235, v177, v178
	v_cvt_pk_bf16_f32 v236, v179, v187
	v_cvt_pk_bf16_f32 v237, v188, v189
	s_waitcnt lgkmcnt(5)
	v_mfma_f32_32x32x16_bf16 v[64:79], v[48:51], v[106:109], v[32:47]
	s_waitcnt lgkmcnt(3)
	v_mfma_f32_32x32x16_bf16 v[48:63], v[206:209], v[106:109], v[32:47]
	ds_read_b128 v[206:209], v140 offset:96
	ds_read_b128 v[238:241], v140 offset:6752
	v_mfma_f32_32x32x16_bf16 v[64:79], v[202:205], v[102:105], v[64:79]
	s_waitcnt lgkmcnt(3)
	v_mfma_f32_32x32x16_bf16 v[48:63], v[214:217], v[102:105], v[48:63]
	ds_read_b128 v[202:205], v140 offset:128
	ds_read_b128 v[214:217], v140 offset:6784
	v_mfma_f32_32x32x16_bf16 v[64:79], v[210:213], v[92:95], v[64:79]
	s_waitcnt lgkmcnt(4)
	v_mfma_f32_32x32x16_bf16 v[48:63], v[218:221], v[92:95], v[48:63]
	ds_read_b128 v[210:213], v140 offset:160
	ds_read_b128 v[218:221], v140 offset:6816
	s_waitcnt lgkmcnt(5)
	v_mfma_f32_32x32x16_bf16 v[64:79], v[206:209], v[88:91], v[64:79]
	s_waitcnt lgkmcnt(4)
	v_mfma_f32_32x32x16_bf16 v[48:63], v[238:241], v[88:91], v[48:63]
	ds_read_b64_tr_b16 v[206:207], v97 offset:35840
	ds_read_b64_tr_b16 v[208:209], v97 offset:36992
	ds_read_b64_tr_b16 v[240:241], v97 offset:37056
	ds_read_b64_tr_b16 v[238:239], v97 offset:35904
	s_waitcnt lgkmcnt(7)
	v_mfma_f32_32x32x16_bf16 v[64:79], v[202:205], v[84:87], v[64:79]
	s_waitcnt lgkmcnt(6)
	v_mfma_f32_32x32x16_bf16 v[48:63], v[214:217], v[84:87], v[48:63]
	ds_read_b64_tr_b16 v[202:203], v97 offset:38144
	ds_read_b64_tr_b16 v[204:205], v97 offset:39296
	ds_read_b64_tr_b16 v[216:217], v97 offset:39360
	ds_read_b64_tr_b16 v[214:215], v97 offset:38208
	s_waitcnt lgkmcnt(9)
	v_mfma_f32_32x32x16_bf16 v[64:79], v[210:213], v[80:83], v[64:79]
	s_waitcnt lgkmcnt(8)
	v_mfma_f32_32x32x16_bf16 v[48:63], v[218:221], v[80:83], v[48:63]
	ds_read_b64_tr_b16 v[210:211], v97 offset:40448
	ds_read_b64_tr_b16 v[212:213], v97 offset:41600
	ds_read_b64_tr_b16 v[220:221], v97 offset:41664
	ds_read_b64_tr_b16 v[218:219], v97 offset:40512
	s_waitcnt lgkmcnt(10)
	v_mfma_f32_32x32x16_bf16 v[16:31], v[206:209], v[190:193], v[16:31]
	s_waitcnt lgkmcnt(8)
	v_mfma_f32_32x32x16_bf16 v[0:15], v[238:241], v[190:193], v[0:15]
	ds_read_b64_tr_b16 v[190:191], v97 offset:42752
	ds_read_b64_tr_b16 v[192:193], v97 offset:43904
	ds_read_b64_tr_b16 v[208:209], v97 offset:43968
	ds_read_b64_tr_b16 v[206:207], v97 offset:42816
	s_waitcnt lgkmcnt(10)
	v_mfma_f32_32x32x16_bf16 v[16:31], v[202:205], v[194:197], v[16:31]
	s_waitcnt lgkmcnt(8)
	v_mfma_f32_32x32x16_bf16 v[0:15], v[214:217], v[194:197], v[0:15]
	s_waitcnt lgkmcnt(6)
	v_mfma_f32_32x32x16_bf16 v[16:31], v[210:213], v[198:201], v[16:31]
	s_waitcnt lgkmcnt(4)
	v_mfma_f32_32x32x16_bf16 v[0:15], v[218:221], v[198:201], v[0:15]
	s_waitcnt lgkmcnt(2)
	v_mfma_f32_32x32x16_bf16 v[16:31], v[190:193], v[234:237], v[16:31]
	s_waitcnt lgkmcnt(0)
	v_mfma_f32_32x32x16_bf16 v[0:15], v[206:209], v[234:237], v[0:15]
	s_waitcnt vmcnt(1)
	ds_write_b128 v142, v[130:133] offset:13312
	s_and_saveexec_b64 s[6:7], s[38:39]
	v_add3_u32 v130, 0, v145, v146
	ds_write_b128 v130, v[122:125] offset:13440
	s_or_b64 exec, exec, s[6:7]
	v_add_f32_e32 v122, v167, v151
	v_add_f32_e32 v122, 0, v122
	v_add_f32_e32 v123, v168, v152
	v_add_f32_e32 v122, v123, v122
	v_add_f32_e32 v123, v169, v153
	v_add_f32_e32 v122, v123, v122
	v_add_f32_e32 v123, v170, v154
	v_add_f32_e32 v122, v123, v122
	v_add_f32_e32 v123, v171, v155
	v_add_f32_e32 v122, v123, v122
	v_add_f32_e32 v123, v172, v156
	v_add_f32_e32 v122, v123, v122
	v_add_f32_e32 v123, v173, v157
	v_add_f32_e32 v122, v123, v122
	v_add_f32_e32 v123, v174, v158
	v_add_f32_e32 v122, v123, v122
	v_add_f32_e32 v123, v175, v159
	v_add_f32_e32 v122, v123, v122
	v_add_f32_e32 v123, v176, v160
	v_add_f32_e32 v122, v123, v122
	v_add_f32_e32 v123, v177, v161
	v_add_f32_e32 v122, v123, v122
	v_add_f32_e32 v123, v178, v162
	v_add_f32_e32 v122, v123, v122
	v_add_f32_e32 v123, v179, v163
	v_add_f32_e32 v122, v123, v122
	v_add_f32_e32 v123, v187, v164
	v_add_f32_e32 v122, v123, v122
	v_add_f32_e32 v123, v188, v165
	v_add_f32_e32 v122, v123, v122
	v_add_f32_e32 v123, v189, v166
	v_add_f32_e32 v122, v123, v122
	v_add_f32_e32 v130, v136, v122
	v_lshlrev_b64 v[122:123], 10, v[138:139]
	v_lshl_add_u64 v[122:123], s[92:93], 0, v[122:123]
	v_lshl_add_u64 v[122:123], v[122:123], 0, s[68:69]
	v_lshl_add_u64 v[122:123], v[122:123], 0, v[98:99]
	s_mov_b32 s6, 0x2030000
	v_add_co_u32_e32 v122, vcc, s6, v122
	s_waitcnt vmcnt(0)
	ds_write_b128 v150, v[126:129] offset:26624
	v_addc_co_u32_e32 v123, vcc, 0, v123, vcc
	global_load_dwordx4 v[122:125], v[122:123], off offset:128
	v_max3_f32 v126, v64, v65, v48
	v_max3_f32 v127, v66, v67, v49
	s_waitcnt lgkmcnt(0)
	s_barrier
	s_nop 0
	v_max3_f32 v126, v126, v50, v51
	v_max3_f32 v127, v127, v70, v71
	s_nop 0
	v_max3_f32 v126, v126, v68, v69
	v_max3_f32 v127, v127, v54, v55
	s_nop 0
	v_max3_f32 v126, v126, v52, v53
	v_max3_f32 v127, v127, v74, v75
	s_nop 0
	v_max3_f32 v126, v126, v72, v73
	v_max3_f32 v127, v127, v58, v59
	s_nop 0
	v_max3_f32 v126, v126, v56, v57
	v_max3_f32 v127, v127, v78, v79
	s_nop 0
	v_max3_f32 v126, v126, v76, v77
	v_max3_f32 v127, v127, v62, v63
	s_nop 0
	v_max3_f32 v126, v126, v60, v61
	s_nop 0
	v_max3_f32 v126, v126, v127, v127
	v_mov_b32_e32 v127, v126
	s_nop 1
	v_permlane32_swap_b32 v127, v126
	v_max_f32_e32 v126, v126, v127
	s_waitcnt lgkmcnt(0)
	s_nop 0
	v_cmp_lt_f32_e32 vcc, s78, v126
	s_cbranch_vccz .LBB0_160
	v_max_f32_e32 v32, v126, v126
	v_max_f32_e32 v32, 0, v32
	v_exp_f32_e64 v34, -v32
	v_add_f32_e32 v33, v137, v32
	v_pk_add_f32 v[64:65], v[64:65], v[32:33] op_sel_hi:[1,0] neg_lo:[0,1] neg_hi:[0,1]
	v_pk_add_f32 v[48:49], v[48:49], v[32:33] op_sel_hi:[1,0] neg_lo:[0,1] neg_hi:[0,1]
	v_pk_add_f32 v[66:67], v[66:67], v[32:33] op_sel_hi:[1,0] neg_lo:[0,1] neg_hi:[0,1]
	v_pk_add_f32 v[50:51], v[50:51], v[32:33] op_sel_hi:[1,0] neg_lo:[0,1] neg_hi:[0,1]
	v_pk_add_f32 v[68:69], v[68:69], v[32:33] op_sel_hi:[1,0] neg_lo:[0,1] neg_hi:[0,1]
	v_pk_add_f32 v[52:53], v[52:53], v[32:33] op_sel_hi:[1,0] neg_lo:[0,1] neg_hi:[0,1]
	v_pk_add_f32 v[70:71], v[70:71], v[32:33] op_sel_hi:[1,0] neg_lo:[0,1] neg_hi:[0,1]
	v_pk_add_f32 v[54:55], v[54:55], v[32:33] op_sel_hi:[1,0] neg_lo:[0,1] neg_hi:[0,1]
	v_pk_add_f32 v[72:73], v[72:73], v[32:33] op_sel_hi:[1,0] neg_lo:[0,1] neg_hi:[0,1]
	v_pk_add_f32 v[56:57], v[56:57], v[32:33] op_sel_hi:[1,0] neg_lo:[0,1] neg_hi:[0,1]
	v_pk_add_f32 v[74:75], v[74:75], v[32:33] op_sel_hi:[1,0] neg_lo:[0,1] neg_hi:[0,1]
	v_pk_add_f32 v[58:59], v[58:59], v[32:33] op_sel_hi:[1,0] neg_lo:[0,1] neg_hi:[0,1]
	v_pk_add_f32 v[76:77], v[76:77], v[32:33] op_sel_hi:[1,0] neg_lo:[0,1] neg_hi:[0,1]
	v_pk_add_f32 v[60:61], v[60:61], v[32:33] op_sel_hi:[1,0] neg_lo:[0,1] neg_hi:[0,1]
	v_pk_add_f32 v[78:79], v[78:79], v[32:33] op_sel_hi:[1,0] neg_lo:[0,1] neg_hi:[0,1]
	v_pk_add_f32 v[62:63], v[62:63], v[32:33] op_sel_hi:[1,0] neg_lo:[0,1] neg_hi:[0,1]
	v_xor_b32_e32 v32, 0x80000000, v33
	v_mul_f32_e32 v130, v130, v34
	v_pk_mul_f32 v[30:31], v[30:31], v[34:35] op_sel_hi:[1,0]
	v_pk_mul_f32 v[28:29], v[28:29], v[34:35] op_sel_hi:[1,0]
	v_pk_mul_f32 v[26:27], v[26:27], v[34:35] op_sel_hi:[1,0]
	v_pk_mul_f32 v[24:25], v[24:25], v[34:35] op_sel_hi:[1,0]
	v_pk_mul_f32 v[22:23], v[22:23], v[34:35] op_sel_hi:[1,0]
	v_pk_mul_f32 v[20:21], v[20:21], v[34:35] op_sel_hi:[1,0]
	v_pk_mul_f32 v[18:19], v[18:19], v[34:35] op_sel_hi:[1,0]
	v_pk_mul_f32 v[16:17], v[16:17], v[34:35] op_sel_hi:[1,0]
	v_pk_mul_f32 v[14:15], v[14:15], v[34:35] op_sel_hi:[1,0]
	v_pk_mul_f32 v[12:13], v[12:13], v[34:35] op_sel_hi:[1,0]
	v_pk_mul_f32 v[10:11], v[10:11], v[34:35] op_sel_hi:[1,0]
	v_pk_mul_f32 v[8:9], v[8:9], v[34:35] op_sel_hi:[1,0]
	v_pk_mul_f32 v[6:7], v[6:7], v[34:35] op_sel_hi:[1,0]
	v_pk_mul_f32 v[4:5], v[4:5], v[34:35] op_sel_hi:[1,0]
	v_pk_mul_f32 v[2:3], v[2:3], v[34:35] op_sel_hi:[1,0]
	v_pk_mul_f32 v[0:1], v[0:1], v[34:35] op_sel_hi:[1,0]
	v_mov_b32_e32 v33, v32
	v_mov_b32_e32 v34, v32
	v_mov_b32_e32 v35, v32
	v_mov_b32_e32 v36, v32
	v_mov_b32_e32 v37, v32
	v_mov_b32_e32 v38, v32
	v_mov_b32_e32 v39, v32
	v_mov_b32_e32 v40, v32
	v_mov_b32_e32 v41, v32
	v_mov_b32_e32 v42, v32
	v_mov_b32_e32 v43, v32
	v_mov_b32_e32 v44, v32
	v_mov_b32_e32 v45, v32
	v_mov_b32_e32 v46, v32
	v_mov_b32_e32 v47, v32
.LBB0_160:
	v_exp_f32_e32 v131, v64
	v_exp_f32_e32 v151, v48
	v_exp_f32_e32 v48, v65
	v_exp_f32_e32 v126, v49
	v_mov_b32_e32 v49, v99
	v_add_f32_e32 v127, v151, v131
	v_exp_f32_e32 v132, v51
	v_pk_add_f32 v[64:65], v[126:127], v[48:49]
	v_exp_f32_e32 v49, v66
	v_pk_add_f32 v[128:129], v[64:65], v[64:65] op_sel_hi:[0,1]
	v_exp_f32_e32 v65, v50
	v_exp_f32_e32 v128, v67
	v_exp_f32_e32 v68, v68
	v_exp_f32_e32 v127, v52
	v_add_f32_e32 v133, v65, v49
	v_pk_add_f32 v[50:51], v[132:133], v[128:129]
	v_exp_f32_e32 v136, v53
	v_pk_add_f32 v[50:51], v[50:51], v[50:51] op_sel_hi:[0,1]
	v_exp_f32_e32 v50, v69
	v_add_f32_e32 v137, v127, v68
	v_exp_f32_e32 v129, v54
	v_exp_f32_e32 v138, v55
	v_pk_add_f32 v[52:53], v[136:137], v[50:51]
	v_exp_f32_e32 v51, v70
	v_pk_add_f32 v[52:53], v[52:53], v[52:53] op_sel_hi:[0,1]
	v_exp_f32_e32 v52, v71
	v_exp_f32_e32 v133, v56
	v_add_f32_e32 v139, v129, v51
	v_exp_f32_e32 v152, v57
	v_pk_add_f32 v[54:55], v[138:139], v[52:53]
	v_exp_f32_e32 v53, v72
	v_pk_add_f32 v[54:55], v[54:55], v[54:55] op_sel_hi:[0,1]
	v_exp_f32_e32 v54, v73
	v_exp_f32_e32 v137, v58
	v_add_f32_e32 v153, v133, v53
	v_exp_f32_e32 v154, v59
	v_pk_add_f32 v[56:57], v[152:153], v[54:55]
	v_exp_f32_e32 v55, v74
	v_pk_add_f32 v[56:57], v[56:57], v[56:57] op_sel_hi:[0,1]
	v_exp_f32_e32 v56, v75
	v_exp_f32_e32 v139, v60
	v_add_f32_e32 v155, v137, v55
	v_exp_f32_e32 v156, v61
	v_pk_add_f32 v[58:59], v[154:155], v[56:57]
	v_exp_f32_e32 v57, v76
	v_pk_add_f32 v[58:59], v[58:59], v[58:59] op_sel_hi:[0,1]
	v_exp_f32_e32 v58, v77
	v_exp_f32_e32 v158, v63
	v_add_f32_e32 v157, v139, v57
	v_cvt_pk_bf16_f32 v66, v131, v48
	v_pk_add_f32 v[60:61], v[156:157], v[58:59]
	v_exp_f32_e32 v59, v78
	v_pk_add_f32 v[60:61], v[60:61], v[60:61] op_sel_hi:[0,1]
	v_exp_f32_e32 v78, v62
	v_exp_f32_e32 v60, v79
	v_cvt_pk_bf16_f32 v67, v49, v128
	v_cvt_pk_bf16_f32 v74, v151, v126
	v_add_f32_e32 v159, v78, v59
	v_pk_add_f32 v[62:63], v[158:159], v[60:61]
	v_cvt_pk_bf16_f32 v75, v65, v132
	v_add_f32_e32 v61, v62, v63
	v_add_f32_e32 v64, v130, v61
	v_cvt_pk_bf16_f32 v76, v127, v136
	v_cvt_pk_bf16_f32 v77, v129, v138
	v_cvt_pk_bf16_f32 v126, v133, v152
	v_cvt_pk_bf16_f32 v127, v137, v154
	v_cvt_pk_bf16_f32 v128, v139, v156
	v_cvt_pk_bf16_f32 v129, v78, v158
	ds_read_b128 v[130:133], v140 offset:19968
	ds_read_b128 v[136:139], v140 offset:13312
	ds_read_b128 v[152:155], v140 offset:13344
	ds_read_b128 v[156:159], v140 offset:20000
	ds_read_b128 v[160:163], v140 offset:13376
	ds_read_b128 v[164:167], v140 offset:20032
	v_cvt_pk_bf16_f32 v68, v68, v50
	v_cvt_pk_bf16_f32 v69, v51, v52
	v_cvt_pk_bf16_f32 v70, v53, v54
	v_cvt_pk_bf16_f32 v71, v55, v56
	v_cvt_pk_bf16_f32 v72, v57, v58
	v_cvt_pk_bf16_f32 v73, v59, v60
	s_waitcnt lgkmcnt(4)
	v_mfma_f32_32x32x16_bf16 v[48:63], v[136:139], v[106:109], v[32:47]
	v_mfma_f32_32x32x16_bf16 v[32:47], v[130:133], v[106:109], v[32:47]
	ds_read_b128 v[130:133], v140 offset:13408
	ds_read_b128 v[136:139], v140 offset:20064
	s_waitcnt lgkmcnt(5)
	v_mfma_f32_32x32x16_bf16 v[48:63], v[152:155], v[102:105], v[48:63]
	s_waitcnt lgkmcnt(4)
	v_mfma_f32_32x32x16_bf16 v[32:47], v[156:159], v[102:105], v[32:47]
	ds_read_b128 v[152:155], v140 offset:13440
	ds_read_b128 v[156:159], v140 offset:20096
	s_waitcnt lgkmcnt(5)
	v_mfma_f32_32x32x16_bf16 v[48:63], v[160:163], v[92:95], v[48:63]
	s_waitcnt lgkmcnt(4)
	v_mfma_f32_32x32x16_bf16 v[32:47], v[164:167], v[92:95], v[32:47]
	ds_read_b128 v[160:163], v140 offset:13472
	ds_read_b128 v[164:167], v140 offset:20128
	s_waitcnt lgkmcnt(5)
	v_mfma_f32_32x32x16_bf16 v[48:63], v[130:133], v[88:91], v[48:63]
	s_waitcnt lgkmcnt(4)
	v_mfma_f32_32x32x16_bf16 v[32:47], v[136:139], v[88:91], v[32:47]
	ds_read_b64_tr_b16 v[130:131], v97 offset:26624
	ds_read_b64_tr_b16 v[132:133], v97 offset:27776
	ds_read_b64_tr_b16 v[138:139], v97 offset:27840
	ds_read_b64_tr_b16 v[136:137], v97 offset:26688
	s_waitcnt lgkmcnt(7)
	v_mfma_f32_32x32x16_bf16 v[48:63], v[152:155], v[84:87], v[48:63]
	s_waitcnt lgkmcnt(6)
	v_mfma_f32_32x32x16_bf16 v[32:47], v[156:159], v[84:87], v[32:47]
	ds_read_b64_tr_b16 v[152:153], v97 offset:28928
	ds_read_b64_tr_b16 v[154:155], v97 offset:30080
	ds_read_b64_tr_b16 v[158:159], v97 offset:30144
	ds_read_b64_tr_b16 v[156:157], v97 offset:28992
	s_waitcnt lgkmcnt(9)
	v_mfma_f32_32x32x16_bf16 v[48:63], v[160:163], v[80:83], v[48:63]
	s_waitcnt lgkmcnt(8)
	v_mfma_f32_32x32x16_bf16 v[32:47], v[164:167], v[80:83], v[32:47]
	ds_read_b64_tr_b16 v[160:161], v97 offset:31232
	ds_read_b64_tr_b16 v[162:163], v97 offset:32384
	ds_read_b64_tr_b16 v[166:167], v97 offset:32448
	ds_read_b64_tr_b16 v[164:165], v97 offset:31296
	s_waitcnt lgkmcnt(10)
	v_mfma_f32_32x32x16_bf16 v[16:31], v[130:133], v[66:69], v[16:31]
	s_waitcnt lgkmcnt(8)
	v_mfma_f32_32x32x16_bf16 v[0:15], v[136:139], v[66:69], v[0:15]
	ds_read_b64_tr_b16 v[66:67], v97 offset:33536
	ds_read_b64_tr_b16 v[68:69], v97 offset:34688
	ds_read_b64_tr_b16 v[132:133], v97 offset:34752
	ds_read_b64_tr_b16 v[130:131], v97 offset:33600
	s_waitcnt lgkmcnt(10)
	v_mfma_f32_32x32x16_bf16 v[16:31], v[152:155], v[70:73], v[16:31]
	s_waitcnt lgkmcnt(8)
	v_mfma_f32_32x32x16_bf16 v[0:15], v[156:159], v[70:73], v[0:15]
	s_waitcnt lgkmcnt(6)
	v_mfma_f32_32x32x16_bf16 v[16:31], v[160:163], v[74:77], v[16:31]
	s_waitcnt lgkmcnt(4)
	v_mfma_f32_32x32x16_bf16 v[0:15], v[164:167], v[74:77], v[0:15]
	s_waitcnt lgkmcnt(2)
	v_mfma_f32_32x32x16_bf16 v[16:31], v[66:69], v[126:129], v[16:31]
	s_waitcnt lgkmcnt(0)
	v_mfma_f32_32x32x16_bf16 v[0:15], v[130:133], v[126:129], v[0:15]
	v_max3_f32 v65, v48, v49, v32
	v_max3_f32 v66, v50, v51, v33
	s_waitcnt vmcnt(0)
	ds_write_b128 v150, v[122:125] offset:35840
	v_max3_f32 v65, v65, v34, v35
	v_max3_f32 v66, v66, v54, v55
	s_waitcnt lgkmcnt(0)
	s_barrier
	s_nop 0
	v_max3_f32 v65, v65, v52, v53
	v_max3_f32 v66, v66, v38, v39
	s_nop 0
	v_max3_f32 v65, v65, v36, v37
	v_max3_f32 v66, v66, v58, v59
	s_nop 0
	v_max3_f32 v65, v65, v56, v57
	v_max3_f32 v66, v66, v42, v43
	s_nop 0
	v_max3_f32 v65, v65, v40, v41
	v_max3_f32 v66, v66, v62, v63
	s_nop 0
	v_max3_f32 v65, v65, v60, v61
	v_max3_f32 v66, v66, v46, v47
	s_nop 0
	v_max3_f32 v65, v65, v44, v45
	s_nop 0
	v_max3_f32 v65, v65, v66, v66
	v_mov_b32_e32 v66, v65
	s_nop 1
	v_permlane32_swap_b32 v66, v65
	v_max_f32_e32 v65, v65, v66
	s_waitcnt lgkmcnt(0)
	s_nop 0
	v_cmp_lt_f32_e32 vcc, s78, v65
	s_cbranch_vccz .LBB0_162
	v_max_f32_e32 v65, v65, v65
	v_max_f32_e32 v66, 0, v65
	v_exp_f32_e64 v68, -v66
	v_pk_add_f32 v[48:49], v[48:49], v[66:67] op_sel_hi:[1,0] neg_lo:[0,1] neg_hi:[0,1]
	v_pk_add_f32 v[32:33], v[32:33], v[66:67] op_sel_hi:[1,0] neg_lo:[0,1] neg_hi:[0,1]
	v_pk_add_f32 v[50:51], v[50:51], v[66:67] op_sel_hi:[1,0] neg_lo:[0,1] neg_hi:[0,1]
	v_mul_f32_e32 v64, v64, v68
	v_pk_add_f32 v[34:35], v[34:35], v[66:67] op_sel_hi:[1,0] neg_lo:[0,1] neg_hi:[0,1]
	v_pk_add_f32 v[52:53], v[52:53], v[66:67] op_sel_hi:[1,0] neg_lo:[0,1] neg_hi:[0,1]
	v_pk_add_f32 v[36:37], v[36:37], v[66:67] op_sel_hi:[1,0] neg_lo:[0,1] neg_hi:[0,1]
	v_pk_add_f32 v[54:55], v[54:55], v[66:67] op_sel_hi:[1,0] neg_lo:[0,1] neg_hi:[0,1]
	v_pk_add_f32 v[38:39], v[38:39], v[66:67] op_sel_hi:[1,0] neg_lo:[0,1] neg_hi:[0,1]
	v_pk_add_f32 v[56:57], v[56:57], v[66:67] op_sel_hi:[1,0] neg_lo:[0,1] neg_hi:[0,1]
	v_pk_add_f32 v[40:41], v[40:41], v[66:67] op_sel_hi:[1,0] neg_lo:[0,1] neg_hi:[0,1]
	v_pk_add_f32 v[58:59], v[58:59], v[66:67] op_sel_hi:[1,0] neg_lo:[0,1] neg_hi:[0,1]
	v_pk_add_f32 v[42:43], v[42:43], v[66:67] op_sel_hi:[1,0] neg_lo:[0,1] neg_hi:[0,1]
	v_pk_add_f32 v[60:61], v[60:61], v[66:67] op_sel_hi:[1,0] neg_lo:[0,1] neg_hi:[0,1]
	v_pk_add_f32 v[44:45], v[44:45], v[66:67] op_sel_hi:[1,0] neg_lo:[0,1] neg_hi:[0,1]
	v_pk_add_f32 v[62:63], v[62:63], v[66:67] op_sel_hi:[1,0] neg_lo:[0,1] neg_hi:[0,1]
	v_pk_add_f32 v[46:47], v[46:47], v[66:67] op_sel_hi:[1,0] neg_lo:[0,1] neg_hi:[0,1]
	v_pk_mul_f32 v[30:31], v[30:31], v[68:69] op_sel_hi:[1,0]
	v_pk_mul_f32 v[28:29], v[28:29], v[68:69] op_sel_hi:[1,0]
	v_pk_mul_f32 v[26:27], v[26:27], v[68:69] op_sel_hi:[1,0]
	v_pk_mul_f32 v[24:25], v[24:25], v[68:69] op_sel_hi:[1,0]
	v_pk_mul_f32 v[22:23], v[22:23], v[68:69] op_sel_hi:[1,0]
	v_pk_mul_f32 v[20:21], v[20:21], v[68:69] op_sel_hi:[1,0]
	v_pk_mul_f32 v[18:19], v[18:19], v[68:69] op_sel_hi:[1,0]
	v_pk_mul_f32 v[16:17], v[16:17], v[68:69] op_sel_hi:[1,0]
	v_pk_mul_f32 v[14:15], v[14:15], v[68:69] op_sel_hi:[1,0]
	v_pk_mul_f32 v[12:13], v[12:13], v[68:69] op_sel_hi:[1,0]
	v_pk_mul_f32 v[10:11], v[10:11], v[68:69] op_sel_hi:[1,0]
	v_pk_mul_f32 v[8:9], v[8:9], v[68:69] op_sel_hi:[1,0]
	v_pk_mul_f32 v[6:7], v[6:7], v[68:69] op_sel_hi:[1,0]
	v_pk_mul_f32 v[4:5], v[4:5], v[68:69] op_sel_hi:[1,0]
	v_pk_mul_f32 v[2:3], v[2:3], v[68:69] op_sel_hi:[1,0]
	v_pk_mul_f32 v[0:1], v[0:1], v[68:69] op_sel_hi:[1,0]

.LBB0_168:
	s_or_b64 exec, exec, s[6:7]
	v_add_u32_e32 v74, s1, v141
	v_ashrrev_i32_e32 v75, 31, v74
	v_sub_f32_e32 v55, v40, v47
	v_sub_f32_e32 v56, v41, v47
	v_sub_f32_e32 v40, v22, v47
	v_sub_f32_e32 v41, v23, v47
	v_lshlrev_b64 v[22:23], 10, v[74:75]
	v_lshl_add_u64 v[22:23], s[92:93], 0, v[22:23]
	v_lshl_add_u64 v[22:23], v[22:23], 0, s[68:69]
	v_lshl_add_u64 v[22:23], v[22:23], 0, v[98:99]
	s_mov_b32 s1, 0x2010000
	v_add_co_u32_e32 v22, vcc, s1, v22
	v_sub_f32_e32 v30, v30, v47
	s_nop 0
	v_addc_co_u32_e32 v23, vcc, 0, v23, vcc
	global_load_dwordx4 v[68:71], v[22:23], off offset:128
	v_sub_f32_e32 v14, v14, v47
	v_sub_f32_e32 v31, v31, v47
	v_sub_f32_e32 v15, v15, v47
	v_exp_f32_e32 v61, v14
	v_exp_f32_e32 v62, v30
	v_sub_f32_e32 v49, v34, v47
	v_sub_f32_e32 v34, v16, v47
	v_exp_f32_e32 v16, v15
	v_exp_f32_e32 v30, v31
	v_sub_f32_e32 v50, v35, v47
	v_sub_f32_e32 v35, v17, v47
	v_add_f32_e32 v31, v62, v61
	v_mov_b32_e32 v17, v99
	v_sub_f32_e32 v46, v32, v47
	v_pk_add_f32 v[14:15], v[30:31], v[16:17]
	v_sub_f32_e32 v48, v33, v47
	v_pk_add_f32 v[32:33], v[14:15], v[14:15] op_sel_hi:[0,1]
	v_exp_f32_e32 v17, v34
	v_exp_f32_e32 v31, v46
	v_exp_f32_e32 v32, v35
	v_exp_f32_e32 v34, v48
	v_sub_f32_e32 v51, v36, v47
	v_add_f32_e32 v35, v31, v17
	v_sub_f32_e32 v36, v18, v47
	v_pk_add_f32 v[14:15], v[34:35], v[32:33]
	v_sub_f32_e32 v52, v37, v47
	v_sub_f32_e32 v37, v19, v47
	v_pk_add_f32 v[18:19], v[14:15], v[14:15] op_sel_hi:[0,1]
	v_exp_f32_e32 v33, v36
	v_exp_f32_e32 v35, v49
	v_exp_f32_e32 v18, v37
	v_exp_f32_e32 v36, v50
	v_sub_f32_e32 v53, v38, v47
	v_add_f32_e32 v37, v35, v33
	v_sub_f32_e32 v38, v20, v47
	v_pk_add_f32 v[14:15], v[36:37], v[18:19]
	v_sub_f32_e32 v54, v39, v47
	v_sub_f32_e32 v39, v21, v47
	v_pk_add_f32 v[20:21], v[14:15], v[14:15] op_sel_hi:[0,1]
	v_exp_f32_e32 v19, v38
	v_exp_f32_e32 v37, v51
	v_exp_f32_e32 v20, v39
	v_exp_f32_e32 v38, v52
	v_sub_f32_e32 v57, v42, v47
	v_add_f32_e32 v39, v37, v19
	v_sub_f32_e32 v42, v24, v47
	v_pk_add_f32 v[14:15], v[38:39], v[20:21]
	v_exp_f32_e32 v21, v40
	v_pk_add_f32 v[22:23], v[14:15], v[14:15] op_sel_hi:[0,1]
	v_exp_f32_e32 v39, v53
	v_exp_f32_e32 v22, v41
	v_exp_f32_e32 v40, v54
	v_sub_f32_e32 v58, v43, v47
	v_add_f32_e32 v41, v39, v21
	v_sub_f32_e32 v43, v25, v47
	v_pk_add_f32 v[14:15], v[40:41], v[22:23]
	v_exp_f32_e32 v23, v42
	v_pk_add_f32 v[24:25], v[14:15], v[14:15] op_sel_hi:[0,1]
	v_exp_f32_e32 v41, v55
	v_exp_f32_e32 v24, v43
	v_exp_f32_e32 v42, v56
	v_sub_f32_e32 v59, v44, v47
	v_add_f32_e32 v43, v41, v23
	v_sub_f32_e32 v44, v26, v47
	v_pk_add_f32 v[14:15], v[42:43], v[24:25]
	v_sub_f32_e32 v60, v45, v47
	v_sub_f32_e32 v45, v27, v47
	v_pk_add_f32 v[26:27], v[14:15], v[14:15] op_sel_hi:[0,1]
	v_exp_f32_e32 v25, v44
	v_exp_f32_e32 v43, v57
	v_exp_f32_e32 v26, v45
	v_exp_f32_e32 v44, v58
	v_sub_f32_e32 v46, v28, v47
	v_add_f32_e32 v45, v43, v25
	v_sub_f32_e32 v48, v29, v47
	v_pk_add_f32 v[14:15], v[44:45], v[26:27]
	v_exp_f32_e32 v27, v46
	v_pk_add_f32 v[28:29], v[14:15], v[14:15] op_sel_hi:[0,1]
	v_exp_f32_e32 v45, v59
	v_exp_f32_e32 v28, v48
	v_exp_f32_e32 v48, v60
	s_waitcnt lgkmcnt(0)
	s_barrier
	v_add_f32_e32 v49, v45, v27
	v_exp_f32_e64 v0, -v47
	v_pk_add_f32 v[50:51], v[48:49], v[28:29]
	v_cvt_pk_bf16_f32 v114, v61, v16
	v_cvt_pk_bf16_f32 v115, v17, v32
	v_cvt_pk_bf16_f32 v116, v33, v18
	v_cvt_pk_bf16_f32 v117, v19, v20
	v_cvt_pk_bf16_f32 v118, v21, v22
	v_cvt_pk_bf16_f32 v119, v23, v24
	v_cvt_pk_bf16_f32 v120, v25, v26
	v_cvt_pk_bf16_f32 v121, v27, v28
	v_cvt_pk_bf16_f32 v122, v62, v30
	v_cvt_pk_bf16_f32 v123, v31, v34
	ds_read_b128 v[16:19], v140 offset:13312
	ds_read_b128 v[20:23], v140 offset:13344
	ds_read_b128 v[24:27], v140 offset:19968
	ds_read_b128 v[28:31], v140 offset:13376
	ds_read_b128 v[130:133], v140 offset:20000
	ds_read_b128 v[136:139], v140 offset:20032
	v_mul_f32_e32 v0, 0, v0
	v_pk_add_f32 v[50:51], v[50:51], v[50:51] op_sel:[0,1] op_sel_hi:[1,0]
	v_mov_b32_e32 v46, v0
	v_mov_b32_e32 v51, v99
	v_pk_add_f32 v[72:73], v[46:47], v[50:51]
	v_mov_b32_e32 v1, v0
	v_xor_b32_e32 v32, 0x80000000, v73
	v_mov_b32_e32 v2, v0
	v_mov_b32_e32 v3, v0
	v_mov_b32_e32 v4, v0
	v_mov_b32_e32 v5, v0
	v_mov_b32_e32 v6, v0
	v_mov_b32_e32 v7, v0
	v_mov_b32_e32 v8, v0
	v_mov_b32_e32 v9, v0
	v_mov_b32_e32 v10, v0
	v_mov_b32_e32 v11, v0
	v_mov_b32_e32 v12, v0
	v_mov_b32_e32 v13, v0
	v_mov_b32_e32 v14, v0
	v_mov_b32_e32 v15, v0
	v_cvt_pk_bf16_f32 v124, v35, v36
	v_cvt_pk_bf16_f32 v125, v37, v38
	v_cvt_pk_bf16_f32 v126, v39, v40
	v_cvt_pk_bf16_f32 v127, v41, v42
	v_cvt_pk_bf16_f32 v128, v43, v44
	v_cvt_pk_bf16_f32 v129, v45, v48
	v_mov_b32_e32 v33, v32
	v_mov_b32_e32 v34, v32
	v_mov_b32_e32 v35, v32
	v_mov_b32_e32 v36, v32
	v_mov_b32_e32 v37, v32
	v_mov_b32_e32 v38, v32
	v_mov_b32_e32 v39, v32
	v_mov_b32_e32 v40, v32
	v_mov_b32_e32 v41, v32
	v_mov_b32_e32 v42, v32
	v_mov_b32_e32 v43, v32
	v_mov_b32_e32 v44, v32
	v_mov_b32_e32 v45, v32
	v_mov_b32_e32 v46, v32
	v_mov_b32_e32 v47, v32
	s_waitcnt lgkmcnt(5)
	s_nop 0
	v_mfma_f32_32x32x16_bf16 v[48:63], v[16:19], v[106:109], v[32:47]
	s_waitcnt lgkmcnt(3)
	v_mfma_f32_32x32x16_bf16 v[32:47], v[24:27], v[106:109], v[32:47]
	ds_read_b128 v[16:19], v140 offset:13408
	ds_read_b128 v[24:27], v140 offset:20064
	v_mfma_f32_32x32x16_bf16 v[48:63], v[20:23], v[102:105], v[48:63]
	s_waitcnt lgkmcnt(3)
	v_mfma_f32_32x32x16_bf16 v[32:47], v[130:133], v[102:105], v[32:47]
	ds_read_b128 v[20:23], v140 offset:13440
	ds_read_b128 v[130:133], v140 offset:20096
	v_mfma_f32_32x32x16_bf16 v[48:63], v[28:31], v[92:95], v[48:63]
	s_waitcnt lgkmcnt(4)
	v_mfma_f32_32x32x16_bf16 v[32:47], v[136:139], v[92:95], v[32:47]
	ds_read_b128 v[28:31], v140 offset:13472
	ds_read_b128 v[136:139], v140 offset:20128
	s_waitcnt lgkmcnt(5)
	v_mfma_f32_32x32x16_bf16 v[48:63], v[16:19], v[88:91], v[48:63]
	s_waitcnt lgkmcnt(4)
	v_mfma_f32_32x32x16_bf16 v[32:47], v[24:27], v[88:91], v[32:47]
	ds_read_b64_tr_b16 v[144:145], v97 offset:26624
	ds_read_b64_tr_b16 v[146:147], v97 offset:27776
	ds_read_b64_tr_b16 v[152:153], v97 offset:27840
	ds_read_b64_tr_b16 v[150:151], v97 offset:26688
	s_waitcnt lgkmcnt(7)
	v_mfma_f32_32x32x16_bf16 v[48:63], v[20:23], v[84:87], v[48:63]
	s_waitcnt lgkmcnt(6)
	v_mfma_f32_32x32x16_bf16 v[32:47], v[130:133], v[84:87], v[32:47]
	ds_read_b64_tr_b16 v[130:131], v97 offset:28928
	ds_read_b64_tr_b16 v[132:133], v97 offset:30080
	ds_read_b64_tr_b16 v[156:157], v97 offset:30144
	ds_read_b64_tr_b16 v[154:155], v97 offset:28992
	s_waitcnt lgkmcnt(9)
	v_mfma_f32_32x32x16_bf16 v[48:63], v[28:31], v[80:83], v[48:63]
	s_waitcnt lgkmcnt(8)
	v_mfma_f32_32x32x16_bf16 v[32:47], v[136:139], v[80:83], v[32:47]
	ds_read_b64_tr_b16 v[136:137], v97 offset:31232
	ds_read_b64_tr_b16 v[138:139], v97 offset:32384
	ds_read_b64_tr_b16 v[160:161], v97 offset:32448
	ds_read_b64_tr_b16 v[158:159], v97 offset:31296
	s_waitcnt lgkmcnt(10)
	v_mfma_f32_32x32x16_bf16 v[16:31], v[144:147], v[114:117], v[0:15]
	s_waitcnt lgkmcnt(8)
	v_mfma_f32_32x32x16_bf16 v[0:15], v[150:153], v[114:117], v[0:15]
	ds_read_b64_tr_b16 v[114:115], v97 offset:33536
	ds_read_b64_tr_b16 v[116:117], v97 offset:34688
	ds_read_b64_tr_b16 v[146:147], v97 offset:34752
	ds_read_b64_tr_b16 v[144:145], v97 offset:33600
	s_waitcnt lgkmcnt(10)
	v_mfma_f32_32x32x16_bf16 v[16:31], v[130:133], v[118:121], v[16:31]
	s_waitcnt lgkmcnt(8)
	v_mfma_f32_32x32x16_bf16 v[0:15], v[154:157], v[118:121], v[0:15]
	s_waitcnt lgkmcnt(6)
	v_mfma_f32_32x32x16_bf16 v[16:31], v[136:139], v[122:125], v[16:31]
	s_waitcnt lgkmcnt(4)
	v_mfma_f32_32x32x16_bf16 v[0:15], v[158:161], v[122:125], v[0:15]
	s_waitcnt lgkmcnt(2)
	v_mfma_f32_32x32x16_bf16 v[16:31], v[114:117], v[126:129], v[16:31]
	s_waitcnt lgkmcnt(0)
	v_mfma_f32_32x32x16_bf16 v[0:15], v[144:147], v[126:129], v[0:15]
	s_nop 15
	s_nop 7
	s_nop 0
	v_max3_f32 v79, v48, v49, v32
	v_max3_f32 v114, v50, v51, v33
	s_nop 0
	v_max3_f32 v79, v79, v34, v35
	v_max3_f32 v114, v114, v54, v55
	s_nop 0
	v_max3_f32 v79, v79, v52, v53
	v_max3_f32 v114, v114, v38, v39
	s_nop 0
	v_max3_f32 v79, v79, v36, v37
	v_max3_f32 v114, v114, v58, v59
	s_nop 0
	v_max3_f32 v79, v79, v56, v57
	v_max3_f32 v114, v114, v42, v43
	s_nop 0
	v_max3_f32 v79, v79, v40, v41
	v_max3_f32 v114, v114, v62, v63
	s_nop 0
	v_max3_f32 v79, v79, v60, v61
	v_max3_f32 v114, v114, v46, v47
	s_nop 0
	v_max3_f32 v79, v79, v44, v45
	s_nop 0
	v_max3_f32 v79, v79, v114, v114
	v_mov_b32_e32 v114, v79
	s_nop 1
	v_permlane32_swap_b32 v114, v79
	v_max_f32_e32 v79, v79, v114
	s_waitcnt lgkmcnt(0)
	s_nop 0
	v_cmp_lt_f32_e32 vcc, s78, v79
	s_cbranch_vccz .LBB0_170
	v_max_f32_e32 v79, v79, v79
	v_max_f32_e32 v79, 0, v79
	v_exp_f32_e64 v114, -v79
	v_pk_add_f32 v[116:117], v[72:73], v[78:79]
	v_pk_mul_f32 v[30:31], v[30:31], v[114:115] op_sel_hi:[1,0]
	v_mov_b32_e32 v116, v79
	v_pk_add_f32 v[48:49], v[48:49], v[116:117] op_sel_hi:[1,0] neg_lo:[0,1] neg_hi:[0,1]
	v_pk_add_f32 v[32:33], v[32:33], v[116:117] op_sel_hi:[1,0] neg_lo:[0,1] neg_hi:[0,1]
	v_pk_add_f32 v[50:51], v[50:51], v[116:117] op_sel_hi:[1,0] neg_lo:[0,1] neg_hi:[0,1]
	v_pk_add_f32 v[34:35], v[34:35], v[116:117] op_sel_hi:[1,0] neg_lo:[0,1] neg_hi:[0,1]
	v_pk_add_f32 v[52:53], v[52:53], v[116:117] op_sel_hi:[1,0] neg_lo:[0,1] neg_hi:[0,1]
	v_pk_add_f32 v[36:37], v[36:37], v[116:117] op_sel_hi:[1,0] neg_lo:[0,1] neg_hi:[0,1]
	v_pk_add_f32 v[54:55], v[54:55], v[116:117] op_sel_hi:[1,0] neg_lo:[0,1] neg_hi:[0,1]
	v_pk_add_f32 v[38:39], v[38:39], v[116:117] op_sel_hi:[1,0] neg_lo:[0,1] neg_hi:[0,1]
	v_pk_add_f32 v[56:57], v[56:57], v[116:117] op_sel_hi:[1,0] neg_lo:[0,1] neg_hi:[0,1]
	v_pk_add_f32 v[40:41], v[40:41], v[116:117] op_sel_hi:[1,0] neg_lo:[0,1] neg_hi:[0,1]
	v_pk_add_f32 v[58:59], v[58:59], v[116:117] op_sel_hi:[1,0] neg_lo:[0,1] neg_hi:[0,1]
	v_pk_add_f32 v[42:43], v[42:43], v[116:117] op_sel_hi:[1,0] neg_lo:[0,1] neg_hi:[0,1]
	v_pk_add_f32 v[60:61], v[60:61], v[116:117] op_sel_hi:[1,0] neg_lo:[0,1] neg_hi:[0,1]
	v_pk_add_f32 v[44:45], v[44:45], v[116:117] op_sel_hi:[1,0] neg_lo:[0,1] neg_hi:[0,1]
	v_pk_add_f32 v[62:63], v[62:63], v[116:117] op_sel_hi:[1,0] neg_lo:[0,1] neg_hi:[0,1]
	v_pk_add_f32 v[46:47], v[46:47], v[116:117] op_sel_hi:[1,0] neg_lo:[0,1] neg_hi:[0,1]
	v_pk_mul_f32 v[28:29], v[28:29], v[114:115] op_sel_hi:[1,0]
	v_pk_mul_f32 v[26:27], v[26:27], v[114:115] op_sel_hi:[1,0]
	v_pk_mul_f32 v[24:25], v[24:25], v[114:115] op_sel_hi:[1,0]
	v_pk_mul_f32 v[22:23], v[22:23], v[114:115] op_sel_hi:[1,0]
	v_pk_mul_f32 v[20:21], v[20:21], v[114:115] op_sel_hi:[1,0]
	v_pk_mul_f32 v[18:19], v[18:19], v[114:115] op_sel_hi:[1,0]
	v_pk_mul_f32 v[16:17], v[16:17], v[114:115] op_sel_hi:[1,0]
	v_pk_mul_f32 v[14:15], v[14:15], v[114:115] op_sel_hi:[1,0]
	v_pk_mul_f32 v[12:13], v[12:13], v[114:115] op_sel_hi:[1,0]
	v_pk_mul_f32 v[10:11], v[10:11], v[114:115] op_sel_hi:[1,0]
	v_pk_mul_f32 v[8:9], v[8:9], v[114:115] op_sel_hi:[1,0]
	v_pk_mul_f32 v[6:7], v[6:7], v[114:115] op_sel_hi:[1,0]
	v_pk_mul_f32 v[4:5], v[4:5], v[114:115] op_sel_hi:[1,0]
	v_pk_mul_f32 v[2:3], v[2:3], v[114:115] op_sel_hi:[1,0]
	v_pk_mul_f32 v[0:1], v[0:1], v[114:115] op_sel_hi:[1,0]
	v_mul_f32_e32 v72, v72, v114
	v_mov_b32_e32 v73, v117

.LBB0_174:
	s_or_b64 exec, exec, s[6:7]
	v_exp_f32_e32 v48, v48
	v_exp_f32_e32 v79, v32
	v_exp_f32_e32 v49, v49
	v_exp_f32_e32 v100, v33
	v_exp_f32_e32 v50, v50
	v_exp_f32_e32 v34, v34
	v_exp_f32_e32 v51, v51
	v_exp_f32_e32 v35, v35
	v_add_f32_e32 v32, v79, v48
	v_exp_f32_e32 v52, v52
	v_exp_f32_e32 v36, v36
	v_add_f32_e32 v32, 0, v32
	v_add_f32_e32 v33, v100, v49
	v_add_f32_e32 v32, v33, v32
	v_add_f32_e32 v33, v34, v50
	v_add_f32_e32 v32, v33, v32
	v_add_f32_e32 v33, v35, v51
	v_add_f32_e32 v32, v33, v32
	v_add_f32_e32 v33, v36, v52
	v_add_f32_e32 v101, v33, v32
	v_lshlrev_b64 v[32:33], 10, v[74:75]
	v_lshl_add_u64 v[32:33], s[92:93], 0, v[32:33]
	v_lshl_add_u64 v[32:33], v[32:33], 0, s[68:69]
	v_lshl_add_u64 v[32:33], v[32:33], 0, v[98:99]
	s_mov_b32 s1, 0x2020000
	v_add_co_u32_e32 v32, vcc, s1, v32
	v_exp_f32_e32 v53, v53
	s_nop 0
	v_addc_co_u32_e32 v33, vcc, 0, v33, vcc
	global_load_dwordx4 v[64:67], v[32:33], off offset:128
	v_exp_f32_e32 v37, v37
	v_exp_f32_e32 v54, v54
	v_exp_f32_e32 v38, v38
	v_exp_f32_e32 v32, v55
	v_exp_f32_e32 v33, v39
	v_exp_f32_e32 v56, v56
	v_exp_f32_e32 v40, v40
	v_add_f32_e32 v114, v37, v53
	v_exp_f32_e32 v57, v57
	v_exp_f32_e32 v41, v41
	v_add_f32_e32 v39, v114, v101
	v_add_f32_e32 v55, v38, v54
	v_exp_f32_e32 v58, v58
	v_exp_f32_e32 v42, v42
	v_add_f32_e32 v39, v55, v39
	v_add_f32_e32 v55, v33, v32
	v_exp_f32_e32 v59, v59
	v_exp_f32_e32 v43, v43
	v_add_f32_e32 v39, v55, v39
	v_add_f32_e32 v55, v40, v56
	v_exp_f32_e32 v60, v60
	v_exp_f32_e32 v44, v44
	s_waitcnt lgkmcnt(0)
	s_barrier
	v_add_f32_e32 v39, v55, v39
	v_add_f32_e32 v55, v41, v57
	v_exp_f32_e32 v61, v61
	v_exp_f32_e32 v45, v45
	ds_read_b128 v[130:133], v140
	ds_read_b128 v[136:139], v140 offset:32
	ds_read_b128 v[142:145], v140 offset:6656
	ds_read_b128 v[150:153], v140 offset:64
	ds_read_b128 v[154:157], v140 offset:6688
	ds_read_b128 v[158:161], v140 offset:6720
	v_add_f32_e32 v39, v55, v39
	v_add_f32_e32 v55, v42, v58
	v_exp_f32_e32 v62, v62
	v_exp_f32_e32 v46, v46
	v_add_f32_e32 v39, v55, v39
	v_add_f32_e32 v55, v43, v59
	v_exp_f32_e32 v63, v63
	v_exp_f32_e32 v47, v47
	v_add_f32_e32 v39, v55, v39
	v_add_f32_e32 v55, v44, v60
	v_add_f32_e32 v39, v55, v39
	v_add_f32_e32 v55, v45, v61
	v_add_f32_e32 v39, v55, v39
	v_add_f32_e32 v55, v46, v62
	v_add_f32_e32 v39, v55, v39
	v_add_f32_e32 v55, v47, v63
	v_add_f32_e32 v39, v55, v39
	v_cvt_pk_bf16_f32 v117, v54, v32
	v_xor_b32_e32 v32, 0x80000000, v73
	v_add_f32_e32 v72, v72, v39
	v_cvt_pk_bf16_f32 v123, v34, v35
	v_cvt_pk_bf16_f32 v124, v36, v37
	v_cvt_pk_bf16_f32 v125, v38, v33
	v_cvt_pk_bf16_f32 v126, v40, v41
	v_cvt_pk_bf16_f32 v127, v42, v43
	v_cvt_pk_bf16_f32 v128, v44, v45
	v_cvt_pk_bf16_f32 v129, v46, v47
	v_mov_b32_e32 v33, v32
	v_mov_b32_e32 v34, v32
	v_mov_b32_e32 v35, v32
	v_mov_b32_e32 v36, v32
	v_mov_b32_e32 v37, v32
	v_mov_b32_e32 v38, v32
	v_mov_b32_e32 v39, v32
	v_mov_b32_e32 v40, v32
	v_mov_b32_e32 v41, v32
	v_mov_b32_e32 v42, v32
	v_mov_b32_e32 v43, v32
	v_mov_b32_e32 v44, v32
	v_mov_b32_e32 v45, v32
	v_mov_b32_e32 v46, v32
	v_mov_b32_e32 v47, v32
	v_cvt_pk_bf16_f32 v114, v48, v49
	v_cvt_pk_bf16_f32 v115, v50, v51
	v_cvt_pk_bf16_f32 v116, v52, v53
	v_cvt_pk_bf16_f32 v118, v56, v57
	v_cvt_pk_bf16_f32 v119, v58, v59
	v_cvt_pk_bf16_f32 v120, v60, v61
	v_cvt_pk_bf16_f32 v121, v62, v63
	v_cvt_pk_bf16_f32 v122, v79, v100
	s_waitcnt lgkmcnt(5)
	v_mfma_f32_32x32x16_bf16 v[48:63], v[130:133], v[106:109], v[32:47]
	s_waitcnt lgkmcnt(3)
	v_mfma_f32_32x32x16_bf16 v[32:47], v[142:145], v[106:109], v[32:47]
	ds_read_b128 v[130:133], v140 offset:96
	ds_read_b128 v[142:145], v140 offset:6752
	v_mfma_f32_32x32x16_bf16 v[48:63], v[136:139], v[102:105], v[48:63]
	s_waitcnt lgkmcnt(3)
	v_mfma_f32_32x32x16_bf16 v[32:47], v[154:157], v[102:105], v[32:47]
	ds_read_b128 v[136:139], v140 offset:128
	ds_read_b128 v[154:157], v140 offset:6784
	v_mfma_f32_32x32x16_bf16 v[48:63], v[150:153], v[92:95], v[48:63]
	s_waitcnt lgkmcnt(4)
	v_mfma_f32_32x32x16_bf16 v[32:47], v[158:161], v[92:95], v[32:47]
	ds_read_b128 v[150:153], v140 offset:160
	ds_read_b128 v[158:161], v140 offset:6816
	s_waitcnt lgkmcnt(5)
	v_mfma_f32_32x32x16_bf16 v[48:63], v[130:133], v[88:91], v[48:63]
	s_waitcnt lgkmcnt(4)
	v_mfma_f32_32x32x16_bf16 v[32:47], v[142:145], v[88:91], v[32:47]
	ds_read_b64_tr_b16 v[130:131], v97 offset:35840
	ds_read_b64_tr_b16 v[132:133], v97 offset:36992
	ds_read_b64_tr_b16 v[144:145], v97 offset:37056
	ds_read_b64_tr_b16 v[142:143], v97 offset:35904
	s_waitcnt lgkmcnt(7)
	v_mfma_f32_32x32x16_bf16 v[48:63], v[136:139], v[84:87], v[48:63]
	s_waitcnt lgkmcnt(6)
	v_mfma_f32_32x32x16_bf16 v[32:47], v[154:157], v[84:87], v[32:47]
	ds_read_b64_tr_b16 v[136:137], v97 offset:38144
	ds_read_b64_tr_b16 v[138:139], v97 offset:39296
	ds_read_b64_tr_b16 v[156:157], v97 offset:39360
	ds_read_b64_tr_b16 v[154:155], v97 offset:38208
	s_waitcnt lgkmcnt(9)
	v_mfma_f32_32x32x16_bf16 v[48:63], v[150:153], v[80:83], v[48:63]
	s_waitcnt lgkmcnt(8)
	v_mfma_f32_32x32x16_bf16 v[32:47], v[158:161], v[80:83], v[32:47]
	ds_read_b64_tr_b16 v[150:151], v97 offset:40448
	ds_read_b64_tr_b16 v[152:153], v97 offset:41600
	ds_read_b64_tr_b16 v[160:161], v97 offset:41664
	ds_read_b64_tr_b16 v[158:159], v97 offset:40512
	s_waitcnt lgkmcnt(10)
	v_mfma_f32_32x32x16_bf16 v[16:31], v[130:133], v[114:117], v[16:31]
	s_waitcnt lgkmcnt(8)
	v_mfma_f32_32x32x16_bf16 v[0:15], v[142:145], v[114:117], v[0:15]
	ds_read_b64_tr_b16 v[114:115], v97 offset:42752
	ds_read_b64_tr_b16 v[116:117], v97 offset:43904
	ds_read_b64_tr_b16 v[132:133], v97 offset:43968
	ds_read_b64_tr_b16 v[130:131], v97 offset:42816
	s_waitcnt lgkmcnt(10)
	v_mfma_f32_32x32x16_bf16 v[16:31], v[136:139], v[118:121], v[16:31]
	s_waitcnt lgkmcnt(8)
	v_mfma_f32_32x32x16_bf16 v[0:15], v[154:157], v[118:121], v[0:15]
	s_waitcnt lgkmcnt(6)
	v_mfma_f32_32x32x16_bf16 v[16:31], v[150:153], v[122:125], v[16:31]
	s_waitcnt lgkmcnt(4)
	v_mfma_f32_32x32x16_bf16 v[0:15], v[158:161], v[122:125], v[0:15]
	s_waitcnt lgkmcnt(2)
	v_mfma_f32_32x32x16_bf16 v[16:31], v[114:117], v[126:129], v[16:31]
	s_waitcnt lgkmcnt(0)
	v_mfma_f32_32x32x16_bf16 v[0:15], v[130:133], v[126:129], v[0:15]
	s_nop 15
	s_nop 7
	s_nop 0
	v_max3_f32 v79, v48, v49, v32
	v_max3_f32 v100, v50, v51, v33
	s_nop 0
	v_max3_f32 v79, v79, v34, v35
	v_max3_f32 v100, v100, v54, v55
	s_nop 0
	v_max3_f32 v79, v79, v52, v53
	v_max3_f32 v100, v100, v38, v39
	s_nop 0
	v_max3_f32 v79, v79, v36, v37
	v_max3_f32 v100, v100, v58, v59
	s_nop 0
	v_max3_f32 v79, v79, v56, v57
	v_max3_f32 v100, v100, v42, v43
	s_nop 0
	v_max3_f32 v79, v79, v40, v41
	v_max3_f32 v100, v100, v62, v63
	s_nop 0
	v_max3_f32 v79, v79, v60, v61
	v_max3_f32 v100, v100, v46, v47
	s_nop 0
	v_max3_f32 v79, v79, v44, v45
	s_nop 0
	v_max3_f32 v79, v79, v100, v100
	v_mov_b32_e32 v100, v79
	s_nop 1
	v_permlane32_swap_b32 v100, v79
	v_max_f32_e32 v79, v79, v100
	s_waitcnt lgkmcnt(0)
	s_nop 0
	v_cmp_lt_f32_e32 vcc, s78, v79
	s_cbranch_vccz .LBB0_176
	v_max_f32_e32 v79, v79, v79
	v_max_f32_e32 v100, 0, v79
	v_exp_f32_e64 v114, -v100
	v_add_f32_e32 v73, v73, v100
	v_pk_add_f32 v[48:49], v[48:49], v[100:101] op_sel_hi:[1,0] neg_lo:[0,1] neg_hi:[0,1]
	v_pk_add_f32 v[32:33], v[32:33], v[100:101] op_sel_hi:[1,0] neg_lo:[0,1] neg_hi:[0,1]
	v_mul_f32_e32 v72, v72, v114
	v_pk_add_f32 v[50:51], v[50:51], v[100:101] op_sel_hi:[1,0] neg_lo:[0,1] neg_hi:[0,1]
	v_pk_add_f32 v[34:35], v[34:35], v[100:101] op_sel_hi:[1,0] neg_lo:[0,1] neg_hi:[0,1]
	v_pk_add_f32 v[52:53], v[52:53], v[100:101] op_sel_hi:[1,0] neg_lo:[0,1] neg_hi:[0,1]
	v_pk_add_f32 v[36:37], v[36:37], v[100:101] op_sel_hi:[1,0] neg_lo:[0,1] neg_hi:[0,1]
	v_pk_add_f32 v[54:55], v[54:55], v[100:101] op_sel_hi:[1,0] neg_lo:[0,1] neg_hi:[0,1]
	v_pk_add_f32 v[38:39], v[38:39], v[100:101] op_sel_hi:[1,0] neg_lo:[0,1] neg_hi:[0,1]
	v_pk_add_f32 v[56:57], v[56:57], v[100:101] op_sel_hi:[1,0] neg_lo:[0,1] neg_hi:[0,1]
	v_pk_add_f32 v[40:41], v[40:41], v[100:101] op_sel_hi:[1,0] neg_lo:[0,1] neg_hi:[0,1]
	v_pk_add_f32 v[58:59], v[58:59], v[100:101] op_sel_hi:[1,0] neg_lo:[0,1] neg_hi:[0,1]
	v_pk_add_f32 v[42:43], v[42:43], v[100:101] op_sel_hi:[1,0] neg_lo:[0,1] neg_hi:[0,1]
	v_pk_add_f32 v[60:61], v[60:61], v[100:101] op_sel_hi:[1,0] neg_lo:[0,1] neg_hi:[0,1]
	v_pk_add_f32 v[44:45], v[44:45], v[100:101] op_sel_hi:[1,0] neg_lo:[0,1] neg_hi:[0,1]
	v_pk_add_f32 v[62:63], v[62:63], v[100:101] op_sel_hi:[1,0] neg_lo:[0,1] neg_hi:[0,1]
	v_pk_add_f32 v[46:47], v[46:47], v[100:101] op_sel_hi:[1,0] neg_lo:[0,1] neg_hi:[0,1]
	v_pk_mul_f32 v[30:31], v[30:31], v[114:115] op_sel_hi:[1,0]
	v_pk_mul_f32 v[28:29], v[28:29], v[114:115] op_sel_hi:[1,0]
	v_pk_mul_f32 v[26:27], v[26:27], v[114:115] op_sel_hi:[1,0]
	v_pk_mul_f32 v[24:25], v[24:25], v[114:115] op_sel_hi:[1,0]
	v_pk_mul_f32 v[22:23], v[22:23], v[114:115] op_sel_hi:[1,0]
	v_pk_mul_f32 v[20:21], v[20:21], v[114:115] op_sel_hi:[1,0]
	v_pk_mul_f32 v[18:19], v[18:19], v[114:115] op_sel_hi:[1,0]
	v_pk_mul_f32 v[16:17], v[16:17], v[114:115] op_sel_hi:[1,0]
	v_pk_mul_f32 v[14:15], v[14:15], v[114:115] op_sel_hi:[1,0]
	v_pk_mul_f32 v[12:13], v[12:13], v[114:115] op_sel_hi:[1,0]
	v_pk_mul_f32 v[10:11], v[10:11], v[114:115] op_sel_hi:[1,0]
	v_pk_mul_f32 v[8:9], v[8:9], v[114:115] op_sel_hi:[1,0]
	v_pk_mul_f32 v[6:7], v[6:7], v[114:115] op_sel_hi:[1,0]
	v_pk_mul_f32 v[4:5], v[4:5], v[114:115] op_sel_hi:[1,0]
	v_pk_mul_f32 v[2:3], v[2:3], v[114:115] op_sel_hi:[1,0]
	v_pk_mul_f32 v[0:1], v[0:1], v[114:115] op_sel_hi:[1,0]
.LBB0_176:
	s_waitcnt vmcnt(1)
	ds_write_b128 v78, v[68:71] offset:13312
	s_and_saveexec_b64 s[6:7], s[38:39]
	ds_write_b128 v77, v[110:113] offset:13440
	s_or_b64 exec, exec, s[6:7]
	v_exp_f32_e32 v48, v48
	v_exp_f32_e32 v77, v32
	v_exp_f32_e32 v49, v49
	v_exp_f32_e32 v78, v33
	v_exp_f32_e32 v50, v50
	v_exp_f32_e32 v34, v34
	v_exp_f32_e32 v51, v51
	v_exp_f32_e32 v35, v35
	v_add_f32_e32 v32, v77, v48
	v_exp_f32_e32 v52, v52
	v_exp_f32_e32 v36, v36
	v_add_f32_e32 v32, 0, v32
	v_add_f32_e32 v33, v78, v49
	v_add_f32_e32 v32, v33, v32
	v_add_f32_e32 v33, v34, v50
	v_add_f32_e32 v32, v33, v32
	v_add_f32_e32 v33, v35, v51
	v_add_f32_e32 v32, v33, v32
	v_add_f32_e32 v33, v36, v52
	v_add_f32_e32 v79, v33, v32
	v_lshlrev_b64 v[32:33], 10, v[74:75]
	v_lshl_add_u64 v[32:33], s[92:93], 0, v[32:33]
	v_lshl_add_u64 v[32:33], v[32:33], 0, s[68:69]
	v_lshl_add_u64 v[32:33], v[32:33], 0, v[98:99]
	s_mov_b32 s1, 0x2030000
	v_add_co_u32_e32 v32, vcc, s1, v32
	v_exp_f32_e32 v53, v53
	s_nop 0
	v_addc_co_u32_e32 v33, vcc, 0, v33, vcc
	global_load_dwordx4 v[68:71], v[32:33], off offset:128
	v_exp_f32_e32 v37, v37
	v_exp_f32_e32 v54, v54
	v_exp_f32_e32 v38, v38
	v_exp_f32_e32 v55, v55
	v_exp_f32_e32 v32, v39
	v_exp_f32_e32 v56, v56
	v_exp_f32_e32 v40, v40
	v_add_f32_e32 v100, v37, v53
	v_exp_f32_e32 v57, v57
	v_exp_f32_e32 v41, v41
	v_add_f32_e32 v33, v100, v79
	v_add_f32_e32 v39, v38, v54
	v_exp_f32_e32 v58, v58
	v_exp_f32_e32 v42, v42
	v_add_f32_e32 v33, v39, v33
	v_add_f32_e32 v39, v32, v55
	v_exp_f32_e32 v59, v59
	v_exp_f32_e32 v43, v43
	s_waitcnt vmcnt(1)
	ds_write_b128 v76, v[64:67] offset:26624
	v_add_f32_e32 v33, v39, v33
	v_add_f32_e32 v39, v40, v56
	v_exp_f32_e32 v60, v60
	v_exp_f32_e32 v44, v44
	s_waitcnt lgkmcnt(0)
	s_barrier
	v_add_f32_e32 v33, v39, v33
	v_add_f32_e32 v39, v41, v57
	v_exp_f32_e32 v61, v61
	v_exp_f32_e32 v45, v45
	ds_read_b128 v[64:67], v140 offset:13312
	ds_read_b128 v[126:129], v140 offset:13344
	ds_read_b128 v[130:133], v140 offset:19968
	ds_read_b128 v[136:139], v140 offset:13376
	ds_read_b128 v[142:145], v140 offset:20000
	ds_read_b128 v[150:153], v140 offset:20032
	v_add_f32_e32 v33, v39, v33
	v_add_f32_e32 v39, v42, v58
	v_exp_f32_e32 v62, v62
	v_exp_f32_e32 v46, v46
	v_add_f32_e32 v33, v39, v33
	v_add_f32_e32 v39, v43, v59
	v_exp_f32_e32 v63, v63
	v_exp_f32_e32 v47, v47
	v_add_f32_e32 v33, v39, v33
	v_add_f32_e32 v39, v44, v60
	v_add_f32_e32 v33, v39, v33
	v_add_f32_e32 v39, v45, v61
	v_add_f32_e32 v33, v39, v33
	v_add_f32_e32 v39, v46, v62
	v_add_f32_e32 v33, v39, v33
	v_add_f32_e32 v39, v47, v63
	v_add_f32_e32 v33, v39, v33
	v_cvt_pk_bf16_f32 v121, v38, v32
	v_xor_b32_e32 v32, 0x80000000, v73
	v_add_f32_e32 v72, v72, v33
	v_cvt_pk_bf16_f32 v119, v34, v35
	v_cvt_pk_bf16_f32 v120, v36, v37
	v_cvt_pk_bf16_f32 v122, v40, v41
	v_cvt_pk_bf16_f32 v123, v42, v43
	v_cvt_pk_bf16_f32 v124, v44, v45
	v_cvt_pk_bf16_f32 v125, v46, v47
	v_mov_b32_e32 v33, v32
	v_mov_b32_e32 v34, v32
	v_mov_b32_e32 v35, v32
	v_mov_b32_e32 v36, v32
	v_mov_b32_e32 v37, v32
	v_mov_b32_e32 v38, v32
	v_mov_b32_e32 v39, v32
	v_mov_b32_e32 v40, v32
	v_mov_b32_e32 v41, v32
	v_mov_b32_e32 v42, v32
	v_mov_b32_e32 v43, v32
	v_mov_b32_e32 v44, v32
	v_mov_b32_e32 v45, v32
	v_mov_b32_e32 v46, v32
	v_mov_b32_e32 v47, v32
	v_cvt_pk_bf16_f32 v110, v48, v49
	v_cvt_pk_bf16_f32 v111, v50, v51
	v_cvt_pk_bf16_f32 v112, v52, v53
	v_cvt_pk_bf16_f32 v113, v54, v55
	v_cvt_pk_bf16_f32 v114, v56, v57
	v_cvt_pk_bf16_f32 v115, v58, v59
	v_cvt_pk_bf16_f32 v116, v60, v61
	v_cvt_pk_bf16_f32 v117, v62, v63
	v_cvt_pk_bf16_f32 v118, v77, v78
	s_waitcnt lgkmcnt(5)
	v_mfma_f32_32x32x16_bf16 v[48:63], v[64:67], v[106:109], v[32:47]
	s_waitcnt lgkmcnt(3)
	v_mfma_f32_32x32x16_bf16 v[32:47], v[130:133], v[106:109], v[32:47]
	ds_read_b128 v[64:67], v140 offset:13408
	ds_read_b128 v[106:109], v140 offset:20064
	v_mfma_f32_32x32x16_bf16 v[48:63], v[126:129], v[102:105], v[48:63]
	s_waitcnt lgkmcnt(3)
	v_mfma_f32_32x32x16_bf16 v[32:47], v[142:145], v[102:105], v[32:47]
	ds_read_b128 v[100:103], v140 offset:13440
	ds_read_b128 v[126:129], v140 offset:20096
	v_mfma_f32_32x32x16_bf16 v[48:63], v[136:139], v[92:95], v[48:63]
	s_waitcnt lgkmcnt(4)
	v_mfma_f32_32x32x16_bf16 v[32:47], v[150:153], v[92:95], v[32:47]
	ds_read_b128 v[92:95], v140 offset:13472
	ds_read_b128 v[130:133], v140 offset:20128
	s_waitcnt lgkmcnt(5)
	v_mfma_f32_32x32x16_bf16 v[48:63], v[64:67], v[88:91], v[48:63]
	s_waitcnt lgkmcnt(4)
	v_mfma_f32_32x32x16_bf16 v[32:47], v[106:109], v[88:91], v[32:47]
	ds_read_b64_tr_b16 v[64:65], v97 offset:26624
	ds_read_b64_tr_b16 v[66:67], v97 offset:27776
	ds_read_b64_tr_b16 v[90:91], v97 offset:27840
	ds_read_b64_tr_b16 v[88:89], v97 offset:26688
	s_waitcnt lgkmcnt(7)
	v_mfma_f32_32x32x16_bf16 v[48:63], v[100:103], v[84:87], v[48:63]
	s_waitcnt lgkmcnt(6)
	v_mfma_f32_32x32x16_bf16 v[32:47], v[126:129], v[84:87], v[32:47]
	ds_read_b64_tr_b16 v[84:85], v97 offset:28928
	ds_read_b64_tr_b16 v[86:87], v97 offset:30080
	ds_read_b64_tr_b16 v[102:103], v97 offset:30144
	ds_read_b64_tr_b16 v[100:101], v97 offset:28992
	s_waitcnt lgkmcnt(9)
	v_mfma_f32_32x32x16_bf16 v[48:63], v[92:95], v[80:83], v[48:63]
	s_waitcnt lgkmcnt(8)
	v_mfma_f32_32x32x16_bf16 v[32:47], v[130:133], v[80:83], v[32:47]
	ds_read_b64_tr_b16 v[78:79], v97 offset:31232
	ds_read_b64_tr_b16 v[80:81], v97 offset:32384
	ds_read_b64_tr_b16 v[94:95], v97 offset:32448
	ds_read_b64_tr_b16 v[92:93], v97 offset:31296
	s_waitcnt lgkmcnt(10)
	v_mfma_f32_32x32x16_bf16 v[16:31], v[64:67], v[110:113], v[16:31]
	s_waitcnt lgkmcnt(8)
	v_mfma_f32_32x32x16_bf16 v[0:15], v[88:91], v[110:113], v[0:15]
	ds_read_b64_tr_b16 v[64:65], v97 offset:33536
	ds_read_b64_tr_b16 v[66:67], v97 offset:34688
	ds_read_b64_tr_b16 v[90:91], v97 offset:34752
	ds_read_b64_tr_b16 v[88:89], v97 offset:33600
	s_waitcnt lgkmcnt(10)
	v_mfma_f32_32x32x16_bf16 v[16:31], v[84:87], v[114:117], v[16:31]
	s_waitcnt lgkmcnt(8)
	v_mfma_f32_32x32x16_bf16 v[0:15], v[100:103], v[114:117], v[0:15]
	s_waitcnt lgkmcnt(6)
	v_mfma_f32_32x32x16_bf16 v[16:31], v[78:81], v[118:121], v[16:31]
	s_waitcnt lgkmcnt(4)
	v_mfma_f32_32x32x16_bf16 v[0:15], v[92:95], v[118:121], v[0:15]
	s_waitcnt lgkmcnt(2)
	v_mfma_f32_32x32x16_bf16 v[16:31], v[64:67], v[122:125], v[16:31]
	s_waitcnt lgkmcnt(0)
	v_mfma_f32_32x32x16_bf16 v[0:15], v[88:91], v[122:125], v[0:15]
	s_nop 15
	s_nop 7
	s_nop 0
	v_max3_f32 v64, v48, v49, v32
	v_max3_f32 v65, v50, v51, v33
	s_nop 0
	v_max3_f32 v64, v64, v34, v35
	v_max3_f32 v65, v65, v54, v55
	s_nop 0
	v_max3_f32 v64, v64, v52, v53
	v_max3_f32 v65, v65, v38, v39
	s_nop 0
	v_max3_f32 v64, v64, v36, v37
	v_max3_f32 v65, v65, v58, v59
	s_nop 0
	v_max3_f32 v64, v64, v56, v57
	v_max3_f32 v65, v65, v42, v43
	s_nop 0
	v_max3_f32 v64, v64, v40, v41
	v_max3_f32 v65, v65, v62, v63
	s_nop 0
	v_max3_f32 v64, v64, v60, v61
	v_max3_f32 v65, v65, v46, v47
	s_nop 0
	v_max3_f32 v64, v64, v44, v45
	s_nop 0
	v_max3_f32 v64, v64, v65, v65
	v_mov_b32_e32 v65, v64
	s_nop 1
	v_permlane32_swap_b32 v65, v64
	v_max_f32_e32 v64, v64, v65
	s_waitcnt lgkmcnt(0)
	s_nop 0
	v_cmp_lt_f32_e32 vcc, s78, v64
	s_cbranch_vccz .LBB0_180
	v_max_f32_e32 v64, v64, v64
	v_max_f32_e32 v64, 0, v64
	v_exp_f32_e64 v66, -v64
	v_pk_add_f32 v[48:49], v[48:49], v[64:65] op_sel_hi:[1,0] neg_lo:[0,1] neg_hi:[0,1]
	v_pk_add_f32 v[32:33], v[32:33], v[64:65] op_sel_hi:[1,0] neg_lo:[0,1] neg_hi:[0,1]
	v_pk_add_f32 v[50:51], v[50:51], v[64:65] op_sel_hi:[1,0] neg_lo:[0,1] neg_hi:[0,1]
	v_mul_f32_e32 v72, v72, v66
	v_pk_add_f32 v[34:35], v[34:35], v[64:65] op_sel_hi:[1,0] neg_lo:[0,1] neg_hi:[0,1]
	v_pk_add_f32 v[52:53], v[52:53], v[64:65] op_sel_hi:[1,0] neg_lo:[0,1] neg_hi:[0,1]
	v_pk_add_f32 v[36:37], v[36:37], v[64:65] op_sel_hi:[1,0] neg_lo:[0,1] neg_hi:[0,1]
	v_pk_add_f32 v[54:55], v[54:55], v[64:65] op_sel_hi:[1,0] neg_lo:[0,1] neg_hi:[0,1]
	v_pk_add_f32 v[38:39], v[38:39], v[64:65] op_sel_hi:[1,0] neg_lo:[0,1] neg_hi:[0,1]
	v_pk_add_f32 v[56:57], v[56:57], v[64:65] op_sel_hi:[1,0] neg_lo:[0,1] neg_hi:[0,1]
	v_pk_add_f32 v[40:41], v[40:41], v[64:65] op_sel_hi:[1,0] neg_lo:[0,1] neg_hi:[0,1]
	v_pk_add_f32 v[58:59], v[58:59], v[64:65] op_sel_hi:[1,0] neg_lo:[0,1] neg_hi:[0,1]
	v_pk_add_f32 v[42:43], v[42:43], v[64:65] op_sel_hi:[1,0] neg_lo:[0,1] neg_hi:[0,1]
	v_pk_add_f32 v[60:61], v[60:61], v[64:65] op_sel_hi:[1,0] neg_lo:[0,1] neg_hi:[0,1]
	v_pk_add_f32 v[44:45], v[44:45], v[64:65] op_sel_hi:[1,0] neg_lo:[0,1] neg_hi:[0,1]
	v_pk_add_f32 v[62:63], v[62:63], v[64:65] op_sel_hi:[1,0] neg_lo:[0,1] neg_hi:[0,1]
	v_pk_add_f32 v[46:47], v[46:47], v[64:65] op_sel_hi:[1,0] neg_lo:[0,1] neg_hi:[0,1]
	v_pk_mul_f32 v[30:31], v[30:31], v[66:67] op_sel_hi:[1,0]
	v_pk_mul_f32 v[28:29], v[28:29], v[66:67] op_sel_hi:[1,0]
	v_pk_mul_f32 v[26:27], v[26:27], v[66:67] op_sel_hi:[1,0]
	v_pk_mul_f32 v[24:25], v[24:25], v[66:67] op_sel_hi:[1,0]
	v_pk_mul_f32 v[22:23], v[22:23], v[66:67] op_sel_hi:[1,0]
	v_pk_mul_f32 v[20:21], v[20:21], v[66:67] op_sel_hi:[1,0]
	v_pk_mul_f32 v[18:19], v[18:19], v[66:67] op_sel_hi:[1,0]
	v_pk_mul_f32 v[16:17], v[16:17], v[66:67] op_sel_hi:[1,0]
	v_pk_mul_f32 v[14:15], v[14:15], v[66:67] op_sel_hi:[1,0]
	v_pk_mul_f32 v[12:13], v[12:13], v[66:67] op_sel_hi:[1,0]
	v_pk_mul_f32 v[10:11], v[10:11], v[66:67] op_sel_hi:[1,0]
	v_pk_mul_f32 v[8:9], v[8:9], v[66:67] op_sel_hi:[1,0]
	v_pk_mul_f32 v[6:7], v[6:7], v[66:67] op_sel_hi:[1,0]
	v_pk_mul_f32 v[4:5], v[4:5], v[66:67] op_sel_hi:[1,0]
	v_pk_mul_f32 v[2:3], v[2:3], v[66:67] op_sel_hi:[1,0]
	v_pk_mul_f32 v[0:1], v[0:1], v[66:67] op_sel_hi:[1,0]

.LBB0_183:
	s_andn2_b64 vcc, exec, s[0:1]
	s_cbranch_vccnz .LBB0_223
	s_lshl_b32 s0, s13, 5
	s_add_i32 s1, s14, 0xfffffc00
	s_and_b32 s19, s0, 0xfffff000
	s_bfe_u32 s0, s14, 0x50001
	v_readfirstlane_b32 s8, v149
	s_lshr_b32 s7, s1, 7
	s_lshl_b32 s22, s0, 7
	s_lshr_b32 s6, s8, 1
	s_lshl_b32 s9, s7, 12
	s_and_b32 s6, s6, 0x60
	s_or_b32 s18, s22, s9
	s_cmp_eq_u32 s0, 0
	s_cselect_b32 s11, 6, 4
	s_cmp_eq_u32 s0, 31
	s_waitcnt vmcnt(0)
	v_and_b32_e32 v12, 31, v149
	s_cselect_b32 s37, 8, 10
	s_bfe_u32 s9, s14, 0x10006
	s_lshl_b32 s1, s1, 1
	v_or_b32_e32 v14, s6, v12
	s_lshl_b32 s0, s9, 2
	s_and_b32 s1, s1, 2
	v_or_b32_e32 v98, s18, v14
	s_ashr_i32 s6, s8, 8
	s_or_b32 s0, s0, s1
	v_mov_b64_e32 v[4:5], s[90:91]
	s_lshl_b32 s25, s7, 8
	s_add_i32 s0, s0, s6
	s_waitcnt lgkmcnt(0)
	v_mad_u64_u32 v[0:1], s[6:7], v98, s85, v[4:5]
	s_lshl_b32 s6, s0, 6
	s_ashr_i32 s1, s0, 31
	v_bfe_u32 v13, v149, 5, 1
	s_sub_i32 s10, s37, s11
	s_ashr_i32 s7, s6, 31
	s_lshl_b64 s[0:1], s[0:1], 2
	v_readlane_b32 s12, v255, 52
	v_lshl_add_u64 v[0:1], s[6:7], 1, v[0:1]
	v_lshlrev_b32_e32 v6, 4, v13
	v_mov_b32_e32 v7, v99
	s_add_u32 s0, s12, s0
	v_readlane_b32 s12, v255, 54
	v_lshl_add_u64 v[0:1], v[0:1], 0, v[6:7]
	s_addc_u32 s1, s12, s1
	s_waitcnt vmcnt(0)
	v_ashrrev_i32_e32 v119, 3, v149
	s_or_b32 s16, s25, 0x8000
	global_load_dwordx4 v[66:69], v[0:1], off
	global_load_dwordx4 v[70:73], v[0:1], off offset:32
	global_load_dwordx4 v[74:77], v[0:1], off offset:64
	global_load_dwordx4 v[78:81], v[0:1], off offset:96
	v_add_u32_e32 v0, s16, v119
	global_load_dword v7, v99, s[0:1]
	v_and_b32_e32 v15, 7, v149
	v_mad_i64_i32 v[0:1], s[0:1], v0, s85, v[4:5]
	s_lshl_b32 s68, s9, 7
	v_lshl_add_u64 v[0:1], v[0:1], 0, s[68:69]
	v_lshlrev_b32_e32 v8, 4, v15
	v_mov_b32_e32 v9, v99
	v_lshl_add_u64 v[10:11], v[0:1], 0, v[8:9]
	v_add_u32_e32 v16, s25, v119
	global_load_dwordx4 v[0:3], v[10:11], off offset:1024
	v_add_u32_e32 v17, 0x8040, v16
	v_mad_i64_i32 v[4:5], s[0:1], v17, s85, v[4:5]
	v_lshl_add_u64 v[4:5], v[4:5], 0, s[68:69]
	v_lshl_add_u64 v[100:101], v[4:5], 0, v[8:9]
	s_barrier
	global_load_dwordx4 v[82:85], v[100:101], off offset:1024
	global_load_dwordx4 v[86:89], v[10:11], off offset:1280
	s_movk_i32 s12, 0x90
	v_mul_lo_u32 v11, v119, s12
	v_add3_u32 v120, 0, v11, v8
	v_lshrrev_b32_e32 v5, 2, v149
	v_and_b32_e32 v9, 16, v149
	v_lshlrev_b32_e32 v10, 2, v149
	v_lshlrev_b32_e32 v148, 2, v13
	v_and_b32_e32 v4, 63, v149
	v_and_or_b32 v9, v10, 12, v9
	v_mul_u32_u24_e32 v10, 0x90, v12
	v_and_or_b32 v5, v5, 3, v148
	s_lshl_b32 s36, s9, 6
	v_cmp_gt_u32_e32 vcc, 32, v4
	v_lshlrev_b32_e32 v4, 3, v15
	v_lshlrev_b32_e32 v8, 1, v9
	v_add3_u32 v121, 0, v6, v10
	v_or_b32_e32 v6, 0xffffff00, v148
	v_mul_u32_u24_e32 v5, 0x90, v5
	s_add_i32 s17, s10, 4
	s_addk_i32 s18, 0xfe80
	s_or_b32 s27, s36, 0x200
	s_or_b32 s26, s36, 0x280
	s_mov_b64 s[0:1], -1
	v_cndmask_b32_e64 v110, 0, 1.0, vcc
	v_add3_u32 v118, v8, v5, 0
	s_cmpk_lt_u32 s8, 0x100
	v_add_u32_e32 v111, 0x8080, v16
	v_sub_u32_e32 v122, v6, v14
	v_lshlrev_b32_e32 v116, 1, v4
	s_movk_i32 s20, 0x101
	s_mov_b32 s21, 0xf149f2ca
	s_movk_i32 s23, 0xfeff
	s_waitcnt vmcnt(3)
	v_mul_f32_e32 v103, 0x3fb8aa3b, v7
	v_xor_b32_e32 v32, 0x80000000, v103
	s_waitcnt vmcnt(2)
	ds_write_b128 v120, v[0:3]
	s_waitcnt lgkmcnt(0)
	s_barrier
	s_cbranch_scc1 .LBB0_203
	ds_read_b128 v[0:3], v121 offset:4672
	ds_read_b128 v[4:7], v121 offset:4640
	ds_read_b128 v[8:11], v121
	ds_read_b128 v[12:15], v121 offset:32
	ds_read_b128 v[50:53], v121 offset:64
	ds_read_b128 v[54:57], v121 offset:4608
	s_add_i32 s15, s11, -5
	v_mov_b32_e32 v33, v32
	v_mov_b32_e32 v34, v32
	v_mov_b32_e32 v35, v32
	v_mov_b32_e32 v36, v32
	v_mov_b32_e32 v37, v32
	v_mov_b32_e32 v38, v32
	v_mov_b32_e32 v39, v32
	v_mov_b32_e32 v40, v32
	v_mov_b32_e32 v41, v32
	v_mov_b32_e32 v42, v32
	v_mov_b32_e32 v43, v32
	v_mov_b32_e32 v44, v32
	v_mov_b32_e32 v45, v32
	v_mov_b32_e32 v46, v32
	v_mov_b32_e32 v47, v32
	s_waitcnt lgkmcnt(3)
	s_nop 0
	v_mfma_f32_32x32x16_bf16 v[16:31], v[8:11], v[66:69], v[32:47]
	v_mov_b64_e32 v[48:49], v[46:47]
	s_nop 5
	v_mov_b64_e32 v[46:47], v[44:45]
	v_mov_b64_e32 v[44:45], v[42:43]
	v_mov_b64_e32 v[42:43], v[40:41]
	v_mov_b64_e32 v[40:41], v[38:39]
	v_mov_b64_e32 v[38:39], v[36:37]
	v_mov_b64_e32 v[36:37], v[34:35]
	v_mov_b64_e32 v[34:35], v[32:33]
	s_waitcnt lgkmcnt(0)
	s_nop 0
	v_mfma_f32_32x32x16_bf16 v[34:49], v[54:57], v[66:69], v[34:49]
	ds_read_b128 v[8:11], v121 offset:96
	ds_read_b128 v[54:57], v121 offset:4704
	v_mfma_f32_32x32x16_bf16 v[16:31], v[12:15], v[70:73], v[16:31]
	v_mfma_f32_32x32x16_bf16 v[34:49], v[4:7], v[70:73], v[34:49]
	v_mfma_f32_32x32x16_bf16 v[16:31], v[50:53], v[74:77], v[16:31]
	v_mfma_f32_32x32x16_bf16 v[34:49], v[0:3], v[74:77], v[34:49]
	s_waitcnt lgkmcnt(1)
	v_mfma_f32_32x32x16_bf16 v[16:31], v[8:11], v[78:81], v[16:31]
	s_waitcnt lgkmcnt(0)
	v_mfma_f32_32x32x16_bf16 v[34:49], v[54:57], v[78:81], v[34:49]
	v_mov_b64_e32 v[106:107], s[90:91]
	v_mad_i64_i32 v[0:1], s[0:1], v111, s85, v[106:107]
	s_lshl_b32 s68, s36, 1
	v_lshl_add_u64 v[0:1], v[0:1], 0, s[68:69]
	v_mov_b32_e32 v117, v99
	s_waitcnt vmcnt(1)
	ds_write_b128 v120, v[82:85] offset:13312
	s_waitcnt vmcnt(0)
	ds_write_b128 v120, v[86:89] offset:26624
	v_lshl_add_u64 v[0:1], v[0:1], 0, v[116:117]
	global_load_dwordx4 v[90:93], v[0:1], off offset:1024
	global_load_dwordx4 v[94:97], v[100:101], off offset:1280
	v_max3_f32 v2, v16, v17, v34
	v_max3_f32 v3, v18, v19, v35
	v_cmp_lt_i32_e32 vcc, v232, v226
	v_max3_f32 v2, v2, v36, v37
	v_max3_f32 v3, v3, v22, v23
	s_waitcnt lgkmcnt(0)
	s_barrier
	s_mov_b32 s12, 2
	v_max3_f32 v2, v2, v20, v21
	v_max3_f32 v3, v3, v40, v41
	s_nop 0
	v_max3_f32 v2, v2, v38, v39
	v_max3_f32 v3, v3, v26, v27
	s_nop 0
	v_max3_f32 v2, v2, v24, v25
	v_max3_f32 v3, v3, v44, v45
	s_nop 0
	v_max3_f32 v2, v2, v42, v43
	v_max3_f32 v3, v3, v30, v31
	s_nop 0
	v_max3_f32 v2, v2, v28, v29
	v_max3_f32 v3, v3, v48, v49
	s_nop 0
	v_max3_f32 v2, v2, v46, v47
	s_nop 0
	v_max3_f32 v2, v2, v3, v3
	v_cndmask_b32_e32 v3, v225, v232, vcc
	v_lshlrev_b32_e32 v123, 2, v3
	v_mov_b32_e32 v3, v2
	s_nop 1
	v_permlane32_swap_b32 v3, v2
	v_max_f32_e32 v2, v2, v3
	s_waitcnt lgkmcnt(0)
	s_nop 0
	v_max_f32_e32 v2, v2, v2
	v_max_f32_e32 v33, 0, v2
	v_sub_f32_e32 v34, v34, v33
	v_sub_f32_e32 v16, v16, v33
	v_sub_f32_e32 v15, v49, v33
	v_sub_f32_e32 v49, v31, v33
	v_sub_f32_e32 v31, v47, v33
	v_sub_f32_e32 v47, v29, v33
	v_sub_f32_e32 v29, v45, v33
	v_sub_f32_e32 v45, v27, v33
	v_sub_f32_e32 v27, v43, v33
	v_sub_f32_e32 v43, v25, v33
	v_sub_f32_e32 v25, v41, v33
	v_sub_f32_e32 v41, v23, v33
	v_sub_f32_e32 v23, v39, v33
	v_sub_f32_e32 v39, v21, v33
	v_sub_f32_e32 v21, v37, v33
	v_sub_f32_e32 v37, v19, v33
	v_sub_f32_e32 v19, v35, v33
	v_sub_f32_e32 v17, v17, v33
	v_exp_f32_e32 v52, v16
	v_exp_f32_e32 v53, v34
	v_exp_f32_e32 v16, v17
	v_exp_f32_e32 v34, v19
	v_mov_b32_e32 v17, v99
	v_add_f32_e32 v35, v53, v52
	v_sub_f32_e32 v36, v36, v33
	v_sub_f32_e32 v51, v18, v33
	v_pk_add_f32 v[18:19], v[34:35], v[16:17]
	v_exp_f32_e32 v17, v51
	v_pk_add_f32 v[18:19], v[18:19], v[18:19] op_sel_hi:[0,1]
	v_exp_f32_e32 v35, v36
	v_exp_f32_e32 v18, v37
	v_exp_f32_e32 v36, v21
	v_sub_f32_e32 v38, v38, v33
	v_add_f32_e32 v37, v35, v17
	v_sub_f32_e32 v51, v20, v33
	v_pk_add_f32 v[20:21], v[36:37], v[18:19]
	v_exp_f32_e32 v19, v51
	v_pk_add_f32 v[20:21], v[20:21], v[20:21] op_sel_hi:[0,1]
	v_exp_f32_e32 v37, v38
	v_exp_f32_e32 v20, v39
	v_exp_f32_e32 v38, v23
	v_sub_f32_e32 v40, v40, v33
	v_add_f32_e32 v39, v37, v19
	v_sub_f32_e32 v51, v22, v33
	v_pk_add_f32 v[22:23], v[38:39], v[20:21]
	v_exp_f32_e32 v21, v51
	v_pk_add_f32 v[22:23], v[22:23], v[22:23] op_sel_hi:[0,1]
	v_exp_f32_e32 v39, v40
	v_exp_f32_e32 v22, v41
	v_exp_f32_e32 v40, v25
	v_sub_f32_e32 v42, v42, v33
	v_add_f32_e32 v41, v39, v21
	v_sub_f32_e32 v51, v24, v33
	v_pk_add_f32 v[24:25], v[40:41], v[22:23]
	v_exp_f32_e32 v23, v51
	v_pk_add_f32 v[24:25], v[24:25], v[24:25] op_sel_hi:[0,1]
	v_exp_f32_e32 v41, v42
	v_exp_f32_e32 v24, v43
	v_exp_f32_e32 v42, v27
	v_sub_f32_e32 v44, v44, v33
	v_add_f32_e32 v43, v41, v23
	v_sub_f32_e32 v51, v26, v33
	v_pk_add_f32 v[26:27], v[42:43], v[24:25]
	v_exp_f32_e32 v25, v51
	v_pk_add_f32 v[26:27], v[26:27], v[26:27] op_sel_hi:[0,1]
	v_exp_f32_e32 v43, v44
	v_exp_f32_e32 v26, v45
	v_exp_f32_e32 v44, v29
	v_sub_f32_e32 v46, v46, v33
	v_add_f32_e32 v45, v43, v25
	v_sub_f32_e32 v51, v28, v33
	v_pk_add_f32 v[28:29], v[44:45], v[26:27]
	v_exp_f32_e32 v27, v51
	v_pk_add_f32 v[28:29], v[28:29], v[28:29] op_sel_hi:[0,1]
	v_exp_f32_e32 v45, v46
	v_exp_f32_e32 v28, v47
	v_exp_f32_e32 v46, v31
	v_sub_f32_e32 v48, v48, v33
	v_add_f32_e32 v47, v45, v27
	v_sub_f32_e32 v51, v30, v33
	v_pk_add_f32 v[30:31], v[46:47], v[28:29]
	v_exp_f32_e32 v29, v51
	v_pk_add_f32 v[30:31], v[30:31], v[30:31] op_sel_hi:[0,1]
	v_exp_f32_e32 v47, v48
	v_exp_f32_e64 v50, -v33
	v_exp_f32_e32 v30, v49
	v_exp_f32_e32 v48, v15
	v_add_f32_e32 v49, v47, v29
	v_mul_f32_e32 v0, 0, v50
	v_mul_f32_e32 v102, v110, v50
	v_pk_add_f32 v[50:51], v[48:49], v[30:31]
	v_cvt_pk_bf16_f32 v112, v52, v16
	v_cvt_pk_bf16_f32 v113, v17, v18
	v_cvt_pk_bf16_f32 v114, v19, v20
	v_cvt_pk_bf16_f32 v115, v21, v22
	v_cvt_pk_bf16_f32 v124, v23, v24
	v_cvt_pk_bf16_f32 v125, v25, v26
	v_cvt_pk_bf16_f32 v126, v27, v28
	v_cvt_pk_bf16_f32 v127, v29, v30
	ds_read_b128 v[16:19], v121 offset:13312
	ds_read_b128 v[20:23], v121 offset:13344
	ds_read_b128 v[24:27], v121 offset:17920
	ds_read_b128 v[28:31], v121 offset:13376
	ds_read_b128 v[136:139], v121 offset:17952
	ds_read_b128 v[140:143], v121 offset:17984
	v_pk_add_f32 v[50:51], v[50:51], v[50:51] op_sel:[0,1] op_sel_hi:[1,0]
	v_cvt_pk_bf16_f32 v128, v53, v34
	v_mov_b32_e32 v51, v33
	v_pk_add_f32 v[104:105], v[102:103], v[50:51]
	v_mov_b32_e32 v1, v0
	v_xor_b32_e32 v34, 0x80000000, v105
	v_mov_b32_e32 v2, v0
	v_mov_b32_e32 v3, v0
	v_mov_b32_e32 v4, v0
	v_mov_b32_e32 v5, v0
	v_mov_b32_e32 v6, v0
	v_mov_b32_e32 v7, v0
	v_mov_b32_e32 v8, v0
	v_mov_b32_e32 v9, v0
	v_mov_b32_e32 v10, v0
	v_mov_b32_e32 v11, v0
	v_mov_b32_e32 v12, v0
	v_mov_b32_e32 v13, v0
	v_mov_b32_e32 v14, v0
	v_mov_b32_e32 v15, v0
	v_cvt_pk_bf16_f32 v129, v35, v36
	v_cvt_pk_bf16_f32 v130, v37, v38
	v_cvt_pk_bf16_f32 v131, v39, v40
	v_cvt_pk_bf16_f32 v132, v41, v42
	v_cvt_pk_bf16_f32 v133, v43, v44
	v_cvt_pk_bf16_f32 v134, v45, v46
	v_cvt_pk_bf16_f32 v135, v47, v48
	v_mov_b32_e32 v35, v34
	v_mov_b32_e32 v36, v34
	v_mov_b32_e32 v37, v34
	v_mov_b32_e32 v38, v34
	v_mov_b32_e32 v39, v34
	v_mov_b32_e32 v40, v34
	v_mov_b32_e32 v41, v34
	v_mov_b32_e32 v42, v34
	v_mov_b32_e32 v43, v34
	v_mov_b32_e32 v44, v34
	v_mov_b32_e32 v45, v34
	v_mov_b32_e32 v46, v34
	v_mov_b32_e32 v47, v34
	v_mov_b32_e32 v48, v34
	v_mov_b32_e32 v49, v34
	s_waitcnt lgkmcnt(5)
	s_nop 0
	v_mfma_f32_32x32x16_bf16 v[50:65], v[16:19], v[66:69], v[34:49]
	s_waitcnt lgkmcnt(3)
	v_mfma_f32_32x32x16_bf16 v[34:49], v[24:27], v[66:69], v[34:49]
	ds_read_b128 v[16:19], v121 offset:13408
	ds_read_b128 v[24:27], v121 offset:18016
	v_mfma_f32_32x32x16_bf16 v[50:65], v[20:23], v[70:73], v[50:65]
	s_waitcnt lgkmcnt(3)
	v_mfma_f32_32x32x16_bf16 v[34:49], v[136:139], v[70:73], v[34:49]
	ds_read_b64_tr_b16 v[136:137], v118 offset:26624
	ds_read_b64_tr_b16 v[138:139], v118 offset:27776
	ds_read_b64_tr_b16 v[146:147], v118 offset:27840
	ds_read_b64_tr_b16 v[144:145], v118 offset:26688
	v_mfma_f32_32x32x16_bf16 v[50:65], v[28:31], v[74:77], v[50:65]
	s_waitcnt lgkmcnt(6)
	v_mfma_f32_32x32x16_bf16 v[34:49], v[140:143], v[74:77], v[34:49]
	ds_read_b64_tr_b16 v[140:141], v118 offset:28928
	ds_read_b64_tr_b16 v[142:143], v118 offset:30080
	ds_read_b64_tr_b16 v[152:153], v118 offset:30144
	ds_read_b64_tr_b16 v[150:151], v118 offset:28992
	s_waitcnt lgkmcnt(9)
	v_mfma_f32_32x32x16_bf16 v[50:65], v[16:19], v[78:81], v[50:65]
	s_waitcnt lgkmcnt(8)
	v_mfma_f32_32x32x16_bf16 v[34:49], v[24:27], v[78:81], v[34:49]
	ds_read_b64_tr_b16 v[154:155], v118 offset:31232
	ds_read_b64_tr_b16 v[156:157], v118 offset:32384
	ds_read_b64_tr_b16 v[160:161], v118 offset:32448
	ds_read_b64_tr_b16 v[158:159], v118 offset:31296
	s_waitcnt lgkmcnt(10)
	v_mfma_f32_32x32x16_bf16 v[16:31], v[136:139], v[112:115], v[0:15]
	s_waitcnt lgkmcnt(8)
	v_mfma_f32_32x32x16_bf16 v[0:15], v[144:147], v[112:115], v[0:15]
	ds_read_b64_tr_b16 v[112:113], v118 offset:33536
	ds_read_b64_tr_b16 v[114:115], v118 offset:34688
	ds_read_b64_tr_b16 v[138:139], v118 offset:34752
	ds_read_b64_tr_b16 v[136:137], v118 offset:33600
	s_waitcnt lgkmcnt(10)
	v_mfma_f32_32x32x16_bf16 v[16:31], v[140:143], v[124:127], v[16:31]
	s_waitcnt lgkmcnt(8)
	v_mfma_f32_32x32x16_bf16 v[0:15], v[150:153], v[124:127], v[0:15]
	s_waitcnt lgkmcnt(6)
	v_mfma_f32_32x32x16_bf16 v[16:31], v[154:157], v[128:131], v[16:31]
	s_waitcnt lgkmcnt(4)
	v_mfma_f32_32x32x16_bf16 v[0:15], v[158:161], v[128:131], v[0:15]
	s_waitcnt lgkmcnt(2)
	v_mfma_f32_32x32x16_bf16 v[16:31], v[112:115], v[132:135], v[16:31]
	s_waitcnt lgkmcnt(0)
	v_mfma_f32_32x32x16_bf16 v[0:15], v[136:139], v[132:135], v[0:15]
	s_or_b32 s0, s25, 0x80c0
	v_add_u32_e32 v33, s0, v119
	s_waitcnt vmcnt(1)
	ds_write_b128 v120, v[90:93]
	s_waitcnt vmcnt(0)
	ds_write_b128 v120, v[94:97] offset:35840
	v_mad_i64_i32 v[90:91], s[0:1], v33, s85, v[106:107]
	s_or_b32 s0, s25, 0x8080
	s_nop 0
	v_add_u32_e32 v33, s0, v119
	v_mad_i64_i32 v[94:95], s[0:1], v33, s85, v[106:107]
	v_lshl_add_u64 v[90:91], v[90:91], 0, s[68:69]
	v_lshl_add_u64 v[94:95], v[94:95], 0, s[68:69]
	v_lshl_add_u64 v[90:91], v[90:91], 0, v[116:117]
	v_lshl_add_u64 v[94:95], v[94:95], 0, v[116:117]
	global_load_dwordx4 v[90:93], v[90:91], off offset:1024
	s_lshl_b32 s0, s11, 6
	global_load_dwordx4 v[94:97], v[94:95], off offset:1280
	s_add_i32 s0, s0, s22
	s_waitcnt lgkmcnt(0)
	s_barrier
	v_lshl_add_u64 v[108:109], s[90:91], 0, v[116:117]
	s_lshl_b32 s68, s27, 1
	s_add_i32 s0, s0, s19
	v_lshl_add_u64 v[106:107], v[108:109], 0, s[68:69]
	s_lshl_b32 s68, s26, 1
	v_add_u32_e32 v33, s0, v119
	s_add_i32 s24, s10, 2
	v_lshl_add_u64 v[108:109], v[108:109], 0, s[68:69]
	v_add_u32_e32 v33, 0xfffffe80, v33

.LBB0_190:
	v_max3_f32 v102, v50, v51, v34
	v_max3_f32 v112, v52, v53, v35
	s_nop 0
	v_max3_f32 v102, v102, v36, v37
	v_max3_f32 v112, v112, v56, v57
	s_nop 0
	v_max3_f32 v102, v102, v54, v55
	v_max3_f32 v112, v112, v40, v41
	s_nop 0
	v_max3_f32 v102, v102, v38, v39
	v_max3_f32 v112, v112, v60, v61
	s_nop 0
	v_max3_f32 v102, v102, v58, v59
	v_max3_f32 v112, v112, v44, v45
	s_nop 0
	v_max3_f32 v102, v102, v42, v43
	v_max3_f32 v112, v112, v64, v65
	s_nop 0
	v_max3_f32 v102, v102, v62, v63
	v_max3_f32 v112, v112, v48, v49
	s_nop 0
	v_max3_f32 v102, v102, v46, v47
	s_nop 0
	v_max3_f32 v102, v102, v112, v112
	v_mov_b32_e32 v112, v102
	s_nop 1
	v_permlane32_swap_b32 v112, v102
	v_max_f32_e32 v102, v102, v112
	s_waitcnt lgkmcnt(0)
	s_nop 0
	v_cmp_lt_f32_e32 vcc, s78, v102
	s_cbranch_vccz .LBB0_192
	v_max_f32_e32 v102, v102, v102
	v_max_f32_e32 v113, 0, v102
	v_exp_f32_e64 v112, -v113
	v_mov_b32_e32 v102, v113
	v_pk_add_f32 v[50:51], v[50:51], v[102:103] op_sel_hi:[1,0] neg_lo:[0,1] neg_hi:[0,1]
	v_pk_add_f32 v[34:35], v[34:35], v[102:103] op_sel_hi:[1,0] neg_lo:[0,1] neg_hi:[0,1]
	v_pk_add_f32 v[114:115], v[104:105], v[112:113]
	v_pk_mul_f32 v[104:105], v[104:105], v[112:113]
	v_pk_add_f32 v[52:53], v[52:53], v[102:103] op_sel_hi:[1,0] neg_lo:[0,1] neg_hi:[0,1]
	v_mov_b32_e32 v105, v115
	v_pk_add_f32 v[36:37], v[36:37], v[102:103] op_sel_hi:[1,0] neg_lo:[0,1] neg_hi:[0,1]
	v_pk_add_f32 v[54:55], v[54:55], v[102:103] op_sel_hi:[1,0] neg_lo:[0,1] neg_hi:[0,1]
	v_pk_add_f32 v[38:39], v[38:39], v[102:103] op_sel_hi:[1,0] neg_lo:[0,1] neg_hi:[0,1]
	v_pk_add_f32 v[56:57], v[56:57], v[102:103] op_sel_hi:[1,0] neg_lo:[0,1] neg_hi:[0,1]
	v_pk_add_f32 v[40:41], v[40:41], v[102:103] op_sel_hi:[1,0] neg_lo:[0,1] neg_hi:[0,1]
	v_pk_add_f32 v[58:59], v[58:59], v[102:103] op_sel_hi:[1,0] neg_lo:[0,1] neg_hi:[0,1]
	v_pk_add_f32 v[42:43], v[42:43], v[102:103] op_sel_hi:[1,0] neg_lo:[0,1] neg_hi:[0,1]
	v_pk_add_f32 v[60:61], v[60:61], v[102:103] op_sel_hi:[1,0] neg_lo:[0,1] neg_hi:[0,1]
	v_pk_add_f32 v[44:45], v[44:45], v[102:103] op_sel_hi:[1,0] neg_lo:[0,1] neg_hi:[0,1]
	v_pk_add_f32 v[62:63], v[62:63], v[102:103] op_sel_hi:[1,0] neg_lo:[0,1] neg_hi:[0,1]
	v_pk_add_f32 v[46:47], v[46:47], v[102:103] op_sel_hi:[1,0] neg_lo:[0,1] neg_hi:[0,1]
	v_pk_add_f32 v[64:65], v[64:65], v[102:103] op_sel_hi:[1,0] neg_lo:[0,1] neg_hi:[0,1]
	v_pk_add_f32 v[48:49], v[48:49], v[102:103] op_sel_hi:[1,0] neg_lo:[0,1] neg_hi:[0,1]
	v_pk_mul_f32 v[30:31], v[30:31], v[112:113] op_sel_hi:[1,0]
	v_pk_mul_f32 v[28:29], v[28:29], v[112:113] op_sel_hi:[1,0]
	v_pk_mul_f32 v[26:27], v[26:27], v[112:113] op_sel_hi:[1,0]
	v_pk_mul_f32 v[24:25], v[24:25], v[112:113] op_sel_hi:[1,0]
	v_pk_mul_f32 v[22:23], v[22:23], v[112:113] op_sel_hi:[1,0]
	v_pk_mul_f32 v[20:21], v[20:21], v[112:113] op_sel_hi:[1,0]
	v_pk_mul_f32 v[18:19], v[18:19], v[112:113] op_sel_hi:[1,0]
	v_pk_mul_f32 v[16:17], v[16:17], v[112:113] op_sel_hi:[1,0]
	v_pk_mul_f32 v[14:15], v[14:15], v[112:113] op_sel_hi:[1,0]
	v_pk_mul_f32 v[12:13], v[12:13], v[112:113] op_sel_hi:[1,0]
	v_pk_mul_f32 v[10:11], v[10:11], v[112:113] op_sel_hi:[1,0]
	v_pk_mul_f32 v[8:9], v[8:9], v[112:113] op_sel_hi:[1,0]
	v_pk_mul_f32 v[6:7], v[6:7], v[112:113] op_sel_hi:[1,0]
	v_pk_mul_f32 v[4:5], v[4:5], v[112:113] op_sel_hi:[1,0]
	v_pk_mul_f32 v[2:3], v[2:3], v[112:113] op_sel_hi:[1,0]
	v_pk_mul_f32 v[0:1], v[0:1], v[112:113] op_sel_hi:[1,0]

.LBB0_200:
	s_lshl_b32 s0, s37, 6
	s_sub_i32 s0, s0, 64
	v_add_u32_e32 v33, s0, v122
	v_cmp_gt_u32_e32 vcc, s20, v33
	s_waitcnt vmcnt(0)
	s_nop 0
	v_cndmask_b32_e32 v92, v233, v50, vcc
	v_add_u32_e32 v50, 0xffffff1f, v33
	v_cmp_lt_u32_e32 vcc, s4, v50
	s_nop 1
	v_cndmask_b32_e32 v108, v233, v34, vcc
	v_add_u32_e32 v34, 0xffffff00, v33
	v_cmp_lt_u32_e32 vcc, s4, v34
	v_add_u32_e32 v34, 0xffffff20, v33
	s_nop 0
	v_cndmask_b32_e32 v93, v233, v51, vcc
	v_cmp_lt_u32_e32 vcc, s4, v34
	v_add_u32_e32 v34, 0xffffff01, v33
	s_nop 0
	v_cndmask_b32_e32 v109, v233, v35, vcc
	v_cmp_lt_u32_e32 vcc, s4, v34
	v_add_u32_e32 v34, 0xffffff21, v33
	v_add_u32_e32 v35, 0xffffff39, v33
	v_cndmask_b32_e32 v90, v233, v52, vcc
	v_cmp_lt_u32_e32 vcc, s4, v34
	v_add_u32_e32 v34, 0xffffff02, v33
	s_nop 0
	v_cndmask_b32_e32 v106, v233, v36, vcc
	v_cmp_lt_u32_e32 vcc, s4, v34
	v_add_u32_e32 v34, 0xffffff22, v33
	s_nop 0
	v_cndmask_b32_e32 v91, v233, v53, vcc
	v_cmp_lt_u32_e32 vcc, s4, v34
	v_add_u32_e32 v34, 0xffffff07, v33
	s_nop 0
	v_cndmask_b32_e32 v107, v233, v37, vcc
	v_cmp_lt_u32_e32 vcc, s4, v34
	v_add_u32_e32 v34, 0xffffff27, v33
	s_nop 0
	v_cndmask_b32_e32 v52, v233, v54, vcc
	v_cmp_lt_u32_e32 vcc, s4, v34
	v_add_u32_e32 v34, 0xffffff08, v33
	s_nop 0
	v_cndmask_b32_e32 v96, v233, v38, vcc
	v_cmp_lt_u32_e32 vcc, s4, v34
	v_add_u32_e32 v34, 0xffffff28, v33
	s_nop 0
	v_cndmask_b32_e32 v53, v233, v55, vcc
	v_cmp_lt_u32_e32 vcc, s4, v34
	v_add_u32_e32 v34, 0xffffff09, v33
	s_nop 0
	v_cndmask_b32_e32 v97, v233, v39, vcc
	v_cmp_lt_u32_e32 vcc, s4, v34
	v_add_u32_e32 v34, 0xffffff29, v33
	s_nop 0
	v_cndmask_b32_e32 v50, v233, v56, vcc
	v_cmp_lt_u32_e32 vcc, s4, v34
	v_add_u32_e32 v34, 0xffffff0a, v33
	s_nop 0
	v_cndmask_b32_e32 v94, v233, v40, vcc
	v_cmp_lt_u32_e32 vcc, s4, v34
	v_add_u32_e32 v34, 0xffffff2a, v33
	s_nop 0
	v_cndmask_b32_e32 v51, v233, v57, vcc
	v_cmp_lt_u32_e32 vcc, s4, v34
	v_add_u32_e32 v34, 0xffffff0f, v33
	s_nop 0
	v_cndmask_b32_e32 v95, v233, v41, vcc
	v_cmp_lt_u32_e32 vcc, s4, v34
	v_add_u32_e32 v34, 0xffffff2f, v33
	s_nop 0
	v_cndmask_b32_e32 v40, v233, v58, vcc
	v_cmp_lt_u32_e32 vcc, s4, v34
	v_add_u32_e32 v34, 0xffffff10, v33
	s_nop 0
	v_cndmask_b32_e32 v56, v233, v42, vcc
	v_cmp_lt_u32_e32 vcc, s4, v34
	v_add_u32_e32 v34, 0xffffff30, v33
	s_nop 0
	v_cndmask_b32_e32 v41, v233, v59, vcc
	v_cmp_lt_u32_e32 vcc, s4, v34
	v_add_u32_e32 v34, 0xffffff11, v33
	s_nop 0
	v_cndmask_b32_e32 v57, v233, v43, vcc
	v_cmp_lt_u32_e32 vcc, s4, v34
	v_add_u32_e32 v34, 0xffffff31, v33
	s_nop 0
	v_cndmask_b32_e32 v38, v233, v60, vcc
	v_cmp_lt_u32_e32 vcc, s4, v34
	v_add_u32_e32 v34, 0xffffff12, v33
	s_nop 0
	v_cndmask_b32_e32 v54, v233, v44, vcc
	v_cmp_lt_u32_e32 vcc, s4, v34
	v_add_u32_e32 v34, 0xffffff32, v33
	s_nop 0
	v_cndmask_b32_e32 v39, v233, v61, vcc
	v_cmp_lt_u32_e32 vcc, s4, v34
	v_add_u32_e32 v34, 0xffffff17, v33
	s_nop 0
	v_cndmask_b32_e32 v55, v233, v45, vcc
	v_cmp_lt_u32_e32 vcc, s4, v34
	v_add_u32_e32 v34, 0xffffff37, v33
	s_nop 0
	v_cndmask_b32_e32 v36, v233, v62, vcc
	v_cmp_lt_u32_e32 vcc, s4, v34
	v_add_u32_e32 v34, 0xffffff18, v33
	s_nop 0
	v_cndmask_b32_e32 v44, v233, v46, vcc
	v_cmp_lt_u32_e32 vcc, s4, v34
	v_add_u32_e32 v34, 0xffffff38, v33
	v_max3_f32 v46, v90, v91, v109
	s_nop 0
	v_cndmask_b32_e32 v37, v233, v63, vcc
	v_cmp_lt_u32_e32 vcc, s4, v34
	v_add_u32_e32 v34, 0xffffff19, v33
	v_max3_f32 v46, v46, v50, v51
	s_nop 0
	v_cndmask_b32_e32 v45, v233, v47, vcc
	v_cmp_lt_u32_e32 vcc, s4, v34
	v_max3_f32 v46, v46, v94, v95
	s_nop 0
	v_max3_f32 v46, v46, v38, v39
	s_nop 0
	v_cndmask_b32_e32 v34, v233, v64, vcc
	v_cmp_lt_u32_e32 vcc, s4, v35
	v_add_u32_e32 v35, 0xffffff1a, v33
	v_add_u32_e32 v33, 0xffffff3a, v33
	v_cndmask_b32_e32 v42, v233, v48, vcc
	v_cmp_lt_u32_e32 vcc, s4, v35
	v_max3_f32 v46, v46, v54, v55
	s_nop 1
	v_cndmask_b32_e32 v35, v233, v65, vcc
	v_cmp_lt_u32_e32 vcc, s4, v33
	v_max3_f32 v33, v92, v93, v108
	v_max3_f32 v46, v46, v34, v35
	s_nop 0
	v_max3_f32 v33, v33, v106, v107
	s_nop 0
	v_max3_f32 v33, v33, v52, v53
	v_cndmask_b32_e32 v43, v233, v49, vcc
	v_max3_f32 v33, v33, v96, v97
	v_max3_f32 v46, v46, v42, v43
	s_nop 0
	v_max3_f32 v33, v33, v40, v41
	s_nop 0
	v_max3_f32 v33, v33, v56, v57
	s_nop 0
	v_max3_f32 v33, v33, v36, v37
	s_nop 0
	v_max3_f32 v33, v33, v44, v45
	s_nop 0
	v_max3_f32 v33, v33, v46, v46
	v_mov_b32_e32 v46, v33
	s_nop 1
	v_permlane32_swap_b32 v46, v33
	v_max_f32_e32 v33, v33, v46
	s_waitcnt lgkmcnt(0)
	s_nop 0
	v_cmp_lt_f32_e32 vcc, s78, v33
	s_cbranch_vccz .LBB0_202
	v_max_f32_e32 v33, v33, v33
	v_max_f32_e32 v46, 0, v33
	v_exp_f32_e64 v48, -v46
	v_pk_add_f32 v[92:93], v[92:93], v[46:47] op_sel_hi:[1,0] neg_lo:[0,1] neg_hi:[0,1]
	v_pk_add_f32 v[108:109], v[108:109], v[46:47] op_sel_hi:[1,0] neg_lo:[0,1] neg_hi:[0,1]
	v_pk_add_f32 v[90:91], v[90:91], v[46:47] op_sel_hi:[1,0] neg_lo:[0,1] neg_hi:[0,1]
	v_mul_f32_e32 v104, v104, v48
	v_pk_add_f32 v[106:107], v[106:107], v[46:47] op_sel_hi:[1,0] neg_lo:[0,1] neg_hi:[0,1]
	v_pk_add_f32 v[52:53], v[52:53], v[46:47] op_sel_hi:[1,0] neg_lo:[0,1] neg_hi:[0,1]
	v_pk_add_f32 v[96:97], v[96:97], v[46:47] op_sel_hi:[1,0] neg_lo:[0,1] neg_hi:[0,1]
	v_pk_add_f32 v[50:51], v[50:51], v[46:47] op_sel_hi:[1,0] neg_lo:[0,1] neg_hi:[0,1]
	v_pk_add_f32 v[94:95], v[94:95], v[46:47] op_sel_hi:[1,0] neg_lo:[0,1] neg_hi:[0,1]
	v_pk_add_f32 v[40:41], v[40:41], v[46:47] op_sel_hi:[1,0] neg_lo:[0,1] neg_hi:[0,1]
	v_pk_add_f32 v[56:57], v[56:57], v[46:47] op_sel_hi:[1,0] neg_lo:[0,1] neg_hi:[0,1]
	v_pk_add_f32 v[38:39], v[38:39], v[46:47] op_sel_hi:[1,0] neg_lo:[0,1] neg_hi:[0,1]
	v_pk_add_f32 v[54:55], v[54:55], v[46:47] op_sel_hi:[1,0] neg_lo:[0,1] neg_hi:[0,1]
	v_pk_add_f32 v[36:37], v[36:37], v[46:47] op_sel_hi:[1,0] neg_lo:[0,1] neg_hi:[0,1]
	v_pk_add_f32 v[44:45], v[44:45], v[46:47] op_sel_hi:[1,0] neg_lo:[0,1] neg_hi:[0,1]
	v_pk_add_f32 v[34:35], v[34:35], v[46:47] op_sel_hi:[1,0] neg_lo:[0,1] neg_hi:[0,1]
	v_pk_add_f32 v[42:43], v[42:43], v[46:47] op_sel_hi:[1,0] neg_lo:[0,1] neg_hi:[0,1]
	v_pk_mul_f32 v[30:31], v[30:31], v[48:49] op_sel_hi:[1,0]
	v_pk_mul_f32 v[28:29], v[28:29], v[48:49] op_sel_hi:[1,0]
	v_pk_mul_f32 v[26:27], v[26:27], v[48:49] op_sel_hi:[1,0]
	v_pk_mul_f32 v[24:25], v[24:25], v[48:49] op_sel_hi:[1,0]
	v_pk_mul_f32 v[22:23], v[22:23], v[48:49] op_sel_hi:[1,0]
	v_pk_mul_f32 v[20:21], v[20:21], v[48:49] op_sel_hi:[1,0]
	v_pk_mul_f32 v[18:19], v[18:19], v[48:49] op_sel_hi:[1,0]
	v_pk_mul_f32 v[16:17], v[16:17], v[48:49] op_sel_hi:[1,0]
	v_pk_mul_f32 v[14:15], v[14:15], v[48:49] op_sel_hi:[1,0]
	v_pk_mul_f32 v[12:13], v[12:13], v[48:49] op_sel_hi:[1,0]
	v_pk_mul_f32 v[10:11], v[10:11], v[48:49] op_sel_hi:[1,0]
	v_pk_mul_f32 v[8:9], v[8:9], v[48:49] op_sel_hi:[1,0]
	v_pk_mul_f32 v[6:7], v[6:7], v[48:49] op_sel_hi:[1,0]
	v_pk_mul_f32 v[4:5], v[4:5], v[48:49] op_sel_hi:[1,0]
	v_pk_mul_f32 v[2:3], v[2:3], v[48:49] op_sel_hi:[1,0]
	v_pk_mul_f32 v[0:1], v[0:1], v[48:49] op_sel_hi:[1,0]

.LBB0_203:
	s_and_b64 vcc, exec, s[0:1]
	s_movk_i32 s68, 0x21ff
	s_cbranch_vccz .LBB0_222
	s_nop 7
	ds_read_b128 v[0:3], v121
	ds_read_b128 v[4:7], v121 offset:32
	ds_read_b128 v[8:11], v121 offset:4608
	ds_read_b128 v[12:15], v121 offset:64
	ds_read_b128 v[48:51], v121 offset:4640
	ds_read_b128 v[52:55], v121 offset:4672
	v_mov_b32_e32 v33, v32
	v_mov_b32_e32 v34, v32
	v_mov_b32_e32 v35, v32
	v_mov_b32_e32 v36, v32
	v_mov_b32_e32 v37, v32
	v_mov_b32_e32 v38, v32
	v_mov_b32_e32 v39, v32
	v_mov_b32_e32 v40, v32
	v_mov_b32_e32 v41, v32
	v_mov_b32_e32 v42, v32
	v_mov_b32_e32 v43, v32
	v_mov_b32_e32 v44, v32
	v_mov_b32_e32 v45, v32
	v_mov_b32_e32 v46, v32
	v_mov_b32_e32 v47, v32
	s_waitcnt lgkmcnt(5)
	s_nop 0
	v_mfma_f32_32x32x16_bf16 v[16:31], v[0:3], v[66:69], v[32:47]
	s_waitcnt lgkmcnt(3)
	v_mfma_f32_32x32x16_bf16 v[32:47], v[8:11], v[66:69], v[32:47]
	ds_read_b128 v[0:3], v121 offset:96
	ds_read_b128 v[8:11], v121 offset:4704
	v_mfma_f32_32x32x16_bf16 v[16:31], v[4:7], v[70:73], v[16:31]
	s_waitcnt lgkmcnt(3)
	v_mfma_f32_32x32x16_bf16 v[32:47], v[48:51], v[70:73], v[32:47]
	v_mfma_f32_32x32x16_bf16 v[16:31], v[12:15], v[74:77], v[16:31]
	s_waitcnt lgkmcnt(2)
	v_mfma_f32_32x32x16_bf16 v[32:47], v[52:55], v[74:77], v[32:47]
	s_waitcnt lgkmcnt(1)
	v_mfma_f32_32x32x16_bf16 v[16:31], v[0:3], v[78:81], v[16:31]
	s_waitcnt lgkmcnt(0)
	v_mfma_f32_32x32x16_bf16 v[32:47], v[8:11], v[78:81], v[32:47]
	s_nop 15
	s_nop 7
	v_cmp_lt_i32_e32 vcc, v232, v226
	v_max3_f32 v0, v16, v17, v32
	v_max3_f32 v1, v18, v19, v33
	s_lshl_b32 s68, s36, 1
	v_max3_f32 v0, v0, v34, v35
	v_max3_f32 v1, v1, v22, v23
	v_mov_b32_e32 v117, v99
	v_max3_f32 v0, v0, v20, v21
	v_max3_f32 v1, v1, v38, v39
	s_nop 0
	v_max3_f32 v0, v0, v36, v37
	v_max3_f32 v1, v1, v26, v27
	s_nop 0
	v_max3_f32 v0, v0, v24, v25
	v_max3_f32 v1, v1, v42, v43
	s_nop 0
	v_max3_f32 v0, v0, v40, v41
	v_max3_f32 v1, v1, v30, v31
	s_nop 0
	v_max3_f32 v0, v0, v28, v29
	v_max3_f32 v1, v1, v46, v47
	s_nop 0
	v_max3_f32 v0, v0, v44, v45
	s_nop 0
	v_max3_f32 v0, v0, v1, v1
	v_cndmask_b32_e32 v1, v225, v232, vcc
	v_lshlrev_b32_e32 v123, 2, v1
	v_mov_b32_e32 v1, v0
	s_nop 1
	v_permlane32_swap_b32 v1, v0
	v_max_f32_e32 v0, v0, v1
	s_waitcnt lgkmcnt(0)
	s_nop 0
	v_max_f32_e32 v0, v0, v0
	v_max_f32_e32 v50, 0, v0
	v_sub_f32_e32 v15, v32, v50
	v_sub_f32_e32 v16, v16, v50
	v_sub_f32_e32 v32, v33, v50
	v_sub_f32_e32 v17, v17, v50
	v_exp_f32_e32 v52, v16
	v_exp_f32_e32 v53, v15
	v_sub_f32_e32 v49, v40, v50
	v_sub_f32_e32 v40, v18, v50
	v_exp_f32_e32 v16, v17
	v_exp_f32_e32 v18, v32
	v_sub_f32_e32 v15, v19, v50
	v_add_f32_e32 v19, v53, v52
	v_mov_b32_e32 v17, v99
	v_sub_f32_e32 v34, v34, v50
	v_pk_add_f32 v[32:33], v[18:19], v[16:17]
	v_sub_f32_e32 v35, v35, v50
	v_pk_add_f32 v[32:33], v[32:33], v[32:33] op_sel_hi:[0,1]
	v_exp_f32_e32 v17, v40
	v_exp_f32_e32 v19, v34
	v_exp_f32_e32 v32, v15
	v_exp_f32_e32 v34, v35
	v_sub_f32_e32 v36, v36, v50
	v_add_f32_e32 v35, v19, v17
	v_sub_f32_e32 v15, v20, v50
	v_sub_f32_e32 v40, v21, v50
	v_pk_add_f32 v[20:21], v[34:35], v[32:33]
	v_sub_f32_e32 v37, v37, v50
	v_pk_add_f32 v[20:21], v[20:21], v[20:21] op_sel_hi:[0,1]
	v_exp_f32_e32 v33, v15
	v_exp_f32_e32 v35, v36
	v_exp_f32_e32 v20, v40
	v_exp_f32_e32 v36, v37
	v_sub_f32_e32 v15, v22, v50
	v_add_f32_e32 v37, v35, v33
	v_sub_f32_e32 v40, v23, v50
	v_pk_add_f32 v[22:23], v[36:37], v[20:21]
	v_sub_f32_e32 v51, v41, v50
	v_pk_add_f32 v[22:23], v[22:23], v[22:23] op_sel_hi:[0,1]
	v_exp_f32_e32 v22, v40
	v_mov_b64_e32 v[40:41], s[90:91]
	v_mad_i64_i32 v[40:41], s[0:1], v111, s85, v[40:41]
	v_lshl_add_u64 v[40:41], v[40:41], 0, s[68:69]
	v_lshl_add_u64 v[40:41], v[40:41], 0, v[116:117]
	global_load_dwordx4 v[90:93], v[40:41], off offset:1024
	global_load_dwordx4 v[94:97], v[100:101], off offset:1280
	v_sub_f32_e32 v38, v38, v50
	v_sub_f32_e32 v39, v39, v50
	v_exp_f32_e32 v21, v15
	v_exp_f32_e32 v37, v38
	v_exp_f32_e32 v38, v39
	v_sub_f32_e32 v15, v24, v50
	v_sub_f32_e32 v54, v25, v50
	v_add_f32_e32 v39, v37, v21
	v_pk_add_f32 v[24:25], v[38:39], v[22:23]
	v_exp_f32_e32 v23, v15
	v_pk_add_f32 v[24:25], v[24:25], v[24:25] op_sel_hi:[0,1]
	v_exp_f32_e32 v39, v49
	v_exp_f32_e32 v24, v54
	v_exp_f32_e32 v40, v51
	v_sub_f32_e32 v42, v42, v50
	v_add_f32_e32 v41, v39, v23
	v_sub_f32_e32 v15, v26, v50
	v_sub_f32_e32 v49, v27, v50
	v_pk_add_f32 v[26:27], v[40:41], v[24:25]
	v_sub_f32_e32 v43, v43, v50
	v_pk_add_f32 v[26:27], v[26:27], v[26:27] op_sel_hi:[0,1]
	v_exp_f32_e32 v25, v15
	v_exp_f32_e32 v41, v42
	v_exp_f32_e32 v26, v49
	v_exp_f32_e32 v42, v43
	v_sub_f32_e32 v44, v44, v50
	v_add_f32_e32 v43, v41, v25
	v_sub_f32_e32 v15, v28, v50
	v_sub_f32_e32 v49, v29, v50
	v_pk_add_f32 v[28:29], v[42:43], v[26:27]
	v_sub_f32_e32 v45, v45, v50
	v_pk_add_f32 v[28:29], v[28:29], v[28:29] op_sel_hi:[0,1]
	v_exp_f32_e32 v27, v15
	v_exp_f32_e32 v43, v44
	v_exp_f32_e32 v28, v49
	v_exp_f32_e32 v44, v45
	v_sub_f32_e32 v46, v46, v50
	v_add_f32_e32 v45, v43, v27
	v_sub_f32_e32 v15, v30, v50
	v_sub_f32_e32 v49, v31, v50
	v_pk_add_f32 v[30:31], v[44:45], v[28:29]
	v_sub_f32_e32 v47, v47, v50
	v_pk_add_f32 v[30:31], v[30:31], v[30:31] op_sel_hi:[0,1]
	v_exp_f32_e32 v29, v15
	v_exp_f32_e32 v45, v46
	v_exp_f32_e64 v48, -v50
	v_exp_f32_e32 v30, v49
	v_exp_f32_e32 v46, v47
	v_add_f32_e32 v47, v45, v29
	v_mul_f32_e32 v0, 0, v48
	v_mul_f32_e32 v102, v110, v48
	v_pk_add_f32 v[48:49], v[46:47], v[30:31]
	s_waitcnt vmcnt(3)
	ds_write_b128 v120, v[82:85] offset:13312
	s_waitcnt vmcnt(2)
	ds_write_b128 v120, v[86:89] offset:26624
	v_pk_add_f32 v[48:49], v[48:49], v[48:49] op_sel:[0,1] op_sel_hi:[1,0]
	s_waitcnt lgkmcnt(0)
	s_barrier
	v_cvt_pk_bf16_f32 v100, v52, v16
	v_mov_b32_e32 v49, v50
	v_pk_add_f32 v[64:65], v[102:103], v[48:49]
	v_cvt_pk_bf16_f32 v101, v17, v32
	v_cvt_pk_bf16_f32 v102, v33, v20
	v_cvt_pk_bf16_f32 v103, v21, v22
	v_cvt_pk_bf16_f32 v104, v23, v24
	v_cvt_pk_bf16_f32 v105, v25, v26
	v_cvt_pk_bf16_f32 v106, v27, v28
	v_cvt_pk_bf16_f32 v107, v29, v30
	v_cvt_pk_bf16_f32 v108, v53, v18
	v_cvt_pk_bf16_f32 v109, v19, v34
	ds_read_b128 v[16:19], v121 offset:13312
	ds_read_b128 v[20:23], v121 offset:13344
	ds_read_b128 v[24:27], v121 offset:17920
	ds_read_b128 v[28:31], v121 offset:13376
	ds_read_b128 v[82:85], v121 offset:17952
	ds_read_b128 v[86:89], v121 offset:17984
	v_xor_b32_e32 v32, 0x80000000, v65
	v_mov_b32_e32 v1, v0
	v_mov_b32_e32 v2, v0
	v_mov_b32_e32 v3, v0
	v_mov_b32_e32 v4, v0
	v_mov_b32_e32 v5, v0
	v_mov_b32_e32 v6, v0
	v_mov_b32_e32 v7, v0
	v_mov_b32_e32 v8, v0
	v_mov_b32_e32 v9, v0
	v_mov_b32_e32 v10, v0
	v_mov_b32_e32 v11, v0
	v_mov_b32_e32 v12, v0
	v_mov_b32_e32 v13, v0
	v_mov_b32_e32 v14, v0
	v_mov_b32_e32 v15, v0
	v_cvt_pk_bf16_f32 v110, v35, v36
	v_cvt_pk_bf16_f32 v111, v37, v38
	v_cvt_pk_bf16_f32 v112, v39, v40
	v_cvt_pk_bf16_f32 v113, v41, v42
	v_cvt_pk_bf16_f32 v114, v43, v44
	v_cvt_pk_bf16_f32 v115, v45, v46
	v_mov_b32_e32 v33, v32
	v_mov_b32_e32 v34, v32
	v_mov_b32_e32 v35, v32
	v_mov_b32_e32 v36, v32
	v_mov_b32_e32 v37, v32
	v_mov_b32_e32 v38, v32
	v_mov_b32_e32 v39, v32
	v_mov_b32_e32 v40, v32
	v_mov_b32_e32 v41, v32
	v_mov_b32_e32 v42, v32
	v_mov_b32_e32 v43, v32
	v_mov_b32_e32 v44, v32
	v_mov_b32_e32 v45, v32
	v_mov_b32_e32 v46, v32
	v_mov_b32_e32 v47, v32
	s_waitcnt lgkmcnt(5)
	s_nop 0
	v_mfma_f32_32x32x16_bf16 v[48:63], v[16:19], v[66:69], v[32:47]
	s_waitcnt lgkmcnt(3)
	v_mfma_f32_32x32x16_bf16 v[32:47], v[24:27], v[66:69], v[32:47]
	ds_read_b128 v[16:19], v121 offset:13408
	ds_read_b128 v[24:27], v121 offset:18016
	v_mfma_f32_32x32x16_bf16 v[48:63], v[20:23], v[70:73], v[48:63]
	s_waitcnt lgkmcnt(3)
	v_mfma_f32_32x32x16_bf16 v[32:47], v[82:85], v[70:73], v[32:47]
	ds_read_b64_tr_b16 v[82:83], v118 offset:26624
	ds_read_b64_tr_b16 v[84:85], v118 offset:27776
	ds_read_b64_tr_b16 v[126:127], v118 offset:27840
	ds_read_b64_tr_b16 v[124:125], v118 offset:26688
	v_mfma_f32_32x32x16_bf16 v[48:63], v[28:31], v[74:77], v[48:63]
	s_waitcnt lgkmcnt(6)
	v_mfma_f32_32x32x16_bf16 v[32:47], v[86:89], v[74:77], v[32:47]
	ds_read_b64_tr_b16 v[86:87], v118 offset:28928
	ds_read_b64_tr_b16 v[88:89], v118 offset:30080
	ds_read_b64_tr_b16 v[130:131], v118 offset:30144
	ds_read_b64_tr_b16 v[128:129], v118 offset:28992
	s_waitcnt lgkmcnt(9)
	v_mfma_f32_32x32x16_bf16 v[48:63], v[16:19], v[78:81], v[48:63]
	s_waitcnt lgkmcnt(8)
	v_mfma_f32_32x32x16_bf16 v[32:47], v[24:27], v[78:81], v[32:47]
	ds_read_b64_tr_b16 v[132:133], v118 offset:31232
	ds_read_b64_tr_b16 v[134:135], v118 offset:32384
	ds_read_b64_tr_b16 v[138:139], v118 offset:32448
	ds_read_b64_tr_b16 v[136:137], v118 offset:31296
	s_waitcnt lgkmcnt(10)
	v_mfma_f32_32x32x16_bf16 v[16:31], v[82:85], v[100:103], v[0:15]
	s_waitcnt lgkmcnt(8)
	v_mfma_f32_32x32x16_bf16 v[0:15], v[124:127], v[100:103], v[0:15]
	ds_read_b64_tr_b16 v[82:83], v118 offset:33536
	ds_read_b64_tr_b16 v[84:85], v118 offset:34688
	ds_read_b64_tr_b16 v[102:103], v118 offset:34752
	ds_read_b64_tr_b16 v[100:101], v118 offset:33600
	s_waitcnt lgkmcnt(10)
	v_mfma_f32_32x32x16_bf16 v[16:31], v[86:89], v[104:107], v[16:31]
	s_waitcnt lgkmcnt(8)
	v_mfma_f32_32x32x16_bf16 v[0:15], v[128:131], v[104:107], v[0:15]
	s_waitcnt lgkmcnt(6)
	v_mfma_f32_32x32x16_bf16 v[16:31], v[132:135], v[108:111], v[16:31]
	s_waitcnt lgkmcnt(4)
	v_mfma_f32_32x32x16_bf16 v[0:15], v[136:139], v[108:111], v[0:15]
	s_waitcnt lgkmcnt(2)
	v_mfma_f32_32x32x16_bf16 v[16:31], v[82:85], v[112:115], v[16:31]
	s_waitcnt lgkmcnt(0)
	v_mfma_f32_32x32x16_bf16 v[0:15], v[100:103], v[112:115], v[0:15]
	s_nop 15
	s_nop 7
	s_nop 0
	v_max3_f32 v82, v48, v49, v32
	v_max3_f32 v83, v50, v51, v33
	s_nop 0
	v_max3_f32 v82, v82, v34, v35
	v_max3_f32 v83, v83, v54, v55
	s_nop 0
	v_max3_f32 v82, v82, v52, v53
	v_max3_f32 v83, v83, v38, v39
	s_nop 0
	v_max3_f32 v82, v82, v36, v37
	v_max3_f32 v83, v83, v58, v59
	s_nop 0
	v_max3_f32 v82, v82, v56, v57
	v_max3_f32 v83, v83, v42, v43
	s_nop 0
	v_max3_f32 v82, v82, v40, v41
	v_max3_f32 v83, v83, v62, v63
	s_nop 0
	v_max3_f32 v82, v82, v60, v61
	v_max3_f32 v83, v83, v46, v47
	s_nop 0
	v_max3_f32 v82, v82, v44, v45
	s_nop 0
	v_max3_f32 v82, v82, v83, v83
	v_mov_b32_e32 v83, v82
	s_nop 1
	v_permlane32_swap_b32 v83, v82
	v_max_f32_e32 v82, v82, v83
	s_waitcnt lgkmcnt(0)
	s_nop 0
	v_cmp_lt_f32_e32 vcc, s78, v82
	s_cbranch_vccz .LBB0_206
	v_max_f32_e32 v82, v82, v82
	v_max_f32_e32 v82, 0, v82
	v_exp_f32_e64 v84, -v82
	v_pk_add_f32 v[48:49], v[48:49], v[82:83] op_sel_hi:[1,0] neg_lo:[0,1] neg_hi:[0,1]
	v_pk_add_f32 v[32:33], v[32:33], v[82:83] op_sel_hi:[1,0] neg_lo:[0,1] neg_hi:[0,1]
	v_pk_add_f32 v[50:51], v[50:51], v[82:83] op_sel_hi:[1,0] neg_lo:[0,1] neg_hi:[0,1]
	v_pk_mul_f32 v[86:87], v[64:65], v[84:85]
	v_pk_add_f32 v[34:35], v[34:35], v[82:83] op_sel_hi:[1,0] neg_lo:[0,1] neg_hi:[0,1]
	v_pk_add_f32 v[52:53], v[52:53], v[82:83] op_sel_hi:[1,0] neg_lo:[0,1] neg_hi:[0,1]
	v_pk_add_f32 v[36:37], v[36:37], v[82:83] op_sel_hi:[1,0] neg_lo:[0,1] neg_hi:[0,1]
	v_pk_add_f32 v[54:55], v[54:55], v[82:83] op_sel_hi:[1,0] neg_lo:[0,1] neg_hi:[0,1]
	v_pk_add_f32 v[38:39], v[38:39], v[82:83] op_sel_hi:[1,0] neg_lo:[0,1] neg_hi:[0,1]
	v_pk_add_f32 v[56:57], v[56:57], v[82:83] op_sel_hi:[1,0] neg_lo:[0,1] neg_hi:[0,1]
	v_pk_add_f32 v[40:41], v[40:41], v[82:83] op_sel_hi:[1,0] neg_lo:[0,1] neg_hi:[0,1]
	v_pk_add_f32 v[58:59], v[58:59], v[82:83] op_sel_hi:[1,0] neg_lo:[0,1] neg_hi:[0,1]
	v_pk_add_f32 v[42:43], v[42:43], v[82:83] op_sel_hi:[1,0] neg_lo:[0,1] neg_hi:[0,1]
	v_pk_add_f32 v[60:61], v[60:61], v[82:83] op_sel_hi:[1,0] neg_lo:[0,1] neg_hi:[0,1]
	v_pk_add_f32 v[44:45], v[44:45], v[82:83] op_sel_hi:[1,0] neg_lo:[0,1] neg_hi:[0,1]
	v_pk_add_f32 v[62:63], v[62:63], v[82:83] op_sel_hi:[1,0] neg_lo:[0,1] neg_hi:[0,1]
	v_pk_add_f32 v[46:47], v[46:47], v[82:83] op_sel_hi:[1,0] neg_lo:[0,1] neg_hi:[0,1]
	v_pk_mul_f32 v[30:31], v[30:31], v[84:85] op_sel_hi:[1,0]
	v_pk_mul_f32 v[28:29], v[28:29], v[84:85] op_sel_hi:[1,0]
	v_pk_mul_f32 v[26:27], v[26:27], v[84:85] op_sel_hi:[1,0]
	v_pk_mul_f32 v[24:25], v[24:25], v[84:85] op_sel_hi:[1,0]
	v_pk_mul_f32 v[22:23], v[22:23], v[84:85] op_sel_hi:[1,0]
	v_pk_mul_f32 v[20:21], v[20:21], v[84:85] op_sel_hi:[1,0]
	v_pk_mul_f32 v[18:19], v[18:19], v[84:85] op_sel_hi:[1,0]
	v_pk_mul_f32 v[16:17], v[16:17], v[84:85] op_sel_hi:[1,0]
	v_pk_mul_f32 v[14:15], v[14:15], v[84:85] op_sel_hi:[1,0]
	v_pk_mul_f32 v[12:13], v[12:13], v[84:85] op_sel_hi:[1,0]
	v_pk_mul_f32 v[10:11], v[10:11], v[84:85] op_sel_hi:[1,0]
	v_pk_mul_f32 v[8:9], v[8:9], v[84:85] op_sel_hi:[1,0]
	v_pk_mul_f32 v[6:7], v[6:7], v[84:85] op_sel_hi:[1,0]
	v_pk_mul_f32 v[4:5], v[4:5], v[84:85] op_sel_hi:[1,0]
	v_pk_mul_f32 v[2:3], v[2:3], v[84:85] op_sel_hi:[1,0]
	v_pk_mul_f32 v[0:1], v[0:1], v[84:85] op_sel_hi:[1,0]
	v_add_f32_e32 v65, v65, v82
	v_mov_b32_e32 v64, v86

.LBB0_211:
	s_nop 15
	s_nop 7
	s_nop 0
	v_max3_f32 v95, v48, v49, v32
	v_max3_f32 v96, v50, v51, v33
	s_nop 0
	v_max3_f32 v95, v95, v34, v35
	v_max3_f32 v96, v96, v54, v55
	s_nop 0
	v_max3_f32 v95, v95, v52, v53
	v_max3_f32 v96, v96, v38, v39
	s_nop 0
	v_max3_f32 v95, v95, v36, v37
	v_max3_f32 v96, v96, v58, v59
	s_nop 0
	v_max3_f32 v95, v95, v56, v57
	v_max3_f32 v96, v96, v42, v43
	s_nop 0
	v_max3_f32 v95, v95, v40, v41
	v_max3_f32 v96, v96, v62, v63
	s_nop 0
	v_max3_f32 v95, v95, v60, v61
	v_max3_f32 v96, v96, v46, v47
	s_nop 0
	v_max3_f32 v95, v95, v44, v45
	s_nop 0
	v_max3_f32 v95, v95, v96, v96
	v_mov_b32_e32 v96, v95
	s_nop 1
	v_permlane32_swap_b32 v96, v95
	v_max_f32_e32 v95, v95, v96
	s_waitcnt lgkmcnt(0)
	s_nop 0
	v_cmp_lt_f32_e32 vcc, s78, v95
	s_cbranch_vccz .LBB0_213
	v_max_f32_e32 v95, v95, v95
	v_max_f32_e32 v96, 0, v95
	v_exp_f32_e64 v100, -v96
	v_add_f32_e32 v65, v65, v96
	v_pk_add_f32 v[48:49], v[48:49], v[96:97] op_sel_hi:[1,0] neg_lo:[0,1] neg_hi:[0,1]
	v_pk_add_f32 v[32:33], v[32:33], v[96:97] op_sel_hi:[1,0] neg_lo:[0,1] neg_hi:[0,1]
	v_mul_f32_e32 v64, v64, v100
	v_pk_add_f32 v[50:51], v[50:51], v[96:97] op_sel_hi:[1,0] neg_lo:[0,1] neg_hi:[0,1]
	v_pk_add_f32 v[34:35], v[34:35], v[96:97] op_sel_hi:[1,0] neg_lo:[0,1] neg_hi:[0,1]
	v_pk_add_f32 v[52:53], v[52:53], v[96:97] op_sel_hi:[1,0] neg_lo:[0,1] neg_hi:[0,1]
	v_pk_add_f32 v[36:37], v[36:37], v[96:97] op_sel_hi:[1,0] neg_lo:[0,1] neg_hi:[0,1]
	v_pk_add_f32 v[54:55], v[54:55], v[96:97] op_sel_hi:[1,0] neg_lo:[0,1] neg_hi:[0,1]
	v_pk_add_f32 v[38:39], v[38:39], v[96:97] op_sel_hi:[1,0] neg_lo:[0,1] neg_hi:[0,1]
	v_pk_add_f32 v[56:57], v[56:57], v[96:97] op_sel_hi:[1,0] neg_lo:[0,1] neg_hi:[0,1]
	v_pk_add_f32 v[40:41], v[40:41], v[96:97] op_sel_hi:[1,0] neg_lo:[0,1] neg_hi:[0,1]
	v_pk_add_f32 v[58:59], v[58:59], v[96:97] op_sel_hi:[1,0] neg_lo:[0,1] neg_hi:[0,1]
	v_pk_add_f32 v[42:43], v[42:43], v[96:97] op_sel_hi:[1,0] neg_lo:[0,1] neg_hi:[0,1]
	v_pk_add_f32 v[60:61], v[60:61], v[96:97] op_sel_hi:[1,0] neg_lo:[0,1] neg_hi:[0,1]
	v_pk_add_f32 v[44:45], v[44:45], v[96:97] op_sel_hi:[1,0] neg_lo:[0,1] neg_hi:[0,1]
	v_pk_add_f32 v[62:63], v[62:63], v[96:97] op_sel_hi:[1,0] neg_lo:[0,1] neg_hi:[0,1]
	v_pk_add_f32 v[46:47], v[46:47], v[96:97] op_sel_hi:[1,0] neg_lo:[0,1] neg_hi:[0,1]
	v_pk_mul_f32 v[30:31], v[30:31], v[100:101] op_sel_hi:[1,0]
	v_pk_mul_f32 v[28:29], v[28:29], v[100:101] op_sel_hi:[1,0]
	v_pk_mul_f32 v[26:27], v[26:27], v[100:101] op_sel_hi:[1,0]
	v_pk_mul_f32 v[24:25], v[24:25], v[100:101] op_sel_hi:[1,0]
	v_pk_mul_f32 v[22:23], v[22:23], v[100:101] op_sel_hi:[1,0]
	v_pk_mul_f32 v[20:21], v[20:21], v[100:101] op_sel_hi:[1,0]
	v_pk_mul_f32 v[18:19], v[18:19], v[100:101] op_sel_hi:[1,0]
	v_pk_mul_f32 v[16:17], v[16:17], v[100:101] op_sel_hi:[1,0]
	v_pk_mul_f32 v[14:15], v[14:15], v[100:101] op_sel_hi:[1,0]
	v_pk_mul_f32 v[12:13], v[12:13], v[100:101] op_sel_hi:[1,0]
	v_pk_mul_f32 v[10:11], v[10:11], v[100:101] op_sel_hi:[1,0]
	v_pk_mul_f32 v[8:9], v[8:9], v[100:101] op_sel_hi:[1,0]
	v_pk_mul_f32 v[6:7], v[6:7], v[100:101] op_sel_hi:[1,0]
	v_pk_mul_f32 v[4:5], v[4:5], v[100:101] op_sel_hi:[1,0]
	v_pk_mul_f32 v[2:3], v[2:3], v[100:101] op_sel_hi:[1,0]
	v_pk_mul_f32 v[0:1], v[0:1], v[100:101] op_sel_hi:[1,0]

.LBB0_227:
	s_or_b64 exec, exec, s[6:7]
	v_lshlrev_b32_e32 v12, 3, v12
	v_lshlrev_b32_e32 v98, 1, v12
	v_lshl_add_u64 v[48:49], v[154:155], 0, v[98:99]
	s_mov_b64 s[6:7], 0x6030000
	s_lshl_b32 s68, s15, 1
	v_lshl_add_u64 v[156:157], v[48:49], 0, s[6:7]
	v_lshl_add_u64 v[14:15], v[154:155], 0, s[68:69]
	v_lshl_add_u64 v[12:13], v[156:157], 0, s[0:1]
	v_lshl_add_u64 v[14:15], v[14:15], 0, v[98:99]
	s_mov_b32 s1, 0x6048000
	v_add_co_u32_e32 v16, vcc, s1, v14
	s_or_b32 s1, s15, 0x500
	s_nop 0
	v_addc_co_u32_e32 v17, vcc, 0, v15, vcc
	s_lshl_b32 s56, s1, 1
	s_mov_b32 s57, s69
	s_mov_b32 s1, 0x6018000
	global_load_dwordx4 v[116:119], v[12:13], off
	global_load_dwordx4 v[120:123], v[16:17], off offset:2048
	v_lshl_add_u64 v[8:9], v[8:9], 0, s[56:57]
	v_add_co_u32_e32 v12, vcc, s1, v14
	s_max_i32 s1, s8, 8
	s_nop 0
	v_addc_co_u32_e32 v13, vcc, 0, v15, vcc
	global_load_dwordx4 v[124:127], v[8:9], off
	global_load_dwordx4 v[128:131], v[12:13], off offset:2560
	s_add_i32 s1, s1, -8
	s_min_u32 s8, s1, 32
	s_mul_i32 s1, s9, 0xb000
	s_add_i32 s9, s1, 0
	v_mov_b32_e32 v12, s9
	s_movk_i32 s6, 0x90
	v_mad_u32_u24 v12, v11, s6, v12
	v_add_u32_e32 v173, v12, v152
	s_waitcnt vmcnt(5)
	ds_write_b128 v173, v[4:7]
	v_mov_b32_e32 v4, 0x1200
	v_mad_u32_u24 v168, v11, s6, v4
	v_add_u32_e32 v4, s9, v168
	v_add_u32_e32 v174, v4, v152
	s_waitcnt vmcnt(4)
	ds_write_b128 v174, v[0:3]
	v_sub_u32_e64 v3, v151, 4 clamp
	v_lshrrev_b32_e32 v0, 2, v149
	v_and_b32_e32 v1, 16, v149
	v_lshlrev_b32_e32 v148, 2, v10
	v_lshlrev_b32_e32 v2, 2, v149
	v_min_u32_e32 v169, 56, v3
	v_max_i32_e32 v3, 8, v166
	v_and_b32_e32 v8, 31, v149
	v_or_b32_e32 v9, 32, v11
	s_waitcnt lgkmcnt(0)
	s_barrier
	v_and_or_b32 v0, v0, 3, v148
	v_and_or_b32 v1, v2, 12, v1
	v_add_u32_e32 v3, -8, v3
	s_min_u32 s15, s16, 48
	v_mul_u32_u24_e32 v0, 0x90, v0
	v_lshlrev_b32_e32 v1, 1, v1
	v_mul_u32_u24_e32 v2, 0x90, v8
	v_min_u32_e32 v170, 48, v3
	s_or_b32 s16, s8, s11
	v_lshl_add_u32 v3, v10, 4, 0
	v_or_b32_e32 v176, s12, v9
	v_mul_u32_u24_e32 v167, 0x90, v11
	s_cmpk_lt_u32 s10, 0x100
	v_add3_u32 v171, v3, v2, s1
	v_add3_u32 v153, v1, v0, s9
	v_lshrrev_b32_e32 v178, 4, v11
	v_bfe_u32 v177, v149, 3, 4
	v_lshrrev_b32_e32 v179, 4, v9
	s_mov_b64 s[6:7], -1
	v_mul_lo_u32 v158, v176, s85
	v_or_b32_e32 v190, 0x80c0, v175
	v_or_b32_e32 v189, 0x80c0, v176
	v_add_u32_e32 v188, 0x8080, v175
	v_add_u32_e32 v187, 0x8080, v176
	s_cbranch_scc1 .LBB0_437
	ds_read_b128 v[0:3], v171
	ds_read_b128 v[4:7], v171 offset:32
	ds_read_b128 v[8:11], v171 offset:4640
	ds_read_b128 v[12:15], v171 offset:4608
	v_readlane_b32 s36, v254, 47
	s_mov_b32 s12, s36
	v_readlane_b32 s37, v254, 48
	v_readlane_b32 s38, v254, 49
	v_readlane_b32 s39, v254, 50
	v_readlane_b32 s40, v254, 51
	v_readlane_b32 s41, v254, 52
	v_readlane_b32 s42, v254, 53
	v_readlane_b32 s43, v254, 54
	v_readlane_b32 s44, v254, 55
	v_readlane_b32 s45, v254, 56
	v_readlane_b32 s46, v254, 57
	v_readlane_b32 s47, v254, 58
	v_readlane_b32 s48, v254, 59
	v_readlane_b32 s49, v254, 60
	v_readlane_b32 s50, v254, 61
	v_readlane_b32 s51, v254, 62
	v_writelane_b32 v254, s12, 47
	s_mov_b32 s37, s36
	s_mov_b32 s38, s36
	v_writelane_b32 v254, s13, 48
	v_writelane_b32 v254, s14, 49
	v_writelane_b32 v254, s15, 50
	v_writelane_b32 v254, s16, 51
	v_writelane_b32 v254, s17, 52
	s_mov_b32 s39, s36
	s_mov_b32 s40, s36
	s_mov_b32 s41, s36
	s_mov_b32 s42, s36
	s_mov_b32 s43, s36
	s_mov_b32 s44, s36
	s_mov_b32 s45, s36
	s_mov_b32 s46, s36
	s_mov_b32 s47, s36
	s_mov_b32 s48, s36
	s_mov_b32 s49, s36
	s_mov_b32 s50, s36
	s_mov_b32 s51, s36
	v_writelane_b32 v254, s18, 53
	v_mov_b64_e32 v[32:33], s[36:37]
	v_writelane_b32 v254, s19, 54
	v_mov_b64_e32 v[34:35], s[38:39]
	v_mov_b64_e32 v[36:37], s[40:41]
	v_mov_b64_e32 v[38:39], s[42:43]
	v_mov_b64_e32 v[40:41], s[44:45]
	v_mov_b64_e32 v[42:43], s[46:47]
	v_mov_b64_e32 v[44:45], s[48:49]
	v_mov_b64_e32 v[46:47], s[50:51]
	v_writelane_b32 v254, s20, 55
	v_writelane_b32 v254, s21, 56
	s_waitcnt lgkmcnt(3)
	v_mfma_f32_32x32x16_bf16 v[16:31], v[0:3], v[100:103], v[32:47]
	v_writelane_b32 v254, s22, 57
	v_writelane_b32 v254, s23, 58
	v_writelane_b32 v254, s24, 59
	v_writelane_b32 v254, s25, 60
	v_writelane_b32 v254, s26, 61
	v_writelane_b32 v254, s27, 62
	s_waitcnt lgkmcnt(0)
	v_mfma_f32_32x32x16_bf16 v[32:47], v[12:15], v[100:103], v[32:47]
	ds_read_b128 v[0:3], v171 offset:64
	ds_read_b128 v[12:15], v171 offset:4672
	v_mfma_f32_32x32x16_bf16 v[16:31], v[4:7], v[104:107], v[16:31]
	v_mfma_f32_32x32x16_bf16 v[32:47], v[8:11], v[104:107], v[32:47]
	ds_read_b128 v[4:7], v171 offset:96
	ds_read_b128 v[8:11], v171 offset:4704
	s_waitcnt lgkmcnt(3)
	v_mfma_f32_32x32x16_bf16 v[16:31], v[0:3], v[108:111], v[16:31]
	s_waitcnt lgkmcnt(2)
	v_mfma_f32_32x32x16_bf16 v[32:47], v[12:15], v[108:111], v[32:47]
	s_waitcnt lgkmcnt(1)
	v_mfma_f32_32x32x16_bf16 v[16:31], v[4:7], v[112:115], v[16:31]
	s_waitcnt lgkmcnt(0)
	v_mfma_f32_32x32x16_bf16 v[32:47], v[8:11], v[112:115], v[32:47]
	s_mov_b32 s1, s69
	v_lshl_add_u64 v[0:1], v[48:49], 0, s[0:1]
	s_mov_b32 s1, 0x6060000
	v_add_co_u32_e32 v0, vcc, s1, v0
	s_waitcnt vmcnt(3)
	ds_write_b128 v173, v[116:119] offset:13312
	s_waitcnt vmcnt(2)
	ds_write_b128 v174, v[120:123] offset:13312
	s_waitcnt vmcnt(1)
	ds_write_b128 v173, v[124:127] offset:26624
	s_waitcnt vmcnt(0)
	ds_write_b128 v174, v[128:131] offset:26624
	v_addc_co_u32_e32 v1, vcc, 0, v1, vcc
	v_mov_b32_e32 v159, v99
	global_load_dwordx4 v[80:83], v[0:1], off
	v_lshl_add_u64 v[0:1], s[90:91], 0, v[158:159]
	v_lshl_add_u64 v[0:1], v[0:1], 0, s[68:69]
	v_lshl_add_u64 v[0:1], v[0:1], 0, v[98:99]
	v_add_co_u32_e32 v2, vcc, s1, v0
	s_mov_b32 s1, 0x6030000
	s_nop 0
	v_addc_co_u32_e32 v3, vcc, 0, v1, vcc
	v_add_co_u32_e32 v0, vcc, s1, v0
	global_load_dwordx4 v[84:87], v[2:3], off offset:2048
	v_lshl_add_u64 v[2:3], v[156:157], 0, s[56:57]
	v_addc_co_u32_e32 v1, vcc, 0, v1, vcc
	global_load_dwordx4 v[88:91], v[2:3], off
	global_load_dwordx4 v[92:95], v[0:1], off offset:2560
	v_max3_f32 v0, v16, v17, v32
	v_max3_f32 v1, v18, v19, v33
	v_cmp_lt_i32_e32 vcc, v232, v226
	v_max3_f32 v0, v0, v34, v35
	v_max3_f32 v1, v1, v22, v23
	s_waitcnt lgkmcnt(0)
	s_barrier
	s_nop 0
	v_max3_f32 v0, v0, v20, v21
	v_max3_f32 v1, v1, v38, v39
	s_nop 0
	v_max3_f32 v0, v0, v36, v37
	v_max3_f32 v1, v1, v26, v27
	s_nop 0
	v_max3_f32 v0, v0, v24, v25
	v_max3_f32 v1, v1, v42, v43
	s_nop 0
	v_max3_f32 v0, v0, v40, v41
	v_max3_f32 v1, v1, v30, v31
	s_nop 0
	v_max3_f32 v0, v0, v28, v29
	v_max3_f32 v1, v1, v46, v47
	s_nop 0
	v_max3_f32 v0, v0, v44, v45
	s_nop 0
	v_max3_f32 v0, v0, v1, v1
	v_cndmask_b32_e32 v1, v225, v232, vcc
	v_lshlrev_b32_e32 v172, 2, v1
	ds_bpermute_b32 v1, v172, v0
	s_waitcnt lgkmcnt(0)
	v_max3_f32 v49, v0, v1, v0
	s_nop 0
	v_sub_f32_e32 v55, v25, v49
	v_sub_f32_e32 v25, v18, v49
	v_sub_f32_e32 v18, v17, v49
	v_sub_f32_e32 v17, v32, v49
	v_sub_f32_e32 v16, v16, v49
	v_sub_f32_e32 v56, v24, v49
	v_sub_f32_e32 v24, v19, v49
	v_sub_f32_e32 v19, v33, v49
	v_exp_f32_e32 v57, v16
	v_exp_f32_e32 v58, v17
	v_exp_f32_e32 v18, v18
	v_exp_f32_e32 v16, v19
	v_mov_b32_e32 v19, v99
	v_add_f32_e32 v17, v58, v57
	v_sub_f32_e32 v48, v47, v49
	v_sub_f32_e32 v47, v30, v49
	v_sub_f32_e32 v51, v29, v49
	v_sub_f32_e32 v52, v28, v49
	v_sub_f32_e32 v30, v39, v49
	v_sub_f32_e32 v39, v23, v49
	v_sub_f32_e32 v28, v21, v49
	v_sub_f32_e32 v29, v20, v49
	v_sub_f32_e32 v23, v34, v49
	v_pk_add_f32 v[20:21], v[16:17], v[18:19]
	v_sub_f32_e32 v50, v31, v49
	v_sub_f32_e32 v31, v38, v49
	v_sub_f32_e32 v38, v22, v49
	v_sub_f32_e32 v22, v35, v49
	v_pk_add_f32 v[20:21], v[20:21], v[20:21] op_sel_hi:[0,1]
	v_exp_f32_e32 v17, v25
	v_exp_f32_e32 v19, v23
	v_exp_f32_e32 v20, v24
	v_exp_f32_e32 v22, v22
	v_sub_f32_e32 v53, v27, v49
	v_add_f32_e32 v23, v19, v17
	v_sub_f32_e32 v27, v36, v49
	v_pk_add_f32 v[24:25], v[22:23], v[20:21]
	v_sub_f32_e32 v54, v26, v49
	v_sub_f32_e32 v26, v37, v49
	v_pk_add_f32 v[24:25], v[24:25], v[24:25] op_sel_hi:[0,1]
	v_exp_f32_e32 v21, v29
	v_exp_f32_e32 v23, v27
	v_exp_f32_e32 v24, v28
	v_exp_f32_e32 v26, v26
	v_exp_f32_e32 v30, v30
	v_add_f32_e32 v27, v23, v21
	v_sub_f32_e32 v40, v40, v49
	v_pk_add_f32 v[28:29], v[26:27], v[24:25]
	v_exp_f32_e32 v25, v38
	v_pk_add_f32 v[28:29], v[28:29], v[28:29] op_sel_hi:[0,1]
	v_exp_f32_e32 v27, v31
	v_exp_f32_e32 v28, v39
	v_sub_f32_e32 v41, v41, v49
	v_exp_f32_e32 v34, v41
	v_add_f32_e32 v31, v27, v25
	v_pk_add_f32 v[32:33], v[30:31], v[28:29]
	v_exp_f32_e32 v29, v56
	v_pk_add_f32 v[32:33], v[32:33], v[32:33] op_sel_hi:[0,1]
	v_exp_f32_e32 v31, v40
	v_exp_f32_e32 v32, v55
	v_sub_f32_e32 v42, v42, v49
	v_sub_f32_e32 v43, v43, v49
	v_add_f32_e32 v35, v31, v29
	v_pk_add_f32 v[36:37], v[34:35], v[32:33]
	v_exp_f32_e32 v33, v54
	v_pk_add_f32 v[36:37], v[36:37], v[36:37] op_sel_hi:[0,1]
	v_exp_f32_e32 v35, v42
	v_exp_f32_e32 v36, v53
	v_exp_f32_e32 v38, v43
	v_sub_f32_e32 v44, v44, v49
	v_add_f32_e32 v39, v35, v33
	v_sub_f32_e32 v45, v45, v49
	v_pk_add_f32 v[40:41], v[38:39], v[36:37]
	v_exp_f32_e32 v37, v52
	v_pk_add_f32 v[40:41], v[40:41], v[40:41] op_sel_hi:[0,1]
	v_exp_f32_e32 v39, v44
	v_exp_f32_e32 v40, v51
	v_exp_f32_e32 v42, v45
	v_sub_f32_e32 v46, v46, v49
	v_add_f32_e32 v43, v39, v37
	v_exp_f32_e64 v0, -v49
	v_pk_add_f32 v[44:45], v[42:43], v[40:41]
	v_exp_f32_e32 v41, v47
	v_pk_add_f32 v[44:45], v[44:45], v[44:45] op_sel_hi:[0,1]
	v_exp_f32_e32 v43, v46
	v_exp_f32_e32 v44, v50
	v_exp_f32_e32 v46, v48
	v_cvt_pk_bf16_f32 v132, v57, v18
	v_add_f32_e32 v47, v43, v41
	v_cvt_pk_bf16_f32 v133, v17, v20
	v_cvt_pk_bf16_f32 v134, v21, v24
	v_cvt_pk_bf16_f32 v135, v25, v28
	v_cvt_pk_bf16_f32 v136, v29, v32
	v_cvt_pk_bf16_f32 v140, v58, v16
	v_cvt_pk_bf16_f32 v141, v19, v22
	v_cvt_pk_bf16_f32 v142, v23, v26
	v_cvt_pk_bf16_f32 v143, v27, v30
	v_cvt_pk_bf16_f32 v144, v31, v34
	ds_read_b128 v[16:19], v171 offset:17920
	ds_read_b128 v[20:23], v171 offset:13312
	ds_read_b128 v[24:27], v171 offset:13344
	ds_read_b128 v[28:31], v171 offset:17952
	v_pk_add_f32 v[50:51], v[46:47], v[44:45]
	v_mul_f32_e32 v0, 0, v0
	v_pk_add_f32 v[50:51], v[50:51], v[50:51] op_sel:[0,1] op_sel_hi:[1,0]
	v_mov_b32_e32 v48, v0
	v_mov_b32_e32 v51, v99
	v_pk_add_f32 v[160:161], v[48:49], v[50:51]
	v_mov_b32_e32 v1, v0
	v_xor_b32_e32 v32, 0x80000000, v161
	v_mov_b32_e32 v2, v0
	v_mov_b32_e32 v3, v0
	v_mov_b32_e32 v4, v0
	v_mov_b32_e32 v5, v0
	v_mov_b32_e32 v6, v0
	v_mov_b32_e32 v7, v0
	v_mov_b32_e32 v8, v0
	v_mov_b32_e32 v9, v0
	v_mov_b32_e32 v10, v0
	v_mov_b32_e32 v11, v0
	v_mov_b32_e32 v12, v0
	v_mov_b32_e32 v13, v0
	v_mov_b32_e32 v14, v0
	v_mov_b32_e32 v15, v0
	v_cvt_pk_bf16_f32 v137, v33, v36
	v_mov_b32_e32 v33, v32
	v_cvt_pk_bf16_f32 v138, v37, v40
	v_cvt_pk_bf16_f32 v139, v41, v44
	v_cvt_pk_bf16_f32 v145, v35, v38
	v_cvt_pk_bf16_f32 v146, v39, v42
	v_cvt_pk_bf16_f32 v147, v43, v46
	v_mov_b32_e32 v34, v32
	v_mov_b32_e32 v35, v32
	v_mov_b32_e32 v36, v32
	v_mov_b32_e32 v37, v32
	v_mov_b32_e32 v38, v32
	v_mov_b32_e32 v39, v32
	v_mov_b32_e32 v40, v32
	v_mov_b32_e32 v41, v32
	v_mov_b32_e32 v42, v32
	v_mov_b32_e32 v43, v32
	v_mov_b32_e32 v44, v32
	v_mov_b32_e32 v45, v32
	v_mov_b32_e32 v46, v32
	v_mov_b32_e32 v47, v32
	v_mov_b64_e32 v[78:79], v[46:47]
	v_mov_b64_e32 v[76:77], v[44:45]
	v_mov_b64_e32 v[74:75], v[42:43]
	v_mov_b64_e32 v[72:73], v[40:41]
	v_mov_b64_e32 v[70:71], v[38:39]
	v_mov_b64_e32 v[68:69], v[36:37]
	v_mov_b64_e32 v[66:67], v[34:35]
	v_mov_b64_e32 v[64:65], v[32:33]
	s_waitcnt lgkmcnt(2)
	v_mfma_f32_32x32x16_bf16 v[48:63], v[20:23], v[100:103], v[32:47]
	v_mfma_f32_32x32x16_bf16 v[64:79], v[16:19], v[100:103], v[64:79]
	ds_read_b128 v[16:19], v171 offset:13376
	ds_read_b128 v[20:23], v171 offset:17984
	s_waitcnt lgkmcnt(3)
	v_mfma_f32_32x32x16_bf16 v[48:63], v[24:27], v[104:107], v[48:63]
	s_waitcnt lgkmcnt(2)
	v_mfma_f32_32x32x16_bf16 v[64:79], v[28:31], v[104:107], v[64:79]
	ds_read_b128 v[24:27], v171 offset:13408
	ds_read_b128 v[28:31], v171 offset:18016
	s_waitcnt lgkmcnt(3)
	v_mfma_f32_32x32x16_bf16 v[48:63], v[16:19], v[108:111], v[48:63]
	s_waitcnt lgkmcnt(2)
	v_mfma_f32_32x32x16_bf16 v[64:79], v[20:23], v[108:111], v[64:79]
	ds_read_b64_tr_b16 v[34:35], v153 offset:26624
	ds_read_b64_tr_b16 v[36:37], v153 offset:27776
	ds_read_b64_tr_b16 v[40:41], v153 offset:27840
	ds_read_b64_tr_b16 v[38:39], v153 offset:26688
	s_waitcnt lgkmcnt(5)
	v_mfma_f32_32x32x16_bf16 v[48:63], v[24:27], v[112:115], v[48:63]
	s_waitcnt lgkmcnt(4)
	v_mfma_f32_32x32x16_bf16 v[64:79], v[28:31], v[112:115], v[64:79]
	ds_read_b64_tr_b16 v[42:43], v153 offset:28928
	ds_read_b64_tr_b16 v[44:45], v153 offset:30080
	ds_read_b64_tr_b16 v[164:165], v153 offset:30144
	ds_read_b64_tr_b16 v[162:163], v153 offset:28992
	s_waitcnt lgkmcnt(6)
	v_mfma_f32_32x32x16_bf16 v[16:31], v[34:37], v[132:135], v[0:15]
	s_waitcnt lgkmcnt(4)
	v_mfma_f32_32x32x16_bf16 v[0:15], v[38:41], v[132:135], v[0:15]
	ds_read_b64_tr_b16 v[34:35], v153 offset:31232
	ds_read_b64_tr_b16 v[36:37], v153 offset:32384
	ds_read_b64_tr_b16 v[40:41], v153 offset:32448
	ds_read_b64_tr_b16 v[38:39], v153 offset:31296
	s_waitcnt lgkmcnt(6)
	v_mfma_f32_32x32x16_bf16 v[16:31], v[42:45], v[136:139], v[16:31]
	s_waitcnt lgkmcnt(4)
	v_mfma_f32_32x32x16_bf16 v[0:15], v[162:165], v[136:139], v[0:15]
	ds_read_b64_tr_b16 v[42:43], v153 offset:33536
	ds_read_b64_tr_b16 v[44:45], v153 offset:34688
	ds_read_b64_tr_b16 v[134:135], v153 offset:34752
	ds_read_b64_tr_b16 v[132:133], v153 offset:33600
	s_waitcnt lgkmcnt(6)
	v_mfma_f32_32x32x16_bf16 v[16:31], v[34:37], v[140:143], v[16:31]
	s_waitcnt lgkmcnt(4)
	v_mfma_f32_32x32x16_bf16 v[0:15], v[38:41], v[140:143], v[0:15]
	s_waitcnt lgkmcnt(2)
	v_mfma_f32_32x32x16_bf16 v[16:31], v[42:45], v[144:147], v[16:31]
	s_waitcnt lgkmcnt(0)
	v_mfma_f32_32x32x16_bf16 v[0:15], v[132:135], v[144:147], v[0:15]
	v_mov_b64_e32 v[34:35], s[90:91]
	v_mad_u64_u32 v[36:37], s[6:7], v190, s85, v[34:35]
	v_lshl_add_u64 v[36:37], v[36:37], 0, s[68:69]
	s_waitcnt vmcnt(3)
	ds_write_b128 v173, v[80:83]
	s_waitcnt vmcnt(2)
	ds_write_b128 v174, v[84:87]
	s_waitcnt vmcnt(1)
	ds_write_b128 v173, v[88:91] offset:35840
	s_waitcnt vmcnt(0)
	ds_write_b128 v174, v[92:95] offset:35840
	v_lshl_add_u64 v[36:37], v[36:37], 0, v[98:99]
	global_load_dwordx4 v[80:83], v[36:37], off offset:2048
	v_mad_u64_u32 v[36:37], s[6:7], v189, s85, v[34:35]
	v_lshl_add_u64 v[36:37], v[36:37], 0, s[68:69]
	v_lshl_add_u64 v[36:37], v[36:37], 0, v[98:99]
	global_load_dwordx4 v[84:87], v[36:37], off offset:2048
	v_mad_u64_u32 v[36:37], s[6:7], v188, s85, v[34:35]
	v_mad_u64_u32 v[34:35], s[6:7], v187, s85, v[34:35]
	v_lshl_add_u64 v[36:37], v[36:37], 0, s[68:69]
	v_lshl_add_u64 v[34:35], v[34:35], 0, s[68:69]
	v_lshl_add_u64 v[36:37], v[36:37], 0, v[98:99]
	v_lshl_add_u64 v[34:35], v[34:35], 0, v[98:99]
	global_load_dwordx4 v[88:91], v[36:37], off offset:2560
	global_load_dwordx4 v[92:95], v[34:35], off offset:2560
	v_max3_f32 v33, v48, v49, v64
	v_max3_f32 v34, v50, v51, v65
	s_waitcnt lgkmcnt(0)
	s_barrier
	s_nop 0
	v_max3_f32 v33, v33, v66, v67
	v_max3_f32 v34, v34, v54, v55
	s_nop 0
	v_max3_f32 v33, v33, v52, v53
	v_max3_f32 v34, v34, v70, v71
	s_nop 0
	v_max3_f32 v33, v33, v68, v69
	v_max3_f32 v34, v34, v58, v59
	s_nop 0
	v_max3_f32 v33, v33, v56, v57
	v_max3_f32 v34, v34, v74, v75
	s_nop 0
	v_max3_f32 v33, v33, v72, v73
	v_max3_f32 v34, v34, v62, v63
	s_nop 0
	v_max3_f32 v33, v33, v60, v61
	v_max3_f32 v34, v34, v78, v79
	s_nop 0
	v_max3_f32 v33, v33, v76, v77
	s_nop 0
	v_max3_f32 v33, v33, v34, v34
	v_mov_b32_e32 v34, v33
	s_nop 1
	v_permlane32_swap_b32 v34, v33
	v_max_f32_e32 v33, v33, v34
	s_waitcnt lgkmcnt(0)
	s_nop 0
	v_cmp_lt_f32_e32 vcc, s78, v33
	s_cbranch_vccz .LBB0_230
	v_max_f32_e32 v32, v33, v33
	v_max_f32_e32 v32, 0, v32
	v_exp_f32_e64 v34, -v32
	v_pk_add_f32 v[48:49], v[48:49], v[32:33] op_sel_hi:[1,0] neg_lo:[0,1] neg_hi:[0,1]
	v_pk_add_f32 v[64:65], v[64:65], v[32:33] op_sel_hi:[1,0] neg_lo:[0,1] neg_hi:[0,1]
	v_pk_add_f32 v[50:51], v[50:51], v[32:33] op_sel_hi:[1,0] neg_lo:[0,1] neg_hi:[0,1]
	v_pk_mul_f32 v[36:37], v[160:161], v[34:35]
	v_add_f32_e32 v161, v161, v32
	v_pk_add_f32 v[66:67], v[66:67], v[32:33] op_sel_hi:[1,0] neg_lo:[0,1] neg_hi:[0,1]
	v_pk_add_f32 v[52:53], v[52:53], v[32:33] op_sel_hi:[1,0] neg_lo:[0,1] neg_hi:[0,1]
	v_pk_add_f32 v[68:69], v[68:69], v[32:33] op_sel_hi:[1,0] neg_lo:[0,1] neg_hi:[0,1]
	v_pk_add_f32 v[54:55], v[54:55], v[32:33] op_sel_hi:[1,0] neg_lo:[0,1] neg_hi:[0,1]
	v_pk_add_f32 v[70:71], v[70:71], v[32:33] op_sel_hi:[1,0] neg_lo:[0,1] neg_hi:[0,1]
	v_pk_add_f32 v[56:57], v[56:57], v[32:33] op_sel_hi:[1,0] neg_lo:[0,1] neg_hi:[0,1]
	v_pk_add_f32 v[72:73], v[72:73], v[32:33] op_sel_hi:[1,0] neg_lo:[0,1] neg_hi:[0,1]
	v_pk_add_f32 v[58:59], v[58:59], v[32:33] op_sel_hi:[1,0] neg_lo:[0,1] neg_hi:[0,1]
	v_pk_add_f32 v[74:75], v[74:75], v[32:33] op_sel_hi:[1,0] neg_lo:[0,1] neg_hi:[0,1]
	v_pk_add_f32 v[60:61], v[60:61], v[32:33] op_sel_hi:[1,0] neg_lo:[0,1] neg_hi:[0,1]
	v_pk_add_f32 v[76:77], v[76:77], v[32:33] op_sel_hi:[1,0] neg_lo:[0,1] neg_hi:[0,1]
	v_pk_add_f32 v[62:63], v[62:63], v[32:33] op_sel_hi:[1,0] neg_lo:[0,1] neg_hi:[0,1]
	v_pk_add_f32 v[78:79], v[78:79], v[32:33] op_sel_hi:[1,0] neg_lo:[0,1] neg_hi:[0,1]
	v_pk_mul_f32 v[30:31], v[30:31], v[34:35] op_sel_hi:[1,0]
	v_pk_mul_f32 v[28:29], v[28:29], v[34:35] op_sel_hi:[1,0]
	v_pk_mul_f32 v[26:27], v[26:27], v[34:35] op_sel_hi:[1,0]
	v_pk_mul_f32 v[24:25], v[24:25], v[34:35] op_sel_hi:[1,0]
	v_pk_mul_f32 v[22:23], v[22:23], v[34:35] op_sel_hi:[1,0]
	v_pk_mul_f32 v[20:21], v[20:21], v[34:35] op_sel_hi:[1,0]
	v_pk_mul_f32 v[18:19], v[18:19], v[34:35] op_sel_hi:[1,0]
	v_pk_mul_f32 v[16:17], v[16:17], v[34:35] op_sel_hi:[1,0]
	v_pk_mul_f32 v[14:15], v[14:15], v[34:35] op_sel_hi:[1,0]
	v_pk_mul_f32 v[12:13], v[12:13], v[34:35] op_sel_hi:[1,0]
	v_pk_mul_f32 v[10:11], v[10:11], v[34:35] op_sel_hi:[1,0]
	v_pk_mul_f32 v[8:9], v[8:9], v[34:35] op_sel_hi:[1,0]
	v_pk_mul_f32 v[6:7], v[6:7], v[34:35] op_sel_hi:[1,0]
	v_pk_mul_f32 v[4:5], v[4:5], v[34:35] op_sel_hi:[1,0]
	v_pk_mul_f32 v[2:3], v[2:3], v[34:35] op_sel_hi:[1,0]
	v_pk_mul_f32 v[0:1], v[0:1], v[34:35] op_sel_hi:[1,0]
	v_xor_b32_e32 v32, 0x80000000, v161
	v_mov_b32_e32 v160, v36

.LBB0_298:
	v_max3_f32 v64, v48, v49, v32
	v_max3_f32 v65, v50, v51, v33
	s_nop 0
	v_max3_f32 v64, v64, v34, v35
	v_max3_f32 v65, v65, v54, v55
	s_nop 0
	v_max3_f32 v64, v64, v52, v53
	v_max3_f32 v65, v65, v38, v39
	s_nop 0
	v_max3_f32 v64, v64, v36, v37
	v_max3_f32 v65, v65, v58, v59
	s_nop 0
	v_max3_f32 v64, v64, v56, v57
	v_max3_f32 v65, v65, v42, v43
	s_nop 0
	v_max3_f32 v64, v64, v40, v41
	v_max3_f32 v65, v65, v62, v63
	s_nop 0
	v_max3_f32 v64, v64, v60, v61
	v_max3_f32 v65, v65, v46, v47
	s_nop 0
	v_max3_f32 v64, v64, v44, v45
	s_nop 0
	v_max3_f32 v64, v64, v65, v65
	v_mov_b32_e32 v65, v64
	s_nop 1
	v_permlane32_swap_b32 v65, v64
	v_max_f32_e32 v64, v64, v65
	s_waitcnt lgkmcnt(0)
	s_nop 0
	v_cmp_lt_f32_e32 vcc, s78, v64
	s_cbranch_vccz .LBB0_300
	v_max_f32_e32 v64, v64, v64
	v_max_f32_e32 v64, 0, v64
	v_exp_f32_e64 v66, -v64
	v_add_f32_e32 v161, v161, v64
	v_pk_add_f32 v[48:49], v[48:49], v[64:65] op_sel_hi:[1,0] neg_lo:[0,1] neg_hi:[0,1]
	v_pk_add_f32 v[32:33], v[32:33], v[64:65] op_sel_hi:[1,0] neg_lo:[0,1] neg_hi:[0,1]
	v_mul_f32_e32 v159, v159, v66
	v_pk_add_f32 v[50:51], v[50:51], v[64:65] op_sel_hi:[1,0] neg_lo:[0,1] neg_hi:[0,1]
	v_pk_add_f32 v[34:35], v[34:35], v[64:65] op_sel_hi:[1,0] neg_lo:[0,1] neg_hi:[0,1]
	v_pk_add_f32 v[52:53], v[52:53], v[64:65] op_sel_hi:[1,0] neg_lo:[0,1] neg_hi:[0,1]
	v_pk_add_f32 v[36:37], v[36:37], v[64:65] op_sel_hi:[1,0] neg_lo:[0,1] neg_hi:[0,1]
	v_pk_add_f32 v[54:55], v[54:55], v[64:65] op_sel_hi:[1,0] neg_lo:[0,1] neg_hi:[0,1]
	v_pk_add_f32 v[38:39], v[38:39], v[64:65] op_sel_hi:[1,0] neg_lo:[0,1] neg_hi:[0,1]
	v_pk_add_f32 v[56:57], v[56:57], v[64:65] op_sel_hi:[1,0] neg_lo:[0,1] neg_hi:[0,1]
	v_pk_add_f32 v[40:41], v[40:41], v[64:65] op_sel_hi:[1,0] neg_lo:[0,1] neg_hi:[0,1]
	v_pk_add_f32 v[58:59], v[58:59], v[64:65] op_sel_hi:[1,0] neg_lo:[0,1] neg_hi:[0,1]
	v_pk_add_f32 v[42:43], v[42:43], v[64:65] op_sel_hi:[1,0] neg_lo:[0,1] neg_hi:[0,1]
	v_pk_add_f32 v[60:61], v[60:61], v[64:65] op_sel_hi:[1,0] neg_lo:[0,1] neg_hi:[0,1]
	v_pk_add_f32 v[44:45], v[44:45], v[64:65] op_sel_hi:[1,0] neg_lo:[0,1] neg_hi:[0,1]
	v_pk_add_f32 v[62:63], v[62:63], v[64:65] op_sel_hi:[1,0] neg_lo:[0,1] neg_hi:[0,1]
	v_pk_add_f32 v[46:47], v[46:47], v[64:65] op_sel_hi:[1,0] neg_lo:[0,1] neg_hi:[0,1]
	v_pk_mul_f32 v[30:31], v[30:31], v[66:67] op_sel_hi:[1,0]
	v_pk_mul_f32 v[28:29], v[28:29], v[66:67] op_sel_hi:[1,0]
	v_pk_mul_f32 v[26:27], v[26:27], v[66:67] op_sel_hi:[1,0]
	v_pk_mul_f32 v[24:25], v[24:25], v[66:67] op_sel_hi:[1,0]
	v_pk_mul_f32 v[22:23], v[22:23], v[66:67] op_sel_hi:[1,0]
	v_pk_mul_f32 v[20:21], v[20:21], v[66:67] op_sel_hi:[1,0]
	v_pk_mul_f32 v[18:19], v[18:19], v[66:67] op_sel_hi:[1,0]
	v_pk_mul_f32 v[16:17], v[16:17], v[66:67] op_sel_hi:[1,0]
	v_pk_mul_f32 v[14:15], v[14:15], v[66:67] op_sel_hi:[1,0]
	v_pk_mul_f32 v[12:13], v[12:13], v[66:67] op_sel_hi:[1,0]
	v_pk_mul_f32 v[10:11], v[10:11], v[66:67] op_sel_hi:[1,0]
	v_pk_mul_f32 v[8:9], v[8:9], v[66:67] op_sel_hi:[1,0]
	v_pk_mul_f32 v[6:7], v[6:7], v[66:67] op_sel_hi:[1,0]
	v_pk_mul_f32 v[4:5], v[4:5], v[66:67] op_sel_hi:[1,0]
	v_pk_mul_f32 v[2:3], v[2:3], v[66:67] op_sel_hi:[1,0]
	v_pk_mul_f32 v[0:1], v[0:1], v[66:67] op_sel_hi:[1,0]

.LBB0_368:
	v_max3_f32 v65, v48, v49, v32
	v_max3_f32 v66, v50, v51, v33
	s_nop 0
	v_max3_f32 v65, v65, v34, v35
	v_max3_f32 v66, v66, v54, v55
	s_nop 0
	v_max3_f32 v65, v65, v52, v53
	v_max3_f32 v66, v66, v38, v39
	s_nop 0
	v_max3_f32 v65, v65, v36, v37
	v_max3_f32 v66, v66, v58, v59
	s_nop 0
	v_max3_f32 v65, v65, v56, v57
	v_max3_f32 v66, v66, v42, v43
	s_nop 0
	v_max3_f32 v65, v65, v40, v41
	v_max3_f32 v66, v66, v62, v63
	s_nop 0
	v_max3_f32 v65, v65, v60, v61
	v_max3_f32 v66, v66, v46, v47
	s_nop 0
	v_max3_f32 v65, v65, v44, v45
	s_nop 0
	v_max3_f32 v65, v65, v66, v66
	v_mov_b32_e32 v66, v65
	s_nop 1
	v_permlane32_swap_b32 v66, v65
	v_max_f32_e32 v65, v65, v66
	s_waitcnt lgkmcnt(0)
	s_nop 0
	v_cmp_lt_f32_e32 vcc, s78, v65
	s_cbranch_vccz .LBB0_370
	v_max_f32_e32 v64, v65, v65
	v_max_f32_e32 v64, 0, v64
	v_exp_f32_e64 v66, -v64
	v_add_f32_e32 v65, v161, v64
	v_pk_add_f32 v[48:49], v[48:49], v[64:65] op_sel_hi:[1,0] neg_lo:[0,1] neg_hi:[0,1]
	v_pk_add_f32 v[32:33], v[32:33], v[64:65] op_sel_hi:[1,0] neg_lo:[0,1] neg_hi:[0,1]
	v_mul_f32_e32 v159, v159, v66
	v_pk_add_f32 v[50:51], v[50:51], v[64:65] op_sel_hi:[1,0] neg_lo:[0,1] neg_hi:[0,1]
	v_pk_add_f32 v[34:35], v[34:35], v[64:65] op_sel_hi:[1,0] neg_lo:[0,1] neg_hi:[0,1]
	v_pk_add_f32 v[52:53], v[52:53], v[64:65] op_sel_hi:[1,0] neg_lo:[0,1] neg_hi:[0,1]
	v_pk_add_f32 v[36:37], v[36:37], v[64:65] op_sel_hi:[1,0] neg_lo:[0,1] neg_hi:[0,1]
	v_pk_add_f32 v[54:55], v[54:55], v[64:65] op_sel_hi:[1,0] neg_lo:[0,1] neg_hi:[0,1]
	v_pk_add_f32 v[38:39], v[38:39], v[64:65] op_sel_hi:[1,0] neg_lo:[0,1] neg_hi:[0,1]
	v_pk_add_f32 v[56:57], v[56:57], v[64:65] op_sel_hi:[1,0] neg_lo:[0,1] neg_hi:[0,1]
	v_pk_add_f32 v[40:41], v[40:41], v[64:65] op_sel_hi:[1,0] neg_lo:[0,1] neg_hi:[0,1]
	v_pk_add_f32 v[58:59], v[58:59], v[64:65] op_sel_hi:[1,0] neg_lo:[0,1] neg_hi:[0,1]
	v_pk_add_f32 v[42:43], v[42:43], v[64:65] op_sel_hi:[1,0] neg_lo:[0,1] neg_hi:[0,1]
	v_pk_add_f32 v[60:61], v[60:61], v[64:65] op_sel_hi:[1,0] neg_lo:[0,1] neg_hi:[0,1]
	v_pk_add_f32 v[44:45], v[44:45], v[64:65] op_sel_hi:[1,0] neg_lo:[0,1] neg_hi:[0,1]
	v_pk_add_f32 v[62:63], v[62:63], v[64:65] op_sel_hi:[1,0] neg_lo:[0,1] neg_hi:[0,1]
	v_pk_add_f32 v[46:47], v[46:47], v[64:65] op_sel_hi:[1,0] neg_lo:[0,1] neg_hi:[0,1]
	v_pk_mul_f32 v[30:31], v[30:31], v[66:67] op_sel_hi:[1,0]
	v_pk_mul_f32 v[28:29], v[28:29], v[66:67] op_sel_hi:[1,0]
	v_pk_mul_f32 v[26:27], v[26:27], v[66:67] op_sel_hi:[1,0]
	v_pk_mul_f32 v[24:25], v[24:25], v[66:67] op_sel_hi:[1,0]
	v_pk_mul_f32 v[22:23], v[22:23], v[66:67] op_sel_hi:[1,0]
	v_pk_mul_f32 v[20:21], v[20:21], v[66:67] op_sel_hi:[1,0]
	v_pk_mul_f32 v[18:19], v[18:19], v[66:67] op_sel_hi:[1,0]
	v_pk_mul_f32 v[16:17], v[16:17], v[66:67] op_sel_hi:[1,0]
	v_pk_mul_f32 v[14:15], v[14:15], v[66:67] op_sel_hi:[1,0]
	v_pk_mul_f32 v[12:13], v[12:13], v[66:67] op_sel_hi:[1,0]
	v_pk_mul_f32 v[10:11], v[10:11], v[66:67] op_sel_hi:[1,0]
	v_pk_mul_f32 v[8:9], v[8:9], v[66:67] op_sel_hi:[1,0]
	v_pk_mul_f32 v[6:7], v[6:7], v[66:67] op_sel_hi:[1,0]
	v_pk_mul_f32 v[4:5], v[4:5], v[66:67] op_sel_hi:[1,0]
	v_pk_mul_f32 v[2:3], v[2:3], v[66:67] op_sel_hi:[1,0]
	v_pk_mul_f32 v[0:1], v[0:1], v[66:67] op_sel_hi:[1,0]
	v_xor_b32_e32 v64, 0x80000000, v65
.LBB0_370:
	ds_read_b128 v[192:195], v171 offset:13312
	ds_read_b128 v[196:199], v171 offset:13344
	ds_read_b128 v[200:203], v171 offset:17920
	ds_read_b128 v[204:207], v171 offset:17952
	v_exp_f32_e32 v93, v48
	v_exp_f32_e32 v163, v32
	v_exp_f32_e32 v94, v49
	v_exp_f32_e32 v164, v33
	v_exp_f32_e32 v82, v52
	v_exp_f32_e32 v97, v36
	v_exp_f32_e32 v83, v53
	s_waitcnt vmcnt(3)
	v_exp_f32_e32 v140, v37
	v_exp_f32_e32 v88, v58
	v_exp_f32_e32 v89, v59
	v_exp_f32_e32 v80, v50
	v_exp_f32_e32 v95, v34
	v_exp_f32_e32 v81, v51
	v_exp_f32_e32 v96, v35
	v_exp_f32_e32 v84, v54
	v_exp_f32_e32 v141, v38
	v_exp_f32_e32 v85, v55
	v_exp_f32_e32 v142, v39
	v_exp_f32_e32 v86, v56
	v_exp_f32_e32 v143, v40
	v_exp_f32_e32 v87, v57
	s_waitcnt vmcnt(2)
	v_exp_f32_e32 v144, v41
	v_exp_f32_e32 v145, v42
	v_exp_f32_e32 v146, v43
	v_exp_f32_e32 v90, v60
	v_exp_f32_e32 v147, v44
	v_exp_f32_e32 v91, v61
	v_exp_f32_e32 v160, v45
	v_exp_f32_e32 v92, v62
	v_exp_f32_e32 v161, v46
	v_exp_f32_e32 v162, v63
	v_exp_f32_e32 v165, v47
	v_mov_b32_e32 v65, v64
	s_bitcmp1_b32 s1, 0
	v_mov_b32_e32 v66, v64
	v_mov_b32_e32 v67, v64
	v_mov_b32_e32 v68, v64
	v_mov_b32_e32 v69, v64
	v_mov_b32_e32 v70, v64
	v_mov_b32_e32 v71, v64
	v_mov_b32_e32 v72, v64
	v_mov_b32_e32 v73, v64
	v_mov_b32_e32 v74, v64
	v_mov_b32_e32 v75, v64
	v_mov_b32_e32 v76, v64
	v_mov_b32_e32 v77, v64
	v_mov_b32_e32 v78, v64
	v_mov_b32_e32 v79, v64
	v_cvt_pk_bf16_f32 v32, v93, v94
	v_cvt_pk_bf16_f32 v34, v82, v83
	v_cvt_pk_bf16_f32 v37, v88, v89
	v_cvt_pk_bf16_f32 v58, v163, v164
	v_cvt_pk_bf16_f32 v60, v97, v140
	s_cselect_b32 s1, 0x2400, 0
	v_cvt_pk_bf16_f32 v33, v80, v81
	v_cvt_pk_bf16_f32 v35, v84, v85
	v_cvt_pk_bf16_f32 v36, v86, v87
	v_cvt_pk_bf16_f32 v38, v90, v91
	v_cvt_pk_bf16_f32 v39, v92, v162
	v_cvt_pk_bf16_f32 v59, v95, v96
	v_cvt_pk_bf16_f32 v61, v141, v142
	v_cvt_pk_bf16_f32 v208, v143, v144
	v_cvt_pk_bf16_f32 v209, v145, v146
	v_cvt_pk_bf16_f32 v210, v147, v160
	v_cvt_pk_bf16_f32 v211, v161, v165
	s_waitcnt lgkmcnt(3)
	v_mfma_f32_32x32x16_bf16 v[42:57], v[192:195], v[100:103], v[64:79]
	s_waitcnt lgkmcnt(1)
	v_mfma_f32_32x32x16_bf16 v[64:79], v[200:203], v[100:103], v[64:79]
	ds_read_b128 v[192:195], v171 offset:13376
	ds_read_b128 v[200:203], v171 offset:17984
	v_mfma_f32_32x32x16_bf16 v[42:57], v[196:199], v[104:107], v[42:57]
	s_waitcnt lgkmcnt(2)
	v_mfma_f32_32x32x16_bf16 v[64:79], v[204:207], v[104:107], v[64:79]
	ds_read_b128 v[196:199], v171 offset:13408
	ds_read_b128 v[204:207], v171 offset:18016
	s_waitcnt lgkmcnt(3)
	v_mfma_f32_32x32x16_bf16 v[42:57], v[192:195], v[108:111], v[42:57]
	s_waitcnt lgkmcnt(2)
	v_mfma_f32_32x32x16_bf16 v[64:79], v[200:203], v[108:111], v[64:79]
	v_add_u32_e32 v40, s1, v153
	ds_read_b64_tr_b16 v[192:193], v40 offset:26624
	ds_read_b64_tr_b16 v[194:195], v40 offset:27776
	ds_read_b64_tr_b16 v[202:203], v40 offset:27840
	ds_read_b64_tr_b16 v[200:201], v40 offset:26688
	s_waitcnt lgkmcnt(5)
	v_mfma_f32_32x32x16_bf16 v[42:57], v[196:199], v[112:115], v[42:57]
	s_waitcnt lgkmcnt(4)
	v_mfma_f32_32x32x16_bf16 v[64:79], v[204:207], v[112:115], v[64:79]
	ds_read_b64_tr_b16 v[196:197], v40 offset:28928
	ds_read_b64_tr_b16 v[198:199], v40 offset:30080
	ds_read_b64_tr_b16 v[206:207], v40 offset:30144
	ds_read_b64_tr_b16 v[204:205], v40 offset:28992
	s_waitcnt lgkmcnt(6)
	v_mfma_f32_32x32x16_bf16 v[16:31], v[192:195], v[32:35], v[16:31]
	s_waitcnt lgkmcnt(4)
	v_mfma_f32_32x32x16_bf16 v[0:15], v[200:203], v[32:35], v[0:15]
	ds_read_b64_tr_b16 v[32:33], v40 offset:31232
	ds_read_b64_tr_b16 v[34:35], v40 offset:32384
	ds_read_b64_tr_b16 v[194:195], v40 offset:32448
	ds_read_b64_tr_b16 v[192:193], v40 offset:31296
	s_waitcnt lgkmcnt(6)
	v_mfma_f32_32x32x16_bf16 v[16:31], v[196:199], v[36:39], v[16:31]
	s_waitcnt lgkmcnt(4)
	v_mfma_f32_32x32x16_bf16 v[0:15], v[204:207], v[36:39], v[0:15]
	ds_read_b64_tr_b16 v[36:37], v40 offset:33536
	ds_read_b64_tr_b16 v[38:39], v40 offset:34688
	ds_read_b64_tr_b16 v[198:199], v40 offset:34752
	ds_read_b64_tr_b16 v[196:197], v40 offset:33600
	s_waitcnt lgkmcnt(6)
	v_mfma_f32_32x32x16_bf16 v[16:31], v[32:35], v[58:61], v[16:31]
	s_waitcnt lgkmcnt(4)
	v_mfma_f32_32x32x16_bf16 v[0:15], v[192:195], v[58:61], v[0:15]
	s_waitcnt lgkmcnt(2)
	v_mfma_f32_32x32x16_bf16 v[16:31], v[36:39], v[208:211], v[16:31]
	s_waitcnt lgkmcnt(0)
	v_mfma_f32_32x32x16_bf16 v[0:15], v[196:199], v[208:211], v[0:15]
	s_waitcnt vmcnt(1)
	ds_write_b128 v173, v[132:135] offset:35840
	s_waitcnt vmcnt(0)
	ds_write_b128 v174, v[136:139] offset:35840
	s_add_i32 s1, s15, 12
	v_add3_u32 v37, s8, v148, 16
	s_waitcnt lgkmcnt(0)
	s_barrier
	v_sub_u32_e32 v132, v37, v166
	v_sub_u32_e32 v63, v37, v170
	v_sub_u32_e32 v62, s1, v151
	v_lshlrev_b32_e32 v132, 2, v132
	v_mad_i32_i24 v132, v62, s5, v132
	v_add_u32_e32 v132, 0x163a0, v132
	ds_read2_b32 v[34:35], v132 offset0:0 offset1:1
	ds_read2_b32 v[38:39], v132 offset0:2 offset1:3
	ds_read2_b32 v[32:33], v132 offset0:8 offset1:9
	ds_read2_b32 v[40:41], v132 offset0:10 offset1:11
	v_sub_u32_e32 v62, s1, v169
	v_cmp_gt_u32_e64 s[38:39], 16, v63
	v_add_u32_e32 v63, 1, v63
	v_cmp_gt_u32_e64 s[40:41], 16, v63
	v_add_u32_e32 v63, 1, v63
	v_cmp_gt_u32_e64 s[42:43], 16, v63
	v_add_u32_e32 v63, 1, v63
	v_cmp_gt_u32_e64 s[44:45], 16, v63
	v_add_u32_e32 v63, 5, v63
	v_cmp_gt_u32_e64 s[46:47], 16, v63
	v_add_u32_e32 v63, 1, v63
	v_cmp_gt_u32_e64 s[48:49], 16, v63
	v_add_u32_e32 v63, 1, v63
	v_cmp_gt_u32_e64 s[50:51], 16, v63
	v_add_u32_e32 v63, 1, v63
	v_cmp_gt_u32_e64 s[52:53], 16, v63
	v_cmp_gt_u32_e64 s[54:55], 8, v62
	v_add_u32_e32 v62, 1, v62
	v_cmp_gt_u32_e64 s[6:7], 8, v62
	v_add_u32_e32 v62, 1, v62
	v_cmp_gt_u32_e64 s[10:11], 8, v62
	s_waitcnt lgkmcnt(0)
	v_add_f32_e32 v34, v42, v34
	v_add_f32_e32 v35, v43, v35
	v_add_f32_e32 v38, v44, v38
	v_add_f32_e32 v39, v45, v39
	v_add_f32_e32 v32, v46, v32
	v_add_f32_e32 v33, v47, v33
	v_add_f32_e32 v40, v48, v40
	v_add_f32_e32 v41, v49, v41
	s_and_b64 vcc, s[38:39], s[54:55]
	v_cndmask_b32_e32 v34, v233, v34, vcc
	s_and_b64 vcc, s[40:41], s[54:55]
	v_cndmask_b32_e32 v35, v233, v35, vcc
	s_and_b64 vcc, s[42:43], s[54:55]
	v_cndmask_b32_e32 v38, v233, v38, vcc
	s_and_b64 vcc, s[44:45], s[54:55]
	v_cndmask_b32_e32 v39, v233, v39, vcc
	s_and_b64 vcc, s[46:47], s[54:55]
	v_cndmask_b32_e32 v42, v233, v32, vcc
	s_and_b64 vcc, s[48:49], s[54:55]
	v_cndmask_b32_e32 v43, v233, v33, vcc
	s_and_b64 vcc, s[50:51], s[54:55]
	v_cndmask_b32_e32 v46, v233, v40, vcc
	s_and_b64 vcc, s[52:53], s[54:55]
	v_cndmask_b32_e32 v47, v233, v41, vcc
	v_add_u32_e32 v62, 1, v62
	v_cmp_gt_u32_e64 s[54:55], 8, v62
	ds_read2_b32 v[32:33], v132 offset0:62 offset1:63
	ds_read2_b32 v[36:37], v132 offset0:64 offset1:65
	ds_read2_b32 v[40:41], v132 offset0:70 offset1:71
	ds_read2_b32 v[44:45], v132 offset0:72 offset1:73
	s_waitcnt lgkmcnt(0)
	v_add_f32_e32 v32, v64, v32
	v_add_f32_e32 v33, v65, v33
	v_add_f32_e32 v36, v66, v36
	v_add_f32_e32 v37, v67, v37
	v_add_f32_e32 v40, v68, v40
	v_add_f32_e32 v41, v69, v41
	v_add_f32_e32 v44, v70, v44
	v_add_f32_e32 v45, v71, v45
	s_and_b64 vcc, s[38:39], s[10:11]
	v_cndmask_b32_e32 v32, v233, v32, vcc
	s_and_b64 vcc, s[40:41], s[10:11]
	v_cndmask_b32_e32 v33, v233, v33, vcc
	s_and_b64 vcc, s[42:43], s[10:11]
	v_cndmask_b32_e32 v36, v233, v36, vcc
	s_and_b64 vcc, s[44:45], s[10:11]
	v_cndmask_b32_e32 v37, v233, v37, vcc
	s_and_b64 vcc, s[46:47], s[10:11]
	v_cndmask_b32_e32 v40, v233, v40, vcc
	s_and_b64 vcc, s[48:49], s[10:11]
	v_cndmask_b32_e32 v41, v233, v41, vcc
	s_and_b64 vcc, s[50:51], s[10:11]
	v_cndmask_b32_e32 v44, v233, v44, vcc
	s_and_b64 vcc, s[52:53], s[10:11]
	v_cndmask_b32_e32 v45, v233, v45, vcc
	ds_read2_b32 v[58:59], v132 offset0:31 offset1:32
	ds_read2_b32 v[60:61], v132 offset0:33 offset1:34
	ds_read2_b32 v[62:63], v132 offset0:39 offset1:40
	ds_read2_b32 v[64:65], v132 offset0:41 offset1:42
	s_waitcnt lgkmcnt(0)
	v_add_f32_e32 v58, v50, v58
	v_add_f32_e32 v59, v51, v59
	v_add_f32_e32 v60, v52, v60
	v_add_f32_e32 v61, v53, v61
	v_add_f32_e32 v62, v54, v62
	v_add_f32_e32 v63, v55, v63
	v_add_f32_e32 v64, v56, v64
	v_add_f32_e32 v65, v57, v65
	s_and_b64 vcc, s[38:39], s[6:7]
	v_cndmask_b32_e32 v58, v233, v58, vcc
	s_and_b64 vcc, s[40:41], s[6:7]
	v_cndmask_b32_e32 v59, v233, v59, vcc
	s_and_b64 vcc, s[42:43], s[6:7]
	v_cndmask_b32_e32 v60, v233, v60, vcc
	s_and_b64 vcc, s[44:45], s[6:7]
	v_cndmask_b32_e32 v61, v233, v61, vcc
	s_and_b64 vcc, s[46:47], s[6:7]
	v_cndmask_b32_e32 v62, v233, v62, vcc
	s_and_b64 vcc, s[48:49], s[6:7]
	v_cndmask_b32_e32 v63, v233, v63, vcc
	s_and_b64 vcc, s[50:51], s[6:7]
	v_cndmask_b32_e32 v64, v233, v64, vcc
	s_and_b64 vcc, s[52:53], s[6:7]
	v_cndmask_b32_e32 v65, v233, v65, vcc
	ds_read2_b32 v[48:49], v132 offset0:93 offset1:94
	ds_read2_b32 v[50:51], v132 offset0:95 offset1:96
	ds_read2_b32 v[52:53], v132 offset0:101 offset1:102
	ds_read2_b32 v[54:55], v132 offset0:103 offset1:104
	s_waitcnt lgkmcnt(0)
	v_add_f32_e32 v48, v72, v48
	v_add_f32_e32 v49, v73, v49
	v_add_f32_e32 v50, v74, v50
	v_add_f32_e32 v51, v75, v51
	v_add_f32_e32 v52, v76, v52
	v_add_f32_e32 v53, v77, v53
	v_add_f32_e32 v54, v78, v54
	v_add_f32_e32 v55, v79, v55
	s_and_b64 vcc, s[38:39], s[54:55]
	v_cndmask_b32_e32 v48, v233, v48, vcc
	s_and_b64 vcc, s[40:41], s[54:55]
	v_cndmask_b32_e32 v49, v233, v49, vcc
	s_and_b64 vcc, s[42:43], s[54:55]
	v_cndmask_b32_e32 v50, v233, v50, vcc
	s_and_b64 vcc, s[44:45], s[54:55]
	v_cndmask_b32_e32 v51, v233, v51, vcc
	s_and_b64 vcc, s[46:47], s[54:55]
	v_cndmask_b32_e32 v52, v233, v52, vcc
	s_and_b64 vcc, s[48:49], s[54:55]
	v_cndmask_b32_e32 v53, v233, v53, vcc
	s_and_b64 vcc, s[50:51], s[54:55]
	v_cndmask_b32_e32 v54, v233, v54, vcc
	s_and_b64 vcc, s[52:53], s[54:55]
	v_cndmask_b32_e32 v55, v233, v55, vcc
	v_add_f32_e32 v56, v163, v93
	v_add_f32_e32 v57, v164, v94
	v_add_f32_e32 v56, 0, v56
	v_add_f32_e32 v56, v57, v56
	v_add_f32_e32 v57, v95, v80
	v_add_f32_e32 v56, v57, v56
	v_add_f32_e32 v57, v96, v81
	v_add_f32_e32 v56, v57, v56
	v_add_f32_e32 v57, v97, v82
	v_add_f32_e32 v56, v57, v56
	v_add_f32_e32 v57, v140, v83
	v_add_f32_e32 v56, v57, v56
	v_add_f32_e32 v57, v141, v84
	v_add_f32_e32 v56, v57, v56
	v_add_f32_e32 v57, v142, v85
	v_add_f32_e32 v56, v57, v56
	v_add_f32_e32 v57, v143, v86
	v_add_f32_e32 v56, v57, v56
	v_add_f32_e32 v57, v144, v87
	v_add_f32_e32 v56, v57, v56
	v_add_f32_e32 v57, v145, v88
	v_add_f32_e32 v56, v57, v56
	v_add_f32_e32 v57, v146, v89
	v_add_f32_e32 v56, v57, v56
	v_add_f32_e32 v57, v147, v90
	v_add_f32_e32 v56, v57, v56
	v_add_f32_e32 v57, v160, v91
	v_add_f32_e32 v56, v57, v56
	v_add_f32_e32 v57, v161, v92
	v_add_f32_e32 v56, v57, v56
	v_add_f32_e32 v57, v165, v162
	v_add_f32_e32 v56, v57, v56
	v_max3_f32 v57, v34, v35, v32
	v_max3_f32 v66, v38, v39, v33
	v_add_f32_e32 v56, v159, v56
	v_max3_f32 v57, v57, v36, v37
	v_max3_f32 v66, v66, v46, v47
	s_nop 0
	v_max3_f32 v57, v57, v42, v43
	v_max3_f32 v66, v66, v44, v45
	s_nop 0
	v_max3_f32 v57, v57, v40, v41
	v_max3_f32 v66, v66, v60, v61
	s_nop 0
	v_max3_f32 v57, v57, v58, v59
	v_max3_f32 v66, v66, v50, v51
	s_nop 0
	v_max3_f32 v57, v57, v48, v49
	v_max3_f32 v66, v66, v64, v65
	s_nop 0
	v_max3_f32 v57, v57, v62, v63
	v_max3_f32 v66, v66, v54, v55
	s_nop 0
	v_max3_f32 v57, v57, v52, v53
	s_nop 0
	v_max3_f32 v57, v57, v66, v66
	v_mov_b32_e32 v66, v57
	s_nop 1
	v_permlane32_swap_b32 v66, v57
	v_max_f32_e32 v57, v57, v66
	s_waitcnt lgkmcnt(0)
	s_nop 0
	v_cmp_lt_f32_e32 vcc, s78, v57
	s_cbranch_vccz .LBB0_436
	v_max_f32_e32 v57, v57, v57
	v_max_f32_e32 v57, 0, v57
	v_exp_f32_e64 v66, -v57
	v_sub_f32_e32 v65, v65, v57
	v_sub_f32_e32 v64, v64, v57
	v_sub_f32_e32 v63, v63, v57
	v_mul_f32_e32 v56, v56, v66
	v_pk_mul_f32 v[30:31], v[30:31], v[66:67] op_sel_hi:[1,0]
	v_pk_mul_f32 v[28:29], v[28:29], v[66:67] op_sel_hi:[1,0]
	v_pk_mul_f32 v[26:27], v[26:27], v[66:67] op_sel_hi:[1,0]
	v_pk_mul_f32 v[24:25], v[24:25], v[66:67] op_sel_hi:[1,0]
	v_pk_mul_f32 v[22:23], v[22:23], v[66:67] op_sel_hi:[1,0]
	v_pk_mul_f32 v[20:21], v[20:21], v[66:67] op_sel_hi:[1,0]
	v_pk_mul_f32 v[18:19], v[18:19], v[66:67] op_sel_hi:[1,0]
	v_pk_mul_f32 v[16:17], v[16:17], v[66:67] op_sel_hi:[1,0]
	v_pk_mul_f32 v[14:15], v[14:15], v[66:67] op_sel_hi:[1,0]
	v_pk_mul_f32 v[12:13], v[12:13], v[66:67] op_sel_hi:[1,0]
	v_pk_mul_f32 v[10:11], v[10:11], v[66:67] op_sel_hi:[1,0]
	v_pk_mul_f32 v[8:9], v[8:9], v[66:67] op_sel_hi:[1,0]
	v_pk_mul_f32 v[6:7], v[6:7], v[66:67] op_sel_hi:[1,0]
	v_pk_mul_f32 v[4:5], v[4:5], v[66:67] op_sel_hi:[1,0]
	v_pk_mul_f32 v[2:3], v[2:3], v[66:67] op_sel_hi:[1,0]
	v_pk_mul_f32 v[0:1], v[0:1], v[66:67] op_sel_hi:[1,0]
	v_sub_f32_e32 v62, v62, v57
	v_sub_f32_e32 v61, v61, v57
	v_sub_f32_e32 v60, v60, v57
	v_sub_f32_e32 v59, v59, v57
	v_sub_f32_e32 v58, v58, v57
	v_sub_f32_e32 v47, v47, v57
	v_sub_f32_e32 v46, v46, v57
	v_sub_f32_e32 v43, v43, v57
	v_sub_f32_e32 v42, v42, v57
	v_sub_f32_e32 v39, v39, v57
	v_sub_f32_e32 v38, v38, v57
	v_sub_f32_e32 v35, v35, v57
	v_sub_f32_e32 v34, v34, v57
	v_sub_f32_e32 v55, v55, v57
	v_sub_f32_e32 v54, v54, v57
	v_sub_f32_e32 v53, v53, v57
	v_sub_f32_e32 v52, v52, v57
	v_sub_f32_e32 v51, v51, v57
	v_sub_f32_e32 v50, v50, v57
	v_sub_f32_e32 v49, v49, v57
	v_sub_f32_e32 v48, v48, v57
	v_sub_f32_e32 v45, v45, v57
	v_sub_f32_e32 v44, v44, v57
	v_sub_f32_e32 v41, v41, v57
	v_sub_f32_e32 v40, v40, v57
	v_sub_f32_e32 v37, v37, v57
	v_sub_f32_e32 v36, v36, v57
	v_sub_f32_e32 v33, v33, v57
	v_sub_f32_e32 v32, v32, v57

.LBB0_437:
	s_and_b64 vcc, exec, s[6:7]
	s_cbranch_vccz .LBB0_519
	s_nop 8
	ds_read_b128 v[0:3], v171
	ds_read_b128 v[4:7], v171 offset:32
	ds_read_b128 v[8:11], v171 offset:4608
	ds_read_b128 v[12:15], v171 offset:4640
	v_readlane_b32 s36, v254, 47
	s_mov_b32 s12, s36
	v_readlane_b32 s37, v254, 48
	v_readlane_b32 s38, v254, 49
	v_readlane_b32 s39, v254, 50
	v_readlane_b32 s40, v254, 51
	v_readlane_b32 s41, v254, 52
	v_readlane_b32 s42, v254, 53
	v_readlane_b32 s43, v254, 54
	v_readlane_b32 s44, v254, 55
	v_readlane_b32 s45, v254, 56
	v_readlane_b32 s46, v254, 57
	v_readlane_b32 s47, v254, 58
	v_readlane_b32 s48, v254, 59
	v_readlane_b32 s49, v254, 60
	v_readlane_b32 s50, v254, 61
	v_readlane_b32 s51, v254, 62
	v_writelane_b32 v254, s12, 47
	s_mov_b32 s37, s36
	s_mov_b32 s38, s36
	v_writelane_b32 v254, s13, 48
	v_writelane_b32 v254, s14, 49
	v_writelane_b32 v254, s15, 50
	v_writelane_b32 v254, s16, 51
	v_writelane_b32 v254, s17, 52
	s_mov_b32 s39, s36
	s_mov_b32 s40, s36
	s_mov_b32 s41, s36
	s_mov_b32 s42, s36
	s_mov_b32 s43, s36
	s_mov_b32 s44, s36
	s_mov_b32 s45, s36
	s_mov_b32 s46, s36
	s_mov_b32 s47, s36
	s_mov_b32 s48, s36
	s_mov_b32 s49, s36
	s_mov_b32 s50, s36
	s_mov_b32 s51, s36
	v_writelane_b32 v254, s18, 53
	v_mov_b64_e32 v[32:33], s[36:37]
	v_writelane_b32 v254, s19, 54
	v_mov_b64_e32 v[34:35], s[38:39]
	v_mov_b64_e32 v[36:37], s[40:41]
	v_mov_b64_e32 v[38:39], s[42:43]
	v_mov_b64_e32 v[40:41], s[44:45]
	v_mov_b64_e32 v[42:43], s[46:47]
	v_mov_b64_e32 v[44:45], s[48:49]
	v_mov_b64_e32 v[46:47], s[50:51]
	v_writelane_b32 v254, s20, 55
	v_writelane_b32 v254, s21, 56
	s_waitcnt lgkmcnt(3)
	v_mfma_f32_32x32x16_bf16 v[16:31], v[0:3], v[100:103], v[32:47]
	v_writelane_b32 v254, s22, 57
	v_writelane_b32 v254, s23, 58
	v_writelane_b32 v254, s24, 59
	v_writelane_b32 v254, s25, 60
	v_writelane_b32 v254, s26, 61
	v_writelane_b32 v254, s27, 62
	s_waitcnt lgkmcnt(1)
	v_mfma_f32_32x32x16_bf16 v[32:47], v[8:11], v[100:103], v[32:47]
	ds_read_b128 v[0:3], v171 offset:64
	ds_read_b128 v[8:11], v171 offset:4672
	v_mfma_f32_32x32x16_bf16 v[16:31], v[4:7], v[104:107], v[16:31]
	s_waitcnt lgkmcnt(2)
	v_mfma_f32_32x32x16_bf16 v[32:47], v[12:15], v[104:107], v[32:47]
	ds_read_b128 v[4:7], v171 offset:96
	ds_read_b128 v[12:15], v171 offset:4704
	s_waitcnt lgkmcnt(3)
	v_mfma_f32_32x32x16_bf16 v[16:31], v[0:3], v[108:111], v[16:31]
	s_waitcnt lgkmcnt(2)
	v_mfma_f32_32x32x16_bf16 v[32:47], v[8:11], v[108:111], v[32:47]
	s_waitcnt lgkmcnt(1)
	v_mfma_f32_32x32x16_bf16 v[16:31], v[4:7], v[112:115], v[16:31]
	s_waitcnt lgkmcnt(0)
	v_mfma_f32_32x32x16_bf16 v[32:47], v[12:15], v[112:115], v[32:47]
	s_nop 15
	s_nop 7
	v_cmp_lt_i32_e32 vcc, v232, v226
	v_max3_f32 v0, v16, v17, v32
	v_max3_f32 v1, v18, v19, v33
	s_mov_b32 s1, s69
	v_max3_f32 v0, v0, v34, v35
	v_max3_f32 v1, v1, v22, v23
	s_waitcnt vmcnt(3)
	ds_write_b128 v173, v[116:119] offset:13312
	s_waitcnt vmcnt(2)
	ds_write_b128 v174, v[120:123] offset:13312
	s_waitcnt vmcnt(1)
	ds_write_b128 v173, v[124:127] offset:26624
	s_waitcnt vmcnt(0)
	ds_write_b128 v174, v[128:131] offset:26624
	v_max3_f32 v0, v0, v20, v21
	v_max3_f32 v1, v1, v38, v39
	v_mov_b32_e32 v159, v99
	v_max3_f32 v0, v0, v36, v37
	v_max3_f32 v1, v1, v26, v27
	s_mov_b32 s57, s69
	v_max3_f32 v0, v0, v24, v25
	v_max3_f32 v1, v1, v42, v43
	s_nop 0
	v_max3_f32 v0, v0, v40, v41
	v_max3_f32 v1, v1, v30, v31
	s_nop 0
	v_max3_f32 v0, v0, v28, v29
	v_max3_f32 v1, v1, v46, v47
	s_nop 0
	v_max3_f32 v0, v0, v44, v45
	s_nop 0
	v_max3_f32 v0, v0, v1, v1
	v_cndmask_b32_e32 v1, v225, v232, vcc
	v_lshlrev_b32_e32 v172, 2, v1
	ds_bpermute_b32 v1, v172, v0
	s_waitcnt lgkmcnt(0)
	v_max3_f32 v49, v0, v1, v0
	s_nop 0
	v_sub_f32_e32 v32, v32, v49
	v_sub_f32_e32 v16, v16, v49
	v_sub_f32_e32 v33, v33, v49
	v_sub_f32_e32 v48, v47, v49
	v_sub_f32_e32 v47, v17, v49
	v_exp_f32_e32 v64, v16
	v_exp_f32_e32 v65, v32
	v_sub_f32_e32 v50, v18, v49
	v_exp_f32_e32 v18, v47
	v_exp_f32_e32 v16, v33
	v_sub_f32_e32 v51, v19, v49
	v_add_f32_e32 v17, v65, v64
	v_mov_b32_e32 v19, v99
	v_sub_f32_e32 v52, v20, v49
	v_sub_f32_e32 v53, v21, v49
	v_pk_add_f32 v[20:21], v[16:17], v[18:19]
	v_sub_f32_e32 v34, v34, v49
	v_pk_add_f32 v[20:21], v[20:21], v[20:21] op_sel_hi:[0,1]
	v_exp_f32_e32 v17, v50
	v_exp_f32_e32 v19, v34
	v_exp_f32_e32 v20, v51
	v_sub_f32_e32 v55, v23, v49
	v_cvt_pk_bf16_f32 v136, v65, v16
	v_add_f32_e32 v23, v19, v17
	v_cvt_pk_bf16_f32 v145, v17, v20
	v_lshl_add_u64 v[16:17], v[154:155], 0, v[98:99]
	v_lshl_add_u64 v[16:17], v[16:17], 0, s[0:1]
	s_mov_b32 s1, 0x6060000
	v_add_co_u32_e32 v16, vcc, s1, v16
	v_sub_f32_e32 v35, v35, v49
	s_nop 0
	v_addc_co_u32_e32 v17, vcc, 0, v17, vcc
	v_sub_f32_e32 v54, v22, v49
	v_exp_f32_e32 v22, v35
	global_load_dwordx4 v[80:83], v[16:17], off
	v_lshl_add_u64 v[16:17], s[90:91], 0, v[158:159]
	v_lshl_add_u64 v[16:17], v[16:17], 0, s[68:69]
	v_lshl_add_u64 v[16:17], v[16:17], 0, v[98:99]
	v_cvt_pk_bf16_f32 v144, v64, v18
	v_add_co_u32_e32 v18, vcc, s1, v16
	v_cvt_pk_bf16_f32 v137, v19, v22
	s_nop 0
	v_addc_co_u32_e32 v19, vcc, 0, v17, vcc
	s_mov_b32 s1, 0x6030000
	v_add_co_u32_e32 v16, vcc, s1, v16
	global_load_dwordx4 v[84:87], v[18:19], off offset:2048
	v_lshl_add_u64 v[18:19], v[156:157], 0, s[56:57]
	v_addc_co_u32_e32 v17, vcc, 0, v17, vcc
	global_load_dwordx4 v[88:91], v[18:19], off
	global_load_dwordx4 v[92:95], v[16:17], off offset:2560
	v_sub_f32_e32 v36, v36, v49
	v_sub_f32_e32 v56, v24, v49
	v_sub_f32_e32 v57, v25, v49
	v_pk_add_f32 v[24:25], v[22:23], v[20:21]
	v_sub_f32_e32 v37, v37, v49
	v_pk_add_f32 v[24:25], v[24:25], v[24:25] op_sel_hi:[0,1]
	v_exp_f32_e32 v21, v52
	v_exp_f32_e32 v23, v36
	v_sub_f32_e32 v58, v26, v49
	v_exp_f32_e32 v24, v53
	v_exp_f32_e32 v26, v37
	v_sub_f32_e32 v59, v27, v49
	v_add_f32_e32 v27, v23, v21
	v_sub_f32_e32 v38, v38, v49
	v_sub_f32_e32 v60, v28, v49
	v_sub_f32_e32 v61, v29, v49
	v_pk_add_f32 v[28:29], v[26:27], v[24:25]
	v_sub_f32_e32 v39, v39, v49
	v_pk_add_f32 v[28:29], v[28:29], v[28:29] op_sel_hi:[0,1]
	v_exp_f32_e32 v25, v54
	v_exp_f32_e32 v27, v38
	v_sub_f32_e32 v62, v30, v49
	v_exp_f32_e32 v28, v55
	v_exp_f32_e32 v30, v39
	v_sub_f32_e32 v63, v31, v49
	v_add_f32_e32 v31, v27, v25
	v_sub_f32_e32 v40, v40, v49
	v_pk_add_f32 v[32:33], v[30:31], v[28:29]
	v_sub_f32_e32 v41, v41, v49
	v_pk_add_f32 v[32:33], v[32:33], v[32:33] op_sel_hi:[0,1]
	v_exp_f32_e32 v29, v56
	v_exp_f32_e32 v31, v40
	v_exp_f32_e32 v32, v57
	v_exp_f32_e32 v34, v41
	v_sub_f32_e32 v42, v42, v49
	v_add_f32_e32 v35, v31, v29
	v_sub_f32_e32 v43, v43, v49
	v_pk_add_f32 v[36:37], v[34:35], v[32:33]
	v_exp_f32_e32 v33, v58
	v_pk_add_f32 v[36:37], v[36:37], v[36:37] op_sel_hi:[0,1]
	v_exp_f32_e32 v35, v42
	v_exp_f32_e32 v36, v59
	v_exp_f32_e32 v38, v43
	v_sub_f32_e32 v44, v44, v49
	v_add_f32_e32 v39, v35, v33
	v_sub_f32_e32 v45, v45, v49
	v_pk_add_f32 v[40:41], v[38:39], v[36:37]
	v_exp_f32_e32 v37, v60
	v_pk_add_f32 v[40:41], v[40:41], v[40:41] op_sel_hi:[0,1]
	v_exp_f32_e32 v39, v44
	v_exp_f32_e32 v40, v61
	v_exp_f32_e32 v42, v45
	v_sub_f32_e32 v46, v46, v49
	v_add_f32_e32 v43, v39, v37
	v_exp_f32_e64 v0, -v49
	v_pk_add_f32 v[44:45], v[42:43], v[40:41]
	v_exp_f32_e32 v41, v62
	v_pk_add_f32 v[44:45], v[44:45], v[44:45] op_sel_hi:[0,1]
	v_exp_f32_e32 v43, v46
	v_exp_f32_e32 v44, v63
	v_exp_f32_e32 v46, v48
	s_waitcnt lgkmcnt(0)
	s_barrier
	v_add_f32_e32 v47, v43, v41
	v_cvt_pk_bf16_f32 v146, v21, v24
	v_cvt_pk_bf16_f32 v147, v25, v28
	v_cvt_pk_bf16_f32 v140, v29, v32
	v_cvt_pk_bf16_f32 v138, v23, v26
	v_cvt_pk_bf16_f32 v139, v27, v30
	v_cvt_pk_bf16_f32 v132, v31, v34
	ds_read_b128 v[16:19], v171 offset:17920
	ds_read_b128 v[20:23], v171 offset:13312
	ds_read_b128 v[24:27], v171 offset:13344
	ds_read_b128 v[28:31], v171 offset:17952
	v_pk_add_f32 v[50:51], v[46:47], v[44:45]
	v_mul_f32_e32 v0, 0, v0
	v_pk_add_f32 v[50:51], v[50:51], v[50:51] op_sel:[0,1] op_sel_hi:[1,0]
	v_mov_b32_e32 v48, v0
	v_mov_b32_e32 v51, v99
	v_pk_add_f32 v[160:161], v[48:49], v[50:51]
	v_mov_b32_e32 v1, v0
	v_xor_b32_e32 v32, 0x80000000, v161
	v_mov_b32_e32 v2, v0
	v_mov_b32_e32 v3, v0
	v_mov_b32_e32 v4, v0
	v_mov_b32_e32 v5, v0
	v_mov_b32_e32 v6, v0
	v_mov_b32_e32 v7, v0
	v_mov_b32_e32 v8, v0
	v_mov_b32_e32 v9, v0
	v_mov_b32_e32 v10, v0
	v_mov_b32_e32 v11, v0
	v_mov_b32_e32 v12, v0
	v_mov_b32_e32 v13, v0
	v_mov_b32_e32 v14, v0
	v_mov_b32_e32 v15, v0
	v_cvt_pk_bf16_f32 v141, v33, v36
	v_mov_b32_e32 v33, v32
	v_cvt_pk_bf16_f32 v142, v37, v40
	v_cvt_pk_bf16_f32 v143, v41, v44
	v_cvt_pk_bf16_f32 v133, v35, v38
	v_cvt_pk_bf16_f32 v134, v39, v42
	v_cvt_pk_bf16_f32 v135, v43, v46
	v_mov_b32_e32 v34, v32
	v_mov_b32_e32 v35, v32
	v_mov_b32_e32 v36, v32
	v_mov_b32_e32 v37, v32
	v_mov_b32_e32 v38, v32
	v_mov_b32_e32 v39, v32
	v_mov_b32_e32 v40, v32
	v_mov_b32_e32 v41, v32
	v_mov_b32_e32 v42, v32
	v_mov_b32_e32 v43, v32
	v_mov_b32_e32 v44, v32
	v_mov_b32_e32 v45, v32
	v_mov_b32_e32 v46, v32
	v_mov_b32_e32 v47, v32
	v_mov_b64_e32 v[78:79], v[46:47]
	v_mov_b64_e32 v[76:77], v[44:45]
	v_mov_b64_e32 v[74:75], v[42:43]
	v_mov_b64_e32 v[72:73], v[40:41]
	v_mov_b64_e32 v[70:71], v[38:39]
	v_mov_b64_e32 v[68:69], v[36:37]
	v_mov_b64_e32 v[66:67], v[34:35]
	v_mov_b64_e32 v[64:65], v[32:33]
	s_waitcnt lgkmcnt(2)
	v_mfma_f32_32x32x16_bf16 v[48:63], v[20:23], v[100:103], v[32:47]
	v_mfma_f32_32x32x16_bf16 v[64:79], v[16:19], v[100:103], v[64:79]
	ds_read_b128 v[16:19], v171 offset:13376
	ds_read_b128 v[20:23], v171 offset:17984
	s_waitcnt lgkmcnt(3)
	v_mfma_f32_32x32x16_bf16 v[48:63], v[24:27], v[104:107], v[48:63]
	s_waitcnt lgkmcnt(2)
	v_mfma_f32_32x32x16_bf16 v[64:79], v[28:31], v[104:107], v[64:79]
	ds_read_b128 v[24:27], v171 offset:13408
	ds_read_b128 v[28:31], v171 offset:18016
	s_waitcnt lgkmcnt(3)
	v_mfma_f32_32x32x16_bf16 v[48:63], v[16:19], v[108:111], v[48:63]
	s_waitcnt lgkmcnt(2)
	v_mfma_f32_32x32x16_bf16 v[64:79], v[20:23], v[108:111], v[64:79]
	ds_read_b64_tr_b16 v[34:35], v153 offset:26624
	ds_read_b64_tr_b16 v[36:37], v153 offset:27776
	ds_read_b64_tr_b16 v[40:41], v153 offset:27840
	ds_read_b64_tr_b16 v[38:39], v153 offset:26688
	s_waitcnt lgkmcnt(5)
	v_mfma_f32_32x32x16_bf16 v[48:63], v[24:27], v[112:115], v[48:63]
	s_waitcnt lgkmcnt(4)
	v_mfma_f32_32x32x16_bf16 v[64:79], v[28:31], v[112:115], v[64:79]
	ds_read_b64_tr_b16 v[42:43], v153 offset:28928
	ds_read_b64_tr_b16 v[44:45], v153 offset:30080
	ds_read_b64_tr_b16 v[118:119], v153 offset:30144
	ds_read_b64_tr_b16 v[116:117], v153 offset:28992
	s_waitcnt lgkmcnt(6)
	v_mfma_f32_32x32x16_bf16 v[16:31], v[34:37], v[144:147], v[0:15]
	s_waitcnt lgkmcnt(4)
	v_mfma_f32_32x32x16_bf16 v[0:15], v[38:41], v[144:147], v[0:15]
	ds_read_b64_tr_b16 v[34:35], v153 offset:31232
	ds_read_b64_tr_b16 v[36:37], v153 offset:32384
	ds_read_b64_tr_b16 v[40:41], v153 offset:32448
	ds_read_b64_tr_b16 v[38:39], v153 offset:31296
	s_waitcnt lgkmcnt(6)
	v_mfma_f32_32x32x16_bf16 v[16:31], v[42:45], v[140:143], v[16:31]
	s_waitcnt lgkmcnt(4)
	v_mfma_f32_32x32x16_bf16 v[0:15], v[116:119], v[140:143], v[0:15]
	ds_read_b64_tr_b16 v[42:43], v153 offset:33536
	ds_read_b64_tr_b16 v[44:45], v153 offset:34688
	ds_read_b64_tr_b16 v[118:119], v153 offset:34752
	ds_read_b64_tr_b16 v[116:117], v153 offset:33600
	s_waitcnt lgkmcnt(6)
	v_mfma_f32_32x32x16_bf16 v[16:31], v[34:37], v[136:139], v[16:31]
	s_waitcnt lgkmcnt(4)
	v_mfma_f32_32x32x16_bf16 v[0:15], v[38:41], v[136:139], v[0:15]
	s_waitcnt lgkmcnt(2)
	v_mfma_f32_32x32x16_bf16 v[16:31], v[42:45], v[132:135], v[16:31]
	s_waitcnt lgkmcnt(0)
	v_mfma_f32_32x32x16_bf16 v[0:15], v[116:119], v[132:135], v[0:15]
	s_nop 15
	s_nop 7
	s_nop 0
	v_max3_f32 v33, v48, v49, v64
	v_max3_f32 v34, v50, v51, v65
	s_nop 0
	v_max3_f32 v33, v33, v66, v67
	v_max3_f32 v34, v34, v54, v55
	s_nop 0
	v_max3_f32 v33, v33, v52, v53
	v_max3_f32 v34, v34, v70, v71
	s_nop 0
	v_max3_f32 v33, v33, v68, v69
	v_max3_f32 v34, v34, v58, v59
	s_nop 0
	v_max3_f32 v33, v33, v56, v57
	v_max3_f32 v34, v34, v74, v75
	s_nop 0
	v_max3_f32 v33, v33, v72, v73
	v_max3_f32 v34, v34, v62, v63
	s_nop 0
	v_max3_f32 v33, v33, v60, v61
	v_max3_f32 v34, v34, v78, v79
	s_nop 0
	v_max3_f32 v33, v33, v76, v77
	s_nop 0
	v_max3_f32 v33, v33, v34, v34
	v_mov_b32_e32 v34, v33
	s_nop 1
	v_permlane32_swap_b32 v34, v33
	v_max_f32_e32 v33, v33, v34
	s_waitcnt lgkmcnt(0)
	s_nop 0
	v_cmp_lt_f32_e32 vcc, s78, v33
	s_cbranch_vccz .LBB0_440
	v_max_f32_e32 v32, v33, v33
	v_max_f32_e32 v32, 0, v32
	v_exp_f32_e64 v34, -v32
	v_pk_add_f32 v[48:49], v[48:49], v[32:33] op_sel_hi:[1,0] neg_lo:[0,1] neg_hi:[0,1]
	v_pk_add_f32 v[64:65], v[64:65], v[32:33] op_sel_hi:[1,0] neg_lo:[0,1] neg_hi:[0,1]
	v_pk_add_f32 v[50:51], v[50:51], v[32:33] op_sel_hi:[1,0] neg_lo:[0,1] neg_hi:[0,1]
	v_pk_mul_f32 v[36:37], v[160:161], v[34:35]
	v_add_f32_e32 v161, v161, v32
	v_pk_add_f32 v[66:67], v[66:67], v[32:33] op_sel_hi:[1,0] neg_lo:[0,1] neg_hi:[0,1]
	v_pk_add_f32 v[52:53], v[52:53], v[32:33] op_sel_hi:[1,0] neg_lo:[0,1] neg_hi:[0,1]
	v_pk_add_f32 v[68:69], v[68:69], v[32:33] op_sel_hi:[1,0] neg_lo:[0,1] neg_hi:[0,1]
	v_pk_add_f32 v[54:55], v[54:55], v[32:33] op_sel_hi:[1,0] neg_lo:[0,1] neg_hi:[0,1]
	v_pk_add_f32 v[70:71], v[70:71], v[32:33] op_sel_hi:[1,0] neg_lo:[0,1] neg_hi:[0,1]
	v_pk_add_f32 v[56:57], v[56:57], v[32:33] op_sel_hi:[1,0] neg_lo:[0,1] neg_hi:[0,1]
	v_pk_add_f32 v[72:73], v[72:73], v[32:33] op_sel_hi:[1,0] neg_lo:[0,1] neg_hi:[0,1]
	v_pk_add_f32 v[58:59], v[58:59], v[32:33] op_sel_hi:[1,0] neg_lo:[0,1] neg_hi:[0,1]
	v_pk_add_f32 v[74:75], v[74:75], v[32:33] op_sel_hi:[1,0] neg_lo:[0,1] neg_hi:[0,1]
	v_pk_add_f32 v[60:61], v[60:61], v[32:33] op_sel_hi:[1,0] neg_lo:[0,1] neg_hi:[0,1]
	v_pk_add_f32 v[76:77], v[76:77], v[32:33] op_sel_hi:[1,0] neg_lo:[0,1] neg_hi:[0,1]
	v_pk_add_f32 v[62:63], v[62:63], v[32:33] op_sel_hi:[1,0] neg_lo:[0,1] neg_hi:[0,1]
	v_pk_add_f32 v[78:79], v[78:79], v[32:33] op_sel_hi:[1,0] neg_lo:[0,1] neg_hi:[0,1]
	v_pk_mul_f32 v[30:31], v[30:31], v[34:35] op_sel_hi:[1,0]
	v_pk_mul_f32 v[28:29], v[28:29], v[34:35] op_sel_hi:[1,0]
	v_pk_mul_f32 v[26:27], v[26:27], v[34:35] op_sel_hi:[1,0]
	v_pk_mul_f32 v[24:25], v[24:25], v[34:35] op_sel_hi:[1,0]
	v_pk_mul_f32 v[22:23], v[22:23], v[34:35] op_sel_hi:[1,0]
	v_pk_mul_f32 v[20:21], v[20:21], v[34:35] op_sel_hi:[1,0]
	v_pk_mul_f32 v[18:19], v[18:19], v[34:35] op_sel_hi:[1,0]
	v_pk_mul_f32 v[16:17], v[16:17], v[34:35] op_sel_hi:[1,0]
	v_pk_mul_f32 v[14:15], v[14:15], v[34:35] op_sel_hi:[1,0]
	v_pk_mul_f32 v[12:13], v[12:13], v[34:35] op_sel_hi:[1,0]
	v_pk_mul_f32 v[10:11], v[10:11], v[34:35] op_sel_hi:[1,0]
	v_pk_mul_f32 v[8:9], v[8:9], v[34:35] op_sel_hi:[1,0]
	v_pk_mul_f32 v[6:7], v[6:7], v[34:35] op_sel_hi:[1,0]
	v_pk_mul_f32 v[4:5], v[4:5], v[34:35] op_sel_hi:[1,0]
	v_pk_mul_f32 v[2:3], v[2:3], v[34:35] op_sel_hi:[1,0]
	v_pk_mul_f32 v[0:1], v[0:1], v[34:35] op_sel_hi:[1,0]
	v_xor_b32_e32 v32, 0x80000000, v161
	v_mov_b32_e32 v160, v36
.LBB0_440:
	v_exp_f32_e32 v97, v48
	v_exp_f32_e32 v120, v64
	v_exp_f32_e32 v48, v49
	v_exp_f32_e32 v116, v65
	v_mov_b32_e32 v49, v99
	v_add_f32_e32 v117, v120, v97
	v_exp_f32_e32 v118, v67
	v_pk_add_f32 v[64:65], v[116:117], v[48:49]
	v_exp_f32_e32 v49, v50
	v_pk_add_f32 v[64:65], v[64:65], v[64:65] op_sel_hi:[0,1]
	v_exp_f32_e32 v117, v66
	v_exp_f32_e32 v64, v51
	v_exp_f32_e32 v66, v69
	v_cvt_pk_bf16_f32 v128, v97, v48
	v_add_f32_e32 v119, v117, v49
	v_pk_add_f32 v[50:51], v[118:119], v[64:65]
	v_exp_f32_e32 v65, v52
	v_pk_add_f32 v[50:51], v[50:51], v[50:51] op_sel_hi:[0,1]
	v_exp_f32_e32 v119, v68
	v_exp_f32_e32 v50, v53
	v_exp_f32_e32 v68, v71
	v_cvt_pk_bf16_f32 v129, v49, v64
	v_add_f32_e32 v67, v119, v65
	v_pk_add_f32 v[52:53], v[66:67], v[50:51]
	v_exp_f32_e32 v51, v54
	v_pk_add_f32 v[52:53], v[52:53], v[52:53] op_sel_hi:[0,1]
	v_exp_f32_e32 v67, v70
	v_exp_f32_e32 v52, v55
	v_exp_f32_e32 v70, v73
	v_mov_b64_e32 v[48:49], s[90:91]
	v_add_f32_e32 v69, v67, v51
	v_pk_add_f32 v[54:55], v[68:69], v[52:53]
	v_exp_f32_e32 v53, v56
	v_pk_add_f32 v[54:55], v[54:55], v[54:55] op_sel_hi:[0,1]
	v_exp_f32_e32 v69, v72
	v_exp_f32_e32 v54, v57
	v_exp_f32_e32 v72, v75
	v_cvt_pk_bf16_f32 v130, v65, v50
	v_add_f32_e32 v71, v69, v53
	v_pk_add_f32 v[56:57], v[70:71], v[54:55]
	v_exp_f32_e32 v55, v58
	v_pk_add_f32 v[56:57], v[56:57], v[56:57] op_sel_hi:[0,1]
	v_exp_f32_e32 v71, v74
	v_exp_f32_e32 v56, v59
	v_exp_f32_e32 v74, v77
	v_cvt_pk_bf16_f32 v131, v51, v52
	v_add_f32_e32 v73, v71, v55
	v_pk_add_f32 v[58:59], v[72:73], v[56:57]
	v_exp_f32_e32 v57, v60
	v_pk_add_f32 v[58:59], v[58:59], v[58:59] op_sel_hi:[0,1]
	v_exp_f32_e32 v73, v76
	v_exp_f32_e32 v58, v61
	v_mad_u64_u32 v[50:51], s[6:7], v190, s85, v[48:49]
	v_lshl_add_u64 v[50:51], v[50:51], 0, s[68:69]
	v_add_f32_e32 v75, v73, v57
	s_waitcnt vmcnt(3)
	ds_write_b128 v173, v[80:83]
	s_waitcnt vmcnt(2)
	ds_write_b128 v174, v[84:87]
	s_waitcnt vmcnt(1)
	ds_write_b128 v173, v[88:91] offset:35840
	s_waitcnt vmcnt(0)
	ds_write_b128 v174, v[92:95] offset:35840
	v_lshl_add_u64 v[50:51], v[50:51], 0, v[98:99]
	v_pk_add_f32 v[60:61], v[74:75], v[58:59]
	v_cvt_pk_bf16_f32 v122, v119, v66
	v_cvt_pk_bf16_f32 v123, v67, v68
	global_load_dwordx4 v[64:67], v[50:51], off offset:2048
	v_mad_u64_u32 v[50:51], s[6:7], v189, s85, v[48:49]
	v_pk_add_f32 v[60:61], v[60:61], v[60:61] op_sel_hi:[0,1]
	v_exp_f32_e32 v59, v62
	v_exp_f32_e32 v75, v78
	v_lshl_add_u64 v[50:51], v[50:51], 0, s[68:69]
	v_exp_f32_e32 v60, v63
	v_exp_f32_e32 v76, v79
	v_lshl_add_u64 v[50:51], v[50:51], 0, v[98:99]
	v_cvt_pk_bf16_f32 v120, v120, v116
	v_cvt_pk_bf16_f32 v121, v117, v118
	v_cvt_pk_bf16_f32 v116, v69, v70
	v_cvt_pk_bf16_f32 v117, v71, v72
	global_load_dwordx4 v[68:71], v[50:51], off offset:2048
	v_mad_u64_u32 v[50:51], s[6:7], v188, s85, v[48:49]
	v_mad_u64_u32 v[48:49], s[6:7], v187, s85, v[48:49]
	v_lshl_add_u64 v[50:51], v[50:51], 0, s[68:69]
	v_lshl_add_u64 v[48:49], v[48:49], 0, s[68:69]
	v_add_f32_e32 v77, v75, v59
	v_lshl_add_u64 v[50:51], v[50:51], 0, v[98:99]
	v_lshl_add_u64 v[48:49], v[48:49], 0, v[98:99]
	v_pk_add_f32 v[62:63], v[76:77], v[60:61]
	v_cvt_pk_bf16_f32 v118, v73, v74
	v_cvt_pk_bf16_f32 v119, v75, v76
	global_load_dwordx4 v[72:75], v[50:51], off offset:2560
	global_load_dwordx4 v[76:79], v[48:49], off offset:2560
	s_waitcnt lgkmcnt(0)
	s_barrier
	ds_read_b128 v[80:83], v171 offset:4608
	ds_read_b128 v[84:87], v171
	ds_read_b128 v[88:91], v171 offset:32
	ds_read_b128 v[92:95], v171 offset:4640
	v_add_f32_e32 v61, v62, v63
	v_mov_b32_e32 v33, v32
	v_mov_b32_e32 v34, v32
	v_mov_b32_e32 v35, v32
	v_mov_b32_e32 v36, v32
	v_mov_b32_e32 v37, v32
	v_mov_b32_e32 v38, v32
	v_mov_b32_e32 v39, v32
	v_mov_b32_e32 v40, v32
	v_mov_b32_e32 v41, v32
	v_mov_b32_e32 v42, v32
	v_mov_b32_e32 v43, v32
	v_mov_b32_e32 v44, v32
	v_mov_b32_e32 v45, v32
	v_mov_b32_e32 v46, v32
	v_mov_b32_e32 v47, v32
	v_add_f32_e32 v96, v160, v61
	v_cvt_pk_bf16_f32 v124, v53, v54
	v_cvt_pk_bf16_f32 v125, v55, v56
	v_cvt_pk_bf16_f32 v126, v57, v58
	v_cvt_pk_bf16_f32 v127, v59, v60
	s_waitcnt lgkmcnt(2)
	v_mfma_f32_32x32x16_bf16 v[48:63], v[84:87], v[100:103], v[32:47]
	v_mfma_f32_32x32x16_bf16 v[32:47], v[80:83], v[100:103], v[32:47]
	ds_read_b128 v[80:83], v171 offset:64
	ds_read_b128 v[84:87], v171 offset:4672
	s_waitcnt lgkmcnt(3)
	v_mfma_f32_32x32x16_bf16 v[48:63], v[88:91], v[104:107], v[48:63]
	s_waitcnt lgkmcnt(2)
	v_mfma_f32_32x32x16_bf16 v[32:47], v[92:95], v[104:107], v[32:47]
	ds_read_b128 v[88:91], v171 offset:96
	ds_read_b128 v[92:95], v171 offset:4704
	s_waitcnt lgkmcnt(3)
	v_mfma_f32_32x32x16_bf16 v[48:63], v[80:83], v[108:111], v[48:63]
	s_waitcnt lgkmcnt(2)
	v_mfma_f32_32x32x16_bf16 v[32:47], v[84:87], v[108:111], v[32:47]
	ds_read_b64_tr_b16 v[80:81], v153 offset:35840
	ds_read_b64_tr_b16 v[82:83], v153 offset:36992
	ds_read_b64_tr_b16 v[86:87], v153 offset:37056
	ds_read_b64_tr_b16 v[84:85], v153 offset:35904
	s_waitcnt lgkmcnt(5)
	v_mfma_f32_32x32x16_bf16 v[48:63], v[88:91], v[112:115], v[48:63]
	s_waitcnt lgkmcnt(4)
	v_mfma_f32_32x32x16_bf16 v[32:47], v[92:95], v[112:115], v[32:47]
	ds_read_b64_tr_b16 v[88:89], v153 offset:38144
	ds_read_b64_tr_b16 v[90:91], v153 offset:39296
	ds_read_b64_tr_b16 v[94:95], v153 offset:39360
	ds_read_b64_tr_b16 v[92:93], v153 offset:38208
	s_waitcnt lgkmcnt(6)
	v_mfma_f32_32x32x16_bf16 v[16:31], v[80:83], v[128:131], v[16:31]
	s_waitcnt lgkmcnt(4)
	v_mfma_f32_32x32x16_bf16 v[0:15], v[84:87], v[128:131], v[0:15]
	ds_read_b64_tr_b16 v[80:81], v153 offset:40448
	ds_read_b64_tr_b16 v[82:83], v153 offset:41600
	ds_read_b64_tr_b16 v[86:87], v153 offset:41664
	ds_read_b64_tr_b16 v[84:85], v153 offset:40512
	s_waitcnt lgkmcnt(6)
	v_mfma_f32_32x32x16_bf16 v[16:31], v[88:91], v[124:127], v[16:31]
	s_waitcnt lgkmcnt(4)
	v_mfma_f32_32x32x16_bf16 v[0:15], v[92:95], v[124:127], v[0:15]
	ds_read_b64_tr_b16 v[88:89], v153 offset:42752
	ds_read_b64_tr_b16 v[90:91], v153 offset:43904
	ds_read_b64_tr_b16 v[94:95], v153 offset:43968
	ds_read_b64_tr_b16 v[92:93], v153 offset:42816
	s_waitcnt lgkmcnt(6)
	v_mfma_f32_32x32x16_bf16 v[16:31], v[80:83], v[120:123], v[16:31]
	s_waitcnt lgkmcnt(4)
	v_mfma_f32_32x32x16_bf16 v[0:15], v[84:87], v[120:123], v[0:15]
	s_waitcnt lgkmcnt(2)
	v_mfma_f32_32x32x16_bf16 v[16:31], v[88:91], v[116:119], v[16:31]
	s_waitcnt lgkmcnt(0)
	v_mfma_f32_32x32x16_bf16 v[0:15], v[92:95], v[116:119], v[0:15]
	s_nop 15
	s_nop 7
	v_readlane_b32 s26, v255, 43
	v_max3_f32 v80, v48, v49, v32
	v_max3_f32 v81, v50, v51, v33
	v_readlane_b32 s27, v255, 44
	v_max3_f32 v80, v80, v34, v35
	v_max3_f32 v81, v81, v54, v55
	s_nop 0
	v_max3_f32 v80, v80, v52, v53
	v_max3_f32 v81, v81, v38, v39
	s_nop 0
	v_max3_f32 v80, v80, v36, v37
	v_max3_f32 v81, v81, v58, v59
	s_nop 0
	v_max3_f32 v80, v80, v56, v57
	v_max3_f32 v81, v81, v42, v43
	s_nop 0
	v_max3_f32 v80, v80, v40, v41
	v_max3_f32 v81, v81, v62, v63
	s_nop 0
	v_max3_f32 v80, v80, v60, v61
	v_max3_f32 v81, v81, v46, v47
	s_nop 0
	v_max3_f32 v80, v80, v44, v45
	s_nop 0
	v_max3_f32 v80, v80, v81, v81
	v_mov_b32_e32 v81, v80
	s_nop 1
	v_permlane32_swap_b32 v81, v80
	v_max_f32_e32 v80, v80, v81
	s_waitcnt lgkmcnt(0)
	s_nop 0
	v_cmp_lt_f32_e32 vcc, s78, v80
	s_cbranch_vccz .LBB0_442
	v_max_f32_e32 v80, v80, v80
	v_max_f32_e32 v80, 0, v80
	v_exp_f32_e64 v82, -v80
	v_add_f32_e32 v161, v161, v80
	v_pk_add_f32 v[48:49], v[48:49], v[80:81] op_sel_hi:[1,0] neg_lo:[0,1] neg_hi:[0,1]
	v_pk_add_f32 v[32:33], v[32:33], v[80:81] op_sel_hi:[1,0] neg_lo:[0,1] neg_hi:[0,1]
	v_mul_f32_e32 v96, v96, v82
	v_pk_add_f32 v[50:51], v[50:51], v[80:81] op_sel_hi:[1,0] neg_lo:[0,1] neg_hi:[0,1]
	v_pk_add_f32 v[34:35], v[34:35], v[80:81] op_sel_hi:[1,0] neg_lo:[0,1] neg_hi:[0,1]
	v_pk_add_f32 v[52:53], v[52:53], v[80:81] op_sel_hi:[1,0] neg_lo:[0,1] neg_hi:[0,1]
	v_pk_add_f32 v[36:37], v[36:37], v[80:81] op_sel_hi:[1,0] neg_lo:[0,1] neg_hi:[0,1]
	v_pk_add_f32 v[54:55], v[54:55], v[80:81] op_sel_hi:[1,0] neg_lo:[0,1] neg_hi:[0,1]
	v_pk_add_f32 v[38:39], v[38:39], v[80:81] op_sel_hi:[1,0] neg_lo:[0,1] neg_hi:[0,1]
	v_pk_add_f32 v[56:57], v[56:57], v[80:81] op_sel_hi:[1,0] neg_lo:[0,1] neg_hi:[0,1]
	v_pk_add_f32 v[40:41], v[40:41], v[80:81] op_sel_hi:[1,0] neg_lo:[0,1] neg_hi:[0,1]
	v_pk_add_f32 v[58:59], v[58:59], v[80:81] op_sel_hi:[1,0] neg_lo:[0,1] neg_hi:[0,1]
	v_pk_add_f32 v[42:43], v[42:43], v[80:81] op_sel_hi:[1,0] neg_lo:[0,1] neg_hi:[0,1]
	v_pk_add_f32 v[60:61], v[60:61], v[80:81] op_sel_hi:[1,0] neg_lo:[0,1] neg_hi:[0,1]
	v_pk_add_f32 v[44:45], v[44:45], v[80:81] op_sel_hi:[1,0] neg_lo:[0,1] neg_hi:[0,1]
	v_pk_add_f32 v[62:63], v[62:63], v[80:81] op_sel_hi:[1,0] neg_lo:[0,1] neg_hi:[0,1]
	v_pk_add_f32 v[46:47], v[46:47], v[80:81] op_sel_hi:[1,0] neg_lo:[0,1] neg_hi:[0,1]
	v_pk_mul_f32 v[30:31], v[30:31], v[82:83] op_sel_hi:[1,0]
	v_pk_mul_f32 v[28:29], v[28:29], v[82:83] op_sel_hi:[1,0]
	v_pk_mul_f32 v[26:27], v[26:27], v[82:83] op_sel_hi:[1,0]
	v_pk_mul_f32 v[24:25], v[24:25], v[82:83] op_sel_hi:[1,0]
	v_pk_mul_f32 v[22:23], v[22:23], v[82:83] op_sel_hi:[1,0]
	v_pk_mul_f32 v[20:21], v[20:21], v[82:83] op_sel_hi:[1,0]
	v_pk_mul_f32 v[18:19], v[18:19], v[82:83] op_sel_hi:[1,0]
	v_pk_mul_f32 v[16:17], v[16:17], v[82:83] op_sel_hi:[1,0]
	v_pk_mul_f32 v[14:15], v[14:15], v[82:83] op_sel_hi:[1,0]
	v_pk_mul_f32 v[12:13], v[12:13], v[82:83] op_sel_hi:[1,0]
	v_pk_mul_f32 v[10:11], v[10:11], v[82:83] op_sel_hi:[1,0]
	v_pk_mul_f32 v[8:9], v[8:9], v[82:83] op_sel_hi:[1,0]
	v_pk_mul_f32 v[6:7], v[6:7], v[82:83] op_sel_hi:[1,0]
	v_pk_mul_f32 v[4:5], v[4:5], v[82:83] op_sel_hi:[1,0]
	v_pk_mul_f32 v[2:3], v[2:3], v[82:83] op_sel_hi:[1,0]
	v_pk_mul_f32 v[0:1], v[0:1], v[82:83] op_sel_hi:[1,0]
.LBB0_442:
	v_exp_f32_e32 v84, v48
	v_exp_f32_e32 v85, v32
	v_exp_f32_e32 v32, v49
	v_exp_f32_e32 v80, v33
	v_mov_b32_e32 v33, v99
	v_add_f32_e32 v81, v85, v84
	v_exp_f32_e32 v82, v35
	v_pk_add_f32 v[48:49], v[80:81], v[32:33]
	v_exp_f32_e32 v33, v50
	v_pk_add_f32 v[48:49], v[48:49], v[48:49] op_sel_hi:[0,1]
	v_exp_f32_e32 v81, v34
	v_exp_f32_e32 v48, v51
	v_exp_f32_e32 v50, v37
	s_add_i32 s15, s15, -8
	v_add_f32_e32 v83, v81, v33
	v_pk_add_f32 v[34:35], v[82:83], v[48:49]
	v_exp_f32_e32 v49, v52
	v_pk_add_f32 v[34:35], v[34:35], v[34:35] op_sel_hi:[0,1]
	v_exp_f32_e32 v83, v36
	v_exp_f32_e32 v34, v53
	v_exp_f32_e32 v52, v39
	v_or_b32_e32 v122, s15, v178
	v_add_f32_e32 v51, v83, v49
	v_pk_add_f32 v[36:37], v[50:51], v[34:35]
	v_exp_f32_e32 v35, v54
	v_pk_add_f32 v[36:37], v[36:37], v[36:37] op_sel_hi:[0,1]
	v_exp_f32_e32 v51, v38
	v_exp_f32_e32 v36, v55
	v_exp_f32_e32 v54, v41
	v_cvt_pk_bf16_f32 v94, v49, v34
	v_add_f32_e32 v53, v51, v35
	v_pk_add_f32 v[38:39], v[52:53], v[36:37]
	v_exp_f32_e32 v37, v56
	v_pk_add_f32 v[38:39], v[38:39], v[38:39] op_sel_hi:[0,1]
	v_exp_f32_e32 v53, v40
	v_exp_f32_e32 v38, v57
	v_exp_f32_e32 v56, v43
	v_mov_b32_e32 v34, 0x200
	v_add_f32_e32 v55, v53, v37
	v_pk_add_f32 v[40:41], v[54:55], v[38:39]
	v_exp_f32_e32 v39, v58
	v_pk_add_f32 v[40:41], v[40:41], v[40:41] op_sel_hi:[0,1]
	v_exp_f32_e32 v55, v42
	v_exp_f32_e32 v40, v59
	v_exp_f32_e32 v58, v45
	v_add_u32_e32 v124, s16, v177
	v_add_f32_e32 v57, v55, v39
	v_pk_add_f32 v[42:43], v[56:57], v[40:41]
	v_exp_f32_e32 v41, v60
	v_pk_add_f32 v[42:43], v[42:43], v[42:43] op_sel_hi:[0,1]
	v_exp_f32_e32 v57, v44
	v_exp_f32_e32 v42, v61
	v_exp_f32_e32 v60, v47
	v_lshl_add_u32 v120, v122, 6, v34
	v_add_f32_e32 v59, v57, v41
	v_pk_add_f32 v[44:45], v[58:59], v[42:43]
	v_exp_f32_e32 v43, v62
	v_pk_add_f32 v[44:45], v[44:45], v[44:45] op_sel_hi:[0,1]
	v_exp_f32_e32 v59, v46
	v_exp_f32_e32 v44, v63
	v_lshl_add_u64 v[116:117], s[90:91], 0, v[98:99]
	v_cvt_pk_bf16_f32 v92, v84, v32
	v_add_f32_e32 v61, v59, v43
	v_pk_add_f32 v[46:47], v[60:61], v[44:45]
	v_add_u32_e32 v32, v120, v124
	v_add_f32_e32 v45, v46, v47
	v_or_b32_e32 v123, s15, v179
	v_add_f32_e32 v125, v96, v45
	v_mad_i64_i32 v[96:97], s[6:7], v32, s85, v[116:117]
	s_mov_b32 s1, s69
	v_cvt_pk_bf16_f32 v93, v33, v48
	s_waitcnt vmcnt(3)
	ds_write_b128 v173, v[64:67] offset:13312
	s_waitcnt vmcnt(2)
	ds_write_b128 v174, v[68:71] offset:13312
	s_waitcnt vmcnt(1)
	ds_write_b128 v173, v[72:75] offset:26624
	s_waitcnt vmcnt(0)
	ds_write_b128 v174, v[76:79] offset:26624
	v_lshl_add_u64 v[32:33], v[96:97], 0, s[0:1]
	v_lshl_add_u32 v121, v123, 6, v34
	global_load_dwordx4 v[64:67], v[32:33], off
	v_add_u32_e32 v34, v121, v124
	v_mov_b64_e32 v[32:33], s[90:91]
	v_cvt_pk_bf16_f32 v95, v35, v36
	v_mad_i64_i32 v[34:35], s[6:7], v34, s85, v[32:33]
	v_lshl_add_u64 v[34:35], v[34:35], 0, s[68:69]
	v_lshl_add_u64 v[118:119], v[34:35], 0, v[98:99]
	v_add_u32_e32 v34, 0x80c0, v175
	v_mad_u64_u32 v[34:35], s[6:7], v34, s85, v[116:117]
	s_mov_b32 s57, s69
	v_lshl_add_u64 v[34:35], v[34:35], 0, s[56:57]
	global_load_dwordx4 v[72:75], v[34:35], off
	v_add_u32_e32 v34, 0x80c0, v176
	v_mad_u64_u32 v[32:33], s[6:7], v34, s85, v[32:33]
	v_lshl_add_u64 v[32:33], v[32:33], 0, s[68:69]
	v_lshl_add_u64 v[32:33], v[32:33], 0, v[98:99]
	global_load_dwordx4 v[68:71], v[118:119], off offset:2048
	global_load_dwordx4 v[76:79], v[32:33], off offset:2560
	s_waitcnt lgkmcnt(0)
	s_barrier
	ds_read_b128 v[126:129], v171 offset:17920
	ds_read_b128 v[130:133], v171 offset:13312
	ds_read_b128 v[134:137], v171 offset:13344
	ds_read_b128 v[138:141], v171 offset:17952
	v_xor_b32_e32 v32, 0x80000000, v161
	v_cvt_pk_bf16_f32 v88, v37, v38
	v_cvt_pk_bf16_f32 v89, v39, v40
	v_cvt_pk_bf16_f32 v90, v41, v42
	v_cvt_pk_bf16_f32 v91, v43, v44
	v_cvt_pk_bf16_f32 v84, v85, v80
	v_cvt_pk_bf16_f32 v80, v53, v54
	v_mov_b32_e32 v33, v32
	v_mov_b32_e32 v34, v32
	v_mov_b32_e32 v35, v32
	v_mov_b32_e32 v36, v32
	v_mov_b32_e32 v37, v32
	v_mov_b32_e32 v38, v32
	v_mov_b32_e32 v39, v32
	v_mov_b32_e32 v40, v32
	v_mov_b32_e32 v41, v32
	v_mov_b32_e32 v42, v32
	v_mov_b32_e32 v43, v32
	v_mov_b32_e32 v44, v32
	v_mov_b32_e32 v45, v32
	v_mov_b32_e32 v46, v32
	v_mov_b32_e32 v47, v32
	v_cvt_pk_bf16_f32 v85, v81, v82
	v_cvt_pk_bf16_f32 v86, v83, v50
	v_cvt_pk_bf16_f32 v87, v51, v52
	v_cvt_pk_bf16_f32 v81, v55, v56
	v_cvt_pk_bf16_f32 v82, v57, v58
	v_cvt_pk_bf16_f32 v83, v59, v60
	s_waitcnt lgkmcnt(2)
	v_mfma_f32_32x32x16_bf16 v[48:63], v[130:133], v[100:103], v[32:47]
	v_mfma_f32_32x32x16_bf16 v[32:47], v[126:129], v[100:103], v[32:47]
	ds_read_b128 v[126:129], v171 offset:13376
	ds_read_b128 v[130:133], v171 offset:17984
	s_waitcnt lgkmcnt(3)
	v_mfma_f32_32x32x16_bf16 v[48:63], v[134:137], v[104:107], v[48:63]
	s_waitcnt lgkmcnt(2)
	v_mfma_f32_32x32x16_bf16 v[32:47], v[138:141], v[104:107], v[32:47]
	ds_read_b128 v[134:137], v171 offset:13408
	ds_read_b128 v[138:141], v171 offset:18016
	s_waitcnt lgkmcnt(3)
	v_mfma_f32_32x32x16_bf16 v[48:63], v[126:129], v[108:111], v[48:63]
	s_waitcnt lgkmcnt(2)
	v_mfma_f32_32x32x16_bf16 v[32:47], v[130:133], v[108:111], v[32:47]
	ds_read_b64_tr_b16 v[126:127], v153 offset:26624
	ds_read_b64_tr_b16 v[128:129], v153 offset:27776
	ds_read_b64_tr_b16 v[132:133], v153 offset:27840
	ds_read_b64_tr_b16 v[130:131], v153 offset:26688
	s_waitcnt lgkmcnt(5)
	v_mfma_f32_32x32x16_bf16 v[48:63], v[134:137], v[112:115], v[48:63]
	s_waitcnt lgkmcnt(4)
	v_mfma_f32_32x32x16_bf16 v[32:47], v[138:141], v[112:115], v[32:47]
	ds_read_b64_tr_b16 v[134:135], v153 offset:28928
	ds_read_b64_tr_b16 v[136:137], v153 offset:30080
	ds_read_b64_tr_b16 v[140:141], v153 offset:30144
	ds_read_b64_tr_b16 v[138:139], v153 offset:28992
	s_waitcnt lgkmcnt(6)
	v_mfma_f32_32x32x16_bf16 v[16:31], v[126:129], v[92:95], v[16:31]
	s_waitcnt lgkmcnt(4)
	v_mfma_f32_32x32x16_bf16 v[0:15], v[130:133], v[92:95], v[0:15]
	ds_read_b64_tr_b16 v[92:93], v153 offset:31232
	ds_read_b64_tr_b16 v[94:95], v153 offset:32384
	ds_read_b64_tr_b16 v[128:129], v153 offset:32448
	ds_read_b64_tr_b16 v[126:127], v153 offset:31296
	s_waitcnt lgkmcnt(6)
	v_mfma_f32_32x32x16_bf16 v[16:31], v[134:137], v[88:91], v[16:31]
	s_waitcnt lgkmcnt(4)
	v_mfma_f32_32x32x16_bf16 v[0:15], v[138:141], v[88:91], v[0:15]
	ds_read_b64_tr_b16 v[88:89], v153 offset:33536
	ds_read_b64_tr_b16 v[90:91], v153 offset:34688
	ds_read_b64_tr_b16 v[132:133], v153 offset:34752
	ds_read_b64_tr_b16 v[130:131], v153 offset:33600
	s_waitcnt lgkmcnt(6)
	v_mfma_f32_32x32x16_bf16 v[16:31], v[92:95], v[84:87], v[16:31]
	s_waitcnt lgkmcnt(4)
	v_mfma_f32_32x32x16_bf16 v[0:15], v[126:129], v[84:87], v[0:15]
	s_waitcnt lgkmcnt(2)
	v_mfma_f32_32x32x16_bf16 v[16:31], v[88:91], v[80:83], v[16:31]
	s_waitcnt lgkmcnt(0)
	v_mfma_f32_32x32x16_bf16 v[0:15], v[130:133], v[80:83], v[0:15]
	s_nop 15
	s_nop 7
	s_nop 0
	v_max3_f32 v80, v48, v49, v32
	v_max3_f32 v81, v50, v51, v33
	s_nop 0
	v_max3_f32 v80, v80, v34, v35
	v_max3_f32 v81, v81, v54, v55
	s_nop 0
	v_max3_f32 v80, v80, v52, v53
	v_max3_f32 v81, v81, v38, v39
	s_nop 0
	v_max3_f32 v80, v80, v36, v37
	v_max3_f32 v81, v81, v58, v59
	s_nop 0
	v_max3_f32 v80, v80, v56, v57
	v_max3_f32 v81, v81, v42, v43
	s_nop 0
	v_max3_f32 v80, v80, v40, v41
	v_max3_f32 v81, v81, v62, v63
	s_nop 0
	v_max3_f32 v80, v80, v60, v61
	v_max3_f32 v81, v81, v46, v47
	s_nop 0
	v_max3_f32 v80, v80, v44, v45
	s_nop 0
	v_max3_f32 v80, v80, v81, v81
	v_mov_b32_e32 v81, v80
	s_nop 1
	v_permlane32_swap_b32 v81, v80
	v_max_f32_e32 v80, v80, v81
	s_waitcnt lgkmcnt(0)
	s_nop 0
	v_cmp_lt_f32_e32 vcc, s78, v80
	s_cbranch_vccz .LBB0_444
	v_max_f32_e32 v80, v80, v80
	v_max_f32_e32 v80, 0, v80
	v_exp_f32_e64 v82, -v80
	v_add_f32_e32 v161, v161, v80
	v_pk_add_f32 v[48:49], v[48:49], v[80:81] op_sel_hi:[1,0] neg_lo:[0,1] neg_hi:[0,1]
	v_pk_add_f32 v[32:33], v[32:33], v[80:81] op_sel_hi:[1,0] neg_lo:[0,1] neg_hi:[0,1]
	v_mul_f32_e32 v125, v125, v82
	v_pk_add_f32 v[50:51], v[50:51], v[80:81] op_sel_hi:[1,0] neg_lo:[0,1] neg_hi:[0,1]
	v_pk_add_f32 v[34:35], v[34:35], v[80:81] op_sel_hi:[1,0] neg_lo:[0,1] neg_hi:[0,1]
	v_pk_add_f32 v[52:53], v[52:53], v[80:81] op_sel_hi:[1,0] neg_lo:[0,1] neg_hi:[0,1]
	v_pk_add_f32 v[36:37], v[36:37], v[80:81] op_sel_hi:[1,0] neg_lo:[0,1] neg_hi:[0,1]
	v_pk_add_f32 v[54:55], v[54:55], v[80:81] op_sel_hi:[1,0] neg_lo:[0,1] neg_hi:[0,1]
	v_pk_add_f32 v[38:39], v[38:39], v[80:81] op_sel_hi:[1,0] neg_lo:[0,1] neg_hi:[0,1]
	v_pk_add_f32 v[56:57], v[56:57], v[80:81] op_sel_hi:[1,0] neg_lo:[0,1] neg_hi:[0,1]
	v_pk_add_f32 v[40:41], v[40:41], v[80:81] op_sel_hi:[1,0] neg_lo:[0,1] neg_hi:[0,1]
	v_pk_add_f32 v[58:59], v[58:59], v[80:81] op_sel_hi:[1,0] neg_lo:[0,1] neg_hi:[0,1]
	v_pk_add_f32 v[42:43], v[42:43], v[80:81] op_sel_hi:[1,0] neg_lo:[0,1] neg_hi:[0,1]
	v_pk_add_f32 v[60:61], v[60:61], v[80:81] op_sel_hi:[1,0] neg_lo:[0,1] neg_hi:[0,1]
	v_pk_add_f32 v[44:45], v[44:45], v[80:81] op_sel_hi:[1,0] neg_lo:[0,1] neg_hi:[0,1]
	v_pk_add_f32 v[62:63], v[62:63], v[80:81] op_sel_hi:[1,0] neg_lo:[0,1] neg_hi:[0,1]
	v_pk_add_f32 v[46:47], v[46:47], v[80:81] op_sel_hi:[1,0] neg_lo:[0,1] neg_hi:[0,1]
	v_pk_mul_f32 v[30:31], v[30:31], v[82:83] op_sel_hi:[1,0]
	v_pk_mul_f32 v[28:29], v[28:29], v[82:83] op_sel_hi:[1,0]
	v_pk_mul_f32 v[26:27], v[26:27], v[82:83] op_sel_hi:[1,0]
	v_pk_mul_f32 v[24:25], v[24:25], v[82:83] op_sel_hi:[1,0]
	v_pk_mul_f32 v[22:23], v[22:23], v[82:83] op_sel_hi:[1,0]
	v_pk_mul_f32 v[20:21], v[20:21], v[82:83] op_sel_hi:[1,0]
	v_pk_mul_f32 v[18:19], v[18:19], v[82:83] op_sel_hi:[1,0]
	v_pk_mul_f32 v[16:17], v[16:17], v[82:83] op_sel_hi:[1,0]
	v_pk_mul_f32 v[14:15], v[14:15], v[82:83] op_sel_hi:[1,0]
	v_pk_mul_f32 v[12:13], v[12:13], v[82:83] op_sel_hi:[1,0]
	v_pk_mul_f32 v[10:11], v[10:11], v[82:83] op_sel_hi:[1,0]
	v_pk_mul_f32 v[8:9], v[8:9], v[82:83] op_sel_hi:[1,0]
	v_pk_mul_f32 v[6:7], v[6:7], v[82:83] op_sel_hi:[1,0]
	v_pk_mul_f32 v[4:5], v[4:5], v[82:83] op_sel_hi:[1,0]
	v_pk_mul_f32 v[2:3], v[2:3], v[82:83] op_sel_hi:[1,0]
	v_pk_mul_f32 v[0:1], v[0:1], v[82:83] op_sel_hi:[1,0]

.LBB0_446:
	s_add_i32 s11, s16, -1
	s_and_b32 s12, s11, 1
	s_mul_i32 s0, s12, 0x3400
	v_add_u32_e32 v48, s0, v171
	ds_read_b128 v[126:129], v48
	ds_read_b128 v[134:137], v48 offset:32
	ds_read_b128 v[138:141], v48 offset:4608
	ds_read_b128 v[142:145], v48 offset:4640
	s_and_b32 s17, s16, 1
	v_xor_b32_e32 v50, 0x80000000, v161
	s_mul_i32 s0, s17, 0x2400
	v_mov_b32_e32 v51, v50
	v_mov_b32_e32 v52, v50
	v_mov_b32_e32 v53, v50
	v_mov_b32_e32 v54, v50
	v_mov_b32_e32 v55, v50
	v_mov_b32_e32 v56, v50
	v_mov_b32_e32 v57, v50
	v_mov_b32_e32 v58, v50
	v_mov_b32_e32 v59, v50
	v_mov_b32_e32 v60, v50
	v_mov_b32_e32 v61, v50
	v_mov_b32_e32 v62, v50
	v_mov_b32_e32 v63, v50
	v_mov_b32_e32 v64, v50
	v_mov_b32_e32 v65, v50
	v_add_u32_e32 v49, s0, v153
	s_waitcnt lgkmcnt(3)
	v_mfma_f32_32x32x16_bf16 v[66:81], v[126:129], v[100:103], v[50:65]
	s_waitcnt lgkmcnt(1)
	v_mfma_f32_32x32x16_bf16 v[50:65], v[138:141], v[100:103], v[50:65]
	ds_read_b128 v[126:129], v48 offset:64
	ds_read_b128 v[138:141], v48 offset:4672
	v_mfma_f32_32x32x16_bf16 v[66:81], v[134:137], v[104:107], v[66:81]
	s_waitcnt lgkmcnt(2)
	v_mfma_f32_32x32x16_bf16 v[50:65], v[142:145], v[104:107], v[50:65]
	ds_read_b128 v[134:137], v48 offset:96
	ds_read_b128 v[142:145], v48 offset:4704
	s_waitcnt lgkmcnt(3)
	v_mfma_f32_32x32x16_bf16 v[66:81], v[126:129], v[108:111], v[66:81]
	s_waitcnt lgkmcnt(2)
	v_mfma_f32_32x32x16_bf16 v[50:65], v[138:141], v[108:111], v[50:65]
	ds_read_b64_tr_b16 v[126:127], v49 offset:26624
	ds_read_b64_tr_b16 v[128:129], v49 offset:27776
	ds_read_b64_tr_b16 v[140:141], v49 offset:27840
	ds_read_b64_tr_b16 v[138:139], v49 offset:26688
	s_waitcnt lgkmcnt(5)
	v_mfma_f32_32x32x16_bf16 v[66:81], v[134:137], v[112:115], v[66:81]
	s_waitcnt lgkmcnt(4)
	v_mfma_f32_32x32x16_bf16 v[50:65], v[142:145], v[112:115], v[50:65]
	ds_read_b64_tr_b16 v[134:135], v49 offset:28928
	ds_read_b64_tr_b16 v[136:137], v49 offset:30080
	ds_read_b64_tr_b16 v[144:145], v49 offset:30144
	ds_read_b64_tr_b16 v[142:143], v49 offset:28992
	s_waitcnt lgkmcnt(6)
	v_mfma_f32_32x32x16_bf16 v[16:31], v[126:129], v[44:47], v[16:31]
	s_waitcnt lgkmcnt(4)
	v_mfma_f32_32x32x16_bf16 v[0:15], v[138:141], v[44:47], v[0:15]
	ds_read_b64_tr_b16 v[44:45], v49 offset:31232
	ds_read_b64_tr_b16 v[46:47], v49 offset:32384
	ds_read_b64_tr_b16 v[128:129], v49 offset:32448
	ds_read_b64_tr_b16 v[126:127], v49 offset:31296
	s_waitcnt lgkmcnt(6)
	v_mfma_f32_32x32x16_bf16 v[16:31], v[134:137], v[40:43], v[16:31]
	s_waitcnt lgkmcnt(4)
	v_mfma_f32_32x32x16_bf16 v[0:15], v[142:145], v[40:43], v[0:15]
	ds_read_b64_tr_b16 v[40:41], v49 offset:33536
	ds_read_b64_tr_b16 v[42:43], v49 offset:34688
	ds_read_b64_tr_b16 v[136:137], v49 offset:34752
	ds_read_b64_tr_b16 v[134:135], v49 offset:33600
	s_waitcnt lgkmcnt(6)
	v_mfma_f32_32x32x16_bf16 v[16:31], v[44:47], v[36:39], v[16:31]
	s_waitcnt lgkmcnt(4)
	v_mfma_f32_32x32x16_bf16 v[0:15], v[126:129], v[36:39], v[0:15]
	s_waitcnt lgkmcnt(2)
	v_mfma_f32_32x32x16_bf16 v[16:31], v[40:43], v[32:35], v[16:31]
	s_waitcnt lgkmcnt(0)
	v_mfma_f32_32x32x16_bf16 v[0:15], v[134:137], v[32:35], v[0:15]
	s_add_i32 s0, s6, -4
	s_and_b32 s10, s0, 28
	s_sub_i32 s0, s7, 32
	v_and_or_b32 v48, s0, 16, v148
	s_add_i32 s10, s10, s15
	v_add_u32_e32 v48, s8, v48
	v_sub_u32_e32 v98, v48, v166
	v_sub_u32_e32 v49, s10, v151
	v_lshlrev_b32_e32 v98, 2, v98
	v_mad_i32_i24 v98, v49, s5, v98
	v_add_u32_e32 v98, 0x163a0, v98
	ds_read2_b32 v[126:127], v98 offset0:62 offset1:63
	ds_read2_b32 v[128:129], v98 offset0:64 offset1:65
	ds_read2_b32 v[134:135], v98 offset0:70 offset1:71
	ds_read2_b32 v[136:137], v98 offset0:72 offset1:73
	ds_read2_b32 v[138:139], v98 offset0:93 offset1:94
	ds_read2_b32 v[140:141], v98 offset0:95 offset1:96
	ds_read2_b32 v[142:143], v98 offset0:101 offset1:102
	ds_read2_b32 v[144:145], v98 offset0:103 offset1:104
	v_sub_u32_e32 v48, v48, v170
	v_sub_u32_e32 v49, s10, v169
	v_cmp_gt_u32_e64 s[38:39], 16, v48
	v_add_u32_e32 v48, 1, v48
	v_cmp_gt_u32_e64 s[40:41], 16, v48
	v_add_u32_e32 v48, 1, v48
	v_cmp_gt_u32_e64 s[42:43], 16, v48
	v_add_u32_e32 v48, 1, v48
	v_cmp_gt_u32_e64 s[44:45], 16, v48
	v_add_u32_e32 v48, 5, v48
	v_cmp_gt_u32_e64 s[46:47], 16, v48
	v_add_u32_e32 v48, 1, v48
	v_cmp_gt_u32_e64 s[48:49], 16, v48
	v_add_u32_e32 v48, 1, v48
	v_cmp_gt_u32_e64 s[50:51], 16, v48
	v_add_u32_e32 v48, 1, v48
	v_cmp_gt_u32_e64 s[52:53], 16, v48
	v_add_u32_e32 v49, 2, v49
	v_cmp_gt_u32_e64 s[54:55], 8, v49
	v_add_u32_e32 v49, 1, v49
	v_cmp_gt_u32_e64 s[18:19], 8, v49
	s_waitcnt lgkmcnt(0)
	v_add_f32_e32 v126, v50, v126
	v_add_f32_e32 v127, v51, v127
	v_add_f32_e32 v128, v52, v128
	v_add_f32_e32 v129, v53, v129
	v_add_f32_e32 v134, v54, v134
	v_add_f32_e32 v135, v55, v135
	v_add_f32_e32 v136, v56, v136
	v_add_f32_e32 v137, v57, v137
	v_add_f32_e32 v138, v58, v138
	v_add_f32_e32 v139, v59, v139
	v_add_f32_e32 v140, v60, v140
	v_add_f32_e32 v141, v61, v141
	v_add_f32_e32 v142, v62, v142
	v_add_f32_e32 v143, v63, v143
	v_add_f32_e32 v144, v64, v144
	v_add_f32_e32 v145, v65, v145
	ds_read2_b32 v[50:51], v98 offset0:0 offset1:1
	ds_read2_b32 v[52:53], v98 offset0:2 offset1:3
	ds_read2_b32 v[54:55], v98 offset0:8 offset1:9
	ds_read2_b32 v[56:57], v98 offset0:10 offset1:11
	ds_read2_b32 v[58:59], v98 offset0:31 offset1:32
	ds_read2_b32 v[60:61], v98 offset0:33 offset1:34
	ds_read2_b32 v[62:63], v98 offset0:39 offset1:40
	ds_read2_b32 v[64:65], v98 offset0:41 offset1:42
	s_and_b64 vcc, s[38:39], s[54:55]
	v_cndmask_b32_e32 v32, v233, v126, vcc
	s_and_b64 vcc, s[40:41], s[54:55]
	v_cndmask_b32_e32 v33, v233, v127, vcc
	s_and_b64 vcc, s[42:43], s[54:55]
	v_cndmask_b32_e32 v34, v233, v128, vcc
	s_and_b64 vcc, s[44:45], s[54:55]
	v_cndmask_b32_e32 v35, v233, v129, vcc
	s_and_b64 vcc, s[46:47], s[54:55]
	v_cndmask_b32_e32 v36, v233, v134, vcc
	s_and_b64 vcc, s[48:49], s[54:55]
	v_cndmask_b32_e32 v37, v233, v135, vcc
	s_and_b64 vcc, s[50:51], s[54:55]
	v_cndmask_b32_e32 v38, v233, v136, vcc
	s_and_b64 vcc, s[52:53], s[54:55]
	v_cndmask_b32_e32 v39, v233, v137, vcc
	s_and_b64 vcc, s[38:39], s[18:19]
	v_cndmask_b32_e32 v40, v233, v138, vcc
	s_and_b64 vcc, s[40:41], s[18:19]
	v_cndmask_b32_e32 v41, v233, v139, vcc
	s_and_b64 vcc, s[42:43], s[18:19]
	v_cndmask_b32_e32 v42, v233, v140, vcc
	s_and_b64 vcc, s[44:45], s[18:19]
	v_cndmask_b32_e32 v43, v233, v141, vcc
	s_and_b64 vcc, s[46:47], s[18:19]
	v_cndmask_b32_e32 v44, v233, v142, vcc
	s_and_b64 vcc, s[48:49], s[18:19]
	v_cndmask_b32_e32 v45, v233, v143, vcc
	s_and_b64 vcc, s[50:51], s[18:19]
	v_cndmask_b32_e32 v46, v233, v144, vcc
	s_and_b64 vcc, s[52:53], s[18:19]
	v_cndmask_b32_e32 v47, v233, v145, vcc
	v_add_u32_e32 v49, -3, v49
	v_cmp_gt_u32_e64 s[54:55], 8, v49
	v_add_u32_e32 v49, 1, v49
	v_cmp_gt_u32_e64 s[18:19], 8, v49
	s_waitcnt lgkmcnt(0)
	v_add_f32_e32 v50, v66, v50
	v_add_f32_e32 v51, v67, v51
	v_add_f32_e32 v52, v68, v52
	v_add_f32_e32 v53, v69, v53
	v_add_f32_e32 v54, v70, v54
	v_add_f32_e32 v55, v71, v55
	v_add_f32_e32 v56, v72, v56
	v_add_f32_e32 v57, v73, v57
	v_add_f32_e32 v58, v74, v58
	v_add_f32_e32 v59, v75, v59
	v_add_f32_e32 v60, v76, v60
	v_add_f32_e32 v61, v77, v61
	v_add_f32_e32 v62, v78, v62
	v_add_f32_e32 v63, v79, v63
	v_add_f32_e32 v64, v80, v64
	v_add_f32_e32 v65, v81, v65
	s_and_b64 vcc, s[38:39], s[54:55]
	v_cndmask_b32_e32 v48, v233, v50, vcc
	s_and_b64 vcc, s[40:41], s[54:55]
	v_cndmask_b32_e32 v49, v233, v51, vcc
	s_and_b64 vcc, s[42:43], s[54:55]
	v_cndmask_b32_e32 v50, v233, v52, vcc
	s_and_b64 vcc, s[44:45], s[54:55]
	v_cndmask_b32_e32 v51, v233, v53, vcc
	s_and_b64 vcc, s[46:47], s[54:55]
	v_cndmask_b32_e32 v52, v233, v54, vcc
	s_and_b64 vcc, s[48:49], s[54:55]
	v_cndmask_b32_e32 v53, v233, v55, vcc
	s_and_b64 vcc, s[50:51], s[54:55]
	v_cndmask_b32_e32 v54, v233, v56, vcc
	s_and_b64 vcc, s[52:53], s[54:55]
	v_cndmask_b32_e32 v55, v233, v57, vcc
	s_and_b64 vcc, s[38:39], s[18:19]
	v_cndmask_b32_e32 v56, v233, v58, vcc
	s_and_b64 vcc, s[40:41], s[18:19]
	v_cndmask_b32_e32 v57, v233, v59, vcc
	s_and_b64 vcc, s[42:43], s[18:19]
	v_cndmask_b32_e32 v58, v233, v60, vcc
	s_and_b64 vcc, s[44:45], s[18:19]
	v_cndmask_b32_e32 v59, v233, v61, vcc
	s_and_b64 vcc, s[46:47], s[18:19]
	v_cndmask_b32_e32 v60, v233, v62, vcc
	s_and_b64 vcc, s[48:49], s[18:19]
	v_cndmask_b32_e32 v61, v233, v63, vcc
	s_and_b64 vcc, s[50:51], s[18:19]
	v_cndmask_b32_e32 v62, v233, v64, vcc
	s_and_b64 vcc, s[52:53], s[18:19]
	v_cndmask_b32_e32 v63, v233, v65, vcc
	v_max3_f32 v64, v48, v49, v32
	v_max3_f32 v65, v50, v51, v33
	s_nop 0
	v_max3_f32 v64, v64, v34, v35
	v_max3_f32 v65, v65, v54, v55
	s_nop 0
	v_max3_f32 v64, v64, v52, v53
	v_max3_f32 v65, v65, v38, v39
	s_nop 0
	v_max3_f32 v64, v64, v36, v37
	v_max3_f32 v65, v65, v58, v59
	s_nop 0
	v_max3_f32 v64, v64, v56, v57
	v_max3_f32 v65, v65, v42, v43
	s_nop 0
	v_max3_f32 v64, v64, v40, v41
	v_max3_f32 v65, v65, v62, v63
	s_nop 0
	v_max3_f32 v64, v64, v60, v61
	v_max3_f32 v65, v65, v46, v47
	s_nop 0
	v_max3_f32 v64, v64, v44, v45
	s_nop 0
	v_max3_f32 v64, v64, v65, v65
	v_mov_b32_e32 v65, v64
	s_nop 1
	v_permlane32_swap_b32 v65, v64
	v_max_f32_e32 v64, v64, v65
	s_waitcnt lgkmcnt(0)
	s_nop 0
	v_cmp_lt_f32_e32 vcc, s78, v64
	s_cbranch_vccz .LBB0_512
	v_max_f32_e32 v64, v64, v64
	v_max_f32_e32 v64, 0, v64
	v_exp_f32_e64 v66, -v64
	v_add_f32_e32 v161, v161, v64
	v_pk_add_f32 v[48:49], v[48:49], v[64:65] op_sel_hi:[1,0] neg_lo:[0,1] neg_hi:[0,1]
	v_pk_add_f32 v[32:33], v[32:33], v[64:65] op_sel_hi:[1,0] neg_lo:[0,1] neg_hi:[0,1]
	v_mul_f32_e32 v132, v132, v66
	v_pk_add_f32 v[50:51], v[50:51], v[64:65] op_sel_hi:[1,0] neg_lo:[0,1] neg_hi:[0,1]
	v_pk_add_f32 v[34:35], v[34:35], v[64:65] op_sel_hi:[1,0] neg_lo:[0,1] neg_hi:[0,1]
	v_pk_add_f32 v[52:53], v[52:53], v[64:65] op_sel_hi:[1,0] neg_lo:[0,1] neg_hi:[0,1]
	v_pk_add_f32 v[36:37], v[36:37], v[64:65] op_sel_hi:[1,0] neg_lo:[0,1] neg_hi:[0,1]
	v_pk_add_f32 v[54:55], v[54:55], v[64:65] op_sel_hi:[1,0] neg_lo:[0,1] neg_hi:[0,1]
	v_pk_add_f32 v[38:39], v[38:39], v[64:65] op_sel_hi:[1,0] neg_lo:[0,1] neg_hi:[0,1]
	v_pk_add_f32 v[56:57], v[56:57], v[64:65] op_sel_hi:[1,0] neg_lo:[0,1] neg_hi:[0,1]
	v_pk_add_f32 v[40:41], v[40:41], v[64:65] op_sel_hi:[1,0] neg_lo:[0,1] neg_hi:[0,1]
	v_pk_add_f32 v[58:59], v[58:59], v[64:65] op_sel_hi:[1,0] neg_lo:[0,1] neg_hi:[0,1]
	v_pk_add_f32 v[42:43], v[42:43], v[64:65] op_sel_hi:[1,0] neg_lo:[0,1] neg_hi:[0,1]
	v_pk_add_f32 v[60:61], v[60:61], v[64:65] op_sel_hi:[1,0] neg_lo:[0,1] neg_hi:[0,1]
	v_pk_add_f32 v[44:45], v[44:45], v[64:65] op_sel_hi:[1,0] neg_lo:[0,1] neg_hi:[0,1]
	v_pk_add_f32 v[62:63], v[62:63], v[64:65] op_sel_hi:[1,0] neg_lo:[0,1] neg_hi:[0,1]
	v_pk_add_f32 v[46:47], v[46:47], v[64:65] op_sel_hi:[1,0] neg_lo:[0,1] neg_hi:[0,1]
	v_pk_mul_f32 v[30:31], v[30:31], v[66:67] op_sel_hi:[1,0]
	v_pk_mul_f32 v[28:29], v[28:29], v[66:67] op_sel_hi:[1,0]
	v_pk_mul_f32 v[26:27], v[26:27], v[66:67] op_sel_hi:[1,0]
	v_pk_mul_f32 v[24:25], v[24:25], v[66:67] op_sel_hi:[1,0]
	v_pk_mul_f32 v[22:23], v[22:23], v[66:67] op_sel_hi:[1,0]
	v_pk_mul_f32 v[20:21], v[20:21], v[66:67] op_sel_hi:[1,0]
	v_pk_mul_f32 v[18:19], v[18:19], v[66:67] op_sel_hi:[1,0]
	v_pk_mul_f32 v[16:17], v[16:17], v[66:67] op_sel_hi:[1,0]
	v_pk_mul_f32 v[14:15], v[14:15], v[66:67] op_sel_hi:[1,0]
	v_pk_mul_f32 v[12:13], v[12:13], v[66:67] op_sel_hi:[1,0]
	v_pk_mul_f32 v[10:11], v[10:11], v[66:67] op_sel_hi:[1,0]
	v_pk_mul_f32 v[8:9], v[8:9], v[66:67] op_sel_hi:[1,0]
	v_pk_mul_f32 v[6:7], v[6:7], v[66:67] op_sel_hi:[1,0]
	v_pk_mul_f32 v[4:5], v[4:5], v[66:67] op_sel_hi:[1,0]
	v_pk_mul_f32 v[2:3], v[2:3], v[66:67] op_sel_hi:[1,0]
	v_pk_mul_f32 v[0:1], v[0:1], v[66:67] op_sel_hi:[1,0]

.LBB0_539:
	s_or_b64 exec, exec, s[6:7]
	v_add_u32_e32 v34, 0x8080, v142
	v_ashrrev_i32_e32 v35, 31, v34
	v_lshlrev_b64 v[34:35], 10, v[34:35]
	v_lshl_add_u64 v[34:35], s[92:93], 0, v[34:35]
	v_lshl_add_u64 v[34:35], v[34:35], 0, s[68:69]
	v_lshl_add_u64 v[34:35], v[34:35], 0, v[98:99]
	global_load_dwordx4 v[130:133], v[34:35], off offset:128
	v_max3_f32 v33, v48, v49, v64
	v_max3_f32 v34, v50, v51, v65
	s_waitcnt lgkmcnt(0)
	s_barrier
	s_nop 0
	v_max3_f32 v33, v33, v66, v67
	v_max3_f32 v34, v34, v54, v55
	s_nop 0
	v_max3_f32 v33, v33, v52, v53
	v_max3_f32 v34, v34, v70, v71
	s_nop 0
	v_max3_f32 v33, v33, v68, v69
	v_max3_f32 v34, v34, v58, v59
	s_nop 0
	v_max3_f32 v33, v33, v56, v57
	v_max3_f32 v34, v34, v74, v75
	s_nop 0
	v_max3_f32 v33, v33, v72, v73
	v_max3_f32 v34, v34, v62, v63
	s_nop 0
	v_max3_f32 v33, v33, v60, v61
	v_max3_f32 v34, v34, v78, v79
	s_nop 0
	v_max3_f32 v33, v33, v76, v77
	s_nop 0
	v_max3_f32 v33, v33, v34, v34
	v_mov_b32_e32 v34, v33
	s_nop 1
	v_permlane32_swap_b32 v34, v33
	v_max_f32_e32 v33, v33, v34
	s_waitcnt lgkmcnt(0)
	s_nop 0
	v_cmp_lt_f32_e32 vcc, s78, v33
	s_cbranch_vccz .LBB0_541
	v_max_f32_e32 v32, v33, v33
	v_max_f32_e32 v32, 0, v32
	v_exp_f32_e64 v34, -v32
	v_add_f32_e32 v139, v139, v32
	v_pk_add_f32 v[48:49], v[48:49], v[32:33] op_sel_hi:[1,0] neg_lo:[0,1] neg_hi:[0,1]
	v_pk_add_f32 v[64:65], v[64:65], v[32:33] op_sel_hi:[1,0] neg_lo:[0,1] neg_hi:[0,1]
	v_pk_add_f32 v[50:51], v[50:51], v[32:33] op_sel_hi:[1,0] neg_lo:[0,1] neg_hi:[0,1]
	v_pk_add_f32 v[66:67], v[66:67], v[32:33] op_sel_hi:[1,0] neg_lo:[0,1] neg_hi:[0,1]
	v_pk_add_f32 v[52:53], v[52:53], v[32:33] op_sel_hi:[1,0] neg_lo:[0,1] neg_hi:[0,1]
	v_pk_add_f32 v[68:69], v[68:69], v[32:33] op_sel_hi:[1,0] neg_lo:[0,1] neg_hi:[0,1]
	v_pk_add_f32 v[54:55], v[54:55], v[32:33] op_sel_hi:[1,0] neg_lo:[0,1] neg_hi:[0,1]
	v_pk_add_f32 v[70:71], v[70:71], v[32:33] op_sel_hi:[1,0] neg_lo:[0,1] neg_hi:[0,1]
	v_pk_add_f32 v[56:57], v[56:57], v[32:33] op_sel_hi:[1,0] neg_lo:[0,1] neg_hi:[0,1]
	v_pk_add_f32 v[72:73], v[72:73], v[32:33] op_sel_hi:[1,0] neg_lo:[0,1] neg_hi:[0,1]
	v_pk_add_f32 v[58:59], v[58:59], v[32:33] op_sel_hi:[1,0] neg_lo:[0,1] neg_hi:[0,1]
	v_pk_add_f32 v[74:75], v[74:75], v[32:33] op_sel_hi:[1,0] neg_lo:[0,1] neg_hi:[0,1]
	v_pk_add_f32 v[60:61], v[60:61], v[32:33] op_sel_hi:[1,0] neg_lo:[0,1] neg_hi:[0,1]
	v_pk_add_f32 v[76:77], v[76:77], v[32:33] op_sel_hi:[1,0] neg_lo:[0,1] neg_hi:[0,1]
	v_pk_add_f32 v[62:63], v[62:63], v[32:33] op_sel_hi:[1,0] neg_lo:[0,1] neg_hi:[0,1]
	v_pk_add_f32 v[78:79], v[78:79], v[32:33] op_sel_hi:[1,0] neg_lo:[0,1] neg_hi:[0,1]
	v_pk_mul_f32 v[30:31], v[30:31], v[34:35] op_sel_hi:[1,0]
	v_pk_mul_f32 v[28:29], v[28:29], v[34:35] op_sel_hi:[1,0]
	v_pk_mul_f32 v[26:27], v[26:27], v[34:35] op_sel_hi:[1,0]
	v_pk_mul_f32 v[24:25], v[24:25], v[34:35] op_sel_hi:[1,0]
	v_pk_mul_f32 v[22:23], v[22:23], v[34:35] op_sel_hi:[1,0]
	v_pk_mul_f32 v[20:21], v[20:21], v[34:35] op_sel_hi:[1,0]
	v_pk_mul_f32 v[18:19], v[18:19], v[34:35] op_sel_hi:[1,0]
	v_pk_mul_f32 v[16:17], v[16:17], v[34:35] op_sel_hi:[1,0]
	v_pk_mul_f32 v[14:15], v[14:15], v[34:35] op_sel_hi:[1,0]
	v_pk_mul_f32 v[12:13], v[12:13], v[34:35] op_sel_hi:[1,0]
	v_pk_mul_f32 v[10:11], v[10:11], v[34:35] op_sel_hi:[1,0]
	v_pk_mul_f32 v[8:9], v[8:9], v[34:35] op_sel_hi:[1,0]
	v_pk_mul_f32 v[6:7], v[6:7], v[34:35] op_sel_hi:[1,0]
	v_pk_mul_f32 v[4:5], v[4:5], v[34:35] op_sel_hi:[1,0]
	v_pk_mul_f32 v[2:3], v[2:3], v[34:35] op_sel_hi:[1,0]
	v_pk_mul_f32 v[0:1], v[0:1], v[34:35] op_sel_hi:[1,0]
	v_xor_b32_e32 v32, 0x80000000, v139
	v_mul_f32_e32 v138, v138, v34

.LBB0_559:
	v_max3_f32 v65, v48, v49, v32
	v_max3_f32 v66, v50, v51, v33
	s_nop 0
	v_max3_f32 v65, v65, v34, v35
	v_max3_f32 v66, v66, v54, v55
	s_nop 0
	v_max3_f32 v65, v65, v52, v53
	v_max3_f32 v66, v66, v38, v39
	s_nop 0
	v_max3_f32 v65, v65, v36, v37
	v_max3_f32 v66, v66, v58, v59
	s_nop 0
	v_max3_f32 v65, v65, v56, v57
	v_max3_f32 v66, v66, v42, v43
	s_nop 0
	v_max3_f32 v65, v65, v40, v41
	v_max3_f32 v66, v66, v62, v63
	s_nop 0
	v_max3_f32 v65, v65, v60, v61
	v_max3_f32 v66, v66, v46, v47
	s_nop 0
	v_max3_f32 v65, v65, v44, v45
	s_nop 0
	v_max3_f32 v65, v65, v66, v66
	v_mov_b32_e32 v66, v65
	s_nop 1
	v_permlane32_swap_b32 v66, v65
	v_max_f32_e32 v65, v65, v66
	s_waitcnt lgkmcnt(0)
	s_nop 0
	v_cmp_lt_f32_e32 vcc, s78, v65
	s_cbranch_vccz .LBB0_561
	v_max_f32_e32 v64, v65, v65
	v_max_f32_e32 v64, 0, v64
	v_exp_f32_e64 v66, -v64
	v_add_f32_e32 v65, v139, v64
	v_pk_add_f32 v[48:49], v[48:49], v[64:65] op_sel_hi:[1,0] neg_lo:[0,1] neg_hi:[0,1]
	v_pk_add_f32 v[32:33], v[32:33], v[64:65] op_sel_hi:[1,0] neg_lo:[0,1] neg_hi:[0,1]
	v_mul_f32_e32 v138, v138, v66
	v_pk_add_f32 v[50:51], v[50:51], v[64:65] op_sel_hi:[1,0] neg_lo:[0,1] neg_hi:[0,1]
	v_pk_add_f32 v[34:35], v[34:35], v[64:65] op_sel_hi:[1,0] neg_lo:[0,1] neg_hi:[0,1]
	v_pk_add_f32 v[52:53], v[52:53], v[64:65] op_sel_hi:[1,0] neg_lo:[0,1] neg_hi:[0,1]
	v_pk_add_f32 v[36:37], v[36:37], v[64:65] op_sel_hi:[1,0] neg_lo:[0,1] neg_hi:[0,1]
	v_pk_add_f32 v[54:55], v[54:55], v[64:65] op_sel_hi:[1,0] neg_lo:[0,1] neg_hi:[0,1]
	v_pk_add_f32 v[38:39], v[38:39], v[64:65] op_sel_hi:[1,0] neg_lo:[0,1] neg_hi:[0,1]
	v_pk_add_f32 v[56:57], v[56:57], v[64:65] op_sel_hi:[1,0] neg_lo:[0,1] neg_hi:[0,1]
	v_pk_add_f32 v[40:41], v[40:41], v[64:65] op_sel_hi:[1,0] neg_lo:[0,1] neg_hi:[0,1]
	v_pk_add_f32 v[58:59], v[58:59], v[64:65] op_sel_hi:[1,0] neg_lo:[0,1] neg_hi:[0,1]
	v_pk_add_f32 v[42:43], v[42:43], v[64:65] op_sel_hi:[1,0] neg_lo:[0,1] neg_hi:[0,1]
	v_pk_add_f32 v[60:61], v[60:61], v[64:65] op_sel_hi:[1,0] neg_lo:[0,1] neg_hi:[0,1]
	v_pk_add_f32 v[44:45], v[44:45], v[64:65] op_sel_hi:[1,0] neg_lo:[0,1] neg_hi:[0,1]
	v_pk_add_f32 v[62:63], v[62:63], v[64:65] op_sel_hi:[1,0] neg_lo:[0,1] neg_hi:[0,1]
	v_pk_add_f32 v[46:47], v[46:47], v[64:65] op_sel_hi:[1,0] neg_lo:[0,1] neg_hi:[0,1]
	v_pk_mul_f32 v[30:31], v[30:31], v[66:67] op_sel_hi:[1,0]
	v_pk_mul_f32 v[28:29], v[28:29], v[66:67] op_sel_hi:[1,0]
	v_pk_mul_f32 v[26:27], v[26:27], v[66:67] op_sel_hi:[1,0]
	v_pk_mul_f32 v[24:25], v[24:25], v[66:67] op_sel_hi:[1,0]
	v_pk_mul_f32 v[22:23], v[22:23], v[66:67] op_sel_hi:[1,0]
	v_pk_mul_f32 v[20:21], v[20:21], v[66:67] op_sel_hi:[1,0]
	v_pk_mul_f32 v[18:19], v[18:19], v[66:67] op_sel_hi:[1,0]
	v_pk_mul_f32 v[16:17], v[16:17], v[66:67] op_sel_hi:[1,0]
	v_pk_mul_f32 v[14:15], v[14:15], v[66:67] op_sel_hi:[1,0]
	v_pk_mul_f32 v[12:13], v[12:13], v[66:67] op_sel_hi:[1,0]
	v_pk_mul_f32 v[10:11], v[10:11], v[66:67] op_sel_hi:[1,0]
	v_pk_mul_f32 v[8:9], v[8:9], v[66:67] op_sel_hi:[1,0]
	v_pk_mul_f32 v[6:7], v[6:7], v[66:67] op_sel_hi:[1,0]
	v_pk_mul_f32 v[4:5], v[4:5], v[66:67] op_sel_hi:[1,0]
	v_pk_mul_f32 v[2:3], v[2:3], v[66:67] op_sel_hi:[1,0]
	v_pk_mul_f32 v[0:1], v[0:1], v[66:67] op_sel_hi:[1,0]
	v_xor_b32_e32 v64, 0x80000000, v65
.LBB0_561:
	v_exp_f32_e32 v139, v48
	v_exp_f32_e32 v157, v32
	v_exp_f32_e32 v32, v49
	s_waitcnt vmcnt(1)
	v_exp_f32_e32 v122, v33
	v_mov_b32_e32 v33, v99
	v_add_f32_e32 v123, v157, v139
	v_exp_f32_e32 v130, v35
	v_pk_add_f32 v[48:49], v[122:123], v[32:33]
	v_exp_f32_e32 v33, v50
	v_pk_add_f32 v[124:125], v[48:49], v[48:49] op_sel_hi:[0,1]
	v_exp_f32_e32 v49, v34
	v_exp_f32_e32 v124, v51
	v_exp_f32_e32 v52, v52
	v_exp_f32_e32 v123, v36
	v_add_f32_e32 v131, v49, v33
	v_pk_add_f32 v[34:35], v[130:131], v[124:125]
	v_exp_f32_e32 v132, v37
	v_pk_add_f32 v[34:35], v[34:35], v[34:35] op_sel_hi:[0,1]
	v_exp_f32_e32 v34, v53
	v_add_f32_e32 v133, v123, v52
	v_exp_f32_e32 v125, v38
	v_exp_f32_e32 v140, v39
	v_pk_add_f32 v[36:37], v[132:133], v[34:35]
	v_exp_f32_e32 v35, v54
	v_pk_add_f32 v[36:37], v[36:37], v[36:37] op_sel_hi:[0,1]
	v_exp_f32_e32 v36, v55
	v_exp_f32_e32 v131, v40
	v_add_f32_e32 v141, v125, v35
	v_exp_f32_e32 v142, v41
	v_pk_add_f32 v[38:39], v[140:141], v[36:37]
	v_exp_f32_e32 v37, v56
	v_pk_add_f32 v[38:39], v[38:39], v[38:39] op_sel_hi:[0,1]
	v_exp_f32_e32 v38, v57
	v_exp_f32_e32 v133, v42
	v_add_f32_e32 v143, v131, v37
	v_exp_f32_e32 v144, v43
	v_pk_add_f32 v[40:41], v[142:143], v[38:39]
	v_exp_f32_e32 v39, v58
	v_pk_add_f32 v[40:41], v[40:41], v[40:41] op_sel_hi:[0,1]
	v_exp_f32_e32 v40, v59
	v_exp_f32_e32 v141, v44
	v_add_f32_e32 v145, v133, v39
	v_exp_f32_e32 v146, v45
	v_pk_add_f32 v[42:43], v[144:145], v[40:41]
	v_exp_f32_e32 v41, v60
	v_pk_add_f32 v[42:43], v[42:43], v[42:43] op_sel_hi:[0,1]
	v_exp_f32_e32 v42, v61
	v_exp_f32_e32 v158, v47
	v_add_f32_e32 v147, v141, v41
	v_cvt_pk_bf16_f32 v50, v139, v32
	v_pk_add_f32 v[44:45], v[146:147], v[42:43]
	v_exp_f32_e32 v43, v62
	v_pk_add_f32 v[44:45], v[44:45], v[44:45] op_sel_hi:[0,1]
	v_exp_f32_e32 v62, v46
	v_exp_f32_e32 v44, v63
	v_cvt_pk_bf16_f32 v51, v33, v124
	v_cvt_pk_bf16_f32 v58, v157, v122
	v_add_f32_e32 v159, v62, v43
	v_pk_add_f32 v[46:47], v[158:159], v[44:45]
	v_cvt_pk_bf16_f32 v59, v49, v130
	v_add_f32_e32 v45, v46, v47
	v_add_f32_e32 v48, v138, v45
	v_cvt_pk_bf16_f32 v60, v123, v132
	v_cvt_pk_bf16_f32 v61, v125, v140
	v_cvt_pk_bf16_f32 v122, v131, v142
	v_cvt_pk_bf16_f32 v123, v133, v144
	v_cvt_pk_bf16_f32 v124, v141, v146
	v_cvt_pk_bf16_f32 v125, v62, v158
	ds_read_b128 v[130:133], v149 offset:19968
	ds_read_b128 v[138:141], v149 offset:13312
	ds_read_b128 v[142:145], v149 offset:13344
	ds_read_b128 v[158:161], v149 offset:20000
	ds_read_b128 v[162:165], v149 offset:13376
	ds_read_b128 v[166:169], v149 offset:20032
	v_mov_b32_e32 v65, v64
	v_mov_b32_e32 v66, v64
	v_mov_b32_e32 v67, v64
	v_mov_b32_e32 v68, v64
	v_mov_b32_e32 v69, v64
	v_mov_b32_e32 v70, v64
	v_mov_b32_e32 v71, v64
	v_mov_b32_e32 v72, v64
	v_mov_b32_e32 v73, v64
	v_mov_b32_e32 v74, v64
	v_mov_b32_e32 v75, v64
	v_mov_b32_e32 v76, v64
	v_mov_b32_e32 v77, v64
	v_mov_b32_e32 v78, v64
	v_mov_b32_e32 v79, v64
	v_cvt_pk_bf16_f32 v52, v52, v34
	v_cvt_pk_bf16_f32 v53, v35, v36
	v_cvt_pk_bf16_f32 v54, v37, v38
	v_cvt_pk_bf16_f32 v55, v39, v40
	v_cvt_pk_bf16_f32 v56, v41, v42
	v_cvt_pk_bf16_f32 v57, v43, v44
	s_waitcnt lgkmcnt(4)
	v_mfma_f32_32x32x16_bf16 v[32:47], v[138:141], v[106:109], v[64:79]
	v_mfma_f32_32x32x16_bf16 v[64:79], v[130:133], v[106:109], v[64:79]
	ds_read_b128 v[130:133], v149 offset:13408
	ds_read_b128 v[138:141], v149 offset:20064
	s_waitcnt lgkmcnt(5)
	v_mfma_f32_32x32x16_bf16 v[32:47], v[142:145], v[102:105], v[32:47]
	s_waitcnt lgkmcnt(4)
	v_mfma_f32_32x32x16_bf16 v[64:79], v[158:161], v[102:105], v[64:79]
	ds_read_b128 v[142:145], v149 offset:13440
	ds_read_b128 v[158:161], v149 offset:20096
	s_waitcnt lgkmcnt(5)
	v_mfma_f32_32x32x16_bf16 v[32:47], v[162:165], v[92:95], v[32:47]
	s_waitcnt lgkmcnt(4)
	v_mfma_f32_32x32x16_bf16 v[64:79], v[166:169], v[92:95], v[64:79]
	ds_read_b128 v[162:165], v149 offset:13472
	ds_read_b128 v[166:169], v149 offset:20128
	s_waitcnt lgkmcnt(5)
	v_mfma_f32_32x32x16_bf16 v[32:47], v[130:133], v[88:91], v[32:47]
	s_waitcnt lgkmcnt(4)
	v_mfma_f32_32x32x16_bf16 v[64:79], v[138:141], v[88:91], v[64:79]
	ds_read_b64_tr_b16 v[130:131], v97 offset:26624
	ds_read_b64_tr_b16 v[132:133], v97 offset:27776
	ds_read_b64_tr_b16 v[140:141], v97 offset:27840
	ds_read_b64_tr_b16 v[138:139], v97 offset:26688
	s_waitcnt lgkmcnt(7)
	v_mfma_f32_32x32x16_bf16 v[32:47], v[142:145], v[84:87], v[32:47]
	s_waitcnt lgkmcnt(6)
	v_mfma_f32_32x32x16_bf16 v[64:79], v[158:161], v[84:87], v[64:79]
	ds_read_b64_tr_b16 v[142:143], v97 offset:28928
	ds_read_b64_tr_b16 v[144:145], v97 offset:30080
	ds_read_b64_tr_b16 v[160:161], v97 offset:30144
	ds_read_b64_tr_b16 v[158:159], v97 offset:28992
	s_waitcnt lgkmcnt(9)
	v_mfma_f32_32x32x16_bf16 v[32:47], v[162:165], v[80:83], v[32:47]
	s_waitcnt lgkmcnt(8)
	v_mfma_f32_32x32x16_bf16 v[64:79], v[166:169], v[80:83], v[64:79]
	ds_read_b64_tr_b16 v[162:163], v97 offset:31232
	ds_read_b64_tr_b16 v[164:165], v97 offset:32384
	ds_read_b64_tr_b16 v[168:169], v97 offset:32448
	ds_read_b64_tr_b16 v[166:167], v97 offset:31296
	s_waitcnt lgkmcnt(10)
	v_mfma_f32_32x32x16_bf16 v[16:31], v[130:133], v[50:53], v[16:31]
	s_waitcnt lgkmcnt(8)
	v_mfma_f32_32x32x16_bf16 v[0:15], v[138:141], v[50:53], v[0:15]
	ds_read_b64_tr_b16 v[50:51], v97 offset:33536
	ds_read_b64_tr_b16 v[52:53], v97 offset:34688
	ds_read_b64_tr_b16 v[132:133], v97 offset:34752
	ds_read_b64_tr_b16 v[130:131], v97 offset:33600
	s_waitcnt lgkmcnt(10)
	v_mfma_f32_32x32x16_bf16 v[16:31], v[142:145], v[54:57], v[16:31]
	s_waitcnt lgkmcnt(8)
	v_mfma_f32_32x32x16_bf16 v[0:15], v[158:161], v[54:57], v[0:15]
	s_waitcnt lgkmcnt(6)
	v_mfma_f32_32x32x16_bf16 v[16:31], v[162:165], v[58:61], v[16:31]
	s_waitcnt lgkmcnt(4)
	v_mfma_f32_32x32x16_bf16 v[0:15], v[166:169], v[58:61], v[0:15]
	s_waitcnt lgkmcnt(2)
	v_mfma_f32_32x32x16_bf16 v[16:31], v[50:53], v[122:125], v[16:31]
	s_waitcnt lgkmcnt(0)
	v_mfma_f32_32x32x16_bf16 v[0:15], v[130:133], v[122:125], v[0:15]
	v_max3_f32 v49, v32, v33, v64
	v_max3_f32 v50, v34, v35, v65
	s_waitcnt vmcnt(0)
	ds_write_b128 v135, v[126:129] offset:35840
	v_max3_f32 v49, v49, v66, v67
	v_max3_f32 v50, v50, v38, v39
	s_waitcnt lgkmcnt(0)
	s_barrier
	s_nop 0
	v_max3_f32 v49, v49, v36, v37
	v_max3_f32 v50, v50, v70, v71
	s_nop 0
	v_max3_f32 v49, v49, v68, v69
	v_max3_f32 v50, v50, v42, v43
	s_nop 0
	v_max3_f32 v49, v49, v40, v41
	v_max3_f32 v50, v50, v74, v75
	s_nop 0
	v_max3_f32 v49, v49, v72, v73
	v_max3_f32 v50, v50, v46, v47
	s_nop 0
	v_max3_f32 v49, v49, v44, v45
	v_max3_f32 v50, v50, v78, v79
	s_nop 0
	v_max3_f32 v49, v49, v76, v77
	s_nop 0
	v_max3_f32 v49, v49, v50, v50
	v_mov_b32_e32 v50, v49
	s_nop 1
	v_permlane32_swap_b32 v50, v49
	v_max_f32_e32 v49, v49, v50
	s_waitcnt lgkmcnt(0)
	s_nop 0
	v_cmp_lt_f32_e32 vcc, s78, v49
	s_cbranch_vccz .LBB0_563
	v_max_f32_e32 v49, v49, v49
	v_max_f32_e32 v50, 0, v49
	v_exp_f32_e64 v52, -v50
	v_pk_add_f32 v[32:33], v[32:33], v[50:51] op_sel_hi:[1,0] neg_lo:[0,1] neg_hi:[0,1]
	v_pk_add_f32 v[64:65], v[64:65], v[50:51] op_sel_hi:[1,0] neg_lo:[0,1] neg_hi:[0,1]
	v_pk_add_f32 v[34:35], v[34:35], v[50:51] op_sel_hi:[1,0] neg_lo:[0,1] neg_hi:[0,1]
	v_mul_f32_e32 v48, v48, v52
	v_pk_add_f32 v[66:67], v[66:67], v[50:51] op_sel_hi:[1,0] neg_lo:[0,1] neg_hi:[0,1]
	v_pk_add_f32 v[36:37], v[36:37], v[50:51] op_sel_hi:[1,0] neg_lo:[0,1] neg_hi:[0,1]
	v_pk_add_f32 v[68:69], v[68:69], v[50:51] op_sel_hi:[1,0] neg_lo:[0,1] neg_hi:[0,1]
	v_pk_add_f32 v[38:39], v[38:39], v[50:51] op_sel_hi:[1,0] neg_lo:[0,1] neg_hi:[0,1]
	v_pk_add_f32 v[70:71], v[70:71], v[50:51] op_sel_hi:[1,0] neg_lo:[0,1] neg_hi:[0,1]
	v_pk_add_f32 v[40:41], v[40:41], v[50:51] op_sel_hi:[1,0] neg_lo:[0,1] neg_hi:[0,1]
	v_pk_add_f32 v[72:73], v[72:73], v[50:51] op_sel_hi:[1,0] neg_lo:[0,1] neg_hi:[0,1]
	v_pk_add_f32 v[42:43], v[42:43], v[50:51] op_sel_hi:[1,0] neg_lo:[0,1] neg_hi:[0,1]
	v_pk_add_f32 v[74:75], v[74:75], v[50:51] op_sel_hi:[1,0] neg_lo:[0,1] neg_hi:[0,1]
	v_pk_add_f32 v[44:45], v[44:45], v[50:51] op_sel_hi:[1,0] neg_lo:[0,1] neg_hi:[0,1]
	v_pk_add_f32 v[76:77], v[76:77], v[50:51] op_sel_hi:[1,0] neg_lo:[0,1] neg_hi:[0,1]
	v_pk_add_f32 v[46:47], v[46:47], v[50:51] op_sel_hi:[1,0] neg_lo:[0,1] neg_hi:[0,1]
	v_pk_add_f32 v[78:79], v[78:79], v[50:51] op_sel_hi:[1,0] neg_lo:[0,1] neg_hi:[0,1]
	v_pk_mul_f32 v[30:31], v[30:31], v[52:53] op_sel_hi:[1,0]
	v_pk_mul_f32 v[28:29], v[28:29], v[52:53] op_sel_hi:[1,0]
	v_pk_mul_f32 v[26:27], v[26:27], v[52:53] op_sel_hi:[1,0]
	v_pk_mul_f32 v[24:25], v[24:25], v[52:53] op_sel_hi:[1,0]
	v_pk_mul_f32 v[22:23], v[22:23], v[52:53] op_sel_hi:[1,0]
	v_pk_mul_f32 v[20:21], v[20:21], v[52:53] op_sel_hi:[1,0]
	v_pk_mul_f32 v[18:19], v[18:19], v[52:53] op_sel_hi:[1,0]
	v_pk_mul_f32 v[16:17], v[16:17], v[52:53] op_sel_hi:[1,0]
	v_pk_mul_f32 v[14:15], v[14:15], v[52:53] op_sel_hi:[1,0]
	v_pk_mul_f32 v[12:13], v[12:13], v[52:53] op_sel_hi:[1,0]
	v_pk_mul_f32 v[10:11], v[10:11], v[52:53] op_sel_hi:[1,0]
	v_pk_mul_f32 v[8:9], v[8:9], v[52:53] op_sel_hi:[1,0]
	v_pk_mul_f32 v[6:7], v[6:7], v[52:53] op_sel_hi:[1,0]
	v_pk_mul_f32 v[4:5], v[4:5], v[52:53] op_sel_hi:[1,0]
	v_pk_mul_f32 v[2:3], v[2:3], v[52:53] op_sel_hi:[1,0]
	v_pk_mul_f32 v[0:1], v[0:1], v[52:53] op_sel_hi:[1,0]

.LBB0_569:
	s_or_b64 exec, exec, s[6:7]
	v_add_u32_e32 v126, s9, v153
	v_sub_f32_e32 v55, v40, v47
	v_sub_f32_e32 v40, v22, v47
	v_add_u32_e32 v22, 0x8040, v126
	v_sub_f32_e32 v56, v41, v47
	v_sub_f32_e32 v41, v23, v47
	v_ashrrev_i32_e32 v23, 31, v22
	v_lshlrev_b64 v[22:23], 10, v[22:23]
	v_lshl_add_u64 v[22:23], s[92:93], 0, v[22:23]
	v_lshl_add_u64 v[22:23], v[22:23], 0, s[68:69]
	v_lshl_add_u64 v[22:23], v[22:23], 0, v[98:99]
	global_load_dwordx4 v[68:71], v[22:23], off offset:128
	v_sub_f32_e32 v30, v30, v47
	v_sub_f32_e32 v14, v14, v47
	v_sub_f32_e32 v31, v31, v47
	v_sub_f32_e32 v15, v15, v47
	v_exp_f32_e32 v61, v14
	v_exp_f32_e32 v62, v30
	v_sub_f32_e32 v49, v34, v47
	v_sub_f32_e32 v34, v16, v47
	v_exp_f32_e32 v16, v15
	v_exp_f32_e32 v30, v31
	v_sub_f32_e32 v50, v35, v47
	v_sub_f32_e32 v35, v17, v47
	v_add_f32_e32 v31, v62, v61
	v_mov_b32_e32 v17, v99
	v_sub_f32_e32 v46, v32, v47
	v_pk_add_f32 v[14:15], v[30:31], v[16:17]
	v_sub_f32_e32 v48, v33, v47
	v_pk_add_f32 v[32:33], v[14:15], v[14:15] op_sel_hi:[0,1]
	v_exp_f32_e32 v17, v34
	v_exp_f32_e32 v31, v46
	v_exp_f32_e32 v32, v35
	v_exp_f32_e32 v34, v48
	v_sub_f32_e32 v51, v36, v47
	v_add_f32_e32 v35, v31, v17
	v_sub_f32_e32 v36, v18, v47
	v_pk_add_f32 v[14:15], v[34:35], v[32:33]
	v_sub_f32_e32 v52, v37, v47
	v_sub_f32_e32 v37, v19, v47
	v_pk_add_f32 v[18:19], v[14:15], v[14:15] op_sel_hi:[0,1]
	v_exp_f32_e32 v33, v36
	v_exp_f32_e32 v35, v49
	v_exp_f32_e32 v18, v37
	v_exp_f32_e32 v36, v50
	v_sub_f32_e32 v53, v38, v47
	v_add_f32_e32 v37, v35, v33
	v_sub_f32_e32 v38, v20, v47
	v_pk_add_f32 v[14:15], v[36:37], v[18:19]
	v_sub_f32_e32 v54, v39, v47
	v_sub_f32_e32 v39, v21, v47
	v_pk_add_f32 v[20:21], v[14:15], v[14:15] op_sel_hi:[0,1]
	v_exp_f32_e32 v19, v38
	v_exp_f32_e32 v37, v51
	v_exp_f32_e32 v20, v39
	v_exp_f32_e32 v38, v52
	v_sub_f32_e32 v57, v42, v47
	v_add_f32_e32 v39, v37, v19
	v_sub_f32_e32 v42, v24, v47
	v_pk_add_f32 v[14:15], v[38:39], v[20:21]
	v_exp_f32_e32 v21, v40
	v_pk_add_f32 v[22:23], v[14:15], v[14:15] op_sel_hi:[0,1]
	v_exp_f32_e32 v39, v53
	v_exp_f32_e32 v22, v41
	v_exp_f32_e32 v40, v54
	v_sub_f32_e32 v58, v43, v47
	v_add_f32_e32 v41, v39, v21
	v_sub_f32_e32 v43, v25, v47
	v_pk_add_f32 v[14:15], v[40:41], v[22:23]
	v_exp_f32_e32 v23, v42
	v_pk_add_f32 v[24:25], v[14:15], v[14:15] op_sel_hi:[0,1]
	v_exp_f32_e32 v41, v55
	v_exp_f32_e32 v24, v43
	v_exp_f32_e32 v42, v56
	v_sub_f32_e32 v59, v44, v47
	v_add_f32_e32 v43, v41, v23
	v_sub_f32_e32 v44, v26, v47
	v_pk_add_f32 v[14:15], v[42:43], v[24:25]
	v_sub_f32_e32 v60, v45, v47
	v_sub_f32_e32 v45, v27, v47
	v_pk_add_f32 v[26:27], v[14:15], v[14:15] op_sel_hi:[0,1]
	v_exp_f32_e32 v25, v44
	v_exp_f32_e32 v43, v57
	v_exp_f32_e32 v26, v45
	v_exp_f32_e32 v44, v58
	v_sub_f32_e32 v46, v28, v47
	v_add_f32_e32 v45, v43, v25
	v_sub_f32_e32 v48, v29, v47
	v_pk_add_f32 v[14:15], v[44:45], v[26:27]
	v_exp_f32_e32 v27, v46
	v_pk_add_f32 v[28:29], v[14:15], v[14:15] op_sel_hi:[0,1]
	v_exp_f32_e32 v45, v59
	v_exp_f32_e32 v28, v48
	v_exp_f32_e32 v48, v60
	s_waitcnt lgkmcnt(0)
	s_barrier
	v_add_f32_e32 v49, v45, v27
	v_exp_f32_e64 v0, -v47
	v_pk_add_f32 v[50:51], v[48:49], v[28:29]
	v_cvt_pk_bf16_f32 v74, v61, v16
	v_cvt_pk_bf16_f32 v75, v17, v32
	v_cvt_pk_bf16_f32 v76, v33, v18
	v_cvt_pk_bf16_f32 v77, v19, v20
	v_cvt_pk_bf16_f32 v114, v21, v22
	v_cvt_pk_bf16_f32 v115, v23, v24
	v_cvt_pk_bf16_f32 v116, v25, v26
	v_cvt_pk_bf16_f32 v117, v27, v28
	v_cvt_pk_bf16_f32 v118, v62, v30
	v_cvt_pk_bf16_f32 v119, v31, v34
	ds_read_b128 v[16:19], v149 offset:13312
	ds_read_b128 v[20:23], v149 offset:13344
	ds_read_b128 v[24:27], v149 offset:19968
	ds_read_b128 v[28:31], v149 offset:13376
	ds_read_b128 v[138:141], v149 offset:20000
	ds_read_b128 v[142:145], v149 offset:20032
	v_mul_f32_e32 v0, 0, v0
	v_pk_add_f32 v[50:51], v[50:51], v[50:51] op_sel:[0,1] op_sel_hi:[1,0]
	v_mov_b32_e32 v46, v0
	v_mov_b32_e32 v51, v99
	v_pk_add_f32 v[122:123], v[46:47], v[50:51]
	v_mov_b32_e32 v1, v0
	v_xor_b32_e32 v32, 0x80000000, v123
	v_mov_b32_e32 v2, v0
	v_mov_b32_e32 v3, v0
	v_mov_b32_e32 v4, v0
	v_mov_b32_e32 v5, v0
	v_mov_b32_e32 v6, v0
	v_mov_b32_e32 v7, v0
	v_mov_b32_e32 v8, v0
	v_mov_b32_e32 v9, v0
	v_mov_b32_e32 v10, v0
	v_mov_b32_e32 v11, v0
	v_mov_b32_e32 v12, v0
	v_mov_b32_e32 v13, v0
	v_mov_b32_e32 v14, v0
	v_mov_b32_e32 v15, v0
	v_cvt_pk_bf16_f32 v120, v35, v36
	v_cvt_pk_bf16_f32 v121, v37, v38
	v_cvt_pk_bf16_f32 v128, v39, v40
	v_cvt_pk_bf16_f32 v129, v41, v42
	v_cvt_pk_bf16_f32 v130, v43, v44
	v_cvt_pk_bf16_f32 v131, v45, v48
	v_mov_b32_e32 v33, v32
	v_mov_b32_e32 v34, v32
	v_mov_b32_e32 v35, v32
	v_mov_b32_e32 v36, v32
	v_mov_b32_e32 v37, v32
	v_mov_b32_e32 v38, v32
	v_mov_b32_e32 v39, v32
	v_mov_b32_e32 v40, v32
	v_mov_b32_e32 v41, v32
	v_mov_b32_e32 v42, v32
	v_mov_b32_e32 v43, v32
	v_mov_b32_e32 v44, v32
	v_mov_b32_e32 v45, v32
	v_mov_b32_e32 v46, v32
	v_mov_b32_e32 v47, v32
	s_waitcnt lgkmcnt(5)
	s_nop 0
	v_mfma_f32_32x32x16_bf16 v[48:63], v[16:19], v[106:109], v[32:47]
	s_waitcnt lgkmcnt(3)
	v_mfma_f32_32x32x16_bf16 v[32:47], v[24:27], v[106:109], v[32:47]
	ds_read_b128 v[16:19], v149 offset:13408
	ds_read_b128 v[24:27], v149 offset:20064
	v_mfma_f32_32x32x16_bf16 v[48:63], v[20:23], v[102:105], v[48:63]
	s_waitcnt lgkmcnt(3)
	v_mfma_f32_32x32x16_bf16 v[32:47], v[138:141], v[102:105], v[32:47]
	ds_read_b128 v[20:23], v149 offset:13440
	ds_read_b128 v[138:141], v149 offset:20096
	v_mfma_f32_32x32x16_bf16 v[48:63], v[28:31], v[92:95], v[48:63]
	s_waitcnt lgkmcnt(4)
	v_mfma_f32_32x32x16_bf16 v[32:47], v[142:145], v[92:95], v[32:47]
	ds_read_b128 v[28:31], v149 offset:13472
	ds_read_b128 v[142:145], v149 offset:20128
	s_waitcnt lgkmcnt(5)
	v_mfma_f32_32x32x16_bf16 v[48:63], v[16:19], v[88:91], v[48:63]
	s_waitcnt lgkmcnt(4)
	v_mfma_f32_32x32x16_bf16 v[32:47], v[24:27], v[88:91], v[32:47]
	ds_read_b64_tr_b16 v[156:157], v97 offset:26624
	ds_read_b64_tr_b16 v[158:159], v97 offset:27776
	ds_read_b64_tr_b16 v[162:163], v97 offset:27840
	ds_read_b64_tr_b16 v[160:161], v97 offset:26688
	s_waitcnt lgkmcnt(7)
	v_mfma_f32_32x32x16_bf16 v[48:63], v[20:23], v[84:87], v[48:63]
	s_waitcnt lgkmcnt(6)
	v_mfma_f32_32x32x16_bf16 v[32:47], v[138:141], v[84:87], v[32:47]
	ds_read_b64_tr_b16 v[138:139], v97 offset:28928
	ds_read_b64_tr_b16 v[140:141], v97 offset:30080
	ds_read_b64_tr_b16 v[166:167], v97 offset:30144
	ds_read_b64_tr_b16 v[164:165], v97 offset:28992
	s_waitcnt lgkmcnt(9)
	v_mfma_f32_32x32x16_bf16 v[48:63], v[28:31], v[80:83], v[48:63]
	s_waitcnt lgkmcnt(8)
	v_mfma_f32_32x32x16_bf16 v[32:47], v[142:145], v[80:83], v[32:47]
	ds_read_b64_tr_b16 v[142:143], v97 offset:31232
	ds_read_b64_tr_b16 v[144:145], v97 offset:32384
	ds_read_b64_tr_b16 v[170:171], v97 offset:32448
	ds_read_b64_tr_b16 v[168:169], v97 offset:31296
	s_waitcnt lgkmcnt(10)
	v_mfma_f32_32x32x16_bf16 v[16:31], v[156:159], v[74:77], v[0:15]
	s_waitcnt lgkmcnt(8)
	v_mfma_f32_32x32x16_bf16 v[0:15], v[160:163], v[74:77], v[0:15]
	ds_read_b64_tr_b16 v[74:75], v97 offset:33536
	ds_read_b64_tr_b16 v[76:77], v97 offset:34688
	ds_read_b64_tr_b16 v[158:159], v97 offset:34752
	ds_read_b64_tr_b16 v[156:157], v97 offset:33600
	s_waitcnt lgkmcnt(10)
	v_mfma_f32_32x32x16_bf16 v[16:31], v[138:141], v[114:117], v[16:31]
	s_waitcnt lgkmcnt(8)
	v_mfma_f32_32x32x16_bf16 v[0:15], v[164:167], v[114:117], v[0:15]
	s_waitcnt lgkmcnt(6)
	v_mfma_f32_32x32x16_bf16 v[16:31], v[142:145], v[118:121], v[16:31]
	s_waitcnt lgkmcnt(4)
	v_mfma_f32_32x32x16_bf16 v[0:15], v[168:171], v[118:121], v[0:15]
	s_waitcnt lgkmcnt(2)
	v_mfma_f32_32x32x16_bf16 v[16:31], v[74:77], v[128:131], v[16:31]
	s_waitcnt lgkmcnt(0)
	v_mfma_f32_32x32x16_bf16 v[0:15], v[156:159], v[128:131], v[0:15]
	s_nop 15
	s_nop 7
	s_nop 0
	v_max3_f32 v74, v48, v49, v32
	v_max3_f32 v75, v50, v51, v33
	s_nop 0
	v_max3_f32 v74, v74, v34, v35
	v_max3_f32 v75, v75, v54, v55
	s_nop 0
	v_max3_f32 v74, v74, v52, v53
	v_max3_f32 v75, v75, v38, v39
	s_nop 0
	v_max3_f32 v74, v74, v36, v37
	v_max3_f32 v75, v75, v58, v59
	s_nop 0
	v_max3_f32 v74, v74, v56, v57
	v_max3_f32 v75, v75, v42, v43
	s_nop 0
	v_max3_f32 v74, v74, v40, v41
	v_max3_f32 v75, v75, v62, v63
	s_nop 0
	v_max3_f32 v74, v74, v60, v61
	v_max3_f32 v75, v75, v46, v47
	s_nop 0
	v_max3_f32 v74, v74, v44, v45
	s_nop 0
	v_max3_f32 v74, v74, v75, v75
	v_mov_b32_e32 v75, v74
	s_nop 1
	v_permlane32_swap_b32 v75, v74
	v_max_f32_e32 v74, v74, v75
	s_waitcnt lgkmcnt(0)
	s_nop 0
	v_cmp_lt_f32_e32 vcc, s78, v74
	s_cbranch_vccz .LBB0_571
	v_max_f32_e32 v74, v74, v74
	v_max_f32_e32 v75, 0, v74
	v_exp_f32_e64 v74, -v75
	s_nop 0
	v_pk_add_f32 v[76:77], v[122:123], v[74:75]
	s_nop 0
	v_mov_b32_e32 v76, v75
	v_pk_add_f32 v[48:49], v[48:49], v[76:77] op_sel_hi:[1,0] neg_lo:[0,1] neg_hi:[0,1]
	v_pk_add_f32 v[32:33], v[32:33], v[76:77] op_sel_hi:[1,0] neg_lo:[0,1] neg_hi:[0,1]
	v_pk_add_f32 v[50:51], v[50:51], v[76:77] op_sel_hi:[1,0] neg_lo:[0,1] neg_hi:[0,1]
	v_pk_add_f32 v[34:35], v[34:35], v[76:77] op_sel_hi:[1,0] neg_lo:[0,1] neg_hi:[0,1]
	v_pk_add_f32 v[52:53], v[52:53], v[76:77] op_sel_hi:[1,0] neg_lo:[0,1] neg_hi:[0,1]
	v_pk_add_f32 v[36:37], v[36:37], v[76:77] op_sel_hi:[1,0] neg_lo:[0,1] neg_hi:[0,1]
	v_pk_add_f32 v[54:55], v[54:55], v[76:77] op_sel_hi:[1,0] neg_lo:[0,1] neg_hi:[0,1]
	v_pk_add_f32 v[38:39], v[38:39], v[76:77] op_sel_hi:[1,0] neg_lo:[0,1] neg_hi:[0,1]
	v_pk_add_f32 v[56:57], v[56:57], v[76:77] op_sel_hi:[1,0] neg_lo:[0,1] neg_hi:[0,1]
	v_pk_add_f32 v[40:41], v[40:41], v[76:77] op_sel_hi:[1,0] neg_lo:[0,1] neg_hi:[0,1]
	v_pk_add_f32 v[58:59], v[58:59], v[76:77] op_sel_hi:[1,0] neg_lo:[0,1] neg_hi:[0,1]
	v_pk_add_f32 v[42:43], v[42:43], v[76:77] op_sel_hi:[1,0] neg_lo:[0,1] neg_hi:[0,1]
	v_pk_add_f32 v[60:61], v[60:61], v[76:77] op_sel_hi:[1,0] neg_lo:[0,1] neg_hi:[0,1]
	v_pk_add_f32 v[44:45], v[44:45], v[76:77] op_sel_hi:[1,0] neg_lo:[0,1] neg_hi:[0,1]
	v_pk_add_f32 v[62:63], v[62:63], v[76:77] op_sel_hi:[1,0] neg_lo:[0,1] neg_hi:[0,1]
	v_pk_add_f32 v[46:47], v[46:47], v[76:77] op_sel_hi:[1,0] neg_lo:[0,1] neg_hi:[0,1]
	v_pk_mul_f32 v[30:31], v[30:31], v[74:75] op_sel_hi:[1,0]
	v_pk_mul_f32 v[28:29], v[28:29], v[74:75] op_sel_hi:[1,0]
	v_pk_mul_f32 v[26:27], v[26:27], v[74:75] op_sel_hi:[1,0]
	v_pk_mul_f32 v[24:25], v[24:25], v[74:75] op_sel_hi:[1,0]
	v_pk_mul_f32 v[22:23], v[22:23], v[74:75] op_sel_hi:[1,0]
	v_pk_mul_f32 v[20:21], v[20:21], v[74:75] op_sel_hi:[1,0]
	v_pk_mul_f32 v[18:19], v[18:19], v[74:75] op_sel_hi:[1,0]
	v_pk_mul_f32 v[16:17], v[16:17], v[74:75] op_sel_hi:[1,0]
	v_pk_mul_f32 v[14:15], v[14:15], v[74:75] op_sel_hi:[1,0]
	v_pk_mul_f32 v[12:13], v[12:13], v[74:75] op_sel_hi:[1,0]
	v_pk_mul_f32 v[10:11], v[10:11], v[74:75] op_sel_hi:[1,0]
	v_pk_mul_f32 v[8:9], v[8:9], v[74:75] op_sel_hi:[1,0]
	v_pk_mul_f32 v[6:7], v[6:7], v[74:75] op_sel_hi:[1,0]
	v_pk_mul_f32 v[4:5], v[4:5], v[74:75] op_sel_hi:[1,0]
	v_pk_mul_f32 v[2:3], v[2:3], v[74:75] op_sel_hi:[1,0]
	v_pk_mul_f32 v[0:1], v[0:1], v[74:75] op_sel_hi:[1,0]
	v_mul_f32_e32 v122, v122, v74
	v_mov_b32_e32 v123, v77

.LBB0_575:
	s_or_b64 exec, exec, s[6:7]
	v_exp_f32_e32 v48, v48
	v_exp_f32_e32 v78, v32
	v_exp_f32_e32 v49, v49
	v_exp_f32_e32 v79, v33
	v_exp_f32_e32 v50, v50
	v_exp_f32_e32 v34, v34
	v_exp_f32_e32 v51, v51
	v_exp_f32_e32 v35, v35
	v_add_f32_e32 v32, v78, v48
	v_exp_f32_e32 v52, v52
	v_exp_f32_e32 v36, v36
	v_add_f32_e32 v32, 0, v32
	v_add_f32_e32 v33, v79, v49
	v_add_f32_e32 v32, v33, v32
	v_add_f32_e32 v33, v34, v50
	v_add_f32_e32 v32, v33, v32
	v_add_f32_e32 v33, v35, v51
	v_add_f32_e32 v32, v33, v32
	v_add_f32_e32 v33, v36, v52
	v_add_f32_e32 v74, v33, v32
	v_add_u32_e32 v32, 0x8080, v126
	v_ashrrev_i32_e32 v33, 31, v32
	v_lshlrev_b64 v[32:33], 10, v[32:33]
	v_lshl_add_u64 v[32:33], s[92:93], 0, v[32:33]
	v_lshl_add_u64 v[32:33], v[32:33], 0, s[68:69]
	v_lshl_add_u64 v[32:33], v[32:33], 0, v[98:99]
	global_load_dwordx4 v[68:71], v[32:33], off offset:128
	v_exp_f32_e32 v53, v53
	v_exp_f32_e32 v37, v37
	v_exp_f32_e32 v54, v54
	v_exp_f32_e32 v38, v38
	v_exp_f32_e32 v32, v55
	v_exp_f32_e32 v33, v39
	v_exp_f32_e32 v56, v56
	v_exp_f32_e32 v40, v40
	v_add_f32_e32 v75, v37, v53
	v_exp_f32_e32 v57, v57
	v_exp_f32_e32 v41, v41
	v_add_f32_e32 v39, v75, v74
	v_add_f32_e32 v55, v38, v54
	v_exp_f32_e32 v58, v58
	v_exp_f32_e32 v42, v42
	v_add_f32_e32 v39, v55, v39
	v_add_f32_e32 v55, v33, v32
	v_exp_f32_e32 v59, v59
	v_exp_f32_e32 v43, v43
	v_add_f32_e32 v39, v55, v39
	v_add_f32_e32 v55, v40, v56
	v_exp_f32_e32 v60, v60
	v_exp_f32_e32 v44, v44
	s_waitcnt lgkmcnt(0)
	s_barrier
	v_add_f32_e32 v39, v55, v39
	v_add_f32_e32 v55, v41, v57
	v_exp_f32_e32 v61, v61
	v_exp_f32_e32 v45, v45
	ds_read_b128 v[138:141], v149
	ds_read_b128 v[142:145], v149 offset:32
	ds_read_b128 v[154:157], v149 offset:6656
	ds_read_b128 v[158:161], v149 offset:64
	ds_read_b128 v[162:165], v149 offset:6688
	ds_read_b128 v[166:169], v149 offset:6720
	v_add_f32_e32 v39, v55, v39
	v_add_f32_e32 v55, v42, v58
	v_exp_f32_e32 v62, v62
	v_exp_f32_e32 v46, v46
	v_add_f32_e32 v39, v55, v39
	v_add_f32_e32 v55, v43, v59
	v_exp_f32_e32 v63, v63
	v_exp_f32_e32 v47, v47
	v_add_f32_e32 v39, v55, v39
	v_add_f32_e32 v55, v44, v60
	v_add_f32_e32 v39, v55, v39
	v_add_f32_e32 v55, v45, v61
	v_add_f32_e32 v39, v55, v39
	v_add_f32_e32 v55, v46, v62
	v_add_f32_e32 v39, v55, v39
	v_add_f32_e32 v55, v47, v63
	v_add_f32_e32 v39, v55, v39
	v_cvt_pk_bf16_f32 v77, v54, v32
	v_xor_b32_e32 v32, 0x80000000, v123
	v_add_f32_e32 v122, v122, v39
	v_cvt_pk_bf16_f32 v74, v48, v49
	v_cvt_pk_bf16_f32 v119, v34, v35
	v_cvt_pk_bf16_f32 v120, v36, v37
	v_cvt_pk_bf16_f32 v121, v38, v33
	v_cvt_pk_bf16_f32 v128, v40, v41
	v_cvt_pk_bf16_f32 v129, v42, v43
	v_cvt_pk_bf16_f32 v130, v44, v45
	v_cvt_pk_bf16_f32 v131, v46, v47
	v_mov_b32_e32 v33, v32
	v_mov_b32_e32 v34, v32
	v_mov_b32_e32 v35, v32
	v_mov_b32_e32 v36, v32
	v_mov_b32_e32 v37, v32
	v_mov_b32_e32 v38, v32
	v_mov_b32_e32 v39, v32
	v_mov_b32_e32 v40, v32
	v_mov_b32_e32 v41, v32
	v_mov_b32_e32 v42, v32
	v_mov_b32_e32 v43, v32
	v_mov_b32_e32 v44, v32
	v_mov_b32_e32 v45, v32
	v_mov_b32_e32 v46, v32
	v_mov_b32_e32 v47, v32
	v_cvt_pk_bf16_f32 v75, v50, v51
	v_cvt_pk_bf16_f32 v76, v52, v53
	v_cvt_pk_bf16_f32 v114, v56, v57
	v_cvt_pk_bf16_f32 v115, v58, v59
	v_cvt_pk_bf16_f32 v116, v60, v61
	v_cvt_pk_bf16_f32 v117, v62, v63
	v_cvt_pk_bf16_f32 v118, v78, v79
	s_waitcnt lgkmcnt(5)
	v_mfma_f32_32x32x16_bf16 v[48:63], v[138:141], v[106:109], v[32:47]
	s_waitcnt lgkmcnt(3)
	v_mfma_f32_32x32x16_bf16 v[32:47], v[154:157], v[106:109], v[32:47]
	ds_read_b128 v[138:141], v149 offset:96
	ds_read_b128 v[154:157], v149 offset:6752
	v_mfma_f32_32x32x16_bf16 v[48:63], v[142:145], v[102:105], v[48:63]
	s_waitcnt lgkmcnt(3)
	v_mfma_f32_32x32x16_bf16 v[32:47], v[162:165], v[102:105], v[32:47]
	ds_read_b128 v[142:145], v149 offset:128
	ds_read_b128 v[162:165], v149 offset:6784
	v_mfma_f32_32x32x16_bf16 v[48:63], v[158:161], v[92:95], v[48:63]
	s_waitcnt lgkmcnt(4)
	v_mfma_f32_32x32x16_bf16 v[32:47], v[166:169], v[92:95], v[32:47]
	ds_read_b128 v[158:161], v149 offset:160
	ds_read_b128 v[166:169], v149 offset:6816
	s_waitcnt lgkmcnt(5)
	v_mfma_f32_32x32x16_bf16 v[48:63], v[138:141], v[88:91], v[48:63]
	s_waitcnt lgkmcnt(4)
	v_mfma_f32_32x32x16_bf16 v[32:47], v[154:157], v[88:91], v[32:47]
	ds_read_b64_tr_b16 v[138:139], v97 offset:35840
	ds_read_b64_tr_b16 v[140:141], v97 offset:36992
	ds_read_b64_tr_b16 v[156:157], v97 offset:37056
	ds_read_b64_tr_b16 v[154:155], v97 offset:35904
	s_waitcnt lgkmcnt(7)
	v_mfma_f32_32x32x16_bf16 v[48:63], v[142:145], v[84:87], v[48:63]
	s_waitcnt lgkmcnt(6)
	v_mfma_f32_32x32x16_bf16 v[32:47], v[162:165], v[84:87], v[32:47]
	ds_read_b64_tr_b16 v[142:143], v97 offset:38144
	ds_read_b64_tr_b16 v[144:145], v97 offset:39296
	ds_read_b64_tr_b16 v[164:165], v97 offset:39360
	ds_read_b64_tr_b16 v[162:163], v97 offset:38208
	s_waitcnt lgkmcnt(9)
	v_mfma_f32_32x32x16_bf16 v[48:63], v[158:161], v[80:83], v[48:63]
	s_waitcnt lgkmcnt(8)
	v_mfma_f32_32x32x16_bf16 v[32:47], v[166:169], v[80:83], v[32:47]
	ds_read_b64_tr_b16 v[158:159], v97 offset:40448
	ds_read_b64_tr_b16 v[160:161], v97 offset:41600
	ds_read_b64_tr_b16 v[168:169], v97 offset:41664
	ds_read_b64_tr_b16 v[166:167], v97 offset:40512
	s_waitcnt lgkmcnt(10)
	v_mfma_f32_32x32x16_bf16 v[16:31], v[138:141], v[74:77], v[16:31]
	s_waitcnt lgkmcnt(8)
	v_mfma_f32_32x32x16_bf16 v[0:15], v[154:157], v[74:77], v[0:15]
	ds_read_b64_tr_b16 v[74:75], v97 offset:42752
	ds_read_b64_tr_b16 v[76:77], v97 offset:43904
	ds_read_b64_tr_b16 v[140:141], v97 offset:43968
	ds_read_b64_tr_b16 v[138:139], v97 offset:42816
	s_waitcnt lgkmcnt(10)
	v_mfma_f32_32x32x16_bf16 v[16:31], v[142:145], v[114:117], v[16:31]
	s_waitcnt lgkmcnt(8)
	v_mfma_f32_32x32x16_bf16 v[0:15], v[162:165], v[114:117], v[0:15]
	s_waitcnt lgkmcnt(6)
	v_mfma_f32_32x32x16_bf16 v[16:31], v[158:161], v[118:121], v[16:31]
	s_waitcnt lgkmcnt(4)
	v_mfma_f32_32x32x16_bf16 v[0:15], v[166:169], v[118:121], v[0:15]
	s_waitcnt lgkmcnt(2)
	v_mfma_f32_32x32x16_bf16 v[16:31], v[74:77], v[128:131], v[16:31]
	s_waitcnt lgkmcnt(0)
	v_mfma_f32_32x32x16_bf16 v[0:15], v[138:141], v[128:131], v[0:15]
	s_nop 15
	s_nop 7
	s_nop 0
	v_max3_f32 v74, v48, v49, v32
	v_max3_f32 v75, v50, v51, v33
	s_nop 0
	v_max3_f32 v74, v74, v34, v35
	v_max3_f32 v75, v75, v54, v55
	s_nop 0
	v_max3_f32 v74, v74, v52, v53
	v_max3_f32 v75, v75, v38, v39
	s_nop 0
	v_max3_f32 v74, v74, v36, v37
	v_max3_f32 v75, v75, v58, v59
	s_nop 0
	v_max3_f32 v74, v74, v56, v57
	v_max3_f32 v75, v75, v42, v43
	s_nop 0
	v_max3_f32 v74, v74, v40, v41
	v_max3_f32 v75, v75, v62, v63
	s_nop 0
	v_max3_f32 v74, v74, v60, v61
	v_max3_f32 v75, v75, v46, v47
	s_nop 0
	v_max3_f32 v74, v74, v44, v45
	s_nop 0
	v_max3_f32 v74, v74, v75, v75
	v_mov_b32_e32 v75, v74
	s_nop 1
	v_permlane32_swap_b32 v75, v74
	v_max_f32_e32 v74, v74, v75
	s_waitcnt lgkmcnt(0)
	s_nop 0
	v_cmp_lt_f32_e32 vcc, s78, v74
	s_cbranch_vccz .LBB0_577
	v_max_f32_e32 v74, v74, v74
	v_max_f32_e32 v74, 0, v74
	v_exp_f32_e64 v76, -v74
	v_add_f32_e32 v123, v123, v74
	v_pk_add_f32 v[48:49], v[48:49], v[74:75] op_sel_hi:[1,0] neg_lo:[0,1] neg_hi:[0,1]
	v_pk_add_f32 v[32:33], v[32:33], v[74:75] op_sel_hi:[1,0] neg_lo:[0,1] neg_hi:[0,1]
	v_mul_f32_e32 v122, v122, v76
	v_pk_add_f32 v[50:51], v[50:51], v[74:75] op_sel_hi:[1,0] neg_lo:[0,1] neg_hi:[0,1]
	v_pk_add_f32 v[34:35], v[34:35], v[74:75] op_sel_hi:[1,0] neg_lo:[0,1] neg_hi:[0,1]
	v_pk_add_f32 v[52:53], v[52:53], v[74:75] op_sel_hi:[1,0] neg_lo:[0,1] neg_hi:[0,1]
	v_pk_add_f32 v[36:37], v[36:37], v[74:75] op_sel_hi:[1,0] neg_lo:[0,1] neg_hi:[0,1]
	v_pk_add_f32 v[54:55], v[54:55], v[74:75] op_sel_hi:[1,0] neg_lo:[0,1] neg_hi:[0,1]
	v_pk_add_f32 v[38:39], v[38:39], v[74:75] op_sel_hi:[1,0] neg_lo:[0,1] neg_hi:[0,1]
	v_pk_add_f32 v[56:57], v[56:57], v[74:75] op_sel_hi:[1,0] neg_lo:[0,1] neg_hi:[0,1]
	v_pk_add_f32 v[40:41], v[40:41], v[74:75] op_sel_hi:[1,0] neg_lo:[0,1] neg_hi:[0,1]
	v_pk_add_f32 v[58:59], v[58:59], v[74:75] op_sel_hi:[1,0] neg_lo:[0,1] neg_hi:[0,1]
	v_pk_add_f32 v[42:43], v[42:43], v[74:75] op_sel_hi:[1,0] neg_lo:[0,1] neg_hi:[0,1]
	v_pk_add_f32 v[60:61], v[60:61], v[74:75] op_sel_hi:[1,0] neg_lo:[0,1] neg_hi:[0,1]
	v_pk_add_f32 v[44:45], v[44:45], v[74:75] op_sel_hi:[1,0] neg_lo:[0,1] neg_hi:[0,1]
	v_pk_add_f32 v[62:63], v[62:63], v[74:75] op_sel_hi:[1,0] neg_lo:[0,1] neg_hi:[0,1]
	v_pk_add_f32 v[46:47], v[46:47], v[74:75] op_sel_hi:[1,0] neg_lo:[0,1] neg_hi:[0,1]
	v_pk_mul_f32 v[30:31], v[30:31], v[76:77] op_sel_hi:[1,0]
	v_pk_mul_f32 v[28:29], v[28:29], v[76:77] op_sel_hi:[1,0]
	v_pk_mul_f32 v[26:27], v[26:27], v[76:77] op_sel_hi:[1,0]
	v_pk_mul_f32 v[24:25], v[24:25], v[76:77] op_sel_hi:[1,0]
	v_pk_mul_f32 v[22:23], v[22:23], v[76:77] op_sel_hi:[1,0]
	v_pk_mul_f32 v[20:21], v[20:21], v[76:77] op_sel_hi:[1,0]
	v_pk_mul_f32 v[18:19], v[18:19], v[76:77] op_sel_hi:[1,0]
	v_pk_mul_f32 v[16:17], v[16:17], v[76:77] op_sel_hi:[1,0]
	v_pk_mul_f32 v[14:15], v[14:15], v[76:77] op_sel_hi:[1,0]
	v_pk_mul_f32 v[12:13], v[12:13], v[76:77] op_sel_hi:[1,0]
	v_pk_mul_f32 v[10:11], v[10:11], v[76:77] op_sel_hi:[1,0]
	v_pk_mul_f32 v[8:9], v[8:9], v[76:77] op_sel_hi:[1,0]
	v_pk_mul_f32 v[6:7], v[6:7], v[76:77] op_sel_hi:[1,0]
	v_pk_mul_f32 v[4:5], v[4:5], v[76:77] op_sel_hi:[1,0]
	v_pk_mul_f32 v[2:3], v[2:3], v[76:77] op_sel_hi:[1,0]
	v_pk_mul_f32 v[0:1], v[0:1], v[76:77] op_sel_hi:[1,0]

.LBB0_582:
	s_add_i32 s8, s1, -1
	s_and_b32 s9, s8, 1
	s_mul_i32 s6, s9, 0x3400
	v_add_u32_e32 v98, s6, v149
	ds_read_b128 v[130:133], v98
	ds_read_b128 v[138:141], v98 offset:32
	ds_read_b128 v[142:145], v98 offset:6656
	ds_read_b128 v[152:155], v98 offset:64
	ds_read_b128 v[156:159], v98 offset:6688
	ds_read_b128 v[160:163], v98 offset:6720
	s_and_b32 s6, s1, 1
	v_xor_b32_e32 v32, 0x80000000, v123
	s_mul_i32 s7, s6, 0x2400
	v_mov_b32_e32 v33, v32
	v_mov_b32_e32 v34, v32
	v_mov_b32_e32 v35, v32
	v_mov_b32_e32 v36, v32
	v_mov_b32_e32 v37, v32
	v_mov_b32_e32 v38, v32
	v_mov_b32_e32 v39, v32
	v_mov_b32_e32 v40, v32
	v_mov_b32_e32 v41, v32
	v_mov_b32_e32 v42, v32
	v_mov_b32_e32 v43, v32
	v_mov_b32_e32 v44, v32
	v_mov_b32_e32 v45, v32
	v_mov_b32_e32 v46, v32
	v_mov_b32_e32 v47, v32
	v_add_u32_e32 v125, s7, v97
	s_waitcnt lgkmcnt(5)
	v_mfma_f32_32x32x16_bf16 v[48:63], v[130:133], v[106:109], v[32:47]
	s_waitcnt lgkmcnt(3)
	v_mfma_f32_32x32x16_bf16 v[32:47], v[142:145], v[106:109], v[32:47]
	ds_read_b128 v[130:133], v98 offset:96
	ds_read_b128 v[142:145], v98 offset:6752
	v_mfma_f32_32x32x16_bf16 v[48:63], v[138:141], v[102:105], v[48:63]
	s_waitcnt lgkmcnt(3)
	v_mfma_f32_32x32x16_bf16 v[32:47], v[156:159], v[102:105], v[32:47]
	ds_read_b128 v[138:141], v98 offset:128
	ds_read_b128 v[156:159], v98 offset:6784
	v_mfma_f32_32x32x16_bf16 v[48:63], v[152:155], v[92:95], v[48:63]
	s_waitcnt lgkmcnt(4)
	v_mfma_f32_32x32x16_bf16 v[32:47], v[160:163], v[92:95], v[32:47]
	ds_read_b128 v[152:155], v98 offset:160
	ds_read_b128 v[160:163], v98 offset:6816
	s_waitcnt lgkmcnt(5)
	v_mfma_f32_32x32x16_bf16 v[48:63], v[130:133], v[88:91], v[48:63]
	s_waitcnt lgkmcnt(4)
	v_mfma_f32_32x32x16_bf16 v[32:47], v[142:145], v[88:91], v[32:47]
	ds_read_b64_tr_b16 v[130:131], v125 offset:26624
	ds_read_b64_tr_b16 v[132:133], v125 offset:27776
	ds_read_b64_tr_b16 v[144:145], v125 offset:27840
	ds_read_b64_tr_b16 v[142:143], v125 offset:26688
	s_waitcnt lgkmcnt(7)
	v_mfma_f32_32x32x16_bf16 v[48:63], v[138:141], v[84:87], v[48:63]
	s_waitcnt lgkmcnt(6)
	v_mfma_f32_32x32x16_bf16 v[32:47], v[156:159], v[84:87], v[32:47]
	ds_read_b64_tr_b16 v[138:139], v125 offset:28928
	ds_read_b64_tr_b16 v[140:141], v125 offset:30080
	ds_read_b64_tr_b16 v[158:159], v125 offset:30144
	ds_read_b64_tr_b16 v[156:157], v125 offset:28992
	s_waitcnt lgkmcnt(9)
	v_mfma_f32_32x32x16_bf16 v[48:63], v[152:155], v[80:83], v[48:63]
	s_waitcnt lgkmcnt(8)
	v_mfma_f32_32x32x16_bf16 v[32:47], v[160:163], v[80:83], v[32:47]
	ds_read_b64_tr_b16 v[152:153], v125 offset:31232
	ds_read_b64_tr_b16 v[154:155], v125 offset:32384
	ds_read_b64_tr_b16 v[162:163], v125 offset:32448
	ds_read_b64_tr_b16 v[160:161], v125 offset:31296
	s_waitcnt lgkmcnt(10)
	v_mfma_f32_32x32x16_bf16 v[16:31], v[130:133], v[118:121], v[16:31]
	s_waitcnt lgkmcnt(8)
	v_mfma_f32_32x32x16_bf16 v[0:15], v[142:145], v[118:121], v[0:15]
	ds_read_b64_tr_b16 v[118:119], v125 offset:33536
	ds_read_b64_tr_b16 v[120:121], v125 offset:34688
	ds_read_b64_tr_b16 v[132:133], v125 offset:34752
	ds_read_b64_tr_b16 v[130:131], v125 offset:33600
	s_waitcnt lgkmcnt(10)
	v_mfma_f32_32x32x16_bf16 v[16:31], v[138:141], v[114:117], v[16:31]
	s_waitcnt lgkmcnt(8)
	v_mfma_f32_32x32x16_bf16 v[0:15], v[156:159], v[114:117], v[0:15]
	s_waitcnt lgkmcnt(6)
	v_mfma_f32_32x32x16_bf16 v[16:31], v[152:155], v[76:79], v[16:31]
	s_waitcnt lgkmcnt(4)
	v_mfma_f32_32x32x16_bf16 v[0:15], v[160:163], v[76:79], v[0:15]
	s_waitcnt lgkmcnt(2)
	v_mfma_f32_32x32x16_bf16 v[16:31], v[118:121], v[72:75], v[16:31]
	s_waitcnt lgkmcnt(0)
	v_mfma_f32_32x32x16_bf16 v[0:15], v[130:133], v[72:75], v[0:15]
	s_nop 15
	s_nop 7
	s_nop 0
	v_max3_f32 v72, v48, v49, v32
	v_max3_f32 v73, v50, v51, v33
	s_nop 0
	v_max3_f32 v72, v72, v34, v35
	v_max3_f32 v73, v73, v54, v55
	s_nop 0
	v_max3_f32 v72, v72, v52, v53
	v_max3_f32 v73, v73, v38, v39
	s_nop 0
	v_max3_f32 v72, v72, v36, v37
	v_max3_f32 v73, v73, v58, v59
	s_nop 0
	v_max3_f32 v72, v72, v56, v57
	v_max3_f32 v73, v73, v42, v43
	s_nop 0
	v_max3_f32 v72, v72, v40, v41
	v_max3_f32 v73, v73, v62, v63
	s_nop 0
	v_max3_f32 v72, v72, v60, v61
	v_max3_f32 v73, v73, v46, v47
	s_nop 0
	v_max3_f32 v72, v72, v44, v45
	s_nop 0
	v_max3_f32 v72, v72, v73, v73
	v_mov_b32_e32 v73, v72
	s_nop 1
	v_permlane32_swap_b32 v73, v72
	v_max_f32_e32 v72, v72, v73
	s_waitcnt lgkmcnt(0)
	s_nop 0
	v_cmp_lt_f32_e32 vcc, s78, v72
	s_cbranch_vccz .LBB0_584
	v_max_f32_e32 v72, v72, v72
	v_max_f32_e32 v72, 0, v72
	v_exp_f32_e64 v74, -v72
	v_add_f32_e32 v123, v123, v72
	v_pk_add_f32 v[48:49], v[48:49], v[72:73] op_sel_hi:[1,0] neg_lo:[0,1] neg_hi:[0,1]
	v_pk_add_f32 v[32:33], v[32:33], v[72:73] op_sel_hi:[1,0] neg_lo:[0,1] neg_hi:[0,1]
	v_mul_f32_e32 v122, v122, v74
	v_pk_add_f32 v[50:51], v[50:51], v[72:73] op_sel_hi:[1,0] neg_lo:[0,1] neg_hi:[0,1]
	v_pk_add_f32 v[34:35], v[34:35], v[72:73] op_sel_hi:[1,0] neg_lo:[0,1] neg_hi:[0,1]
	v_pk_add_f32 v[52:53], v[52:53], v[72:73] op_sel_hi:[1,0] neg_lo:[0,1] neg_hi:[0,1]
	v_pk_add_f32 v[36:37], v[36:37], v[72:73] op_sel_hi:[1,0] neg_lo:[0,1] neg_hi:[0,1]
	v_pk_add_f32 v[54:55], v[54:55], v[72:73] op_sel_hi:[1,0] neg_lo:[0,1] neg_hi:[0,1]
	v_pk_add_f32 v[38:39], v[38:39], v[72:73] op_sel_hi:[1,0] neg_lo:[0,1] neg_hi:[0,1]
	v_pk_add_f32 v[56:57], v[56:57], v[72:73] op_sel_hi:[1,0] neg_lo:[0,1] neg_hi:[0,1]
	v_pk_add_f32 v[40:41], v[40:41], v[72:73] op_sel_hi:[1,0] neg_lo:[0,1] neg_hi:[0,1]
	v_pk_add_f32 v[58:59], v[58:59], v[72:73] op_sel_hi:[1,0] neg_lo:[0,1] neg_hi:[0,1]
	v_pk_add_f32 v[42:43], v[42:43], v[72:73] op_sel_hi:[1,0] neg_lo:[0,1] neg_hi:[0,1]
	v_pk_add_f32 v[60:61], v[60:61], v[72:73] op_sel_hi:[1,0] neg_lo:[0,1] neg_hi:[0,1]
	v_pk_add_f32 v[44:45], v[44:45], v[72:73] op_sel_hi:[1,0] neg_lo:[0,1] neg_hi:[0,1]
	v_pk_add_f32 v[62:63], v[62:63], v[72:73] op_sel_hi:[1,0] neg_lo:[0,1] neg_hi:[0,1]
	v_pk_add_f32 v[46:47], v[46:47], v[72:73] op_sel_hi:[1,0] neg_lo:[0,1] neg_hi:[0,1]
	v_pk_mul_f32 v[30:31], v[30:31], v[74:75] op_sel_hi:[1,0]
	v_pk_mul_f32 v[28:29], v[28:29], v[74:75] op_sel_hi:[1,0]
	v_pk_mul_f32 v[26:27], v[26:27], v[74:75] op_sel_hi:[1,0]
	v_pk_mul_f32 v[24:25], v[24:25], v[74:75] op_sel_hi:[1,0]
	v_pk_mul_f32 v[22:23], v[22:23], v[74:75] op_sel_hi:[1,0]
	v_pk_mul_f32 v[20:21], v[20:21], v[74:75] op_sel_hi:[1,0]
	v_pk_mul_f32 v[18:19], v[18:19], v[74:75] op_sel_hi:[1,0]
	v_pk_mul_f32 v[16:17], v[16:17], v[74:75] op_sel_hi:[1,0]
	v_pk_mul_f32 v[14:15], v[14:15], v[74:75] op_sel_hi:[1,0]
	v_pk_mul_f32 v[12:13], v[12:13], v[74:75] op_sel_hi:[1,0]
	v_pk_mul_f32 v[10:11], v[10:11], v[74:75] op_sel_hi:[1,0]
	v_pk_mul_f32 v[8:9], v[8:9], v[74:75] op_sel_hi:[1,0]
	v_pk_mul_f32 v[6:7], v[6:7], v[74:75] op_sel_hi:[1,0]
	v_pk_mul_f32 v[4:5], v[4:5], v[74:75] op_sel_hi:[1,0]
	v_pk_mul_f32 v[2:3], v[2:3], v[74:75] op_sel_hi:[1,0]
	v_pk_mul_f32 v[0:1], v[0:1], v[74:75] op_sel_hi:[1,0]

.LBB0_595:
	s_waitcnt vmcnt(1)
	ds_read_b128 v[64:67], v149 offset:13312
	ds_read_b128 v[110:113], v149 offset:13344
	ds_read_b128 v[124:127], v149 offset:19968
	ds_read_b128 v[128:131], v149 offset:13376
	ds_read_b128 v[138:141], v149 offset:20000
	ds_read_b128 v[142:145], v149 offset:20032
	v_xor_b32_e32 v32, 0x80000000, v123
	v_mov_b32_e32 v33, v32
	v_mov_b32_e32 v34, v32
	v_mov_b32_e32 v35, v32
	v_mov_b32_e32 v36, v32
	v_mov_b32_e32 v37, v32
	v_mov_b32_e32 v38, v32
	v_mov_b32_e32 v39, v32
	v_mov_b32_e32 v40, v32
	v_mov_b32_e32 v41, v32
	v_mov_b32_e32 v42, v32
	v_mov_b32_e32 v43, v32
	v_mov_b32_e32 v44, v32
	v_mov_b32_e32 v45, v32
	v_mov_b32_e32 v46, v32
	v_mov_b32_e32 v47, v32
	s_waitcnt lgkmcnt(5)
	s_nop 0
	v_mfma_f32_32x32x16_bf16 v[48:63], v[64:67], v[106:109], v[32:47]
	s_waitcnt lgkmcnt(3)
	v_mfma_f32_32x32x16_bf16 v[32:47], v[124:127], v[106:109], v[32:47]
	ds_read_b128 v[64:67], v149 offset:13408
	ds_read_b128 v[106:109], v149 offset:20064
	v_mfma_f32_32x32x16_bf16 v[48:63], v[110:113], v[102:105], v[48:63]
	s_waitcnt lgkmcnt(3)
	v_mfma_f32_32x32x16_bf16 v[32:47], v[138:141], v[102:105], v[32:47]
	ds_read_b128 v[100:103], v149 offset:13440
	ds_read_b128 v[110:113], v149 offset:20096
	v_mfma_f32_32x32x16_bf16 v[48:63], v[128:131], v[92:95], v[48:63]
	s_waitcnt lgkmcnt(4)
	v_mfma_f32_32x32x16_bf16 v[32:47], v[142:145], v[92:95], v[32:47]
	ds_read_b128 v[92:95], v149 offset:13472
	ds_read_b128 v[124:127], v149 offset:20128
	s_waitcnt lgkmcnt(5)
	v_mfma_f32_32x32x16_bf16 v[48:63], v[64:67], v[88:91], v[48:63]
	s_waitcnt lgkmcnt(4)
	v_mfma_f32_32x32x16_bf16 v[32:47], v[106:109], v[88:91], v[32:47]
	ds_read_b64_tr_b16 v[64:65], v97 offset:26624
	ds_read_b64_tr_b16 v[66:67], v97 offset:27776
	ds_read_b64_tr_b16 v[90:91], v97 offset:27840
	ds_read_b64_tr_b16 v[88:89], v97 offset:26688
	s_waitcnt lgkmcnt(7)
	v_mfma_f32_32x32x16_bf16 v[48:63], v[100:103], v[84:87], v[48:63]
	s_waitcnt lgkmcnt(6)
	v_mfma_f32_32x32x16_bf16 v[32:47], v[110:113], v[84:87], v[32:47]
	ds_read_b64_tr_b16 v[84:85], v97 offset:28928
	ds_read_b64_tr_b16 v[86:87], v97 offset:30080
	ds_read_b64_tr_b16 v[102:103], v97 offset:30144
	ds_read_b64_tr_b16 v[100:101], v97 offset:28992
	s_waitcnt lgkmcnt(9)
	v_mfma_f32_32x32x16_bf16 v[48:63], v[92:95], v[80:83], v[48:63]
	s_waitcnt lgkmcnt(8)
	v_mfma_f32_32x32x16_bf16 v[32:47], v[124:127], v[80:83], v[32:47]
	ds_read_b64_tr_b16 v[80:81], v97 offset:31232
	ds_read_b64_tr_b16 v[82:83], v97 offset:32384
	ds_read_b64_tr_b16 v[94:95], v97 offset:32448
	ds_read_b64_tr_b16 v[92:93], v97 offset:31296
	s_waitcnt lgkmcnt(10)
	v_mfma_f32_32x32x16_bf16 v[16:31], v[64:67], v[118:121], v[16:31]
	s_waitcnt lgkmcnt(8)
	v_mfma_f32_32x32x16_bf16 v[0:15], v[88:91], v[118:121], v[0:15]
	ds_read_b64_tr_b16 v[64:65], v97 offset:33536
	ds_read_b64_tr_b16 v[66:67], v97 offset:34688
	ds_read_b64_tr_b16 v[90:91], v97 offset:34752
	ds_read_b64_tr_b16 v[88:89], v97 offset:33600
	s_waitcnt lgkmcnt(10)
	v_mfma_f32_32x32x16_bf16 v[16:31], v[84:87], v[114:117], v[16:31]
	s_waitcnt lgkmcnt(8)
	v_mfma_f32_32x32x16_bf16 v[0:15], v[100:103], v[114:117], v[0:15]
	s_waitcnt lgkmcnt(6)
	v_mfma_f32_32x32x16_bf16 v[16:31], v[80:83], v[76:79], v[16:31]
	s_waitcnt lgkmcnt(4)
	v_mfma_f32_32x32x16_bf16 v[0:15], v[92:95], v[76:79], v[0:15]
	s_waitcnt lgkmcnt(2)
	v_mfma_f32_32x32x16_bf16 v[16:31], v[64:67], v[72:75], v[16:31]
	s_waitcnt lgkmcnt(0)
	v_mfma_f32_32x32x16_bf16 v[0:15], v[88:91], v[72:75], v[0:15]
	s_nop 15
	s_nop 7
	s_nop 0
	v_max3_f32 v64, v48, v49, v32
	v_max3_f32 v65, v50, v51, v33
	s_nop 0
	v_max3_f32 v64, v64, v34, v35
	v_max3_f32 v65, v65, v54, v55
	s_nop 0
	v_max3_f32 v64, v64, v52, v53
	v_max3_f32 v65, v65, v38, v39
	s_nop 0
	v_max3_f32 v64, v64, v36, v37
	v_max3_f32 v65, v65, v58, v59
	s_nop 0
	v_max3_f32 v64, v64, v56, v57
	v_max3_f32 v65, v65, v42, v43
	s_nop 0
	v_max3_f32 v64, v64, v40, v41
	v_max3_f32 v65, v65, v62, v63
	s_nop 0
	v_max3_f32 v64, v64, v60, v61
	v_max3_f32 v65, v65, v46, v47
	s_nop 0
	v_max3_f32 v64, v64, v44, v45
	s_nop 0
	v_max3_f32 v64, v64, v65, v65
	v_mov_b32_e32 v65, v64
	s_nop 1
	v_permlane32_swap_b32 v65, v64
	v_max_f32_e32 v64, v64, v65
	s_waitcnt lgkmcnt(0)
	s_nop 0
	v_cmp_lt_f32_e32 vcc, s78, v64
	s_cbranch_vccz .LBB0_93
	v_max_f32_e32 v64, v64, v64
	v_max_f32_e32 v64, 0, v64
	v_exp_f32_e64 v66, -v64
	v_pk_add_f32 v[48:49], v[48:49], v[64:65] op_sel_hi:[1,0] neg_lo:[0,1] neg_hi:[0,1]
	v_pk_add_f32 v[32:33], v[32:33], v[64:65] op_sel_hi:[1,0] neg_lo:[0,1] neg_hi:[0,1]
	v_pk_add_f32 v[50:51], v[50:51], v[64:65] op_sel_hi:[1,0] neg_lo:[0,1] neg_hi:[0,1]
	v_mul_f32_e32 v122, v122, v66
	v_pk_add_f32 v[34:35], v[34:35], v[64:65] op_sel_hi:[1,0] neg_lo:[0,1] neg_hi:[0,1]
	v_pk_add_f32 v[52:53], v[52:53], v[64:65] op_sel_hi:[1,0] neg_lo:[0,1] neg_hi:[0,1]
	v_pk_add_f32 v[36:37], v[36:37], v[64:65] op_sel_hi:[1,0] neg_lo:[0,1] neg_hi:[0,1]
	v_pk_add_f32 v[54:55], v[54:55], v[64:65] op_sel_hi:[1,0] neg_lo:[0,1] neg_hi:[0,1]
	v_pk_add_f32 v[38:39], v[38:39], v[64:65] op_sel_hi:[1,0] neg_lo:[0,1] neg_hi:[0,1]
	v_pk_add_f32 v[56:57], v[56:57], v[64:65] op_sel_hi:[1,0] neg_lo:[0,1] neg_hi:[0,1]
	v_pk_add_f32 v[40:41], v[40:41], v[64:65] op_sel_hi:[1,0] neg_lo:[0,1] neg_hi:[0,1]
	v_pk_add_f32 v[58:59], v[58:59], v[64:65] op_sel_hi:[1,0] neg_lo:[0,1] neg_hi:[0,1]
	v_pk_add_f32 v[42:43], v[42:43], v[64:65] op_sel_hi:[1,0] neg_lo:[0,1] neg_hi:[0,1]
	v_pk_add_f32 v[60:61], v[60:61], v[64:65] op_sel_hi:[1,0] neg_lo:[0,1] neg_hi:[0,1]
	v_pk_add_f32 v[44:45], v[44:45], v[64:65] op_sel_hi:[1,0] neg_lo:[0,1] neg_hi:[0,1]
	v_pk_add_f32 v[62:63], v[62:63], v[64:65] op_sel_hi:[1,0] neg_lo:[0,1] neg_hi:[0,1]
	v_pk_add_f32 v[46:47], v[46:47], v[64:65] op_sel_hi:[1,0] neg_lo:[0,1] neg_hi:[0,1]
	v_pk_mul_f32 v[30:31], v[30:31], v[66:67] op_sel_hi:[1,0]
	v_pk_mul_f32 v[28:29], v[28:29], v[66:67] op_sel_hi:[1,0]
	v_pk_mul_f32 v[26:27], v[26:27], v[66:67] op_sel_hi:[1,0]
	v_pk_mul_f32 v[24:25], v[24:25], v[66:67] op_sel_hi:[1,0]
	v_pk_mul_f32 v[22:23], v[22:23], v[66:67] op_sel_hi:[1,0]
	v_pk_mul_f32 v[20:21], v[20:21], v[66:67] op_sel_hi:[1,0]
	v_pk_mul_f32 v[18:19], v[18:19], v[66:67] op_sel_hi:[1,0]
	v_pk_mul_f32 v[16:17], v[16:17], v[66:67] op_sel_hi:[1,0]
	v_pk_mul_f32 v[14:15], v[14:15], v[66:67] op_sel_hi:[1,0]
	v_pk_mul_f32 v[12:13], v[12:13], v[66:67] op_sel_hi:[1,0]
	v_pk_mul_f32 v[10:11], v[10:11], v[66:67] op_sel_hi:[1,0]
	v_pk_mul_f32 v[8:9], v[8:9], v[66:67] op_sel_hi:[1,0]
	v_pk_mul_f32 v[6:7], v[6:7], v[66:67] op_sel_hi:[1,0]
	v_pk_mul_f32 v[4:5], v[4:5], v[66:67] op_sel_hi:[1,0]
	v_pk_mul_f32 v[2:3], v[2:3], v[66:67] op_sel_hi:[1,0]
	v_pk_mul_f32 v[0:1], v[0:1], v[66:67] op_sel_hi:[1,0]
	s_branch .LBB0_93
